# S5 power tables stored lane-major (every table load is 1 KiB contiguous instead of 64 cache lines); row-wise phases hand-written
# speedup vs baseline: 1.4054x; 1.0261x over previous
.Lss3_body:
	s_mul_i32 s10, s36, 0xf0f1
	s_lshr_b32 s10, s10, 22
	s_mul_i32 s11, s10, 68
	s_sub_i32 s8, s36, s11
	s_and_b32 s7, s10, 15
	s_lshr_b32 s6, s10, 4
	s_lshl_b32 s10, s8, 6
	s_lshl_b32 s11, s6, 8
	s_add_i32 s9, s10, s11
	s_lshl_b32 s11, s6, 12
	s_add_i32 s11, s11, s10
	s_add_i32 s11, s11, 0x300
	s_cmp_lt_u32 s8, 4
	s_cselect_b32 s9, s9, s11
	v_mov_b32_e32 v0, 0
	v_mov_b32_e32 v1, 0
	v_mov_b32_e32 v2, 0
	v_mov_b32_e32 v3, 0
	v_mov_b32_e32 v4, 0
	v_mov_b32_e32 v5, 0
	v_mov_b32_e32 v6, 0
	v_mov_b32_e32 v7, 0
	v_mov_b32_e32 v8, 0
	v_mov_b32_e32 v9, 0
	v_mov_b32_e32 v10, 0
	v_mov_b32_e32 v11, 0
	v_mov_b32_e32 v12, 0
	v_mov_b32_e32 v13, 0
	v_mov_b32_e32 v14, 0
	v_mov_b32_e32 v15, 0
	v_and_b32_e32 v207, 15, v205
	v_mul_u32_u24_e32 v207, 0xe00, v207
	v_and_b32_e32 v208, 16, v205
	v_add_u32_e32 v207, v207, v208
	s_mul_i32 s18, s9, 0xe00
	s_lshl_b32 s19, s7, 5
	s_add_i32 s18, s18, s19
	s_add_u32 s18, s18, 0x5e00c00
	s_add_u32 s18, s4, s18
	s_addc_u32 s19, s5, 0
	s_mov_b32 exec_hi, 0
	global_load_dwordx4 v[0:3], v207, s[18:19]
	s_add_u32 s18, s18, 0xe000
	s_addc_u32 s19, s19, 0
	global_load_dwordx4 v[4:7], v207, s[18:19]
	s_add_u32 s18, s18, 0xe000
	s_addc_u32 s19, s19, 0
	global_load_dwordx4 v[8:11], v207, s[18:19]
	s_add_u32 s18, s18, 0xe000
	s_addc_u32 s19, s19, 0
	global_load_dwordx4 v[12:15], v207, s[18:19]
	s_mov_b64 exec, -1
	v_mov_b32_e32 v64, 0
	v_mov_b32_e32 v65, 0
	v_mov_b32_e32 v66, 0
	v_mov_b32_e32 v67, 0
	v_mov_b32_e32 v68, 0
	v_mov_b32_e32 v69, 0
	v_mov_b32_e32 v70, 0
	v_mov_b32_e32 v71, 0
	v_mov_b32_e32 v72, 0
	v_mov_b32_e32 v73, 0
	v_mov_b32_e32 v74, 0
	v_mov_b32_e32 v75, 0
	v_mov_b32_e32 v76, 0
	v_mov_b32_e32 v77, 0
	v_mov_b32_e32 v78, 0
	v_mov_b32_e32 v79, 0
	v_lshlrev_b32_e32 v134, 4, v205
	v_add_u32_e32 v208, 0x1000, v134
	v_and_b32_e32 v135, 15, v205
	v_lshlrev_b32_e32 v136, 8, v135
	v_lshlrev_b32_e32 v135, 6, v135
	v_and_b32_e32 v207, 16, v205
	v_lshl_add_u32 v135, v207, 1, v135
	v_lshrrev_b32_e32 v207, 4, v205
	v_lshl_add_u32 v136, v207, 4, v136
	v_lshlrev_b32_e32 v206, 5, v207
	v_readlane_b32 s10, v247, 28
	s_mov_b32 s11, s8
	s_lshl_b32 s16, s10, 1
	s_add_i32 s16, s16, 0
	s_lshl_b32 s16, s16, 4
	s_add_i32 s16, s16, s7
	s_lshl_b32 s17, s6, 1
	s_add_i32 s17, s17, 0
	s_lshl_b32 s17, s17, 4
	s_add_i32 s17, s17, s7
	s_mul_i32 s17, s17, 68
	s_add_i32 s17, s17, s11
	s_lshl_b32 s17, s17, 6
	s_lshl_b32 s20, s16, 12
	s_add_u32 s20, s20, 0x11fb20
	s_add_u32 s20, s4, s20
	s_addc_u32 s21, s5, 0
	s_add_u32 s22, s20, 0x40000
	s_addc_u32 s23, s21, 0
	s_lshl_b32 s38, s16, 12
	s_add_u32 s38, s38, 0x19fb20
	s_add_u32 s38, s4, s38
	s_addc_u32 s39, s5, 0
	s_add_u32 s40, s38, 0x40000
	s_addc_u32 s41, s39, 0
	s_lshl_b32 s42, s16, 15
	s_add_u32 s42, s42, 0xf900000
	s_add_u32 s42, s4, s42
	s_addc_u32 s43, s5, 0
	s_lshl_b32 s44, s17, 3
	s_add_u32 s44, s44, 0x740000
	s_add_u32 s44, s4, s44
	s_addc_u32 s45, s5, 0
	s_mov_b32 exec_hi, 0
	global_load_dwordx4 v[64:67], v135, s[20:21]
	global_load_dwordx4 v[68:71], v135, s[20:21] offset:16
	global_load_dwordx4 v[72:75], v135, s[22:23]
	global_load_dwordx4 v[76:79], v135, s[22:23] offset:16
	s_mov_b64 exec, -1
	s_add_u32 s20, s20, 0x400
	s_addc_u32 s21, s21, 0
	s_add_u32 s22, s22, 0x400
	s_addc_u32 s23, s23, 0
	global_load_dwordx4 v[138:141], v134, s[42:43] offset:0
	global_load_dwordx4 v[142:145], v134, s[42:43] offset:1024
	global_load_dwordx4 v[146:149], v134, s[42:43] offset:2048
	global_load_dwordx4 v[150:153], v134, s[42:43] offset:3072
	global_load_dwordx4 v[154:157], v208, s[42:43] offset:0
	global_load_dwordx4 v[158:161], v208, s[42:43] offset:1024
	global_load_dwordx4 v[162:165], v208, s[42:43] offset:2048
	global_load_dwordx4 v[166:169], v208, s[42:43] offset:3072
	global_load_dwordx4 v[170:173], v206, s[44:45]
	global_load_dwordx4 v[174:177], v206, s[44:45] offset:16
	s_add_u32 s42, s42, 0x2000
	s_addc_u32 s43, s43, 0
	s_add_u32 s44, s44, 0x80
	s_addc_u32 s45, s45, 0
	s_waitcnt vmcnt(14)
	s_waitcnt vmcnt(10)
	v_cvt_pk_bf16_f32 v64, v64, v65
	v_cvt_pk_bf16_f32 v65, v66, v67
	v_cvt_pk_bf16_f32 v66, v68, v69
	v_cvt_pk_bf16_f32 v67, v70, v71
	v_cvt_pk_bf16_f32 v72, v72, v73
	v_cvt_pk_bf16_f32 v73, v74, v75
	v_cvt_pk_bf16_f32 v74, v76, v77
	v_cvt_pk_bf16_f32 v75, v78, v79
	global_load_dwordx4 v[80:83], v136, s[38:39]
	global_load_dwordx4 v[84:87], v136, s[40:41]
	s_add_u32 s38, s38, 0x40
	s_addc_u32 s39, s39, 0
	s_add_u32 s40, s40, 0x40
	s_addc_u32 s41, s41, 0
	s_nop 0
	v_mfma_f32_16x16x32_bf16 v[32:35], v[64:67], v[0:3], 0
	v_mfma_f32_16x16x32_bf16 v[36:39], v[72:75], v[0:3], 0
	v_mfma_f32_16x16x32_bf16 v[40:43], v[64:67], v[4:7], 0
	v_mfma_f32_16x16x32_bf16 v[44:47], v[72:75], v[4:7], 0
	v_mfma_f32_16x16x32_bf16 v[48:51], v[64:67], v[8:11], 0
	v_mfma_f32_16x16x32_bf16 v[52:55], v[72:75], v[8:11], 0
	v_mfma_f32_16x16x32_bf16 v[56:59], v[64:67], v[12:15], 0
	v_mfma_f32_16x16x32_bf16 v[60:63], v[72:75], v[12:15], 0
	s_mov_b32 exec_hi, 0
	global_load_dwordx4 v[64:67], v135, s[20:21]
	global_load_dwordx4 v[68:71], v135, s[20:21] offset:16
	global_load_dwordx4 v[72:75], v135, s[22:23]
	global_load_dwordx4 v[76:79], v135, s[22:23] offset:16
	s_mov_b64 exec, -1
	s_add_u32 s20, s20, 0x400
	s_addc_u32 s21, s21, 0
	s_add_u32 s22, s22, 0x400
	s_addc_u32 s23, s23, 0
	global_load_dwordx4 v[100:103], v134, s[42:43] offset:0
	global_load_dwordx4 v[104:107], v134, s[42:43] offset:1024
	global_load_dwordx4 v[108:111], v134, s[42:43] offset:2048
	global_load_dwordx4 v[112:115], v134, s[42:43] offset:3072
	global_load_dwordx4 v[116:119], v208, s[42:43] offset:0
	global_load_dwordx4 v[120:123], v208, s[42:43] offset:1024
	global_load_dwordx4 v[124:127], v208, s[42:43] offset:2048
	global_load_dwordx4 v[128:131], v208, s[42:43] offset:3072
	global_load_dwordx4 v[178:181], v206, s[44:45]
	global_load_dwordx4 v[182:185], v206, s[44:45] offset:16
	s_add_u32 s42, s42, 0x2000
	s_addc_u32 s43, s43, 0
	s_add_u32 s44, s44, 0x80
	s_addc_u32 s45, s45, 0
	s_waitcnt vmcnt(16)
	v_mul_f32_e32 v132, v171, v157
	v_mul_f32_e32 v133, v170, v157
	v_fma_f32 v170, v170, v156, -v132
	v_fma_f32 v171, v171, v156, v133
	v_mul_f32_e32 v132, v173, v161
	v_mul_f32_e32 v133, v172, v161
	v_fma_f32 v172, v172, v160, -v132
	v_fma_f32 v173, v173, v160, v133
	v_mul_f32_e32 v132, v175, v165
	v_mul_f32_e32 v133, v174, v165
	v_fma_f32 v174, v174, v164, -v132
	v_fma_f32 v175, v175, v164, v133
	v_mul_f32_e32 v132, v177, v169
	v_mul_f32_e32 v133, v176, v169
	v_fma_f32 v176, v176, v168, -v132
	v_fma_f32 v177, v177, v168, v133
	v_mul_f32_e32 v132, v32, v139
	v_mul_f32_e32 v32, v32, v138
	v_fma_f32 v32, -v36, v139, v32
	v_fma_f32 v36, v36, v138, v132
	v_mul_f32_e32 v133, v33, v143
	v_mul_f32_e32 v33, v33, v142
	v_fma_f32 v33, -v37, v143, v33
	v_fma_f32 v37, v37, v142, v133
	v_mul_f32_e32 v132, v34, v147
	v_mul_f32_e32 v34, v34, v146
	v_fma_f32 v34, -v38, v147, v34
	v_fma_f32 v38, v38, v146, v132
	v_mul_f32_e32 v133, v35, v151
	v_mul_f32_e32 v35, v35, v150
	v_fma_f32 v35, -v39, v151, v35
	v_fma_f32 v39, v39, v150, v133
	v_add_f32_dpp v32, v32, v32 row_shr:1 row_mask:0xf bank_mask:0xf bound_ctrl:1
	v_add_f32_dpp v33, v33, v33 row_shr:1 row_mask:0xf bank_mask:0xf bound_ctrl:1
	v_add_f32_dpp v34, v34, v34 row_shr:1 row_mask:0xf bank_mask:0xf bound_ctrl:1
	v_add_f32_dpp v35, v35, v35 row_shr:1 row_mask:0xf bank_mask:0xf bound_ctrl:1
	v_add_f32_dpp v36, v36, v36 row_shr:1 row_mask:0xf bank_mask:0xf bound_ctrl:1
	v_add_f32_dpp v37, v37, v37 row_shr:1 row_mask:0xf bank_mask:0xf bound_ctrl:1
	v_add_f32_dpp v38, v38, v38 row_shr:1 row_mask:0xf bank_mask:0xf bound_ctrl:1
	v_add_f32_dpp v39, v39, v39 row_shr:1 row_mask:0xf bank_mask:0xf bound_ctrl:1
	v_add_f32_dpp v32, v32, v32 row_shr:2 row_mask:0xf bank_mask:0xf bound_ctrl:1
	v_add_f32_dpp v33, v33, v33 row_shr:2 row_mask:0xf bank_mask:0xf bound_ctrl:1
	v_add_f32_dpp v34, v34, v34 row_shr:2 row_mask:0xf bank_mask:0xf bound_ctrl:1
	v_add_f32_dpp v35, v35, v35 row_shr:2 row_mask:0xf bank_mask:0xf bound_ctrl:1
	v_add_f32_dpp v36, v36, v36 row_shr:2 row_mask:0xf bank_mask:0xf bound_ctrl:1
	v_add_f32_dpp v37, v37, v37 row_shr:2 row_mask:0xf bank_mask:0xf bound_ctrl:1
	v_add_f32_dpp v38, v38, v38 row_shr:2 row_mask:0xf bank_mask:0xf bound_ctrl:1
	v_add_f32_dpp v39, v39, v39 row_shr:2 row_mask:0xf bank_mask:0xf bound_ctrl:1
	v_add_f32_dpp v32, v32, v32 row_shr:4 row_mask:0xf bank_mask:0xf bound_ctrl:1
	v_add_f32_dpp v33, v33, v33 row_shr:4 row_mask:0xf bank_mask:0xf bound_ctrl:1
	v_add_f32_dpp v34, v34, v34 row_shr:4 row_mask:0xf bank_mask:0xf bound_ctrl:1
	v_add_f32_dpp v35, v35, v35 row_shr:4 row_mask:0xf bank_mask:0xf bound_ctrl:1
	v_add_f32_dpp v36, v36, v36 row_shr:4 row_mask:0xf bank_mask:0xf bound_ctrl:1
	v_add_f32_dpp v37, v37, v37 row_shr:4 row_mask:0xf bank_mask:0xf bound_ctrl:1
	v_add_f32_dpp v38, v38, v38 row_shr:4 row_mask:0xf bank_mask:0xf bound_ctrl:1
	v_add_f32_dpp v39, v39, v39 row_shr:4 row_mask:0xf bank_mask:0xf bound_ctrl:1
	v_add_f32_dpp v32, v32, v32 row_shr:8 row_mask:0xf bank_mask:0xf bound_ctrl:1
	v_add_f32_dpp v33, v33, v33 row_shr:8 row_mask:0xf bank_mask:0xf bound_ctrl:1
	v_add_f32_dpp v34, v34, v34 row_shr:8 row_mask:0xf bank_mask:0xf bound_ctrl:1
	v_add_f32_dpp v35, v35, v35 row_shr:8 row_mask:0xf bank_mask:0xf bound_ctrl:1
	v_add_f32_dpp v36, v36, v36 row_shr:8 row_mask:0xf bank_mask:0xf bound_ctrl:1
	v_add_f32_dpp v37, v37, v37 row_shr:8 row_mask:0xf bank_mask:0xf bound_ctrl:1
	v_add_f32_dpp v38, v38, v38 row_shr:8 row_mask:0xf bank_mask:0xf bound_ctrl:1
	v_add_f32_dpp v39, v39, v39 row_shr:8 row_mask:0xf bank_mask:0xf bound_ctrl:1
	v_mov_b32_dpp v88, v32 row_newbcast:15 row_mask:0xf bank_mask:0xf
	v_mov_b32_dpp v89, v33 row_newbcast:15 row_mask:0xf bank_mask:0xf
	v_mov_b32_dpp v90, v34 row_newbcast:15 row_mask:0xf bank_mask:0xf
	v_mov_b32_dpp v91, v35 row_newbcast:15 row_mask:0xf bank_mask:0xf
	v_mov_b32_dpp v92, v36 row_newbcast:15 row_mask:0xf bank_mask:0xf
	v_mov_b32_dpp v93, v37 row_newbcast:15 row_mask:0xf bank_mask:0xf
	v_mov_b32_dpp v94, v38 row_newbcast:15 row_mask:0xf bank_mask:0xf
	v_mov_b32_dpp v95, v39 row_newbcast:15 row_mask:0xf bank_mask:0xf
	v_add_f32_e32 v32, v32, v170
	v_add_f32_e32 v36, v36, v171
	v_add_f32_e32 v33, v33, v172
	v_add_f32_e32 v37, v37, v173
	v_add_f32_e32 v34, v34, v174
	v_add_f32_e32 v38, v38, v175
	v_add_f32_e32 v35, v35, v176
	v_add_f32_e32 v39, v39, v177
	v_mul_f32_e32 v132, v32, v141
	v_mul_f32_e32 v32, v32, v140
	v_fma_f32 v32, -v36, v141, v32
	v_fma_f32 v36, v36, v140, v132
	v_mul_f32_e32 v133, v33, v145
	v_mul_f32_e32 v33, v33, v144
	v_fma_f32 v33, -v37, v145, v33
	v_fma_f32 v37, v37, v144, v133
	v_mul_f32_e32 v132, v34, v149
	v_mul_f32_e32 v34, v34, v148
	v_fma_f32 v34, -v38, v149, v34
	v_fma_f32 v38, v38, v148, v132
	v_mul_f32_e32 v133, v35, v153
	v_mul_f32_e32 v35, v35, v152
	v_fma_f32 v35, -v39, v153, v35
	v_fma_f32 v39, v39, v152, v133
	v_add_f32_e32 v88, v88, v170
	v_add_f32_e32 v92, v92, v171
	v_mul_f32_e32 v132, v92, v155
	v_mul_f32_e32 v171, v88, v155
	v_fma_f32 v170, v88, v154, -v132
	v_fma_f32 v171, v92, v154, v171
	v_add_f32_e32 v89, v89, v172
	v_add_f32_e32 v93, v93, v173
	v_mul_f32_e32 v133, v93, v159
	v_mul_f32_e32 v173, v89, v159
	v_fma_f32 v172, v89, v158, -v133
	v_fma_f32 v173, v93, v158, v173
	v_add_f32_e32 v90, v90, v174
	v_add_f32_e32 v94, v94, v175
	v_mul_f32_e32 v132, v94, v163
	v_mul_f32_e32 v175, v90, v163
	v_fma_f32 v174, v90, v162, -v132
	v_fma_f32 v175, v94, v162, v175
	v_add_f32_e32 v91, v91, v176
	v_add_f32_e32 v95, v95, v177
	v_mul_f32_e32 v133, v95, v167
	v_mul_f32_e32 v177, v91, v167
	v_fma_f32 v176, v91, v166, -v133
	v_fma_f32 v177, v95, v166, v177
	v_mul_f32_e32 v132, v40, v139
	v_mul_f32_e32 v40, v40, v138
	v_fma_f32 v40, -v44, v139, v40
	v_fma_f32 v44, v44, v138, v132
	v_mul_f32_e32 v133, v41, v143
	v_mul_f32_e32 v41, v41, v142
	v_fma_f32 v41, -v45, v143, v41
	v_fma_f32 v45, v45, v142, v133
	v_mul_f32_e32 v132, v42, v147
	v_mul_f32_e32 v42, v42, v146
	v_fma_f32 v42, -v46, v147, v42
	v_fma_f32 v46, v46, v146, v132
	v_mul_f32_e32 v133, v43, v151
	v_mul_f32_e32 v43, v43, v150
	v_fma_f32 v43, -v47, v151, v43
	v_fma_f32 v47, v47, v150, v133
	v_add_f32_dpp v40, v40, v40 row_shr:1 row_mask:0xf bank_mask:0xf bound_ctrl:1
	v_add_f32_dpp v41, v41, v41 row_shr:1 row_mask:0xf bank_mask:0xf bound_ctrl:1
	v_add_f32_dpp v42, v42, v42 row_shr:1 row_mask:0xf bank_mask:0xf bound_ctrl:1
	v_add_f32_dpp v43, v43, v43 row_shr:1 row_mask:0xf bank_mask:0xf bound_ctrl:1
	v_add_f32_dpp v44, v44, v44 row_shr:1 row_mask:0xf bank_mask:0xf bound_ctrl:1
	v_add_f32_dpp v45, v45, v45 row_shr:1 row_mask:0xf bank_mask:0xf bound_ctrl:1
	v_add_f32_dpp v46, v46, v46 row_shr:1 row_mask:0xf bank_mask:0xf bound_ctrl:1
	v_add_f32_dpp v47, v47, v47 row_shr:1 row_mask:0xf bank_mask:0xf bound_ctrl:1
	v_add_f32_dpp v40, v40, v40 row_shr:2 row_mask:0xf bank_mask:0xf bound_ctrl:1
	v_add_f32_dpp v41, v41, v41 row_shr:2 row_mask:0xf bank_mask:0xf bound_ctrl:1
	v_add_f32_dpp v42, v42, v42 row_shr:2 row_mask:0xf bank_mask:0xf bound_ctrl:1
	v_add_f32_dpp v43, v43, v43 row_shr:2 row_mask:0xf bank_mask:0xf bound_ctrl:1
	v_add_f32_dpp v44, v44, v44 row_shr:2 row_mask:0xf bank_mask:0xf bound_ctrl:1
	v_add_f32_dpp v45, v45, v45 row_shr:2 row_mask:0xf bank_mask:0xf bound_ctrl:1
	v_add_f32_dpp v46, v46, v46 row_shr:2 row_mask:0xf bank_mask:0xf bound_ctrl:1
	v_add_f32_dpp v47, v47, v47 row_shr:2 row_mask:0xf bank_mask:0xf bound_ctrl:1
	v_add_f32_dpp v40, v40, v40 row_shr:4 row_mask:0xf bank_mask:0xf bound_ctrl:1
	v_add_f32_dpp v41, v41, v41 row_shr:4 row_mask:0xf bank_mask:0xf bound_ctrl:1
	v_add_f32_dpp v42, v42, v42 row_shr:4 row_mask:0xf bank_mask:0xf bound_ctrl:1
	v_add_f32_dpp v43, v43, v43 row_shr:4 row_mask:0xf bank_mask:0xf bound_ctrl:1
	v_add_f32_dpp v44, v44, v44 row_shr:4 row_mask:0xf bank_mask:0xf bound_ctrl:1
	v_add_f32_dpp v45, v45, v45 row_shr:4 row_mask:0xf bank_mask:0xf bound_ctrl:1
	v_add_f32_dpp v46, v46, v46 row_shr:4 row_mask:0xf bank_mask:0xf bound_ctrl:1
	v_add_f32_dpp v47, v47, v47 row_shr:4 row_mask:0xf bank_mask:0xf bound_ctrl:1
	v_add_f32_dpp v40, v40, v40 row_shr:8 row_mask:0xf bank_mask:0xf bound_ctrl:1
	v_add_f32_dpp v41, v41, v41 row_shr:8 row_mask:0xf bank_mask:0xf bound_ctrl:1
	v_add_f32_dpp v42, v42, v42 row_shr:8 row_mask:0xf bank_mask:0xf bound_ctrl:1
	v_add_f32_dpp v43, v43, v43 row_shr:8 row_mask:0xf bank_mask:0xf bound_ctrl:1
	v_add_f32_dpp v44, v44, v44 row_shr:8 row_mask:0xf bank_mask:0xf bound_ctrl:1
	v_add_f32_dpp v45, v45, v45 row_shr:8 row_mask:0xf bank_mask:0xf bound_ctrl:1
	v_add_f32_dpp v46, v46, v46 row_shr:8 row_mask:0xf bank_mask:0xf bound_ctrl:1
	v_add_f32_dpp v47, v47, v47 row_shr:8 row_mask:0xf bank_mask:0xf bound_ctrl:1
	v_mov_b32_dpp v88, v40 row_newbcast:15 row_mask:0xf bank_mask:0xf
	v_mov_b32_dpp v89, v41 row_newbcast:15 row_mask:0xf bank_mask:0xf
	v_mov_b32_dpp v90, v42 row_newbcast:15 row_mask:0xf bank_mask:0xf
	v_mov_b32_dpp v91, v43 row_newbcast:15 row_mask:0xf bank_mask:0xf
	v_mov_b32_dpp v92, v44 row_newbcast:15 row_mask:0xf bank_mask:0xf
	v_mov_b32_dpp v93, v45 row_newbcast:15 row_mask:0xf bank_mask:0xf
	v_mov_b32_dpp v94, v46 row_newbcast:15 row_mask:0xf bank_mask:0xf
	v_mov_b32_dpp v95, v47 row_newbcast:15 row_mask:0xf bank_mask:0xf
	v_add_f32_e32 v40, v40, v170
	v_add_f32_e32 v44, v44, v171
	v_add_f32_e32 v41, v41, v172
	v_add_f32_e32 v45, v45, v173
	v_add_f32_e32 v42, v42, v174
	v_add_f32_e32 v46, v46, v175
	v_add_f32_e32 v43, v43, v176
	v_add_f32_e32 v47, v47, v177
	v_mul_f32_e32 v132, v40, v141
	v_mul_f32_e32 v40, v40, v140
	v_fma_f32 v40, -v44, v141, v40
	v_fma_f32 v44, v44, v140, v132
	v_mul_f32_e32 v133, v41, v145
	v_mul_f32_e32 v41, v41, v144
	v_fma_f32 v41, -v45, v145, v41
	v_fma_f32 v45, v45, v144, v133
	v_mul_f32_e32 v132, v42, v149
	v_mul_f32_e32 v42, v42, v148
	v_fma_f32 v42, -v46, v149, v42
	v_fma_f32 v46, v46, v148, v132
	v_mul_f32_e32 v133, v43, v153
	v_mul_f32_e32 v43, v43, v152
	v_fma_f32 v43, -v47, v153, v43
	v_fma_f32 v47, v47, v152, v133
	v_add_f32_e32 v88, v88, v170
	v_add_f32_e32 v92, v92, v171
	v_mul_f32_e32 v132, v92, v155
	v_mul_f32_e32 v171, v88, v155
	v_fma_f32 v170, v88, v154, -v132
	v_fma_f32 v171, v92, v154, v171
	v_add_f32_e32 v89, v89, v172
	v_add_f32_e32 v93, v93, v173
	v_mul_f32_e32 v133, v93, v159
	v_mul_f32_e32 v173, v89, v159
	v_fma_f32 v172, v89, v158, -v133
	v_fma_f32 v173, v93, v158, v173
	v_add_f32_e32 v90, v90, v174
	v_add_f32_e32 v94, v94, v175
	v_mul_f32_e32 v132, v94, v163
	v_mul_f32_e32 v175, v90, v163
	v_fma_f32 v174, v90, v162, -v132
	v_fma_f32 v175, v94, v162, v175
	v_add_f32_e32 v91, v91, v176
	v_add_f32_e32 v95, v95, v177
	v_mul_f32_e32 v133, v95, v167
	v_mul_f32_e32 v177, v91, v167
	v_fma_f32 v176, v91, v166, -v133
	v_fma_f32 v177, v95, v166, v177
	v_mul_f32_e32 v132, v48, v139
	v_mul_f32_e32 v48, v48, v138
	v_fma_f32 v48, -v52, v139, v48
	v_fma_f32 v52, v52, v138, v132
	v_mul_f32_e32 v133, v49, v143
	v_mul_f32_e32 v49, v49, v142
	v_fma_f32 v49, -v53, v143, v49
	v_fma_f32 v53, v53, v142, v133
	v_mul_f32_e32 v132, v50, v147
	v_mul_f32_e32 v50, v50, v146
	v_fma_f32 v50, -v54, v147, v50
	v_fma_f32 v54, v54, v146, v132
	v_mul_f32_e32 v133, v51, v151
	v_mul_f32_e32 v51, v51, v150
	v_fma_f32 v51, -v55, v151, v51
	v_fma_f32 v55, v55, v150, v133
	v_add_f32_dpp v48, v48, v48 row_shr:1 row_mask:0xf bank_mask:0xf bound_ctrl:1
	v_add_f32_dpp v49, v49, v49 row_shr:1 row_mask:0xf bank_mask:0xf bound_ctrl:1
	v_add_f32_dpp v50, v50, v50 row_shr:1 row_mask:0xf bank_mask:0xf bound_ctrl:1
	v_add_f32_dpp v51, v51, v51 row_shr:1 row_mask:0xf bank_mask:0xf bound_ctrl:1
	v_add_f32_dpp v52, v52, v52 row_shr:1 row_mask:0xf bank_mask:0xf bound_ctrl:1
	v_add_f32_dpp v53, v53, v53 row_shr:1 row_mask:0xf bank_mask:0xf bound_ctrl:1
	v_add_f32_dpp v54, v54, v54 row_shr:1 row_mask:0xf bank_mask:0xf bound_ctrl:1
	v_add_f32_dpp v55, v55, v55 row_shr:1 row_mask:0xf bank_mask:0xf bound_ctrl:1
	v_add_f32_dpp v48, v48, v48 row_shr:2 row_mask:0xf bank_mask:0xf bound_ctrl:1
	v_add_f32_dpp v49, v49, v49 row_shr:2 row_mask:0xf bank_mask:0xf bound_ctrl:1
	v_add_f32_dpp v50, v50, v50 row_shr:2 row_mask:0xf bank_mask:0xf bound_ctrl:1
	v_add_f32_dpp v51, v51, v51 row_shr:2 row_mask:0xf bank_mask:0xf bound_ctrl:1
	v_add_f32_dpp v52, v52, v52 row_shr:2 row_mask:0xf bank_mask:0xf bound_ctrl:1
	v_add_f32_dpp v53, v53, v53 row_shr:2 row_mask:0xf bank_mask:0xf bound_ctrl:1
	v_add_f32_dpp v54, v54, v54 row_shr:2 row_mask:0xf bank_mask:0xf bound_ctrl:1
	v_add_f32_dpp v55, v55, v55 row_shr:2 row_mask:0xf bank_mask:0xf bound_ctrl:1
	v_add_f32_dpp v48, v48, v48 row_shr:4 row_mask:0xf bank_mask:0xf bound_ctrl:1
	v_add_f32_dpp v49, v49, v49 row_shr:4 row_mask:0xf bank_mask:0xf bound_ctrl:1
	v_add_f32_dpp v50, v50, v50 row_shr:4 row_mask:0xf bank_mask:0xf bound_ctrl:1
	v_add_f32_dpp v51, v51, v51 row_shr:4 row_mask:0xf bank_mask:0xf bound_ctrl:1
	v_add_f32_dpp v52, v52, v52 row_shr:4 row_mask:0xf bank_mask:0xf bound_ctrl:1
	v_add_f32_dpp v53, v53, v53 row_shr:4 row_mask:0xf bank_mask:0xf bound_ctrl:1
	v_add_f32_dpp v54, v54, v54 row_shr:4 row_mask:0xf bank_mask:0xf bound_ctrl:1
	v_add_f32_dpp v55, v55, v55 row_shr:4 row_mask:0xf bank_mask:0xf bound_ctrl:1
	v_add_f32_dpp v48, v48, v48 row_shr:8 row_mask:0xf bank_mask:0xf bound_ctrl:1
	v_add_f32_dpp v49, v49, v49 row_shr:8 row_mask:0xf bank_mask:0xf bound_ctrl:1
	v_add_f32_dpp v50, v50, v50 row_shr:8 row_mask:0xf bank_mask:0xf bound_ctrl:1
	v_add_f32_dpp v51, v51, v51 row_shr:8 row_mask:0xf bank_mask:0xf bound_ctrl:1
	v_add_f32_dpp v52, v52, v52 row_shr:8 row_mask:0xf bank_mask:0xf bound_ctrl:1
	v_add_f32_dpp v53, v53, v53 row_shr:8 row_mask:0xf bank_mask:0xf bound_ctrl:1
	v_add_f32_dpp v54, v54, v54 row_shr:8 row_mask:0xf bank_mask:0xf bound_ctrl:1
	v_add_f32_dpp v55, v55, v55 row_shr:8 row_mask:0xf bank_mask:0xf bound_ctrl:1
	v_mov_b32_dpp v88, v48 row_newbcast:15 row_mask:0xf bank_mask:0xf
	v_mov_b32_dpp v89, v49 row_newbcast:15 row_mask:0xf bank_mask:0xf
	v_mov_b32_dpp v90, v50 row_newbcast:15 row_mask:0xf bank_mask:0xf
	v_mov_b32_dpp v91, v51 row_newbcast:15 row_mask:0xf bank_mask:0xf
	v_mov_b32_dpp v92, v52 row_newbcast:15 row_mask:0xf bank_mask:0xf
	v_mov_b32_dpp v93, v53 row_newbcast:15 row_mask:0xf bank_mask:0xf
	v_mov_b32_dpp v94, v54 row_newbcast:15 row_mask:0xf bank_mask:0xf
	v_mov_b32_dpp v95, v55 row_newbcast:15 row_mask:0xf bank_mask:0xf
	v_add_f32_e32 v48, v48, v170
	v_add_f32_e32 v52, v52, v171
	v_add_f32_e32 v49, v49, v172
	v_add_f32_e32 v53, v53, v173
	v_add_f32_e32 v50, v50, v174
	v_add_f32_e32 v54, v54, v175
	v_add_f32_e32 v51, v51, v176
	v_add_f32_e32 v55, v55, v177
	v_mul_f32_e32 v132, v48, v141
	v_mul_f32_e32 v48, v48, v140
	v_fma_f32 v48, -v52, v141, v48
	v_fma_f32 v52, v52, v140, v132
	v_mul_f32_e32 v133, v49, v145
	v_mul_f32_e32 v49, v49, v144
	v_fma_f32 v49, -v53, v145, v49
	v_fma_f32 v53, v53, v144, v133
	v_mul_f32_e32 v132, v50, v149
	v_mul_f32_e32 v50, v50, v148
	v_fma_f32 v50, -v54, v149, v50
	v_fma_f32 v54, v54, v148, v132
	v_mul_f32_e32 v133, v51, v153
	v_mul_f32_e32 v51, v51, v152
	v_fma_f32 v51, -v55, v153, v51
	v_fma_f32 v55, v55, v152, v133
	v_add_f32_e32 v88, v88, v170
	v_add_f32_e32 v92, v92, v171
	v_mul_f32_e32 v132, v92, v155
	v_mul_f32_e32 v171, v88, v155
	v_fma_f32 v170, v88, v154, -v132
	v_fma_f32 v171, v92, v154, v171
	v_add_f32_e32 v89, v89, v172
	v_add_f32_e32 v93, v93, v173
	v_mul_f32_e32 v133, v93, v159
	v_mul_f32_e32 v173, v89, v159
	v_fma_f32 v172, v89, v158, -v133
	v_fma_f32 v173, v93, v158, v173
	v_add_f32_e32 v90, v90, v174
	v_add_f32_e32 v94, v94, v175
	v_mul_f32_e32 v132, v94, v163
	v_mul_f32_e32 v175, v90, v163
	v_fma_f32 v174, v90, v162, -v132
	v_fma_f32 v175, v94, v162, v175
	v_add_f32_e32 v91, v91, v176
	v_add_f32_e32 v95, v95, v177
	v_mul_f32_e32 v133, v95, v167
	v_mul_f32_e32 v177, v91, v167
	v_fma_f32 v176, v91, v166, -v133
	v_fma_f32 v177, v95, v166, v177
	v_mul_f32_e32 v132, v56, v139
	v_mul_f32_e32 v56, v56, v138
	v_fma_f32 v56, -v60, v139, v56
	v_fma_f32 v60, v60, v138, v132
	v_mul_f32_e32 v133, v57, v143
	v_mul_f32_e32 v57, v57, v142
	v_fma_f32 v57, -v61, v143, v57
	v_fma_f32 v61, v61, v142, v133
	v_mul_f32_e32 v132, v58, v147
	v_mul_f32_e32 v58, v58, v146
	v_fma_f32 v58, -v62, v147, v58
	v_fma_f32 v62, v62, v146, v132
	v_mul_f32_e32 v133, v59, v151
	v_mul_f32_e32 v59, v59, v150
	v_fma_f32 v59, -v63, v151, v59
	v_fma_f32 v63, v63, v150, v133
	v_add_f32_dpp v56, v56, v56 row_shr:1 row_mask:0xf bank_mask:0xf bound_ctrl:1
	v_add_f32_dpp v57, v57, v57 row_shr:1 row_mask:0xf bank_mask:0xf bound_ctrl:1
	v_add_f32_dpp v58, v58, v58 row_shr:1 row_mask:0xf bank_mask:0xf bound_ctrl:1
	v_add_f32_dpp v59, v59, v59 row_shr:1 row_mask:0xf bank_mask:0xf bound_ctrl:1
	v_add_f32_dpp v60, v60, v60 row_shr:1 row_mask:0xf bank_mask:0xf bound_ctrl:1
	v_add_f32_dpp v61, v61, v61 row_shr:1 row_mask:0xf bank_mask:0xf bound_ctrl:1
	v_add_f32_dpp v62, v62, v62 row_shr:1 row_mask:0xf bank_mask:0xf bound_ctrl:1
	v_add_f32_dpp v63, v63, v63 row_shr:1 row_mask:0xf bank_mask:0xf bound_ctrl:1
	v_add_f32_dpp v56, v56, v56 row_shr:2 row_mask:0xf bank_mask:0xf bound_ctrl:1
	v_add_f32_dpp v57, v57, v57 row_shr:2 row_mask:0xf bank_mask:0xf bound_ctrl:1
	v_add_f32_dpp v58, v58, v58 row_shr:2 row_mask:0xf bank_mask:0xf bound_ctrl:1
	v_add_f32_dpp v59, v59, v59 row_shr:2 row_mask:0xf bank_mask:0xf bound_ctrl:1
	v_add_f32_dpp v60, v60, v60 row_shr:2 row_mask:0xf bank_mask:0xf bound_ctrl:1
	v_add_f32_dpp v61, v61, v61 row_shr:2 row_mask:0xf bank_mask:0xf bound_ctrl:1
	v_add_f32_dpp v62, v62, v62 row_shr:2 row_mask:0xf bank_mask:0xf bound_ctrl:1
	v_add_f32_dpp v63, v63, v63 row_shr:2 row_mask:0xf bank_mask:0xf bound_ctrl:1
	v_add_f32_dpp v56, v56, v56 row_shr:4 row_mask:0xf bank_mask:0xf bound_ctrl:1
	v_add_f32_dpp v57, v57, v57 row_shr:4 row_mask:0xf bank_mask:0xf bound_ctrl:1
	v_add_f32_dpp v58, v58, v58 row_shr:4 row_mask:0xf bank_mask:0xf bound_ctrl:1
	v_add_f32_dpp v59, v59, v59 row_shr:4 row_mask:0xf bank_mask:0xf bound_ctrl:1
	v_add_f32_dpp v60, v60, v60 row_shr:4 row_mask:0xf bank_mask:0xf bound_ctrl:1
	v_add_f32_dpp v61, v61, v61 row_shr:4 row_mask:0xf bank_mask:0xf bound_ctrl:1
	v_add_f32_dpp v62, v62, v62 row_shr:4 row_mask:0xf bank_mask:0xf bound_ctrl:1
	v_add_f32_dpp v63, v63, v63 row_shr:4 row_mask:0xf bank_mask:0xf bound_ctrl:1
	v_add_f32_dpp v56, v56, v56 row_shr:8 row_mask:0xf bank_mask:0xf bound_ctrl:1
	v_add_f32_dpp v57, v57, v57 row_shr:8 row_mask:0xf bank_mask:0xf bound_ctrl:1
	v_add_f32_dpp v58, v58, v58 row_shr:8 row_mask:0xf bank_mask:0xf bound_ctrl:1
	v_add_f32_dpp v59, v59, v59 row_shr:8 row_mask:0xf bank_mask:0xf bound_ctrl:1
	v_add_f32_dpp v60, v60, v60 row_shr:8 row_mask:0xf bank_mask:0xf bound_ctrl:1
	v_add_f32_dpp v61, v61, v61 row_shr:8 row_mask:0xf bank_mask:0xf bound_ctrl:1
	v_add_f32_dpp v62, v62, v62 row_shr:8 row_mask:0xf bank_mask:0xf bound_ctrl:1
	v_add_f32_dpp v63, v63, v63 row_shr:8 row_mask:0xf bank_mask:0xf bound_ctrl:1
	v_mov_b32_dpp v88, v56 row_newbcast:15 row_mask:0xf bank_mask:0xf
	v_mov_b32_dpp v89, v57 row_newbcast:15 row_mask:0xf bank_mask:0xf
	v_mov_b32_dpp v90, v58 row_newbcast:15 row_mask:0xf bank_mask:0xf
	v_mov_b32_dpp v91, v59 row_newbcast:15 row_mask:0xf bank_mask:0xf
	v_mov_b32_dpp v92, v60 row_newbcast:15 row_mask:0xf bank_mask:0xf
	v_mov_b32_dpp v93, v61 row_newbcast:15 row_mask:0xf bank_mask:0xf
	v_mov_b32_dpp v94, v62 row_newbcast:15 row_mask:0xf bank_mask:0xf
	v_mov_b32_dpp v95, v63 row_newbcast:15 row_mask:0xf bank_mask:0xf
	v_add_f32_e32 v56, v56, v170
	v_add_f32_e32 v60, v60, v171
	v_add_f32_e32 v57, v57, v172
	v_add_f32_e32 v61, v61, v173
	v_add_f32_e32 v58, v58, v174
	v_add_f32_e32 v62, v62, v175
	v_add_f32_e32 v59, v59, v176
	v_add_f32_e32 v63, v63, v177
	v_mul_f32_e32 v132, v56, v141
	v_mul_f32_e32 v56, v56, v140
	v_fma_f32 v56, -v60, v141, v56
	v_fma_f32 v60, v60, v140, v132
	v_mul_f32_e32 v133, v57, v145
	v_mul_f32_e32 v57, v57, v144
	v_fma_f32 v57, -v61, v145, v57
	v_fma_f32 v61, v61, v144, v133
	v_mul_f32_e32 v132, v58, v149
	v_mul_f32_e32 v58, v58, v148
	v_fma_f32 v58, -v62, v149, v58
	v_fma_f32 v62, v62, v148, v132
	v_mul_f32_e32 v133, v59, v153
	v_mul_f32_e32 v59, v59, v152
	v_fma_f32 v59, -v63, v153, v59
	v_fma_f32 v63, v63, v152, v133
	v_add_f32_e32 v88, v88, v170
	v_add_f32_e32 v92, v92, v171
	v_mul_f32_e32 v132, v92, v155
	v_mul_f32_e32 v171, v88, v155
	v_fma_f32 v170, v88, v154, -v132
	v_fma_f32 v171, v92, v154, v171
	v_add_f32_e32 v89, v89, v172
	v_add_f32_e32 v93, v93, v173
	v_mul_f32_e32 v133, v93, v159
	v_mul_f32_e32 v173, v89, v159
	v_fma_f32 v172, v89, v158, -v133
	v_fma_f32 v173, v93, v158, v173
	v_add_f32_e32 v90, v90, v174
	v_add_f32_e32 v94, v94, v175
	v_mul_f32_e32 v132, v94, v163
	v_mul_f32_e32 v175, v90, v163
	v_fma_f32 v174, v90, v162, -v132
	v_fma_f32 v175, v94, v162, v175
	v_add_f32_e32 v91, v91, v176
	v_add_f32_e32 v95, v95, v177
	v_mul_f32_e32 v133, v95, v167
	v_mul_f32_e32 v177, v91, v167
	v_fma_f32 v176, v91, v166, -v133
	v_fma_f32 v177, v95, v166, v177
	s_waitcnt vmcnt(14)
	v_cvt_pk_bf16_f32 v80, v80, v81
	v_cvt_pk_bf16_f32 v81, v82, v83
	v_cvt_pk_bf16_f32 v82, -v84, -v85
	v_cvt_pk_bf16_f32 v83, -v86, -v87
	v_cvt_pk_bf16_f32 v96, v32, v33
	v_cvt_pk_bf16_f32 v97, v34, v35
	v_cvt_pk_bf16_f32 v98, v36, v37
	v_cvt_pk_bf16_f32 v99, v38, v39
	s_nop 1
	v_mfma_f32_16x16x32_bf16 v[16:19], v[80:83], v[96:99], 0
	v_cvt_pk_bf16_f32 v96, v40, v41
	v_cvt_pk_bf16_f32 v97, v42, v43
	v_cvt_pk_bf16_f32 v98, v44, v45
	v_cvt_pk_bf16_f32 v99, v46, v47
	s_nop 1
	v_mfma_f32_16x16x32_bf16 v[20:23], v[80:83], v[96:99], 0
	v_cvt_pk_bf16_f32 v96, v48, v49
	v_cvt_pk_bf16_f32 v97, v50, v51
	v_cvt_pk_bf16_f32 v98, v52, v53
	v_cvt_pk_bf16_f32 v99, v54, v55
	s_nop 1
	v_mfma_f32_16x16x32_bf16 v[24:27], v[80:83], v[96:99], 0
	v_cvt_pk_bf16_f32 v96, v56, v57
	v_cvt_pk_bf16_f32 v97, v58, v59
	v_cvt_pk_bf16_f32 v98, v60, v61
	v_cvt_pk_bf16_f32 v99, v62, v63
	s_nop 1
	v_mfma_f32_16x16x32_bf16 v[28:31], v[80:83], v[96:99], 0
	s_waitcnt vmcnt(10)
	v_cvt_pk_bf16_f32 v64, v64, v65
	v_cvt_pk_bf16_f32 v65, v66, v67
	v_cvt_pk_bf16_f32 v66, v68, v69
	v_cvt_pk_bf16_f32 v67, v70, v71
	v_cvt_pk_bf16_f32 v72, v72, v73
	v_cvt_pk_bf16_f32 v73, v74, v75
	v_cvt_pk_bf16_f32 v74, v76, v77
	v_cvt_pk_bf16_f32 v75, v78, v79
	global_load_dwordx4 v[80:83], v136, s[38:39]
	global_load_dwordx4 v[84:87], v136, s[40:41]
	s_add_u32 s38, s38, 0x40
	s_addc_u32 s39, s39, 0
	s_add_u32 s40, s40, 0x40
	s_addc_u32 s41, s41, 0
	s_nop 0
	v_mfma_f32_16x16x32_bf16 v[32:35], v[64:67], v[0:3], 0
	v_mfma_f32_16x16x32_bf16 v[36:39], v[72:75], v[0:3], 0
	v_mfma_f32_16x16x32_bf16 v[40:43], v[64:67], v[4:7], 0
	v_mfma_f32_16x16x32_bf16 v[44:47], v[72:75], v[4:7], 0
	v_mfma_f32_16x16x32_bf16 v[48:51], v[64:67], v[8:11], 0
	v_mfma_f32_16x16x32_bf16 v[52:55], v[72:75], v[8:11], 0
	v_mfma_f32_16x16x32_bf16 v[56:59], v[64:67], v[12:15], 0
	v_mfma_f32_16x16x32_bf16 v[60:63], v[72:75], v[12:15], 0
	s_mov_b32 exec_hi, 0
	global_load_dwordx4 v[64:67], v135, s[20:21]
	global_load_dwordx4 v[68:71], v135, s[20:21] offset:16
	global_load_dwordx4 v[72:75], v135, s[22:23]
	global_load_dwordx4 v[76:79], v135, s[22:23] offset:16
	s_mov_b64 exec, -1
	s_add_u32 s20, s20, 0x400
	s_addc_u32 s21, s21, 0
	s_add_u32 s22, s22, 0x400
	s_addc_u32 s23, s23, 0
	global_load_dwordx4 v[138:141], v134, s[42:43] offset:0
	global_load_dwordx4 v[142:145], v134, s[42:43] offset:1024
	global_load_dwordx4 v[146:149], v134, s[42:43] offset:2048
	global_load_dwordx4 v[150:153], v134, s[42:43] offset:3072
	global_load_dwordx4 v[154:157], v208, s[42:43] offset:0
	global_load_dwordx4 v[158:161], v208, s[42:43] offset:1024
	global_load_dwordx4 v[162:165], v208, s[42:43] offset:2048
	global_load_dwordx4 v[166:169], v208, s[42:43] offset:3072
	global_load_dwordx4 v[170:173], v206, s[44:45]
	global_load_dwordx4 v[174:177], v206, s[44:45] offset:16
	s_add_u32 s42, s42, 0x2000
	s_addc_u32 s43, s43, 0
	s_add_u32 s44, s44, 0x80
	s_addc_u32 s45, s45, 0
	s_waitcnt vmcnt(16)
	v_mul_f32_e32 v132, v179, v119
	v_mul_f32_e32 v133, v178, v119
	v_fma_f32 v178, v178, v118, -v132
	v_fma_f32 v179, v179, v118, v133
	v_mul_f32_e32 v132, v181, v123
	v_mul_f32_e32 v133, v180, v123
	v_fma_f32 v180, v180, v122, -v132
	v_fma_f32 v181, v181, v122, v133
	v_mul_f32_e32 v132, v183, v127
	v_mul_f32_e32 v133, v182, v127
	v_fma_f32 v182, v182, v126, -v132
	v_fma_f32 v183, v183, v126, v133
	v_mul_f32_e32 v132, v185, v131
	v_mul_f32_e32 v133, v184, v131
	v_fma_f32 v184, v184, v130, -v132
	v_fma_f32 v185, v185, v130, v133
	v_mul_f32_e32 v132, v32, v101
	v_mul_f32_e32 v32, v32, v100
	v_fma_f32 v32, -v36, v101, v32
	v_fma_f32 v36, v36, v100, v132
	v_mul_f32_e32 v133, v33, v105
	v_mul_f32_e32 v33, v33, v104
	v_fma_f32 v33, -v37, v105, v33
	v_fma_f32 v37, v37, v104, v133
	v_mul_f32_e32 v132, v34, v109
	v_mul_f32_e32 v34, v34, v108
	v_fma_f32 v34, -v38, v109, v34
	v_fma_f32 v38, v38, v108, v132
	v_mul_f32_e32 v133, v35, v113
	v_mul_f32_e32 v35, v35, v112
	v_fma_f32 v35, -v39, v113, v35
	v_fma_f32 v39, v39, v112, v133
	v_add_f32_dpp v32, v32, v32 row_shr:1 row_mask:0xf bank_mask:0xf bound_ctrl:1
	v_add_f32_dpp v33, v33, v33 row_shr:1 row_mask:0xf bank_mask:0xf bound_ctrl:1
	v_add_f32_dpp v34, v34, v34 row_shr:1 row_mask:0xf bank_mask:0xf bound_ctrl:1
	v_add_f32_dpp v35, v35, v35 row_shr:1 row_mask:0xf bank_mask:0xf bound_ctrl:1
	v_add_f32_dpp v36, v36, v36 row_shr:1 row_mask:0xf bank_mask:0xf bound_ctrl:1
	v_add_f32_dpp v37, v37, v37 row_shr:1 row_mask:0xf bank_mask:0xf bound_ctrl:1
	v_add_f32_dpp v38, v38, v38 row_shr:1 row_mask:0xf bank_mask:0xf bound_ctrl:1
	v_add_f32_dpp v39, v39, v39 row_shr:1 row_mask:0xf bank_mask:0xf bound_ctrl:1
	v_add_f32_dpp v32, v32, v32 row_shr:2 row_mask:0xf bank_mask:0xf bound_ctrl:1
	v_add_f32_dpp v33, v33, v33 row_shr:2 row_mask:0xf bank_mask:0xf bound_ctrl:1
	v_add_f32_dpp v34, v34, v34 row_shr:2 row_mask:0xf bank_mask:0xf bound_ctrl:1
	v_add_f32_dpp v35, v35, v35 row_shr:2 row_mask:0xf bank_mask:0xf bound_ctrl:1
	v_add_f32_dpp v36, v36, v36 row_shr:2 row_mask:0xf bank_mask:0xf bound_ctrl:1
	v_add_f32_dpp v37, v37, v37 row_shr:2 row_mask:0xf bank_mask:0xf bound_ctrl:1
	v_add_f32_dpp v38, v38, v38 row_shr:2 row_mask:0xf bank_mask:0xf bound_ctrl:1
	v_add_f32_dpp v39, v39, v39 row_shr:2 row_mask:0xf bank_mask:0xf bound_ctrl:1
	v_add_f32_dpp v32, v32, v32 row_shr:4 row_mask:0xf bank_mask:0xf bound_ctrl:1
	v_add_f32_dpp v33, v33, v33 row_shr:4 row_mask:0xf bank_mask:0xf bound_ctrl:1
	v_add_f32_dpp v34, v34, v34 row_shr:4 row_mask:0xf bank_mask:0xf bound_ctrl:1
	v_add_f32_dpp v35, v35, v35 row_shr:4 row_mask:0xf bank_mask:0xf bound_ctrl:1
	v_add_f32_dpp v36, v36, v36 row_shr:4 row_mask:0xf bank_mask:0xf bound_ctrl:1
	v_add_f32_dpp v37, v37, v37 row_shr:4 row_mask:0xf bank_mask:0xf bound_ctrl:1
	v_add_f32_dpp v38, v38, v38 row_shr:4 row_mask:0xf bank_mask:0xf bound_ctrl:1
	v_add_f32_dpp v39, v39, v39 row_shr:4 row_mask:0xf bank_mask:0xf bound_ctrl:1
	v_add_f32_dpp v32, v32, v32 row_shr:8 row_mask:0xf bank_mask:0xf bound_ctrl:1
	v_add_f32_dpp v33, v33, v33 row_shr:8 row_mask:0xf bank_mask:0xf bound_ctrl:1
	v_add_f32_dpp v34, v34, v34 row_shr:8 row_mask:0xf bank_mask:0xf bound_ctrl:1
	v_add_f32_dpp v35, v35, v35 row_shr:8 row_mask:0xf bank_mask:0xf bound_ctrl:1
	v_add_f32_dpp v36, v36, v36 row_shr:8 row_mask:0xf bank_mask:0xf bound_ctrl:1
	v_add_f32_dpp v37, v37, v37 row_shr:8 row_mask:0xf bank_mask:0xf bound_ctrl:1
	v_add_f32_dpp v38, v38, v38 row_shr:8 row_mask:0xf bank_mask:0xf bound_ctrl:1
	v_add_f32_dpp v39, v39, v39 row_shr:8 row_mask:0xf bank_mask:0xf bound_ctrl:1
	v_mov_b32_dpp v88, v32 row_newbcast:15 row_mask:0xf bank_mask:0xf
	v_mov_b32_dpp v89, v33 row_newbcast:15 row_mask:0xf bank_mask:0xf
	v_mov_b32_dpp v90, v34 row_newbcast:15 row_mask:0xf bank_mask:0xf
	v_mov_b32_dpp v91, v35 row_newbcast:15 row_mask:0xf bank_mask:0xf
	v_mov_b32_dpp v92, v36 row_newbcast:15 row_mask:0xf bank_mask:0xf
	v_mov_b32_dpp v93, v37 row_newbcast:15 row_mask:0xf bank_mask:0xf
	v_mov_b32_dpp v94, v38 row_newbcast:15 row_mask:0xf bank_mask:0xf
	v_mov_b32_dpp v95, v39 row_newbcast:15 row_mask:0xf bank_mask:0xf
	v_add_f32_e32 v32, v32, v178
	v_add_f32_e32 v36, v36, v179
	v_add_f32_e32 v33, v33, v180
	v_add_f32_e32 v37, v37, v181
	v_add_f32_e32 v34, v34, v182
	v_add_f32_e32 v38, v38, v183
	v_add_f32_e32 v35, v35, v184
	v_add_f32_e32 v39, v39, v185
	v_mul_f32_e32 v132, v32, v103
	v_mul_f32_e32 v32, v32, v102
	v_fma_f32 v32, -v36, v103, v32
	v_fma_f32 v36, v36, v102, v132
	v_mul_f32_e32 v133, v33, v107
	v_mul_f32_e32 v33, v33, v106
	v_fma_f32 v33, -v37, v107, v33
	v_fma_f32 v37, v37, v106, v133
	v_mul_f32_e32 v132, v34, v111
	v_mul_f32_e32 v34, v34, v110
	v_fma_f32 v34, -v38, v111, v34
	v_fma_f32 v38, v38, v110, v132
	v_mul_f32_e32 v133, v35, v115
	v_mul_f32_e32 v35, v35, v114
	v_fma_f32 v35, -v39, v115, v35
	v_fma_f32 v39, v39, v114, v133
	v_add_f32_e32 v88, v88, v178
	v_add_f32_e32 v92, v92, v179
	v_mul_f32_e32 v132, v92, v117
	v_mul_f32_e32 v179, v88, v117
	v_fma_f32 v178, v88, v116, -v132
	v_fma_f32 v179, v92, v116, v179
	v_add_f32_e32 v89, v89, v180
	v_add_f32_e32 v93, v93, v181
	v_mul_f32_e32 v133, v93, v121
	v_mul_f32_e32 v181, v89, v121
	v_fma_f32 v180, v89, v120, -v133
	v_fma_f32 v181, v93, v120, v181
	v_add_f32_e32 v90, v90, v182
	v_add_f32_e32 v94, v94, v183
	v_mul_f32_e32 v132, v94, v125
	v_mul_f32_e32 v183, v90, v125
	v_fma_f32 v182, v90, v124, -v132
	v_fma_f32 v183, v94, v124, v183
	v_add_f32_e32 v91, v91, v184
	v_add_f32_e32 v95, v95, v185
	v_mul_f32_e32 v133, v95, v129
	v_mul_f32_e32 v185, v91, v129
	v_fma_f32 v184, v91, v128, -v133
	v_fma_f32 v185, v95, v128, v185
	v_mul_f32_e32 v132, v40, v101
	v_mul_f32_e32 v40, v40, v100
	v_fma_f32 v40, -v44, v101, v40
	v_fma_f32 v44, v44, v100, v132
	v_mul_f32_e32 v133, v41, v105
	v_mul_f32_e32 v41, v41, v104
	v_fma_f32 v41, -v45, v105, v41
	v_fma_f32 v45, v45, v104, v133
	v_mul_f32_e32 v132, v42, v109
	v_mul_f32_e32 v42, v42, v108
	v_fma_f32 v42, -v46, v109, v42
	v_fma_f32 v46, v46, v108, v132
	v_mul_f32_e32 v133, v43, v113
	v_mul_f32_e32 v43, v43, v112
	v_fma_f32 v43, -v47, v113, v43
	v_fma_f32 v47, v47, v112, v133
	v_add_f32_dpp v40, v40, v40 row_shr:1 row_mask:0xf bank_mask:0xf bound_ctrl:1
	v_add_f32_dpp v41, v41, v41 row_shr:1 row_mask:0xf bank_mask:0xf bound_ctrl:1
	v_add_f32_dpp v42, v42, v42 row_shr:1 row_mask:0xf bank_mask:0xf bound_ctrl:1
	v_add_f32_dpp v43, v43, v43 row_shr:1 row_mask:0xf bank_mask:0xf bound_ctrl:1
	v_add_f32_dpp v44, v44, v44 row_shr:1 row_mask:0xf bank_mask:0xf bound_ctrl:1
	v_add_f32_dpp v45, v45, v45 row_shr:1 row_mask:0xf bank_mask:0xf bound_ctrl:1
	v_add_f32_dpp v46, v46, v46 row_shr:1 row_mask:0xf bank_mask:0xf bound_ctrl:1
	v_add_f32_dpp v47, v47, v47 row_shr:1 row_mask:0xf bank_mask:0xf bound_ctrl:1
	v_add_f32_dpp v40, v40, v40 row_shr:2 row_mask:0xf bank_mask:0xf bound_ctrl:1
	v_add_f32_dpp v41, v41, v41 row_shr:2 row_mask:0xf bank_mask:0xf bound_ctrl:1
	v_add_f32_dpp v42, v42, v42 row_shr:2 row_mask:0xf bank_mask:0xf bound_ctrl:1
	v_add_f32_dpp v43, v43, v43 row_shr:2 row_mask:0xf bank_mask:0xf bound_ctrl:1
	v_add_f32_dpp v44, v44, v44 row_shr:2 row_mask:0xf bank_mask:0xf bound_ctrl:1
	v_add_f32_dpp v45, v45, v45 row_shr:2 row_mask:0xf bank_mask:0xf bound_ctrl:1
	v_add_f32_dpp v46, v46, v46 row_shr:2 row_mask:0xf bank_mask:0xf bound_ctrl:1
	v_add_f32_dpp v47, v47, v47 row_shr:2 row_mask:0xf bank_mask:0xf bound_ctrl:1
	v_add_f32_dpp v40, v40, v40 row_shr:4 row_mask:0xf bank_mask:0xf bound_ctrl:1
	v_add_f32_dpp v41, v41, v41 row_shr:4 row_mask:0xf bank_mask:0xf bound_ctrl:1
	v_add_f32_dpp v42, v42, v42 row_shr:4 row_mask:0xf bank_mask:0xf bound_ctrl:1
	v_add_f32_dpp v43, v43, v43 row_shr:4 row_mask:0xf bank_mask:0xf bound_ctrl:1
	v_add_f32_dpp v44, v44, v44 row_shr:4 row_mask:0xf bank_mask:0xf bound_ctrl:1
	v_add_f32_dpp v45, v45, v45 row_shr:4 row_mask:0xf bank_mask:0xf bound_ctrl:1
	v_add_f32_dpp v46, v46, v46 row_shr:4 row_mask:0xf bank_mask:0xf bound_ctrl:1
	v_add_f32_dpp v47, v47, v47 row_shr:4 row_mask:0xf bank_mask:0xf bound_ctrl:1
	v_add_f32_dpp v40, v40, v40 row_shr:8 row_mask:0xf bank_mask:0xf bound_ctrl:1
	v_add_f32_dpp v41, v41, v41 row_shr:8 row_mask:0xf bank_mask:0xf bound_ctrl:1
	v_add_f32_dpp v42, v42, v42 row_shr:8 row_mask:0xf bank_mask:0xf bound_ctrl:1
	v_add_f32_dpp v43, v43, v43 row_shr:8 row_mask:0xf bank_mask:0xf bound_ctrl:1
	v_add_f32_dpp v44, v44, v44 row_shr:8 row_mask:0xf bank_mask:0xf bound_ctrl:1
	v_add_f32_dpp v45, v45, v45 row_shr:8 row_mask:0xf bank_mask:0xf bound_ctrl:1
	v_add_f32_dpp v46, v46, v46 row_shr:8 row_mask:0xf bank_mask:0xf bound_ctrl:1
	v_add_f32_dpp v47, v47, v47 row_shr:8 row_mask:0xf bank_mask:0xf bound_ctrl:1
	v_mov_b32_dpp v88, v40 row_newbcast:15 row_mask:0xf bank_mask:0xf
	v_mov_b32_dpp v89, v41 row_newbcast:15 row_mask:0xf bank_mask:0xf
	v_mov_b32_dpp v90, v42 row_newbcast:15 row_mask:0xf bank_mask:0xf
	v_mov_b32_dpp v91, v43 row_newbcast:15 row_mask:0xf bank_mask:0xf
	v_mov_b32_dpp v92, v44 row_newbcast:15 row_mask:0xf bank_mask:0xf
	v_mov_b32_dpp v93, v45 row_newbcast:15 row_mask:0xf bank_mask:0xf
	v_mov_b32_dpp v94, v46 row_newbcast:15 row_mask:0xf bank_mask:0xf
	v_mov_b32_dpp v95, v47 row_newbcast:15 row_mask:0xf bank_mask:0xf
	v_add_f32_e32 v40, v40, v178
	v_add_f32_e32 v44, v44, v179
	v_add_f32_e32 v41, v41, v180
	v_add_f32_e32 v45, v45, v181
	v_add_f32_e32 v42, v42, v182
	v_add_f32_e32 v46, v46, v183
	v_add_f32_e32 v43, v43, v184
	v_add_f32_e32 v47, v47, v185
	v_mul_f32_e32 v132, v40, v103
	v_mul_f32_e32 v40, v40, v102
	v_fma_f32 v40, -v44, v103, v40
	v_fma_f32 v44, v44, v102, v132
	v_mul_f32_e32 v133, v41, v107
	v_mul_f32_e32 v41, v41, v106
	v_fma_f32 v41, -v45, v107, v41
	v_fma_f32 v45, v45, v106, v133
	v_mul_f32_e32 v132, v42, v111
	v_mul_f32_e32 v42, v42, v110
	v_fma_f32 v42, -v46, v111, v42
	v_fma_f32 v46, v46, v110, v132
	v_mul_f32_e32 v133, v43, v115
	v_mul_f32_e32 v43, v43, v114
	v_fma_f32 v43, -v47, v115, v43
	v_fma_f32 v47, v47, v114, v133
	v_add_f32_e32 v88, v88, v178
	v_add_f32_e32 v92, v92, v179
	v_mul_f32_e32 v132, v92, v117
	v_mul_f32_e32 v179, v88, v117
	v_fma_f32 v178, v88, v116, -v132
	v_fma_f32 v179, v92, v116, v179
	v_add_f32_e32 v89, v89, v180
	v_add_f32_e32 v93, v93, v181
	v_mul_f32_e32 v133, v93, v121
	v_mul_f32_e32 v181, v89, v121
	v_fma_f32 v180, v89, v120, -v133
	v_fma_f32 v181, v93, v120, v181
	v_add_f32_e32 v90, v90, v182
	v_add_f32_e32 v94, v94, v183
	v_mul_f32_e32 v132, v94, v125
	v_mul_f32_e32 v183, v90, v125
	v_fma_f32 v182, v90, v124, -v132
	v_fma_f32 v183, v94, v124, v183
	v_add_f32_e32 v91, v91, v184
	v_add_f32_e32 v95, v95, v185
	v_mul_f32_e32 v133, v95, v129
	v_mul_f32_e32 v185, v91, v129
	v_fma_f32 v184, v91, v128, -v133
	v_fma_f32 v185, v95, v128, v185
	v_mul_f32_e32 v132, v48, v101
	v_mul_f32_e32 v48, v48, v100
	v_fma_f32 v48, -v52, v101, v48
	v_fma_f32 v52, v52, v100, v132
	v_mul_f32_e32 v133, v49, v105
	v_mul_f32_e32 v49, v49, v104
	v_fma_f32 v49, -v53, v105, v49
	v_fma_f32 v53, v53, v104, v133
	v_mul_f32_e32 v132, v50, v109
	v_mul_f32_e32 v50, v50, v108
	v_fma_f32 v50, -v54, v109, v50
	v_fma_f32 v54, v54, v108, v132
	v_mul_f32_e32 v133, v51, v113
	v_mul_f32_e32 v51, v51, v112
	v_fma_f32 v51, -v55, v113, v51
	v_fma_f32 v55, v55, v112, v133
	v_add_f32_dpp v48, v48, v48 row_shr:1 row_mask:0xf bank_mask:0xf bound_ctrl:1
	v_add_f32_dpp v49, v49, v49 row_shr:1 row_mask:0xf bank_mask:0xf bound_ctrl:1
	v_add_f32_dpp v50, v50, v50 row_shr:1 row_mask:0xf bank_mask:0xf bound_ctrl:1
	v_add_f32_dpp v51, v51, v51 row_shr:1 row_mask:0xf bank_mask:0xf bound_ctrl:1
	v_add_f32_dpp v52, v52, v52 row_shr:1 row_mask:0xf bank_mask:0xf bound_ctrl:1
	v_add_f32_dpp v53, v53, v53 row_shr:1 row_mask:0xf bank_mask:0xf bound_ctrl:1
	v_add_f32_dpp v54, v54, v54 row_shr:1 row_mask:0xf bank_mask:0xf bound_ctrl:1
	v_add_f32_dpp v55, v55, v55 row_shr:1 row_mask:0xf bank_mask:0xf bound_ctrl:1
	v_add_f32_dpp v48, v48, v48 row_shr:2 row_mask:0xf bank_mask:0xf bound_ctrl:1
	v_add_f32_dpp v49, v49, v49 row_shr:2 row_mask:0xf bank_mask:0xf bound_ctrl:1
	v_add_f32_dpp v50, v50, v50 row_shr:2 row_mask:0xf bank_mask:0xf bound_ctrl:1
	v_add_f32_dpp v51, v51, v51 row_shr:2 row_mask:0xf bank_mask:0xf bound_ctrl:1
	v_add_f32_dpp v52, v52, v52 row_shr:2 row_mask:0xf bank_mask:0xf bound_ctrl:1
	v_add_f32_dpp v53, v53, v53 row_shr:2 row_mask:0xf bank_mask:0xf bound_ctrl:1
	v_add_f32_dpp v54, v54, v54 row_shr:2 row_mask:0xf bank_mask:0xf bound_ctrl:1
	v_add_f32_dpp v55, v55, v55 row_shr:2 row_mask:0xf bank_mask:0xf bound_ctrl:1
	v_add_f32_dpp v48, v48, v48 row_shr:4 row_mask:0xf bank_mask:0xf bound_ctrl:1
	v_add_f32_dpp v49, v49, v49 row_shr:4 row_mask:0xf bank_mask:0xf bound_ctrl:1
	v_add_f32_dpp v50, v50, v50 row_shr:4 row_mask:0xf bank_mask:0xf bound_ctrl:1
	v_add_f32_dpp v51, v51, v51 row_shr:4 row_mask:0xf bank_mask:0xf bound_ctrl:1
	v_add_f32_dpp v52, v52, v52 row_shr:4 row_mask:0xf bank_mask:0xf bound_ctrl:1
	v_add_f32_dpp v53, v53, v53 row_shr:4 row_mask:0xf bank_mask:0xf bound_ctrl:1
	v_add_f32_dpp v54, v54, v54 row_shr:4 row_mask:0xf bank_mask:0xf bound_ctrl:1
	v_add_f32_dpp v55, v55, v55 row_shr:4 row_mask:0xf bank_mask:0xf bound_ctrl:1
	v_add_f32_dpp v48, v48, v48 row_shr:8 row_mask:0xf bank_mask:0xf bound_ctrl:1
	v_add_f32_dpp v49, v49, v49 row_shr:8 row_mask:0xf bank_mask:0xf bound_ctrl:1
	v_add_f32_dpp v50, v50, v50 row_shr:8 row_mask:0xf bank_mask:0xf bound_ctrl:1
	v_add_f32_dpp v51, v51, v51 row_shr:8 row_mask:0xf bank_mask:0xf bound_ctrl:1
	v_add_f32_dpp v52, v52, v52 row_shr:8 row_mask:0xf bank_mask:0xf bound_ctrl:1
	v_add_f32_dpp v53, v53, v53 row_shr:8 row_mask:0xf bank_mask:0xf bound_ctrl:1
	v_add_f32_dpp v54, v54, v54 row_shr:8 row_mask:0xf bank_mask:0xf bound_ctrl:1
	v_add_f32_dpp v55, v55, v55 row_shr:8 row_mask:0xf bank_mask:0xf bound_ctrl:1
	v_mov_b32_dpp v88, v48 row_newbcast:15 row_mask:0xf bank_mask:0xf
	v_mov_b32_dpp v89, v49 row_newbcast:15 row_mask:0xf bank_mask:0xf
	v_mov_b32_dpp v90, v50 row_newbcast:15 row_mask:0xf bank_mask:0xf
	v_mov_b32_dpp v91, v51 row_newbcast:15 row_mask:0xf bank_mask:0xf
	v_mov_b32_dpp v92, v52 row_newbcast:15 row_mask:0xf bank_mask:0xf
	v_mov_b32_dpp v93, v53 row_newbcast:15 row_mask:0xf bank_mask:0xf
	v_mov_b32_dpp v94, v54 row_newbcast:15 row_mask:0xf bank_mask:0xf
	v_mov_b32_dpp v95, v55 row_newbcast:15 row_mask:0xf bank_mask:0xf
	v_add_f32_e32 v48, v48, v178
	v_add_f32_e32 v52, v52, v179
	v_add_f32_e32 v49, v49, v180
	v_add_f32_e32 v53, v53, v181
	v_add_f32_e32 v50, v50, v182
	v_add_f32_e32 v54, v54, v183
	v_add_f32_e32 v51, v51, v184
	v_add_f32_e32 v55, v55, v185
	v_mul_f32_e32 v132, v48, v103
	v_mul_f32_e32 v48, v48, v102
	v_fma_f32 v48, -v52, v103, v48
	v_fma_f32 v52, v52, v102, v132
	v_mul_f32_e32 v133, v49, v107
	v_mul_f32_e32 v49, v49, v106
	v_fma_f32 v49, -v53, v107, v49
	v_fma_f32 v53, v53, v106, v133
	v_mul_f32_e32 v132, v50, v111
	v_mul_f32_e32 v50, v50, v110
	v_fma_f32 v50, -v54, v111, v50
	v_fma_f32 v54, v54, v110, v132
	v_mul_f32_e32 v133, v51, v115
	v_mul_f32_e32 v51, v51, v114
	v_fma_f32 v51, -v55, v115, v51
	v_fma_f32 v55, v55, v114, v133
	v_add_f32_e32 v88, v88, v178
	v_add_f32_e32 v92, v92, v179
	v_mul_f32_e32 v132, v92, v117
	v_mul_f32_e32 v179, v88, v117
	v_fma_f32 v178, v88, v116, -v132
	v_fma_f32 v179, v92, v116, v179
	v_add_f32_e32 v89, v89, v180
	v_add_f32_e32 v93, v93, v181
	v_mul_f32_e32 v133, v93, v121
	v_mul_f32_e32 v181, v89, v121
	v_fma_f32 v180, v89, v120, -v133
	v_fma_f32 v181, v93, v120, v181
	v_add_f32_e32 v90, v90, v182
	v_add_f32_e32 v94, v94, v183
	v_mul_f32_e32 v132, v94, v125
	v_mul_f32_e32 v183, v90, v125
	v_fma_f32 v182, v90, v124, -v132
	v_fma_f32 v183, v94, v124, v183
	v_add_f32_e32 v91, v91, v184
	v_add_f32_e32 v95, v95, v185
	v_mul_f32_e32 v133, v95, v129
	v_mul_f32_e32 v185, v91, v129
	v_fma_f32 v184, v91, v128, -v133
	v_fma_f32 v185, v95, v128, v185
	v_mul_f32_e32 v132, v56, v101
	v_mul_f32_e32 v56, v56, v100
	v_fma_f32 v56, -v60, v101, v56
	v_fma_f32 v60, v60, v100, v132
	v_mul_f32_e32 v133, v57, v105
	v_mul_f32_e32 v57, v57, v104
	v_fma_f32 v57, -v61, v105, v57
	v_fma_f32 v61, v61, v104, v133
	v_mul_f32_e32 v132, v58, v109
	v_mul_f32_e32 v58, v58, v108
	v_fma_f32 v58, -v62, v109, v58
	v_fma_f32 v62, v62, v108, v132
	v_mul_f32_e32 v133, v59, v113
	v_mul_f32_e32 v59, v59, v112
	v_fma_f32 v59, -v63, v113, v59
	v_fma_f32 v63, v63, v112, v133
	v_add_f32_dpp v56, v56, v56 row_shr:1 row_mask:0xf bank_mask:0xf bound_ctrl:1
	v_add_f32_dpp v57, v57, v57 row_shr:1 row_mask:0xf bank_mask:0xf bound_ctrl:1
	v_add_f32_dpp v58, v58, v58 row_shr:1 row_mask:0xf bank_mask:0xf bound_ctrl:1
	v_add_f32_dpp v59, v59, v59 row_shr:1 row_mask:0xf bank_mask:0xf bound_ctrl:1
	v_add_f32_dpp v60, v60, v60 row_shr:1 row_mask:0xf bank_mask:0xf bound_ctrl:1
	v_add_f32_dpp v61, v61, v61 row_shr:1 row_mask:0xf bank_mask:0xf bound_ctrl:1
	v_add_f32_dpp v62, v62, v62 row_shr:1 row_mask:0xf bank_mask:0xf bound_ctrl:1
	v_add_f32_dpp v63, v63, v63 row_shr:1 row_mask:0xf bank_mask:0xf bound_ctrl:1
	v_add_f32_dpp v56, v56, v56 row_shr:2 row_mask:0xf bank_mask:0xf bound_ctrl:1
	v_add_f32_dpp v57, v57, v57 row_shr:2 row_mask:0xf bank_mask:0xf bound_ctrl:1
	v_add_f32_dpp v58, v58, v58 row_shr:2 row_mask:0xf bank_mask:0xf bound_ctrl:1
	v_add_f32_dpp v59, v59, v59 row_shr:2 row_mask:0xf bank_mask:0xf bound_ctrl:1
	v_add_f32_dpp v60, v60, v60 row_shr:2 row_mask:0xf bank_mask:0xf bound_ctrl:1
	v_add_f32_dpp v61, v61, v61 row_shr:2 row_mask:0xf bank_mask:0xf bound_ctrl:1
	v_add_f32_dpp v62, v62, v62 row_shr:2 row_mask:0xf bank_mask:0xf bound_ctrl:1
	v_add_f32_dpp v63, v63, v63 row_shr:2 row_mask:0xf bank_mask:0xf bound_ctrl:1
	v_add_f32_dpp v56, v56, v56 row_shr:4 row_mask:0xf bank_mask:0xf bound_ctrl:1
	v_add_f32_dpp v57, v57, v57 row_shr:4 row_mask:0xf bank_mask:0xf bound_ctrl:1
	v_add_f32_dpp v58, v58, v58 row_shr:4 row_mask:0xf bank_mask:0xf bound_ctrl:1
	v_add_f32_dpp v59, v59, v59 row_shr:4 row_mask:0xf bank_mask:0xf bound_ctrl:1
	v_add_f32_dpp v60, v60, v60 row_shr:4 row_mask:0xf bank_mask:0xf bound_ctrl:1
	v_add_f32_dpp v61, v61, v61 row_shr:4 row_mask:0xf bank_mask:0xf bound_ctrl:1
	v_add_f32_dpp v62, v62, v62 row_shr:4 row_mask:0xf bank_mask:0xf bound_ctrl:1
	v_add_f32_dpp v63, v63, v63 row_shr:4 row_mask:0xf bank_mask:0xf bound_ctrl:1
	v_add_f32_dpp v56, v56, v56 row_shr:8 row_mask:0xf bank_mask:0xf bound_ctrl:1
	v_add_f32_dpp v57, v57, v57 row_shr:8 row_mask:0xf bank_mask:0xf bound_ctrl:1
	v_add_f32_dpp v58, v58, v58 row_shr:8 row_mask:0xf bank_mask:0xf bound_ctrl:1
	v_add_f32_dpp v59, v59, v59 row_shr:8 row_mask:0xf bank_mask:0xf bound_ctrl:1
	v_add_f32_dpp v60, v60, v60 row_shr:8 row_mask:0xf bank_mask:0xf bound_ctrl:1
	v_add_f32_dpp v61, v61, v61 row_shr:8 row_mask:0xf bank_mask:0xf bound_ctrl:1
	v_add_f32_dpp v62, v62, v62 row_shr:8 row_mask:0xf bank_mask:0xf bound_ctrl:1
	v_add_f32_dpp v63, v63, v63 row_shr:8 row_mask:0xf bank_mask:0xf bound_ctrl:1
	v_mov_b32_dpp v88, v56 row_newbcast:15 row_mask:0xf bank_mask:0xf
	v_mov_b32_dpp v89, v57 row_newbcast:15 row_mask:0xf bank_mask:0xf
	v_mov_b32_dpp v90, v58 row_newbcast:15 row_mask:0xf bank_mask:0xf
	v_mov_b32_dpp v91, v59 row_newbcast:15 row_mask:0xf bank_mask:0xf
	v_mov_b32_dpp v92, v60 row_newbcast:15 row_mask:0xf bank_mask:0xf
	v_mov_b32_dpp v93, v61 row_newbcast:15 row_mask:0xf bank_mask:0xf
	v_mov_b32_dpp v94, v62 row_newbcast:15 row_mask:0xf bank_mask:0xf
	v_mov_b32_dpp v95, v63 row_newbcast:15 row_mask:0xf bank_mask:0xf
	v_add_f32_e32 v56, v56, v178
	v_add_f32_e32 v60, v60, v179
	v_add_f32_e32 v57, v57, v180
	v_add_f32_e32 v61, v61, v181
	v_add_f32_e32 v58, v58, v182
	v_add_f32_e32 v62, v62, v183
	v_add_f32_e32 v59, v59, v184
	v_add_f32_e32 v63, v63, v185
	v_mul_f32_e32 v132, v56, v103
	v_mul_f32_e32 v56, v56, v102
	v_fma_f32 v56, -v60, v103, v56
	v_fma_f32 v60, v60, v102, v132
	v_mul_f32_e32 v133, v57, v107
	v_mul_f32_e32 v57, v57, v106
	v_fma_f32 v57, -v61, v107, v57
	v_fma_f32 v61, v61, v106, v133
	v_mul_f32_e32 v132, v58, v111
	v_mul_f32_e32 v58, v58, v110
	v_fma_f32 v58, -v62, v111, v58
	v_fma_f32 v62, v62, v110, v132
	v_mul_f32_e32 v133, v59, v115
	v_mul_f32_e32 v59, v59, v114
	v_fma_f32 v59, -v63, v115, v59
	v_fma_f32 v63, v63, v114, v133
	v_add_f32_e32 v88, v88, v178
	v_add_f32_e32 v92, v92, v179
	v_mul_f32_e32 v132, v92, v117
	v_mul_f32_e32 v179, v88, v117
	v_fma_f32 v178, v88, v116, -v132
	v_fma_f32 v179, v92, v116, v179
	v_add_f32_e32 v89, v89, v180
	v_add_f32_e32 v93, v93, v181
	v_mul_f32_e32 v133, v93, v121
	v_mul_f32_e32 v181, v89, v121
	v_fma_f32 v180, v89, v120, -v133
	v_fma_f32 v181, v93, v120, v181
	v_add_f32_e32 v90, v90, v182
	v_add_f32_e32 v94, v94, v183
	v_mul_f32_e32 v132, v94, v125
	v_mul_f32_e32 v183, v90, v125
	v_fma_f32 v182, v90, v124, -v132
	v_fma_f32 v183, v94, v124, v183
	v_add_f32_e32 v91, v91, v184
	v_add_f32_e32 v95, v95, v185
	v_mul_f32_e32 v133, v95, v129
	v_mul_f32_e32 v185, v91, v129
	v_fma_f32 v184, v91, v128, -v133
	v_fma_f32 v185, v95, v128, v185
	s_waitcnt vmcnt(14)
	v_cvt_pk_bf16_f32 v80, v80, v81
	v_cvt_pk_bf16_f32 v81, v82, v83
	v_cvt_pk_bf16_f32 v82, -v84, -v85
	v_cvt_pk_bf16_f32 v83, -v86, -v87
	v_cvt_pk_bf16_f32 v96, v32, v33
	v_cvt_pk_bf16_f32 v97, v34, v35
	v_cvt_pk_bf16_f32 v98, v36, v37
	v_cvt_pk_bf16_f32 v99, v38, v39
	s_nop 1
	v_mfma_f32_16x16x32_bf16 v[16:19], v[80:83], v[96:99], v[16:19]
	v_cvt_pk_bf16_f32 v96, v40, v41
	v_cvt_pk_bf16_f32 v97, v42, v43
	v_cvt_pk_bf16_f32 v98, v44, v45
	v_cvt_pk_bf16_f32 v99, v46, v47
	s_nop 1
	v_mfma_f32_16x16x32_bf16 v[20:23], v[80:83], v[96:99], v[20:23]
	v_cvt_pk_bf16_f32 v96, v48, v49
	v_cvt_pk_bf16_f32 v97, v50, v51
	v_cvt_pk_bf16_f32 v98, v52, v53
	v_cvt_pk_bf16_f32 v99, v54, v55
	s_nop 1
	v_mfma_f32_16x16x32_bf16 v[24:27], v[80:83], v[96:99], v[24:27]
	v_cvt_pk_bf16_f32 v96, v56, v57
	v_cvt_pk_bf16_f32 v97, v58, v59
	v_cvt_pk_bf16_f32 v98, v60, v61
	v_cvt_pk_bf16_f32 v99, v62, v63
	s_nop 1
	v_mfma_f32_16x16x32_bf16 v[28:31], v[80:83], v[96:99], v[28:31]
	s_waitcnt vmcnt(10)
	v_cvt_pk_bf16_f32 v64, v64, v65
	v_cvt_pk_bf16_f32 v65, v66, v67
	v_cvt_pk_bf16_f32 v66, v68, v69
	v_cvt_pk_bf16_f32 v67, v70, v71
	v_cvt_pk_bf16_f32 v72, v72, v73
	v_cvt_pk_bf16_f32 v73, v74, v75
	v_cvt_pk_bf16_f32 v74, v76, v77
	v_cvt_pk_bf16_f32 v75, v78, v79
	global_load_dwordx4 v[80:83], v136, s[38:39]
	global_load_dwordx4 v[84:87], v136, s[40:41]
	s_add_u32 s38, s38, 0x40
	s_addc_u32 s39, s39, 0
	s_add_u32 s40, s40, 0x40
	s_addc_u32 s41, s41, 0
	s_nop 0
	v_mfma_f32_16x16x32_bf16 v[32:35], v[64:67], v[0:3], 0
	v_mfma_f32_16x16x32_bf16 v[36:39], v[72:75], v[0:3], 0
	v_mfma_f32_16x16x32_bf16 v[40:43], v[64:67], v[4:7], 0
	v_mfma_f32_16x16x32_bf16 v[44:47], v[72:75], v[4:7], 0
	v_mfma_f32_16x16x32_bf16 v[48:51], v[64:67], v[8:11], 0
	v_mfma_f32_16x16x32_bf16 v[52:55], v[72:75], v[8:11], 0
	v_mfma_f32_16x16x32_bf16 v[56:59], v[64:67], v[12:15], 0
	v_mfma_f32_16x16x32_bf16 v[60:63], v[72:75], v[12:15], 0
	s_mov_b32 exec_hi, 0
	global_load_dwordx4 v[64:67], v135, s[20:21]
	global_load_dwordx4 v[68:71], v135, s[20:21] offset:16
	global_load_dwordx4 v[72:75], v135, s[22:23]
	global_load_dwordx4 v[76:79], v135, s[22:23] offset:16
	s_mov_b64 exec, -1
	global_load_dwordx4 v[100:103], v134, s[42:43] offset:0
	global_load_dwordx4 v[104:107], v134, s[42:43] offset:1024
	global_load_dwordx4 v[108:111], v134, s[42:43] offset:2048
	global_load_dwordx4 v[112:115], v134, s[42:43] offset:3072
	global_load_dwordx4 v[116:119], v208, s[42:43] offset:0
	global_load_dwordx4 v[120:123], v208, s[42:43] offset:1024
	global_load_dwordx4 v[124:127], v208, s[42:43] offset:2048
	global_load_dwordx4 v[128:131], v208, s[42:43] offset:3072
	global_load_dwordx4 v[178:181], v206, s[44:45]
	global_load_dwordx4 v[182:185], v206, s[44:45] offset:16
	s_waitcnt vmcnt(16)
	v_mul_f32_e32 v132, v171, v157
	v_mul_f32_e32 v133, v170, v157
	v_fma_f32 v170, v170, v156, -v132
	v_fma_f32 v171, v171, v156, v133
	v_mul_f32_e32 v132, v173, v161
	v_mul_f32_e32 v133, v172, v161
	v_fma_f32 v172, v172, v160, -v132
	v_fma_f32 v173, v173, v160, v133
	v_mul_f32_e32 v132, v175, v165
	v_mul_f32_e32 v133, v174, v165
	v_fma_f32 v174, v174, v164, -v132
	v_fma_f32 v175, v175, v164, v133
	v_mul_f32_e32 v132, v177, v169
	v_mul_f32_e32 v133, v176, v169
	v_fma_f32 v176, v176, v168, -v132
	v_fma_f32 v177, v177, v168, v133
	v_mul_f32_e32 v132, v32, v139
	v_mul_f32_e32 v32, v32, v138
	v_fma_f32 v32, -v36, v139, v32
	v_fma_f32 v36, v36, v138, v132
	v_mul_f32_e32 v133, v33, v143
	v_mul_f32_e32 v33, v33, v142
	v_fma_f32 v33, -v37, v143, v33
	v_fma_f32 v37, v37, v142, v133
	v_mul_f32_e32 v132, v34, v147
	v_mul_f32_e32 v34, v34, v146
	v_fma_f32 v34, -v38, v147, v34
	v_fma_f32 v38, v38, v146, v132
	v_mul_f32_e32 v133, v35, v151
	v_mul_f32_e32 v35, v35, v150
	v_fma_f32 v35, -v39, v151, v35
	v_fma_f32 v39, v39, v150, v133
	v_add_f32_dpp v32, v32, v32 row_shr:1 row_mask:0xf bank_mask:0xf bound_ctrl:1
	v_add_f32_dpp v33, v33, v33 row_shr:1 row_mask:0xf bank_mask:0xf bound_ctrl:1
	v_add_f32_dpp v34, v34, v34 row_shr:1 row_mask:0xf bank_mask:0xf bound_ctrl:1
	v_add_f32_dpp v35, v35, v35 row_shr:1 row_mask:0xf bank_mask:0xf bound_ctrl:1
	v_add_f32_dpp v36, v36, v36 row_shr:1 row_mask:0xf bank_mask:0xf bound_ctrl:1
	v_add_f32_dpp v37, v37, v37 row_shr:1 row_mask:0xf bank_mask:0xf bound_ctrl:1
	v_add_f32_dpp v38, v38, v38 row_shr:1 row_mask:0xf bank_mask:0xf bound_ctrl:1
	v_add_f32_dpp v39, v39, v39 row_shr:1 row_mask:0xf bank_mask:0xf bound_ctrl:1
	v_add_f32_dpp v32, v32, v32 row_shr:2 row_mask:0xf bank_mask:0xf bound_ctrl:1
	v_add_f32_dpp v33, v33, v33 row_shr:2 row_mask:0xf bank_mask:0xf bound_ctrl:1
	v_add_f32_dpp v34, v34, v34 row_shr:2 row_mask:0xf bank_mask:0xf bound_ctrl:1
	v_add_f32_dpp v35, v35, v35 row_shr:2 row_mask:0xf bank_mask:0xf bound_ctrl:1
	v_add_f32_dpp v36, v36, v36 row_shr:2 row_mask:0xf bank_mask:0xf bound_ctrl:1
	v_add_f32_dpp v37, v37, v37 row_shr:2 row_mask:0xf bank_mask:0xf bound_ctrl:1
	v_add_f32_dpp v38, v38, v38 row_shr:2 row_mask:0xf bank_mask:0xf bound_ctrl:1
	v_add_f32_dpp v39, v39, v39 row_shr:2 row_mask:0xf bank_mask:0xf bound_ctrl:1
	v_add_f32_dpp v32, v32, v32 row_shr:4 row_mask:0xf bank_mask:0xf bound_ctrl:1
	v_add_f32_dpp v33, v33, v33 row_shr:4 row_mask:0xf bank_mask:0xf bound_ctrl:1
	v_add_f32_dpp v34, v34, v34 row_shr:4 row_mask:0xf bank_mask:0xf bound_ctrl:1
	v_add_f32_dpp v35, v35, v35 row_shr:4 row_mask:0xf bank_mask:0xf bound_ctrl:1
	v_add_f32_dpp v36, v36, v36 row_shr:4 row_mask:0xf bank_mask:0xf bound_ctrl:1
	v_add_f32_dpp v37, v37, v37 row_shr:4 row_mask:0xf bank_mask:0xf bound_ctrl:1
	v_add_f32_dpp v38, v38, v38 row_shr:4 row_mask:0xf bank_mask:0xf bound_ctrl:1
	v_add_f32_dpp v39, v39, v39 row_shr:4 row_mask:0xf bank_mask:0xf bound_ctrl:1
	v_add_f32_dpp v32, v32, v32 row_shr:8 row_mask:0xf bank_mask:0xf bound_ctrl:1
	v_add_f32_dpp v33, v33, v33 row_shr:8 row_mask:0xf bank_mask:0xf bound_ctrl:1
	v_add_f32_dpp v34, v34, v34 row_shr:8 row_mask:0xf bank_mask:0xf bound_ctrl:1
	v_add_f32_dpp v35, v35, v35 row_shr:8 row_mask:0xf bank_mask:0xf bound_ctrl:1
	v_add_f32_dpp v36, v36, v36 row_shr:8 row_mask:0xf bank_mask:0xf bound_ctrl:1
	v_add_f32_dpp v37, v37, v37 row_shr:8 row_mask:0xf bank_mask:0xf bound_ctrl:1
	v_add_f32_dpp v38, v38, v38 row_shr:8 row_mask:0xf bank_mask:0xf bound_ctrl:1
	v_add_f32_dpp v39, v39, v39 row_shr:8 row_mask:0xf bank_mask:0xf bound_ctrl:1
	v_mov_b32_dpp v88, v32 row_newbcast:15 row_mask:0xf bank_mask:0xf
	v_mov_b32_dpp v89, v33 row_newbcast:15 row_mask:0xf bank_mask:0xf
	v_mov_b32_dpp v90, v34 row_newbcast:15 row_mask:0xf bank_mask:0xf
	v_mov_b32_dpp v91, v35 row_newbcast:15 row_mask:0xf bank_mask:0xf
	v_mov_b32_dpp v92, v36 row_newbcast:15 row_mask:0xf bank_mask:0xf
	v_mov_b32_dpp v93, v37 row_newbcast:15 row_mask:0xf bank_mask:0xf
	v_mov_b32_dpp v94, v38 row_newbcast:15 row_mask:0xf bank_mask:0xf
	v_mov_b32_dpp v95, v39 row_newbcast:15 row_mask:0xf bank_mask:0xf
	v_add_f32_e32 v32, v32, v170
	v_add_f32_e32 v36, v36, v171
	v_add_f32_e32 v33, v33, v172
	v_add_f32_e32 v37, v37, v173
	v_add_f32_e32 v34, v34, v174
	v_add_f32_e32 v38, v38, v175
	v_add_f32_e32 v35, v35, v176
	v_add_f32_e32 v39, v39, v177
	v_mul_f32_e32 v132, v32, v141
	v_mul_f32_e32 v32, v32, v140
	v_fma_f32 v32, -v36, v141, v32
	v_fma_f32 v36, v36, v140, v132
	v_mul_f32_e32 v133, v33, v145
	v_mul_f32_e32 v33, v33, v144
	v_fma_f32 v33, -v37, v145, v33
	v_fma_f32 v37, v37, v144, v133
	v_mul_f32_e32 v132, v34, v149
	v_mul_f32_e32 v34, v34, v148
	v_fma_f32 v34, -v38, v149, v34
	v_fma_f32 v38, v38, v148, v132
	v_mul_f32_e32 v133, v35, v153
	v_mul_f32_e32 v35, v35, v152
	v_fma_f32 v35, -v39, v153, v35
	v_fma_f32 v39, v39, v152, v133
	v_add_f32_e32 v88, v88, v170
	v_add_f32_e32 v92, v92, v171
	v_mul_f32_e32 v132, v92, v155
	v_mul_f32_e32 v171, v88, v155
	v_fma_f32 v170, v88, v154, -v132
	v_fma_f32 v171, v92, v154, v171
	v_add_f32_e32 v89, v89, v172
	v_add_f32_e32 v93, v93, v173
	v_mul_f32_e32 v133, v93, v159
	v_mul_f32_e32 v173, v89, v159
	v_fma_f32 v172, v89, v158, -v133
	v_fma_f32 v173, v93, v158, v173
	v_add_f32_e32 v90, v90, v174
	v_add_f32_e32 v94, v94, v175
	v_mul_f32_e32 v132, v94, v163
	v_mul_f32_e32 v175, v90, v163
	v_fma_f32 v174, v90, v162, -v132
	v_fma_f32 v175, v94, v162, v175
	v_add_f32_e32 v91, v91, v176
	v_add_f32_e32 v95, v95, v177
	v_mul_f32_e32 v133, v95, v167
	v_mul_f32_e32 v177, v91, v167
	v_fma_f32 v176, v91, v166, -v133
	v_fma_f32 v177, v95, v166, v177
	v_mul_f32_e32 v132, v40, v139
	v_mul_f32_e32 v40, v40, v138
	v_fma_f32 v40, -v44, v139, v40
	v_fma_f32 v44, v44, v138, v132
	v_mul_f32_e32 v133, v41, v143
	v_mul_f32_e32 v41, v41, v142
	v_fma_f32 v41, -v45, v143, v41
	v_fma_f32 v45, v45, v142, v133
	v_mul_f32_e32 v132, v42, v147
	v_mul_f32_e32 v42, v42, v146
	v_fma_f32 v42, -v46, v147, v42
	v_fma_f32 v46, v46, v146, v132
	v_mul_f32_e32 v133, v43, v151
	v_mul_f32_e32 v43, v43, v150
	v_fma_f32 v43, -v47, v151, v43
	v_fma_f32 v47, v47, v150, v133
	v_add_f32_dpp v40, v40, v40 row_shr:1 row_mask:0xf bank_mask:0xf bound_ctrl:1
	v_add_f32_dpp v41, v41, v41 row_shr:1 row_mask:0xf bank_mask:0xf bound_ctrl:1
	v_add_f32_dpp v42, v42, v42 row_shr:1 row_mask:0xf bank_mask:0xf bound_ctrl:1
	v_add_f32_dpp v43, v43, v43 row_shr:1 row_mask:0xf bank_mask:0xf bound_ctrl:1
	v_add_f32_dpp v44, v44, v44 row_shr:1 row_mask:0xf bank_mask:0xf bound_ctrl:1
	v_add_f32_dpp v45, v45, v45 row_shr:1 row_mask:0xf bank_mask:0xf bound_ctrl:1
	v_add_f32_dpp v46, v46, v46 row_shr:1 row_mask:0xf bank_mask:0xf bound_ctrl:1
	v_add_f32_dpp v47, v47, v47 row_shr:1 row_mask:0xf bank_mask:0xf bound_ctrl:1
	v_add_f32_dpp v40, v40, v40 row_shr:2 row_mask:0xf bank_mask:0xf bound_ctrl:1
	v_add_f32_dpp v41, v41, v41 row_shr:2 row_mask:0xf bank_mask:0xf bound_ctrl:1
	v_add_f32_dpp v42, v42, v42 row_shr:2 row_mask:0xf bank_mask:0xf bound_ctrl:1
	v_add_f32_dpp v43, v43, v43 row_shr:2 row_mask:0xf bank_mask:0xf bound_ctrl:1
	v_add_f32_dpp v44, v44, v44 row_shr:2 row_mask:0xf bank_mask:0xf bound_ctrl:1
	v_add_f32_dpp v45, v45, v45 row_shr:2 row_mask:0xf bank_mask:0xf bound_ctrl:1
	v_add_f32_dpp v46, v46, v46 row_shr:2 row_mask:0xf bank_mask:0xf bound_ctrl:1
	v_add_f32_dpp v47, v47, v47 row_shr:2 row_mask:0xf bank_mask:0xf bound_ctrl:1
	v_add_f32_dpp v40, v40, v40 row_shr:4 row_mask:0xf bank_mask:0xf bound_ctrl:1
	v_add_f32_dpp v41, v41, v41 row_shr:4 row_mask:0xf bank_mask:0xf bound_ctrl:1
	v_add_f32_dpp v42, v42, v42 row_shr:4 row_mask:0xf bank_mask:0xf bound_ctrl:1
	v_add_f32_dpp v43, v43, v43 row_shr:4 row_mask:0xf bank_mask:0xf bound_ctrl:1
	v_add_f32_dpp v44, v44, v44 row_shr:4 row_mask:0xf bank_mask:0xf bound_ctrl:1
	v_add_f32_dpp v45, v45, v45 row_shr:4 row_mask:0xf bank_mask:0xf bound_ctrl:1
	v_add_f32_dpp v46, v46, v46 row_shr:4 row_mask:0xf bank_mask:0xf bound_ctrl:1
	v_add_f32_dpp v47, v47, v47 row_shr:4 row_mask:0xf bank_mask:0xf bound_ctrl:1
	v_add_f32_dpp v40, v40, v40 row_shr:8 row_mask:0xf bank_mask:0xf bound_ctrl:1
	v_add_f32_dpp v41, v41, v41 row_shr:8 row_mask:0xf bank_mask:0xf bound_ctrl:1
	v_add_f32_dpp v42, v42, v42 row_shr:8 row_mask:0xf bank_mask:0xf bound_ctrl:1
	v_add_f32_dpp v43, v43, v43 row_shr:8 row_mask:0xf bank_mask:0xf bound_ctrl:1
	v_add_f32_dpp v44, v44, v44 row_shr:8 row_mask:0xf bank_mask:0xf bound_ctrl:1
	v_add_f32_dpp v45, v45, v45 row_shr:8 row_mask:0xf bank_mask:0xf bound_ctrl:1
	v_add_f32_dpp v46, v46, v46 row_shr:8 row_mask:0xf bank_mask:0xf bound_ctrl:1
	v_add_f32_dpp v47, v47, v47 row_shr:8 row_mask:0xf bank_mask:0xf bound_ctrl:1
	v_mov_b32_dpp v88, v40 row_newbcast:15 row_mask:0xf bank_mask:0xf
	v_mov_b32_dpp v89, v41 row_newbcast:15 row_mask:0xf bank_mask:0xf
	v_mov_b32_dpp v90, v42 row_newbcast:15 row_mask:0xf bank_mask:0xf
	v_mov_b32_dpp v91, v43 row_newbcast:15 row_mask:0xf bank_mask:0xf
	v_mov_b32_dpp v92, v44 row_newbcast:15 row_mask:0xf bank_mask:0xf
	v_mov_b32_dpp v93, v45 row_newbcast:15 row_mask:0xf bank_mask:0xf
	v_mov_b32_dpp v94, v46 row_newbcast:15 row_mask:0xf bank_mask:0xf
	v_mov_b32_dpp v95, v47 row_newbcast:15 row_mask:0xf bank_mask:0xf
	v_add_f32_e32 v40, v40, v170
	v_add_f32_e32 v44, v44, v171
	v_add_f32_e32 v41, v41, v172
	v_add_f32_e32 v45, v45, v173
	v_add_f32_e32 v42, v42, v174
	v_add_f32_e32 v46, v46, v175
	v_add_f32_e32 v43, v43, v176
	v_add_f32_e32 v47, v47, v177
	v_mul_f32_e32 v132, v40, v141
	v_mul_f32_e32 v40, v40, v140
	v_fma_f32 v40, -v44, v141, v40
	v_fma_f32 v44, v44, v140, v132
	v_mul_f32_e32 v133, v41, v145
	v_mul_f32_e32 v41, v41, v144
	v_fma_f32 v41, -v45, v145, v41
	v_fma_f32 v45, v45, v144, v133
	v_mul_f32_e32 v132, v42, v149
	v_mul_f32_e32 v42, v42, v148
	v_fma_f32 v42, -v46, v149, v42
	v_fma_f32 v46, v46, v148, v132
	v_mul_f32_e32 v133, v43, v153
	v_mul_f32_e32 v43, v43, v152
	v_fma_f32 v43, -v47, v153, v43
	v_fma_f32 v47, v47, v152, v133
	v_add_f32_e32 v88, v88, v170
	v_add_f32_e32 v92, v92, v171
	v_mul_f32_e32 v132, v92, v155
	v_mul_f32_e32 v171, v88, v155
	v_fma_f32 v170, v88, v154, -v132
	v_fma_f32 v171, v92, v154, v171
	v_add_f32_e32 v89, v89, v172
	v_add_f32_e32 v93, v93, v173
	v_mul_f32_e32 v133, v93, v159
	v_mul_f32_e32 v173, v89, v159
	v_fma_f32 v172, v89, v158, -v133
	v_fma_f32 v173, v93, v158, v173
	v_add_f32_e32 v90, v90, v174
	v_add_f32_e32 v94, v94, v175
	v_mul_f32_e32 v132, v94, v163
	v_mul_f32_e32 v175, v90, v163
	v_fma_f32 v174, v90, v162, -v132
	v_fma_f32 v175, v94, v162, v175
	v_add_f32_e32 v91, v91, v176
	v_add_f32_e32 v95, v95, v177
	v_mul_f32_e32 v133, v95, v167
	v_mul_f32_e32 v177, v91, v167
	v_fma_f32 v176, v91, v166, -v133
	v_fma_f32 v177, v95, v166, v177
	v_mul_f32_e32 v132, v48, v139
	v_mul_f32_e32 v48, v48, v138
	v_fma_f32 v48, -v52, v139, v48
	v_fma_f32 v52, v52, v138, v132
	v_mul_f32_e32 v133, v49, v143
	v_mul_f32_e32 v49, v49, v142
	v_fma_f32 v49, -v53, v143, v49
	v_fma_f32 v53, v53, v142, v133
	v_mul_f32_e32 v132, v50, v147
	v_mul_f32_e32 v50, v50, v146
	v_fma_f32 v50, -v54, v147, v50
	v_fma_f32 v54, v54, v146, v132
	v_mul_f32_e32 v133, v51, v151
	v_mul_f32_e32 v51, v51, v150
	v_fma_f32 v51, -v55, v151, v51
	v_fma_f32 v55, v55, v150, v133
	v_add_f32_dpp v48, v48, v48 row_shr:1 row_mask:0xf bank_mask:0xf bound_ctrl:1
	v_add_f32_dpp v49, v49, v49 row_shr:1 row_mask:0xf bank_mask:0xf bound_ctrl:1
	v_add_f32_dpp v50, v50, v50 row_shr:1 row_mask:0xf bank_mask:0xf bound_ctrl:1
	v_add_f32_dpp v51, v51, v51 row_shr:1 row_mask:0xf bank_mask:0xf bound_ctrl:1
	v_add_f32_dpp v52, v52, v52 row_shr:1 row_mask:0xf bank_mask:0xf bound_ctrl:1
	v_add_f32_dpp v53, v53, v53 row_shr:1 row_mask:0xf bank_mask:0xf bound_ctrl:1
	v_add_f32_dpp v54, v54, v54 row_shr:1 row_mask:0xf bank_mask:0xf bound_ctrl:1
	v_add_f32_dpp v55, v55, v55 row_shr:1 row_mask:0xf bank_mask:0xf bound_ctrl:1
	v_add_f32_dpp v48, v48, v48 row_shr:2 row_mask:0xf bank_mask:0xf bound_ctrl:1
	v_add_f32_dpp v49, v49, v49 row_shr:2 row_mask:0xf bank_mask:0xf bound_ctrl:1
	v_add_f32_dpp v50, v50, v50 row_shr:2 row_mask:0xf bank_mask:0xf bound_ctrl:1
	v_add_f32_dpp v51, v51, v51 row_shr:2 row_mask:0xf bank_mask:0xf bound_ctrl:1
	v_add_f32_dpp v52, v52, v52 row_shr:2 row_mask:0xf bank_mask:0xf bound_ctrl:1
	v_add_f32_dpp v53, v53, v53 row_shr:2 row_mask:0xf bank_mask:0xf bound_ctrl:1
	v_add_f32_dpp v54, v54, v54 row_shr:2 row_mask:0xf bank_mask:0xf bound_ctrl:1
	v_add_f32_dpp v55, v55, v55 row_shr:2 row_mask:0xf bank_mask:0xf bound_ctrl:1
	v_add_f32_dpp v48, v48, v48 row_shr:4 row_mask:0xf bank_mask:0xf bound_ctrl:1
	v_add_f32_dpp v49, v49, v49 row_shr:4 row_mask:0xf bank_mask:0xf bound_ctrl:1
	v_add_f32_dpp v50, v50, v50 row_shr:4 row_mask:0xf bank_mask:0xf bound_ctrl:1
	v_add_f32_dpp v51, v51, v51 row_shr:4 row_mask:0xf bank_mask:0xf bound_ctrl:1
	v_add_f32_dpp v52, v52, v52 row_shr:4 row_mask:0xf bank_mask:0xf bound_ctrl:1
	v_add_f32_dpp v53, v53, v53 row_shr:4 row_mask:0xf bank_mask:0xf bound_ctrl:1
	v_add_f32_dpp v54, v54, v54 row_shr:4 row_mask:0xf bank_mask:0xf bound_ctrl:1
	v_add_f32_dpp v55, v55, v55 row_shr:4 row_mask:0xf bank_mask:0xf bound_ctrl:1
	v_add_f32_dpp v48, v48, v48 row_shr:8 row_mask:0xf bank_mask:0xf bound_ctrl:1
	v_add_f32_dpp v49, v49, v49 row_shr:8 row_mask:0xf bank_mask:0xf bound_ctrl:1
	v_add_f32_dpp v50, v50, v50 row_shr:8 row_mask:0xf bank_mask:0xf bound_ctrl:1
	v_add_f32_dpp v51, v51, v51 row_shr:8 row_mask:0xf bank_mask:0xf bound_ctrl:1
	v_add_f32_dpp v52, v52, v52 row_shr:8 row_mask:0xf bank_mask:0xf bound_ctrl:1
	v_add_f32_dpp v53, v53, v53 row_shr:8 row_mask:0xf bank_mask:0xf bound_ctrl:1
	v_add_f32_dpp v54, v54, v54 row_shr:8 row_mask:0xf bank_mask:0xf bound_ctrl:1
	v_add_f32_dpp v55, v55, v55 row_shr:8 row_mask:0xf bank_mask:0xf bound_ctrl:1
	v_mov_b32_dpp v88, v48 row_newbcast:15 row_mask:0xf bank_mask:0xf
	v_mov_b32_dpp v89, v49 row_newbcast:15 row_mask:0xf bank_mask:0xf
	v_mov_b32_dpp v90, v50 row_newbcast:15 row_mask:0xf bank_mask:0xf
	v_mov_b32_dpp v91, v51 row_newbcast:15 row_mask:0xf bank_mask:0xf
	v_mov_b32_dpp v92, v52 row_newbcast:15 row_mask:0xf bank_mask:0xf
	v_mov_b32_dpp v93, v53 row_newbcast:15 row_mask:0xf bank_mask:0xf
	v_mov_b32_dpp v94, v54 row_newbcast:15 row_mask:0xf bank_mask:0xf
	v_mov_b32_dpp v95, v55 row_newbcast:15 row_mask:0xf bank_mask:0xf
	v_add_f32_e32 v48, v48, v170
	v_add_f32_e32 v52, v52, v171
	v_add_f32_e32 v49, v49, v172
	v_add_f32_e32 v53, v53, v173
	v_add_f32_e32 v50, v50, v174
	v_add_f32_e32 v54, v54, v175
	v_add_f32_e32 v51, v51, v176
	v_add_f32_e32 v55, v55, v177
	v_mul_f32_e32 v132, v48, v141
	v_mul_f32_e32 v48, v48, v140
	v_fma_f32 v48, -v52, v141, v48
	v_fma_f32 v52, v52, v140, v132
	v_mul_f32_e32 v133, v49, v145
	v_mul_f32_e32 v49, v49, v144
	v_fma_f32 v49, -v53, v145, v49
	v_fma_f32 v53, v53, v144, v133
	v_mul_f32_e32 v132, v50, v149
	v_mul_f32_e32 v50, v50, v148
	v_fma_f32 v50, -v54, v149, v50
	v_fma_f32 v54, v54, v148, v132
	v_mul_f32_e32 v133, v51, v153
	v_mul_f32_e32 v51, v51, v152
	v_fma_f32 v51, -v55, v153, v51
	v_fma_f32 v55, v55, v152, v133
	v_add_f32_e32 v88, v88, v170
	v_add_f32_e32 v92, v92, v171
	v_mul_f32_e32 v132, v92, v155
	v_mul_f32_e32 v171, v88, v155
	v_fma_f32 v170, v88, v154, -v132
	v_fma_f32 v171, v92, v154, v171
	v_add_f32_e32 v89, v89, v172
	v_add_f32_e32 v93, v93, v173
	v_mul_f32_e32 v133, v93, v159
	v_mul_f32_e32 v173, v89, v159
	v_fma_f32 v172, v89, v158, -v133
	v_fma_f32 v173, v93, v158, v173
	v_add_f32_e32 v90, v90, v174
	v_add_f32_e32 v94, v94, v175
	v_mul_f32_e32 v132, v94, v163
	v_mul_f32_e32 v175, v90, v163
	v_fma_f32 v174, v90, v162, -v132
	v_fma_f32 v175, v94, v162, v175
	v_add_f32_e32 v91, v91, v176
	v_add_f32_e32 v95, v95, v177
	v_mul_f32_e32 v133, v95, v167
	v_mul_f32_e32 v177, v91, v167
	v_fma_f32 v176, v91, v166, -v133
	v_fma_f32 v177, v95, v166, v177
	v_mul_f32_e32 v132, v56, v139
	v_mul_f32_e32 v56, v56, v138
	v_fma_f32 v56, -v60, v139, v56
	v_fma_f32 v60, v60, v138, v132
	v_mul_f32_e32 v133, v57, v143
	v_mul_f32_e32 v57, v57, v142
	v_fma_f32 v57, -v61, v143, v57
	v_fma_f32 v61, v61, v142, v133
	v_mul_f32_e32 v132, v58, v147
	v_mul_f32_e32 v58, v58, v146
	v_fma_f32 v58, -v62, v147, v58
	v_fma_f32 v62, v62, v146, v132
	v_mul_f32_e32 v133, v59, v151
	v_mul_f32_e32 v59, v59, v150
	v_fma_f32 v59, -v63, v151, v59
	v_fma_f32 v63, v63, v150, v133
	v_add_f32_dpp v56, v56, v56 row_shr:1 row_mask:0xf bank_mask:0xf bound_ctrl:1
	v_add_f32_dpp v57, v57, v57 row_shr:1 row_mask:0xf bank_mask:0xf bound_ctrl:1
	v_add_f32_dpp v58, v58, v58 row_shr:1 row_mask:0xf bank_mask:0xf bound_ctrl:1
	v_add_f32_dpp v59, v59, v59 row_shr:1 row_mask:0xf bank_mask:0xf bound_ctrl:1
	v_add_f32_dpp v60, v60, v60 row_shr:1 row_mask:0xf bank_mask:0xf bound_ctrl:1
	v_add_f32_dpp v61, v61, v61 row_shr:1 row_mask:0xf bank_mask:0xf bound_ctrl:1
	v_add_f32_dpp v62, v62, v62 row_shr:1 row_mask:0xf bank_mask:0xf bound_ctrl:1
	v_add_f32_dpp v63, v63, v63 row_shr:1 row_mask:0xf bank_mask:0xf bound_ctrl:1
	v_add_f32_dpp v56, v56, v56 row_shr:2 row_mask:0xf bank_mask:0xf bound_ctrl:1
	v_add_f32_dpp v57, v57, v57 row_shr:2 row_mask:0xf bank_mask:0xf bound_ctrl:1
	v_add_f32_dpp v58, v58, v58 row_shr:2 row_mask:0xf bank_mask:0xf bound_ctrl:1
	v_add_f32_dpp v59, v59, v59 row_shr:2 row_mask:0xf bank_mask:0xf bound_ctrl:1
	v_add_f32_dpp v60, v60, v60 row_shr:2 row_mask:0xf bank_mask:0xf bound_ctrl:1
	v_add_f32_dpp v61, v61, v61 row_shr:2 row_mask:0xf bank_mask:0xf bound_ctrl:1
	v_add_f32_dpp v62, v62, v62 row_shr:2 row_mask:0xf bank_mask:0xf bound_ctrl:1
	v_add_f32_dpp v63, v63, v63 row_shr:2 row_mask:0xf bank_mask:0xf bound_ctrl:1
	v_add_f32_dpp v56, v56, v56 row_shr:4 row_mask:0xf bank_mask:0xf bound_ctrl:1
	v_add_f32_dpp v57, v57, v57 row_shr:4 row_mask:0xf bank_mask:0xf bound_ctrl:1
	v_add_f32_dpp v58, v58, v58 row_shr:4 row_mask:0xf bank_mask:0xf bound_ctrl:1
	v_add_f32_dpp v59, v59, v59 row_shr:4 row_mask:0xf bank_mask:0xf bound_ctrl:1
	v_add_f32_dpp v60, v60, v60 row_shr:4 row_mask:0xf bank_mask:0xf bound_ctrl:1
	v_add_f32_dpp v61, v61, v61 row_shr:4 row_mask:0xf bank_mask:0xf bound_ctrl:1
	v_add_f32_dpp v62, v62, v62 row_shr:4 row_mask:0xf bank_mask:0xf bound_ctrl:1
	v_add_f32_dpp v63, v63, v63 row_shr:4 row_mask:0xf bank_mask:0xf bound_ctrl:1
	v_add_f32_dpp v56, v56, v56 row_shr:8 row_mask:0xf bank_mask:0xf bound_ctrl:1
	v_add_f32_dpp v57, v57, v57 row_shr:8 row_mask:0xf bank_mask:0xf bound_ctrl:1
	v_add_f32_dpp v58, v58, v58 row_shr:8 row_mask:0xf bank_mask:0xf bound_ctrl:1
	v_add_f32_dpp v59, v59, v59 row_shr:8 row_mask:0xf bank_mask:0xf bound_ctrl:1
	v_add_f32_dpp v60, v60, v60 row_shr:8 row_mask:0xf bank_mask:0xf bound_ctrl:1
	v_add_f32_dpp v61, v61, v61 row_shr:8 row_mask:0xf bank_mask:0xf bound_ctrl:1
	v_add_f32_dpp v62, v62, v62 row_shr:8 row_mask:0xf bank_mask:0xf bound_ctrl:1
	v_add_f32_dpp v63, v63, v63 row_shr:8 row_mask:0xf bank_mask:0xf bound_ctrl:1
	v_mov_b32_dpp v88, v56 row_newbcast:15 row_mask:0xf bank_mask:0xf
	v_mov_b32_dpp v89, v57 row_newbcast:15 row_mask:0xf bank_mask:0xf
	v_mov_b32_dpp v90, v58 row_newbcast:15 row_mask:0xf bank_mask:0xf
	v_mov_b32_dpp v91, v59 row_newbcast:15 row_mask:0xf bank_mask:0xf
	v_mov_b32_dpp v92, v60 row_newbcast:15 row_mask:0xf bank_mask:0xf
	v_mov_b32_dpp v93, v61 row_newbcast:15 row_mask:0xf bank_mask:0xf
	v_mov_b32_dpp v94, v62 row_newbcast:15 row_mask:0xf bank_mask:0xf
	v_mov_b32_dpp v95, v63 row_newbcast:15 row_mask:0xf bank_mask:0xf
	v_add_f32_e32 v56, v56, v170
	v_add_f32_e32 v60, v60, v171
	v_add_f32_e32 v57, v57, v172
	v_add_f32_e32 v61, v61, v173
	v_add_f32_e32 v58, v58, v174
	v_add_f32_e32 v62, v62, v175
	v_add_f32_e32 v59, v59, v176
	v_add_f32_e32 v63, v63, v177
	v_mul_f32_e32 v132, v56, v141
	v_mul_f32_e32 v56, v56, v140
	v_fma_f32 v56, -v60, v141, v56
	v_fma_f32 v60, v60, v140, v132
	v_mul_f32_e32 v133, v57, v145
	v_mul_f32_e32 v57, v57, v144
	v_fma_f32 v57, -v61, v145, v57
	v_fma_f32 v61, v61, v144, v133
	v_mul_f32_e32 v132, v58, v149
	v_mul_f32_e32 v58, v58, v148
	v_fma_f32 v58, -v62, v149, v58
	v_fma_f32 v62, v62, v148, v132
	v_mul_f32_e32 v133, v59, v153
	v_mul_f32_e32 v59, v59, v152
	v_fma_f32 v59, -v63, v153, v59
	v_fma_f32 v63, v63, v152, v133
	v_add_f32_e32 v88, v88, v170
	v_add_f32_e32 v92, v92, v171
	v_mul_f32_e32 v132, v92, v155
	v_mul_f32_e32 v171, v88, v155
	v_fma_f32 v170, v88, v154, -v132
	v_fma_f32 v171, v92, v154, v171
	v_add_f32_e32 v89, v89, v172
	v_add_f32_e32 v93, v93, v173
	v_mul_f32_e32 v133, v93, v159
	v_mul_f32_e32 v173, v89, v159
	v_fma_f32 v172, v89, v158, -v133
	v_fma_f32 v173, v93, v158, v173
	v_add_f32_e32 v90, v90, v174
	v_add_f32_e32 v94, v94, v175
	v_mul_f32_e32 v132, v94, v163
	v_mul_f32_e32 v175, v90, v163
	v_fma_f32 v174, v90, v162, -v132
	v_fma_f32 v175, v94, v162, v175
	v_add_f32_e32 v91, v91, v176
	v_add_f32_e32 v95, v95, v177
	v_mul_f32_e32 v133, v95, v167
	v_mul_f32_e32 v177, v91, v167
	v_fma_f32 v176, v91, v166, -v133
	v_fma_f32 v177, v95, v166, v177
	s_waitcnt vmcnt(14)
	v_cvt_pk_bf16_f32 v80, v80, v81
	v_cvt_pk_bf16_f32 v81, v82, v83
	v_cvt_pk_bf16_f32 v82, -v84, -v85
	v_cvt_pk_bf16_f32 v83, -v86, -v87
	v_cvt_pk_bf16_f32 v96, v32, v33
	v_cvt_pk_bf16_f32 v97, v34, v35
	v_cvt_pk_bf16_f32 v98, v36, v37
	v_cvt_pk_bf16_f32 v99, v38, v39
	s_nop 1
	v_mfma_f32_16x16x32_bf16 v[16:19], v[80:83], v[96:99], v[16:19]
	v_cvt_pk_bf16_f32 v96, v40, v41
	v_cvt_pk_bf16_f32 v97, v42, v43
	v_cvt_pk_bf16_f32 v98, v44, v45
	v_cvt_pk_bf16_f32 v99, v46, v47
	s_nop 1
	v_mfma_f32_16x16x32_bf16 v[20:23], v[80:83], v[96:99], v[20:23]
	v_cvt_pk_bf16_f32 v96, v48, v49
	v_cvt_pk_bf16_f32 v97, v50, v51
	v_cvt_pk_bf16_f32 v98, v52, v53
	v_cvt_pk_bf16_f32 v99, v54, v55
	s_nop 1
	v_mfma_f32_16x16x32_bf16 v[24:27], v[80:83], v[96:99], v[24:27]
	v_cvt_pk_bf16_f32 v96, v56, v57
	v_cvt_pk_bf16_f32 v97, v58, v59
	v_cvt_pk_bf16_f32 v98, v60, v61
	v_cvt_pk_bf16_f32 v99, v62, v63
	s_nop 1
	v_mfma_f32_16x16x32_bf16 v[28:31], v[80:83], v[96:99], v[28:31]
	s_waitcnt vmcnt(10)
	v_cvt_pk_bf16_f32 v64, v64, v65
	v_cvt_pk_bf16_f32 v65, v66, v67
	v_cvt_pk_bf16_f32 v66, v68, v69
	v_cvt_pk_bf16_f32 v67, v70, v71
	v_cvt_pk_bf16_f32 v72, v72, v73
	v_cvt_pk_bf16_f32 v73, v74, v75
	v_cvt_pk_bf16_f32 v74, v76, v77
	v_cvt_pk_bf16_f32 v75, v78, v79
	global_load_dwordx4 v[80:83], v136, s[38:39]
	global_load_dwordx4 v[84:87], v136, s[40:41]
	s_nop 0
	v_mfma_f32_16x16x32_bf16 v[32:35], v[64:67], v[0:3], 0
	v_mfma_f32_16x16x32_bf16 v[36:39], v[72:75], v[0:3], 0
	v_mfma_f32_16x16x32_bf16 v[40:43], v[64:67], v[4:7], 0
	v_mfma_f32_16x16x32_bf16 v[44:47], v[72:75], v[4:7], 0
	v_mfma_f32_16x16x32_bf16 v[48:51], v[64:67], v[8:11], 0
	v_mfma_f32_16x16x32_bf16 v[52:55], v[72:75], v[8:11], 0
	v_mfma_f32_16x16x32_bf16 v[56:59], v[64:67], v[12:15], 0
	v_mfma_f32_16x16x32_bf16 v[60:63], v[72:75], v[12:15], 0
	v_readlane_b32 s10, v247, 28
	s_sub_i32 s11, 3, s8
	s_sub_i32 s17, 71, s8
	s_cmp_lt_u32 s8, 4
	s_cselect_b32 s11, s11, s17
	s_lshl_b32 s16, s10, 1
	s_add_i32 s16, s16, 1
	s_lshl_b32 s16, s16, 4
	s_add_i32 s16, s16, s7
	s_lshl_b32 s17, s6, 1
	s_add_i32 s17, s17, 1
	s_lshl_b32 s17, s17, 4
	s_add_i32 s17, s17, s7
	s_mul_i32 s17, s17, 68
	s_add_i32 s17, s17, s11
	s_lshl_b32 s17, s17, 6
	s_lshl_b32 s20, s16, 12
	s_add_u32 s20, s20, 0x11fb20
	s_add_u32 s20, s4, s20
	s_addc_u32 s21, s5, 0
	s_add_u32 s22, s20, 0x40000
	s_addc_u32 s23, s21, 0
	s_lshl_b32 s38, s16, 12
	s_add_u32 s38, s38, 0x19fb20
	s_add_u32 s38, s4, s38
	s_addc_u32 s39, s5, 0
	s_add_u32 s40, s38, 0x40000
	s_addc_u32 s41, s39, 0
	s_lshl_b32 s42, s16, 15
	s_add_u32 s42, s42, 0xf900000
	s_add_u32 s42, s4, s42
	s_addc_u32 s43, s5, 0
	s_lshl_b32 s44, s17, 3
	s_add_u32 s44, s44, 0x740000
	s_add_u32 s44, s4, s44
	s_addc_u32 s45, s5, 0
	s_mov_b32 exec_hi, 0
	global_load_dwordx4 v[64:67], v135, s[20:21]
	global_load_dwordx4 v[68:71], v135, s[20:21] offset:16
	global_load_dwordx4 v[72:75], v135, s[22:23]
	global_load_dwordx4 v[76:79], v135, s[22:23] offset:16
	s_mov_b64 exec, -1
	s_add_u32 s20, s20, 0x400
	s_addc_u32 s21, s21, 0
	s_add_u32 s22, s22, 0x400
	s_addc_u32 s23, s23, 0
	global_load_dwordx4 v[138:141], v134, s[42:43] offset:0
	global_load_dwordx4 v[142:145], v134, s[42:43] offset:1024
	global_load_dwordx4 v[146:149], v134, s[42:43] offset:2048
	global_load_dwordx4 v[150:153], v134, s[42:43] offset:3072
	global_load_dwordx4 v[154:157], v208, s[42:43] offset:0
	global_load_dwordx4 v[158:161], v208, s[42:43] offset:1024
	global_load_dwordx4 v[162:165], v208, s[42:43] offset:2048
	global_load_dwordx4 v[166:169], v208, s[42:43] offset:3072
	global_load_dwordx4 v[170:173], v206, s[44:45]
	global_load_dwordx4 v[174:177], v206, s[44:45] offset:16
	s_add_u32 s42, s42, 0x2000
	s_addc_u32 s43, s43, 0
	s_add_u32 s44, s44, 0x80
	s_addc_u32 s45, s45, 0
	s_waitcnt vmcnt(16)
	v_mul_f32_e32 v132, v179, v119
	v_mul_f32_e32 v133, v178, v119
	v_fma_f32 v178, v178, v118, -v132
	v_fma_f32 v179, v179, v118, v133
	v_mul_f32_e32 v132, v181, v123
	v_mul_f32_e32 v133, v180, v123
	v_fma_f32 v180, v180, v122, -v132
	v_fma_f32 v181, v181, v122, v133
	v_mul_f32_e32 v132, v183, v127
	v_mul_f32_e32 v133, v182, v127
	v_fma_f32 v182, v182, v126, -v132
	v_fma_f32 v183, v183, v126, v133
	v_mul_f32_e32 v132, v185, v131
	v_mul_f32_e32 v133, v184, v131
	v_fma_f32 v184, v184, v130, -v132
	v_fma_f32 v185, v185, v130, v133
	v_mul_f32_e32 v132, v32, v101
	v_mul_f32_e32 v32, v32, v100
	v_fma_f32 v32, -v36, v101, v32
	v_fma_f32 v36, v36, v100, v132
	v_mul_f32_e32 v133, v33, v105
	v_mul_f32_e32 v33, v33, v104
	v_fma_f32 v33, -v37, v105, v33
	v_fma_f32 v37, v37, v104, v133
	v_mul_f32_e32 v132, v34, v109
	v_mul_f32_e32 v34, v34, v108
	v_fma_f32 v34, -v38, v109, v34
	v_fma_f32 v38, v38, v108, v132
	v_mul_f32_e32 v133, v35, v113
	v_mul_f32_e32 v35, v35, v112
	v_fma_f32 v35, -v39, v113, v35
	v_fma_f32 v39, v39, v112, v133
	v_add_f32_dpp v32, v32, v32 row_shr:1 row_mask:0xf bank_mask:0xf bound_ctrl:1
	v_add_f32_dpp v33, v33, v33 row_shr:1 row_mask:0xf bank_mask:0xf bound_ctrl:1
	v_add_f32_dpp v34, v34, v34 row_shr:1 row_mask:0xf bank_mask:0xf bound_ctrl:1
	v_add_f32_dpp v35, v35, v35 row_shr:1 row_mask:0xf bank_mask:0xf bound_ctrl:1
	v_add_f32_dpp v36, v36, v36 row_shr:1 row_mask:0xf bank_mask:0xf bound_ctrl:1
	v_add_f32_dpp v37, v37, v37 row_shr:1 row_mask:0xf bank_mask:0xf bound_ctrl:1
	v_add_f32_dpp v38, v38, v38 row_shr:1 row_mask:0xf bank_mask:0xf bound_ctrl:1
	v_add_f32_dpp v39, v39, v39 row_shr:1 row_mask:0xf bank_mask:0xf bound_ctrl:1
	v_add_f32_dpp v32, v32, v32 row_shr:2 row_mask:0xf bank_mask:0xf bound_ctrl:1
	v_add_f32_dpp v33, v33, v33 row_shr:2 row_mask:0xf bank_mask:0xf bound_ctrl:1
	v_add_f32_dpp v34, v34, v34 row_shr:2 row_mask:0xf bank_mask:0xf bound_ctrl:1
	v_add_f32_dpp v35, v35, v35 row_shr:2 row_mask:0xf bank_mask:0xf bound_ctrl:1
	v_add_f32_dpp v36, v36, v36 row_shr:2 row_mask:0xf bank_mask:0xf bound_ctrl:1
	v_add_f32_dpp v37, v37, v37 row_shr:2 row_mask:0xf bank_mask:0xf bound_ctrl:1
	v_add_f32_dpp v38, v38, v38 row_shr:2 row_mask:0xf bank_mask:0xf bound_ctrl:1
	v_add_f32_dpp v39, v39, v39 row_shr:2 row_mask:0xf bank_mask:0xf bound_ctrl:1
	v_add_f32_dpp v32, v32, v32 row_shr:4 row_mask:0xf bank_mask:0xf bound_ctrl:1
	v_add_f32_dpp v33, v33, v33 row_shr:4 row_mask:0xf bank_mask:0xf bound_ctrl:1
	v_add_f32_dpp v34, v34, v34 row_shr:4 row_mask:0xf bank_mask:0xf bound_ctrl:1
	v_add_f32_dpp v35, v35, v35 row_shr:4 row_mask:0xf bank_mask:0xf bound_ctrl:1
	v_add_f32_dpp v36, v36, v36 row_shr:4 row_mask:0xf bank_mask:0xf bound_ctrl:1
	v_add_f32_dpp v37, v37, v37 row_shr:4 row_mask:0xf bank_mask:0xf bound_ctrl:1
	v_add_f32_dpp v38, v38, v38 row_shr:4 row_mask:0xf bank_mask:0xf bound_ctrl:1
	v_add_f32_dpp v39, v39, v39 row_shr:4 row_mask:0xf bank_mask:0xf bound_ctrl:1
	v_add_f32_dpp v32, v32, v32 row_shr:8 row_mask:0xf bank_mask:0xf bound_ctrl:1
	v_add_f32_dpp v33, v33, v33 row_shr:8 row_mask:0xf bank_mask:0xf bound_ctrl:1
	v_add_f32_dpp v34, v34, v34 row_shr:8 row_mask:0xf bank_mask:0xf bound_ctrl:1
	v_add_f32_dpp v35, v35, v35 row_shr:8 row_mask:0xf bank_mask:0xf bound_ctrl:1
	v_add_f32_dpp v36, v36, v36 row_shr:8 row_mask:0xf bank_mask:0xf bound_ctrl:1
	v_add_f32_dpp v37, v37, v37 row_shr:8 row_mask:0xf bank_mask:0xf bound_ctrl:1
	v_add_f32_dpp v38, v38, v38 row_shr:8 row_mask:0xf bank_mask:0xf bound_ctrl:1
	v_add_f32_dpp v39, v39, v39 row_shr:8 row_mask:0xf bank_mask:0xf bound_ctrl:1
	v_mov_b32_dpp v88, v32 row_newbcast:15 row_mask:0xf bank_mask:0xf
	v_mov_b32_dpp v89, v33 row_newbcast:15 row_mask:0xf bank_mask:0xf
	v_mov_b32_dpp v90, v34 row_newbcast:15 row_mask:0xf bank_mask:0xf
	v_mov_b32_dpp v91, v35 row_newbcast:15 row_mask:0xf bank_mask:0xf
	v_mov_b32_dpp v92, v36 row_newbcast:15 row_mask:0xf bank_mask:0xf
	v_mov_b32_dpp v93, v37 row_newbcast:15 row_mask:0xf bank_mask:0xf
	v_mov_b32_dpp v94, v38 row_newbcast:15 row_mask:0xf bank_mask:0xf
	v_mov_b32_dpp v95, v39 row_newbcast:15 row_mask:0xf bank_mask:0xf
	v_add_f32_e32 v32, v32, v178
	v_add_f32_e32 v36, v36, v179
	v_add_f32_e32 v33, v33, v180
	v_add_f32_e32 v37, v37, v181
	v_add_f32_e32 v34, v34, v182
	v_add_f32_e32 v38, v38, v183
	v_add_f32_e32 v35, v35, v184
	v_add_f32_e32 v39, v39, v185
	v_mul_f32_e32 v132, v32, v103
	v_mul_f32_e32 v32, v32, v102
	v_fma_f32 v32, -v36, v103, v32
	v_fma_f32 v36, v36, v102, v132
	v_mul_f32_e32 v133, v33, v107
	v_mul_f32_e32 v33, v33, v106
	v_fma_f32 v33, -v37, v107, v33
	v_fma_f32 v37, v37, v106, v133
	v_mul_f32_e32 v132, v34, v111
	v_mul_f32_e32 v34, v34, v110
	v_fma_f32 v34, -v38, v111, v34
	v_fma_f32 v38, v38, v110, v132
	v_mul_f32_e32 v133, v35, v115
	v_mul_f32_e32 v35, v35, v114
	v_fma_f32 v35, -v39, v115, v35
	v_fma_f32 v39, v39, v114, v133
	v_add_f32_e32 v88, v88, v178
	v_add_f32_e32 v92, v92, v179
	v_mul_f32_e32 v132, v92, v117
	v_mul_f32_e32 v179, v88, v117
	v_fma_f32 v178, v88, v116, -v132
	v_fma_f32 v179, v92, v116, v179
	v_add_f32_e32 v89, v89, v180
	v_add_f32_e32 v93, v93, v181
	v_mul_f32_e32 v133, v93, v121
	v_mul_f32_e32 v181, v89, v121
	v_fma_f32 v180, v89, v120, -v133
	v_fma_f32 v181, v93, v120, v181
	v_add_f32_e32 v90, v90, v182
	v_add_f32_e32 v94, v94, v183
	v_mul_f32_e32 v132, v94, v125
	v_mul_f32_e32 v183, v90, v125
	v_fma_f32 v182, v90, v124, -v132
	v_fma_f32 v183, v94, v124, v183
	v_add_f32_e32 v91, v91, v184
	v_add_f32_e32 v95, v95, v185
	v_mul_f32_e32 v133, v95, v129
	v_mul_f32_e32 v185, v91, v129
	v_fma_f32 v184, v91, v128, -v133
	v_fma_f32 v185, v95, v128, v185
	v_mul_f32_e32 v132, v40, v101
	v_mul_f32_e32 v40, v40, v100
	v_fma_f32 v40, -v44, v101, v40
	v_fma_f32 v44, v44, v100, v132
	v_mul_f32_e32 v133, v41, v105
	v_mul_f32_e32 v41, v41, v104
	v_fma_f32 v41, -v45, v105, v41
	v_fma_f32 v45, v45, v104, v133
	v_mul_f32_e32 v132, v42, v109
	v_mul_f32_e32 v42, v42, v108
	v_fma_f32 v42, -v46, v109, v42
	v_fma_f32 v46, v46, v108, v132
	v_mul_f32_e32 v133, v43, v113
	v_mul_f32_e32 v43, v43, v112
	v_fma_f32 v43, -v47, v113, v43
	v_fma_f32 v47, v47, v112, v133
	v_add_f32_dpp v40, v40, v40 row_shr:1 row_mask:0xf bank_mask:0xf bound_ctrl:1
	v_add_f32_dpp v41, v41, v41 row_shr:1 row_mask:0xf bank_mask:0xf bound_ctrl:1
	v_add_f32_dpp v42, v42, v42 row_shr:1 row_mask:0xf bank_mask:0xf bound_ctrl:1
	v_add_f32_dpp v43, v43, v43 row_shr:1 row_mask:0xf bank_mask:0xf bound_ctrl:1
	v_add_f32_dpp v44, v44, v44 row_shr:1 row_mask:0xf bank_mask:0xf bound_ctrl:1
	v_add_f32_dpp v45, v45, v45 row_shr:1 row_mask:0xf bank_mask:0xf bound_ctrl:1
	v_add_f32_dpp v46, v46, v46 row_shr:1 row_mask:0xf bank_mask:0xf bound_ctrl:1
	v_add_f32_dpp v47, v47, v47 row_shr:1 row_mask:0xf bank_mask:0xf bound_ctrl:1
	v_add_f32_dpp v40, v40, v40 row_shr:2 row_mask:0xf bank_mask:0xf bound_ctrl:1
	v_add_f32_dpp v41, v41, v41 row_shr:2 row_mask:0xf bank_mask:0xf bound_ctrl:1
	v_add_f32_dpp v42, v42, v42 row_shr:2 row_mask:0xf bank_mask:0xf bound_ctrl:1
	v_add_f32_dpp v43, v43, v43 row_shr:2 row_mask:0xf bank_mask:0xf bound_ctrl:1
	v_add_f32_dpp v44, v44, v44 row_shr:2 row_mask:0xf bank_mask:0xf bound_ctrl:1
	v_add_f32_dpp v45, v45, v45 row_shr:2 row_mask:0xf bank_mask:0xf bound_ctrl:1
	v_add_f32_dpp v46, v46, v46 row_shr:2 row_mask:0xf bank_mask:0xf bound_ctrl:1
	v_add_f32_dpp v47, v47, v47 row_shr:2 row_mask:0xf bank_mask:0xf bound_ctrl:1
	v_add_f32_dpp v40, v40, v40 row_shr:4 row_mask:0xf bank_mask:0xf bound_ctrl:1
	v_add_f32_dpp v41, v41, v41 row_shr:4 row_mask:0xf bank_mask:0xf bound_ctrl:1
	v_add_f32_dpp v42, v42, v42 row_shr:4 row_mask:0xf bank_mask:0xf bound_ctrl:1
	v_add_f32_dpp v43, v43, v43 row_shr:4 row_mask:0xf bank_mask:0xf bound_ctrl:1
	v_add_f32_dpp v44, v44, v44 row_shr:4 row_mask:0xf bank_mask:0xf bound_ctrl:1
	v_add_f32_dpp v45, v45, v45 row_shr:4 row_mask:0xf bank_mask:0xf bound_ctrl:1
	v_add_f32_dpp v46, v46, v46 row_shr:4 row_mask:0xf bank_mask:0xf bound_ctrl:1
	v_add_f32_dpp v47, v47, v47 row_shr:4 row_mask:0xf bank_mask:0xf bound_ctrl:1
	v_add_f32_dpp v40, v40, v40 row_shr:8 row_mask:0xf bank_mask:0xf bound_ctrl:1
	v_add_f32_dpp v41, v41, v41 row_shr:8 row_mask:0xf bank_mask:0xf bound_ctrl:1
	v_add_f32_dpp v42, v42, v42 row_shr:8 row_mask:0xf bank_mask:0xf bound_ctrl:1
	v_add_f32_dpp v43, v43, v43 row_shr:8 row_mask:0xf bank_mask:0xf bound_ctrl:1
	v_add_f32_dpp v44, v44, v44 row_shr:8 row_mask:0xf bank_mask:0xf bound_ctrl:1
	v_add_f32_dpp v45, v45, v45 row_shr:8 row_mask:0xf bank_mask:0xf bound_ctrl:1
	v_add_f32_dpp v46, v46, v46 row_shr:8 row_mask:0xf bank_mask:0xf bound_ctrl:1
	v_add_f32_dpp v47, v47, v47 row_shr:8 row_mask:0xf bank_mask:0xf bound_ctrl:1
	v_mov_b32_dpp v88, v40 row_newbcast:15 row_mask:0xf bank_mask:0xf
	v_mov_b32_dpp v89, v41 row_newbcast:15 row_mask:0xf bank_mask:0xf
	v_mov_b32_dpp v90, v42 row_newbcast:15 row_mask:0xf bank_mask:0xf
	v_mov_b32_dpp v91, v43 row_newbcast:15 row_mask:0xf bank_mask:0xf
	v_mov_b32_dpp v92, v44 row_newbcast:15 row_mask:0xf bank_mask:0xf
	v_mov_b32_dpp v93, v45 row_newbcast:15 row_mask:0xf bank_mask:0xf
	v_mov_b32_dpp v94, v46 row_newbcast:15 row_mask:0xf bank_mask:0xf
	v_mov_b32_dpp v95, v47 row_newbcast:15 row_mask:0xf bank_mask:0xf
	v_add_f32_e32 v40, v40, v178
	v_add_f32_e32 v44, v44, v179
	v_add_f32_e32 v41, v41, v180
	v_add_f32_e32 v45, v45, v181
	v_add_f32_e32 v42, v42, v182
	v_add_f32_e32 v46, v46, v183
	v_add_f32_e32 v43, v43, v184
	v_add_f32_e32 v47, v47, v185
	v_mul_f32_e32 v132, v40, v103
	v_mul_f32_e32 v40, v40, v102
	v_fma_f32 v40, -v44, v103, v40
	v_fma_f32 v44, v44, v102, v132
	v_mul_f32_e32 v133, v41, v107
	v_mul_f32_e32 v41, v41, v106
	v_fma_f32 v41, -v45, v107, v41
	v_fma_f32 v45, v45, v106, v133
	v_mul_f32_e32 v132, v42, v111
	v_mul_f32_e32 v42, v42, v110
	v_fma_f32 v42, -v46, v111, v42
	v_fma_f32 v46, v46, v110, v132
	v_mul_f32_e32 v133, v43, v115
	v_mul_f32_e32 v43, v43, v114
	v_fma_f32 v43, -v47, v115, v43
	v_fma_f32 v47, v47, v114, v133
	v_add_f32_e32 v88, v88, v178
	v_add_f32_e32 v92, v92, v179
	v_mul_f32_e32 v132, v92, v117
	v_mul_f32_e32 v179, v88, v117
	v_fma_f32 v178, v88, v116, -v132
	v_fma_f32 v179, v92, v116, v179
	v_add_f32_e32 v89, v89, v180
	v_add_f32_e32 v93, v93, v181
	v_mul_f32_e32 v133, v93, v121
	v_mul_f32_e32 v181, v89, v121
	v_fma_f32 v180, v89, v120, -v133
	v_fma_f32 v181, v93, v120, v181
	v_add_f32_e32 v90, v90, v182
	v_add_f32_e32 v94, v94, v183
	v_mul_f32_e32 v132, v94, v125
	v_mul_f32_e32 v183, v90, v125
	v_fma_f32 v182, v90, v124, -v132
	v_fma_f32 v183, v94, v124, v183
	v_add_f32_e32 v91, v91, v184
	v_add_f32_e32 v95, v95, v185
	v_mul_f32_e32 v133, v95, v129
	v_mul_f32_e32 v185, v91, v129
	v_fma_f32 v184, v91, v128, -v133
	v_fma_f32 v185, v95, v128, v185
	v_mul_f32_e32 v132, v48, v101
	v_mul_f32_e32 v48, v48, v100
	v_fma_f32 v48, -v52, v101, v48
	v_fma_f32 v52, v52, v100, v132
	v_mul_f32_e32 v133, v49, v105
	v_mul_f32_e32 v49, v49, v104
	v_fma_f32 v49, -v53, v105, v49
	v_fma_f32 v53, v53, v104, v133
	v_mul_f32_e32 v132, v50, v109
	v_mul_f32_e32 v50, v50, v108
	v_fma_f32 v50, -v54, v109, v50
	v_fma_f32 v54, v54, v108, v132
	v_mul_f32_e32 v133, v51, v113
	v_mul_f32_e32 v51, v51, v112
	v_fma_f32 v51, -v55, v113, v51
	v_fma_f32 v55, v55, v112, v133
	v_add_f32_dpp v48, v48, v48 row_shr:1 row_mask:0xf bank_mask:0xf bound_ctrl:1
	v_add_f32_dpp v49, v49, v49 row_shr:1 row_mask:0xf bank_mask:0xf bound_ctrl:1
	v_add_f32_dpp v50, v50, v50 row_shr:1 row_mask:0xf bank_mask:0xf bound_ctrl:1
	v_add_f32_dpp v51, v51, v51 row_shr:1 row_mask:0xf bank_mask:0xf bound_ctrl:1
	v_add_f32_dpp v52, v52, v52 row_shr:1 row_mask:0xf bank_mask:0xf bound_ctrl:1
	v_add_f32_dpp v53, v53, v53 row_shr:1 row_mask:0xf bank_mask:0xf bound_ctrl:1
	v_add_f32_dpp v54, v54, v54 row_shr:1 row_mask:0xf bank_mask:0xf bound_ctrl:1
	v_add_f32_dpp v55, v55, v55 row_shr:1 row_mask:0xf bank_mask:0xf bound_ctrl:1
	v_add_f32_dpp v48, v48, v48 row_shr:2 row_mask:0xf bank_mask:0xf bound_ctrl:1
	v_add_f32_dpp v49, v49, v49 row_shr:2 row_mask:0xf bank_mask:0xf bound_ctrl:1
	v_add_f32_dpp v50, v50, v50 row_shr:2 row_mask:0xf bank_mask:0xf bound_ctrl:1
	v_add_f32_dpp v51, v51, v51 row_shr:2 row_mask:0xf bank_mask:0xf bound_ctrl:1
	v_add_f32_dpp v52, v52, v52 row_shr:2 row_mask:0xf bank_mask:0xf bound_ctrl:1
	v_add_f32_dpp v53, v53, v53 row_shr:2 row_mask:0xf bank_mask:0xf bound_ctrl:1
	v_add_f32_dpp v54, v54, v54 row_shr:2 row_mask:0xf bank_mask:0xf bound_ctrl:1
	v_add_f32_dpp v55, v55, v55 row_shr:2 row_mask:0xf bank_mask:0xf bound_ctrl:1
	v_add_f32_dpp v48, v48, v48 row_shr:4 row_mask:0xf bank_mask:0xf bound_ctrl:1
	v_add_f32_dpp v49, v49, v49 row_shr:4 row_mask:0xf bank_mask:0xf bound_ctrl:1
	v_add_f32_dpp v50, v50, v50 row_shr:4 row_mask:0xf bank_mask:0xf bound_ctrl:1
	v_add_f32_dpp v51, v51, v51 row_shr:4 row_mask:0xf bank_mask:0xf bound_ctrl:1
	v_add_f32_dpp v52, v52, v52 row_shr:4 row_mask:0xf bank_mask:0xf bound_ctrl:1
	v_add_f32_dpp v53, v53, v53 row_shr:4 row_mask:0xf bank_mask:0xf bound_ctrl:1
	v_add_f32_dpp v54, v54, v54 row_shr:4 row_mask:0xf bank_mask:0xf bound_ctrl:1
	v_add_f32_dpp v55, v55, v55 row_shr:4 row_mask:0xf bank_mask:0xf bound_ctrl:1
	v_add_f32_dpp v48, v48, v48 row_shr:8 row_mask:0xf bank_mask:0xf bound_ctrl:1
	v_add_f32_dpp v49, v49, v49 row_shr:8 row_mask:0xf bank_mask:0xf bound_ctrl:1
	v_add_f32_dpp v50, v50, v50 row_shr:8 row_mask:0xf bank_mask:0xf bound_ctrl:1
	v_add_f32_dpp v51, v51, v51 row_shr:8 row_mask:0xf bank_mask:0xf bound_ctrl:1
	v_add_f32_dpp v52, v52, v52 row_shr:8 row_mask:0xf bank_mask:0xf bound_ctrl:1
	v_add_f32_dpp v53, v53, v53 row_shr:8 row_mask:0xf bank_mask:0xf bound_ctrl:1
	v_add_f32_dpp v54, v54, v54 row_shr:8 row_mask:0xf bank_mask:0xf bound_ctrl:1
	v_add_f32_dpp v55, v55, v55 row_shr:8 row_mask:0xf bank_mask:0xf bound_ctrl:1
	v_mov_b32_dpp v88, v48 row_newbcast:15 row_mask:0xf bank_mask:0xf
	v_mov_b32_dpp v89, v49 row_newbcast:15 row_mask:0xf bank_mask:0xf
	v_mov_b32_dpp v90, v50 row_newbcast:15 row_mask:0xf bank_mask:0xf
	v_mov_b32_dpp v91, v51 row_newbcast:15 row_mask:0xf bank_mask:0xf
	v_mov_b32_dpp v92, v52 row_newbcast:15 row_mask:0xf bank_mask:0xf
	v_mov_b32_dpp v93, v53 row_newbcast:15 row_mask:0xf bank_mask:0xf
	v_mov_b32_dpp v94, v54 row_newbcast:15 row_mask:0xf bank_mask:0xf
	v_mov_b32_dpp v95, v55 row_newbcast:15 row_mask:0xf bank_mask:0xf
	v_add_f32_e32 v48, v48, v178
	v_add_f32_e32 v52, v52, v179
	v_add_f32_e32 v49, v49, v180
	v_add_f32_e32 v53, v53, v181
	v_add_f32_e32 v50, v50, v182
	v_add_f32_e32 v54, v54, v183
	v_add_f32_e32 v51, v51, v184
	v_add_f32_e32 v55, v55, v185
	v_mul_f32_e32 v132, v48, v103
	v_mul_f32_e32 v48, v48, v102
	v_fma_f32 v48, -v52, v103, v48
	v_fma_f32 v52, v52, v102, v132
	v_mul_f32_e32 v133, v49, v107
	v_mul_f32_e32 v49, v49, v106
	v_fma_f32 v49, -v53, v107, v49
	v_fma_f32 v53, v53, v106, v133
	v_mul_f32_e32 v132, v50, v111
	v_mul_f32_e32 v50, v50, v110
	v_fma_f32 v50, -v54, v111, v50
	v_fma_f32 v54, v54, v110, v132
	v_mul_f32_e32 v133, v51, v115
	v_mul_f32_e32 v51, v51, v114
	v_fma_f32 v51, -v55, v115, v51
	v_fma_f32 v55, v55, v114, v133
	v_add_f32_e32 v88, v88, v178
	v_add_f32_e32 v92, v92, v179
	v_mul_f32_e32 v132, v92, v117
	v_mul_f32_e32 v179, v88, v117
	v_fma_f32 v178, v88, v116, -v132
	v_fma_f32 v179, v92, v116, v179
	v_add_f32_e32 v89, v89, v180
	v_add_f32_e32 v93, v93, v181
	v_mul_f32_e32 v133, v93, v121
	v_mul_f32_e32 v181, v89, v121
	v_fma_f32 v180, v89, v120, -v133
	v_fma_f32 v181, v93, v120, v181
	v_add_f32_e32 v90, v90, v182
	v_add_f32_e32 v94, v94, v183
	v_mul_f32_e32 v132, v94, v125
	v_mul_f32_e32 v183, v90, v125
	v_fma_f32 v182, v90, v124, -v132
	v_fma_f32 v183, v94, v124, v183
	v_add_f32_e32 v91, v91, v184
	v_add_f32_e32 v95, v95, v185
	v_mul_f32_e32 v133, v95, v129
	v_mul_f32_e32 v185, v91, v129
	v_fma_f32 v184, v91, v128, -v133
	v_fma_f32 v185, v95, v128, v185
	v_mul_f32_e32 v132, v56, v101
	v_mul_f32_e32 v56, v56, v100
	v_fma_f32 v56, -v60, v101, v56
	v_fma_f32 v60, v60, v100, v132
	v_mul_f32_e32 v133, v57, v105
	v_mul_f32_e32 v57, v57, v104
	v_fma_f32 v57, -v61, v105, v57
	v_fma_f32 v61, v61, v104, v133
	v_mul_f32_e32 v132, v58, v109
	v_mul_f32_e32 v58, v58, v108
	v_fma_f32 v58, -v62, v109, v58
	v_fma_f32 v62, v62, v108, v132
	v_mul_f32_e32 v133, v59, v113
	v_mul_f32_e32 v59, v59, v112
	v_fma_f32 v59, -v63, v113, v59
	v_fma_f32 v63, v63, v112, v133
	v_add_f32_dpp v56, v56, v56 row_shr:1 row_mask:0xf bank_mask:0xf bound_ctrl:1
	v_add_f32_dpp v57, v57, v57 row_shr:1 row_mask:0xf bank_mask:0xf bound_ctrl:1
	v_add_f32_dpp v58, v58, v58 row_shr:1 row_mask:0xf bank_mask:0xf bound_ctrl:1
	v_add_f32_dpp v59, v59, v59 row_shr:1 row_mask:0xf bank_mask:0xf bound_ctrl:1
	v_add_f32_dpp v60, v60, v60 row_shr:1 row_mask:0xf bank_mask:0xf bound_ctrl:1
	v_add_f32_dpp v61, v61, v61 row_shr:1 row_mask:0xf bank_mask:0xf bound_ctrl:1
	v_add_f32_dpp v62, v62, v62 row_shr:1 row_mask:0xf bank_mask:0xf bound_ctrl:1
	v_add_f32_dpp v63, v63, v63 row_shr:1 row_mask:0xf bank_mask:0xf bound_ctrl:1
	v_add_f32_dpp v56, v56, v56 row_shr:2 row_mask:0xf bank_mask:0xf bound_ctrl:1
	v_add_f32_dpp v57, v57, v57 row_shr:2 row_mask:0xf bank_mask:0xf bound_ctrl:1
	v_add_f32_dpp v58, v58, v58 row_shr:2 row_mask:0xf bank_mask:0xf bound_ctrl:1
	v_add_f32_dpp v59, v59, v59 row_shr:2 row_mask:0xf bank_mask:0xf bound_ctrl:1
	v_add_f32_dpp v60, v60, v60 row_shr:2 row_mask:0xf bank_mask:0xf bound_ctrl:1
	v_add_f32_dpp v61, v61, v61 row_shr:2 row_mask:0xf bank_mask:0xf bound_ctrl:1
	v_add_f32_dpp v62, v62, v62 row_shr:2 row_mask:0xf bank_mask:0xf bound_ctrl:1
	v_add_f32_dpp v63, v63, v63 row_shr:2 row_mask:0xf bank_mask:0xf bound_ctrl:1
	v_add_f32_dpp v56, v56, v56 row_shr:4 row_mask:0xf bank_mask:0xf bound_ctrl:1
	v_add_f32_dpp v57, v57, v57 row_shr:4 row_mask:0xf bank_mask:0xf bound_ctrl:1
	v_add_f32_dpp v58, v58, v58 row_shr:4 row_mask:0xf bank_mask:0xf bound_ctrl:1
	v_add_f32_dpp v59, v59, v59 row_shr:4 row_mask:0xf bank_mask:0xf bound_ctrl:1
	v_add_f32_dpp v60, v60, v60 row_shr:4 row_mask:0xf bank_mask:0xf bound_ctrl:1
	v_add_f32_dpp v61, v61, v61 row_shr:4 row_mask:0xf bank_mask:0xf bound_ctrl:1
	v_add_f32_dpp v62, v62, v62 row_shr:4 row_mask:0xf bank_mask:0xf bound_ctrl:1
	v_add_f32_dpp v63, v63, v63 row_shr:4 row_mask:0xf bank_mask:0xf bound_ctrl:1
	v_add_f32_dpp v56, v56, v56 row_shr:8 row_mask:0xf bank_mask:0xf bound_ctrl:1
	v_add_f32_dpp v57, v57, v57 row_shr:8 row_mask:0xf bank_mask:0xf bound_ctrl:1
	v_add_f32_dpp v58, v58, v58 row_shr:8 row_mask:0xf bank_mask:0xf bound_ctrl:1
	v_add_f32_dpp v59, v59, v59 row_shr:8 row_mask:0xf bank_mask:0xf bound_ctrl:1
	v_add_f32_dpp v60, v60, v60 row_shr:8 row_mask:0xf bank_mask:0xf bound_ctrl:1
	v_add_f32_dpp v61, v61, v61 row_shr:8 row_mask:0xf bank_mask:0xf bound_ctrl:1
	v_add_f32_dpp v62, v62, v62 row_shr:8 row_mask:0xf bank_mask:0xf bound_ctrl:1
	v_add_f32_dpp v63, v63, v63 row_shr:8 row_mask:0xf bank_mask:0xf bound_ctrl:1
	v_mov_b32_dpp v88, v56 row_newbcast:15 row_mask:0xf bank_mask:0xf
	v_mov_b32_dpp v89, v57 row_newbcast:15 row_mask:0xf bank_mask:0xf
	v_mov_b32_dpp v90, v58 row_newbcast:15 row_mask:0xf bank_mask:0xf
	v_mov_b32_dpp v91, v59 row_newbcast:15 row_mask:0xf bank_mask:0xf
	v_mov_b32_dpp v92, v60 row_newbcast:15 row_mask:0xf bank_mask:0xf
	v_mov_b32_dpp v93, v61 row_newbcast:15 row_mask:0xf bank_mask:0xf
	v_mov_b32_dpp v94, v62 row_newbcast:15 row_mask:0xf bank_mask:0xf
	v_mov_b32_dpp v95, v63 row_newbcast:15 row_mask:0xf bank_mask:0xf
	v_add_f32_e32 v56, v56, v178
	v_add_f32_e32 v60, v60, v179
	v_add_f32_e32 v57, v57, v180
	v_add_f32_e32 v61, v61, v181
	v_add_f32_e32 v58, v58, v182
	v_add_f32_e32 v62, v62, v183
	v_add_f32_e32 v59, v59, v184
	v_add_f32_e32 v63, v63, v185
	v_mul_f32_e32 v132, v56, v103
	v_mul_f32_e32 v56, v56, v102
	v_fma_f32 v56, -v60, v103, v56
	v_fma_f32 v60, v60, v102, v132
	v_mul_f32_e32 v133, v57, v107
	v_mul_f32_e32 v57, v57, v106
	v_fma_f32 v57, -v61, v107, v57
	v_fma_f32 v61, v61, v106, v133
	v_mul_f32_e32 v132, v58, v111
	v_mul_f32_e32 v58, v58, v110
	v_fma_f32 v58, -v62, v111, v58
	v_fma_f32 v62, v62, v110, v132
	v_mul_f32_e32 v133, v59, v115
	v_mul_f32_e32 v59, v59, v114
	v_fma_f32 v59, -v63, v115, v59
	v_fma_f32 v63, v63, v114, v133
	v_add_f32_e32 v88, v88, v178
	v_add_f32_e32 v92, v92, v179
	v_mul_f32_e32 v132, v92, v117
	v_mul_f32_e32 v179, v88, v117
	v_fma_f32 v178, v88, v116, -v132
	v_fma_f32 v179, v92, v116, v179
	v_add_f32_e32 v89, v89, v180
	v_add_f32_e32 v93, v93, v181
	v_mul_f32_e32 v133, v93, v121
	v_mul_f32_e32 v181, v89, v121
	v_fma_f32 v180, v89, v120, -v133
	v_fma_f32 v181, v93, v120, v181
	v_add_f32_e32 v90, v90, v182
	v_add_f32_e32 v94, v94, v183
	v_mul_f32_e32 v132, v94, v125
	v_mul_f32_e32 v183, v90, v125
	v_fma_f32 v182, v90, v124, -v132
	v_fma_f32 v183, v94, v124, v183
	v_add_f32_e32 v91, v91, v184
	v_add_f32_e32 v95, v95, v185
	v_mul_f32_e32 v133, v95, v129
	v_mul_f32_e32 v185, v91, v129
	v_fma_f32 v184, v91, v128, -v133
	v_fma_f32 v185, v95, v128, v185
	s_waitcnt vmcnt(14)
	v_cvt_pk_bf16_f32 v80, v80, v81
	v_cvt_pk_bf16_f32 v81, v82, v83
	v_cvt_pk_bf16_f32 v82, -v84, -v85
	v_cvt_pk_bf16_f32 v83, -v86, -v87
	v_cvt_pk_bf16_f32 v96, v32, v33
	v_cvt_pk_bf16_f32 v97, v34, v35
	v_cvt_pk_bf16_f32 v98, v36, v37
	v_cvt_pk_bf16_f32 v99, v38, v39
	s_nop 1
	v_mfma_f32_16x16x32_bf16 v[16:19], v[80:83], v[96:99], v[16:19]
	v_cvt_pk_bf16_f32 v96, v40, v41
	v_cvt_pk_bf16_f32 v97, v42, v43
	v_cvt_pk_bf16_f32 v98, v44, v45
	v_cvt_pk_bf16_f32 v99, v46, v47
	s_nop 1
	v_mfma_f32_16x16x32_bf16 v[20:23], v[80:83], v[96:99], v[20:23]
	v_cvt_pk_bf16_f32 v96, v48, v49
	v_cvt_pk_bf16_f32 v97, v50, v51
	v_cvt_pk_bf16_f32 v98, v52, v53
	v_cvt_pk_bf16_f32 v99, v54, v55
	s_nop 1
	v_mfma_f32_16x16x32_bf16 v[24:27], v[80:83], v[96:99], v[24:27]
	v_cvt_pk_bf16_f32 v96, v56, v57
	v_cvt_pk_bf16_f32 v97, v58, v59
	v_cvt_pk_bf16_f32 v98, v60, v61
	v_cvt_pk_bf16_f32 v99, v62, v63
	s_nop 1
	v_mfma_f32_16x16x32_bf16 v[28:31], v[80:83], v[96:99], v[28:31]
	s_waitcnt vmcnt(10)
	v_cvt_pk_bf16_f32 v64, v64, v65
	v_cvt_pk_bf16_f32 v65, v66, v67
	v_cvt_pk_bf16_f32 v66, v68, v69
	v_cvt_pk_bf16_f32 v67, v70, v71
	v_cvt_pk_bf16_f32 v72, v72, v73
	v_cvt_pk_bf16_f32 v73, v74, v75
	v_cvt_pk_bf16_f32 v74, v76, v77
	v_cvt_pk_bf16_f32 v75, v78, v79
	global_load_dwordx4 v[80:83], v136, s[38:39]
	global_load_dwordx4 v[84:87], v136, s[40:41]
	s_add_u32 s38, s38, 0x40
	s_addc_u32 s39, s39, 0
	s_add_u32 s40, s40, 0x40
	s_addc_u32 s41, s41, 0
	s_nop 0
	v_mfma_f32_16x16x32_bf16 v[32:35], v[64:67], v[0:3], 0
	v_mfma_f32_16x16x32_bf16 v[36:39], v[72:75], v[0:3], 0
	v_mfma_f32_16x16x32_bf16 v[40:43], v[64:67], v[4:7], 0
	v_mfma_f32_16x16x32_bf16 v[44:47], v[72:75], v[4:7], 0
	v_mfma_f32_16x16x32_bf16 v[48:51], v[64:67], v[8:11], 0
	v_mfma_f32_16x16x32_bf16 v[52:55], v[72:75], v[8:11], 0
	v_mfma_f32_16x16x32_bf16 v[56:59], v[64:67], v[12:15], 0
	v_mfma_f32_16x16x32_bf16 v[60:63], v[72:75], v[12:15], 0
	s_mov_b32 exec_hi, 0
	global_load_dwordx4 v[64:67], v135, s[20:21]
	global_load_dwordx4 v[68:71], v135, s[20:21] offset:16
	global_load_dwordx4 v[72:75], v135, s[22:23]
	global_load_dwordx4 v[76:79], v135, s[22:23] offset:16
	s_mov_b64 exec, -1
	s_add_u32 s20, s20, 0x400
	s_addc_u32 s21, s21, 0
	s_add_u32 s22, s22, 0x400
	s_addc_u32 s23, s23, 0
	global_load_dwordx4 v[100:103], v134, s[42:43] offset:0
	global_load_dwordx4 v[104:107], v134, s[42:43] offset:1024
	global_load_dwordx4 v[108:111], v134, s[42:43] offset:2048
	global_load_dwordx4 v[112:115], v134, s[42:43] offset:3072
	global_load_dwordx4 v[116:119], v208, s[42:43] offset:0
	global_load_dwordx4 v[120:123], v208, s[42:43] offset:1024
	global_load_dwordx4 v[124:127], v208, s[42:43] offset:2048
	global_load_dwordx4 v[128:131], v208, s[42:43] offset:3072
	global_load_dwordx4 v[178:181], v206, s[44:45]
	global_load_dwordx4 v[182:185], v206, s[44:45] offset:16
	s_add_u32 s42, s42, 0x2000
	s_addc_u32 s43, s43, 0
	s_add_u32 s44, s44, 0x80
	s_addc_u32 s45, s45, 0
	s_waitcnt vmcnt(16)
	v_mul_f32_e32 v132, v171, v157
	v_mul_f32_e32 v133, v170, v157
	v_fma_f32 v170, v170, v156, -v132
	v_fma_f32 v171, v171, v156, v133
	v_mul_f32_e32 v132, v173, v161
	v_mul_f32_e32 v133, v172, v161
	v_fma_f32 v172, v172, v160, -v132
	v_fma_f32 v173, v173, v160, v133
	v_mul_f32_e32 v132, v175, v165
	v_mul_f32_e32 v133, v174, v165
	v_fma_f32 v174, v174, v164, -v132
	v_fma_f32 v175, v175, v164, v133
	v_mul_f32_e32 v132, v177, v169
	v_mul_f32_e32 v133, v176, v169
	v_fma_f32 v176, v176, v168, -v132
	v_fma_f32 v177, v177, v168, v133
	v_mul_f32_e32 v132, v56, v139
	v_mul_f32_e32 v56, v56, v138
	v_fma_f32 v56, -v60, v139, v56
	v_fma_f32 v60, v60, v138, v132
	v_mul_f32_e32 v133, v57, v143
	v_mul_f32_e32 v57, v57, v142
	v_fma_f32 v57, -v61, v143, v57
	v_fma_f32 v61, v61, v142, v133
	v_mul_f32_e32 v132, v58, v147
	v_mul_f32_e32 v58, v58, v146
	v_fma_f32 v58, -v62, v147, v58
	v_fma_f32 v62, v62, v146, v132
	v_mul_f32_e32 v133, v59, v151
	v_mul_f32_e32 v59, v59, v150
	v_fma_f32 v59, -v63, v151, v59
	v_fma_f32 v63, v63, v150, v133
	v_add_f32_dpp v56, v56, v56 row_shl:1 row_mask:0xf bank_mask:0xf bound_ctrl:1
	v_add_f32_dpp v57, v57, v57 row_shl:1 row_mask:0xf bank_mask:0xf bound_ctrl:1
	v_add_f32_dpp v58, v58, v58 row_shl:1 row_mask:0xf bank_mask:0xf bound_ctrl:1
	v_add_f32_dpp v59, v59, v59 row_shl:1 row_mask:0xf bank_mask:0xf bound_ctrl:1
	v_add_f32_dpp v60, v60, v60 row_shl:1 row_mask:0xf bank_mask:0xf bound_ctrl:1
	v_add_f32_dpp v61, v61, v61 row_shl:1 row_mask:0xf bank_mask:0xf bound_ctrl:1
	v_add_f32_dpp v62, v62, v62 row_shl:1 row_mask:0xf bank_mask:0xf bound_ctrl:1
	v_add_f32_dpp v63, v63, v63 row_shl:1 row_mask:0xf bank_mask:0xf bound_ctrl:1
	v_add_f32_dpp v56, v56, v56 row_shl:2 row_mask:0xf bank_mask:0xf bound_ctrl:1
	v_add_f32_dpp v57, v57, v57 row_shl:2 row_mask:0xf bank_mask:0xf bound_ctrl:1
	v_add_f32_dpp v58, v58, v58 row_shl:2 row_mask:0xf bank_mask:0xf bound_ctrl:1
	v_add_f32_dpp v59, v59, v59 row_shl:2 row_mask:0xf bank_mask:0xf bound_ctrl:1
	v_add_f32_dpp v60, v60, v60 row_shl:2 row_mask:0xf bank_mask:0xf bound_ctrl:1
	v_add_f32_dpp v61, v61, v61 row_shl:2 row_mask:0xf bank_mask:0xf bound_ctrl:1
	v_add_f32_dpp v62, v62, v62 row_shl:2 row_mask:0xf bank_mask:0xf bound_ctrl:1
	v_add_f32_dpp v63, v63, v63 row_shl:2 row_mask:0xf bank_mask:0xf bound_ctrl:1
	v_add_f32_dpp v56, v56, v56 row_shl:4 row_mask:0xf bank_mask:0xf bound_ctrl:1
	v_add_f32_dpp v57, v57, v57 row_shl:4 row_mask:0xf bank_mask:0xf bound_ctrl:1
	v_add_f32_dpp v58, v58, v58 row_shl:4 row_mask:0xf bank_mask:0xf bound_ctrl:1
	v_add_f32_dpp v59, v59, v59 row_shl:4 row_mask:0xf bank_mask:0xf bound_ctrl:1
	v_add_f32_dpp v60, v60, v60 row_shl:4 row_mask:0xf bank_mask:0xf bound_ctrl:1
	v_add_f32_dpp v61, v61, v61 row_shl:4 row_mask:0xf bank_mask:0xf bound_ctrl:1
	v_add_f32_dpp v62, v62, v62 row_shl:4 row_mask:0xf bank_mask:0xf bound_ctrl:1
	v_add_f32_dpp v63, v63, v63 row_shl:4 row_mask:0xf bank_mask:0xf bound_ctrl:1
	v_add_f32_dpp v56, v56, v56 row_shl:8 row_mask:0xf bank_mask:0xf bound_ctrl:1
	v_add_f32_dpp v57, v57, v57 row_shl:8 row_mask:0xf bank_mask:0xf bound_ctrl:1
	v_add_f32_dpp v58, v58, v58 row_shl:8 row_mask:0xf bank_mask:0xf bound_ctrl:1
	v_add_f32_dpp v59, v59, v59 row_shl:8 row_mask:0xf bank_mask:0xf bound_ctrl:1
	v_add_f32_dpp v60, v60, v60 row_shl:8 row_mask:0xf bank_mask:0xf bound_ctrl:1
	v_add_f32_dpp v61, v61, v61 row_shl:8 row_mask:0xf bank_mask:0xf bound_ctrl:1
	v_add_f32_dpp v62, v62, v62 row_shl:8 row_mask:0xf bank_mask:0xf bound_ctrl:1
	v_add_f32_dpp v63, v63, v63 row_shl:8 row_mask:0xf bank_mask:0xf bound_ctrl:1
	v_mov_b32_dpp v88, v56 row_newbcast:0 row_mask:0xf bank_mask:0xf
	v_mov_b32_dpp v89, v57 row_newbcast:0 row_mask:0xf bank_mask:0xf
	v_mov_b32_dpp v90, v58 row_newbcast:0 row_mask:0xf bank_mask:0xf
	v_mov_b32_dpp v91, v59 row_newbcast:0 row_mask:0xf bank_mask:0xf
	v_mov_b32_dpp v92, v60 row_newbcast:0 row_mask:0xf bank_mask:0xf
	v_mov_b32_dpp v93, v61 row_newbcast:0 row_mask:0xf bank_mask:0xf
	v_mov_b32_dpp v94, v62 row_newbcast:0 row_mask:0xf bank_mask:0xf
	v_mov_b32_dpp v95, v63 row_newbcast:0 row_mask:0xf bank_mask:0xf
	v_add_f32_e32 v56, v56, v170
	v_add_f32_e32 v60, v60, v171
	v_add_f32_e32 v57, v57, v172
	v_add_f32_e32 v61, v61, v173
	v_add_f32_e32 v58, v58, v174
	v_add_f32_e32 v62, v62, v175
	v_add_f32_e32 v59, v59, v176
	v_add_f32_e32 v63, v63, v177
	v_mul_f32_e32 v132, v56, v141
	v_mul_f32_e32 v56, v56, v140
	v_fma_f32 v56, -v60, v141, v56
	v_fma_f32 v60, v60, v140, v132
	v_mul_f32_e32 v133, v57, v145
	v_mul_f32_e32 v57, v57, v144
	v_fma_f32 v57, -v61, v145, v57
	v_fma_f32 v61, v61, v144, v133
	v_mul_f32_e32 v132, v58, v149
	v_mul_f32_e32 v58, v58, v148
	v_fma_f32 v58, -v62, v149, v58
	v_fma_f32 v62, v62, v148, v132
	v_mul_f32_e32 v133, v59, v153
	v_mul_f32_e32 v59, v59, v152
	v_fma_f32 v59, -v63, v153, v59
	v_fma_f32 v63, v63, v152, v133
	v_add_f32_e32 v88, v88, v170
	v_add_f32_e32 v92, v92, v171
	v_mul_f32_e32 v132, v92, v155
	v_mul_f32_e32 v171, v88, v155
	v_fma_f32 v170, v88, v154, -v132
	v_fma_f32 v171, v92, v154, v171
	v_add_f32_e32 v89, v89, v172
	v_add_f32_e32 v93, v93, v173
	v_mul_f32_e32 v133, v93, v159
	v_mul_f32_e32 v173, v89, v159
	v_fma_f32 v172, v89, v158, -v133
	v_fma_f32 v173, v93, v158, v173
	v_add_f32_e32 v90, v90, v174
	v_add_f32_e32 v94, v94, v175
	v_mul_f32_e32 v132, v94, v163
	v_mul_f32_e32 v175, v90, v163
	v_fma_f32 v174, v90, v162, -v132
	v_fma_f32 v175, v94, v162, v175
	v_add_f32_e32 v91, v91, v176
	v_add_f32_e32 v95, v95, v177
	v_mul_f32_e32 v133, v95, v167
	v_mul_f32_e32 v177, v91, v167
	v_fma_f32 v176, v91, v166, -v133
	v_fma_f32 v177, v95, v166, v177
	v_mul_f32_e32 v132, v48, v139
	v_mul_f32_e32 v48, v48, v138
	v_fma_f32 v48, -v52, v139, v48
	v_fma_f32 v52, v52, v138, v132
	v_mul_f32_e32 v133, v49, v143
	v_mul_f32_e32 v49, v49, v142
	v_fma_f32 v49, -v53, v143, v49
	v_fma_f32 v53, v53, v142, v133
	v_mul_f32_e32 v132, v50, v147
	v_mul_f32_e32 v50, v50, v146
	v_fma_f32 v50, -v54, v147, v50
	v_fma_f32 v54, v54, v146, v132
	v_mul_f32_e32 v133, v51, v151
	v_mul_f32_e32 v51, v51, v150
	v_fma_f32 v51, -v55, v151, v51
	v_fma_f32 v55, v55, v150, v133
	v_add_f32_dpp v48, v48, v48 row_shl:1 row_mask:0xf bank_mask:0xf bound_ctrl:1
	v_add_f32_dpp v49, v49, v49 row_shl:1 row_mask:0xf bank_mask:0xf bound_ctrl:1
	v_add_f32_dpp v50, v50, v50 row_shl:1 row_mask:0xf bank_mask:0xf bound_ctrl:1
	v_add_f32_dpp v51, v51, v51 row_shl:1 row_mask:0xf bank_mask:0xf bound_ctrl:1
	v_add_f32_dpp v52, v52, v52 row_shl:1 row_mask:0xf bank_mask:0xf bound_ctrl:1
	v_add_f32_dpp v53, v53, v53 row_shl:1 row_mask:0xf bank_mask:0xf bound_ctrl:1
	v_add_f32_dpp v54, v54, v54 row_shl:1 row_mask:0xf bank_mask:0xf bound_ctrl:1
	v_add_f32_dpp v55, v55, v55 row_shl:1 row_mask:0xf bank_mask:0xf bound_ctrl:1
	v_add_f32_dpp v48, v48, v48 row_shl:2 row_mask:0xf bank_mask:0xf bound_ctrl:1
	v_add_f32_dpp v49, v49, v49 row_shl:2 row_mask:0xf bank_mask:0xf bound_ctrl:1
	v_add_f32_dpp v50, v50, v50 row_shl:2 row_mask:0xf bank_mask:0xf bound_ctrl:1
	v_add_f32_dpp v51, v51, v51 row_shl:2 row_mask:0xf bank_mask:0xf bound_ctrl:1
	v_add_f32_dpp v52, v52, v52 row_shl:2 row_mask:0xf bank_mask:0xf bound_ctrl:1
	v_add_f32_dpp v53, v53, v53 row_shl:2 row_mask:0xf bank_mask:0xf bound_ctrl:1
	v_add_f32_dpp v54, v54, v54 row_shl:2 row_mask:0xf bank_mask:0xf bound_ctrl:1
	v_add_f32_dpp v55, v55, v55 row_shl:2 row_mask:0xf bank_mask:0xf bound_ctrl:1
	v_add_f32_dpp v48, v48, v48 row_shl:4 row_mask:0xf bank_mask:0xf bound_ctrl:1
	v_add_f32_dpp v49, v49, v49 row_shl:4 row_mask:0xf bank_mask:0xf bound_ctrl:1
	v_add_f32_dpp v50, v50, v50 row_shl:4 row_mask:0xf bank_mask:0xf bound_ctrl:1
	v_add_f32_dpp v51, v51, v51 row_shl:4 row_mask:0xf bank_mask:0xf bound_ctrl:1
	v_add_f32_dpp v52, v52, v52 row_shl:4 row_mask:0xf bank_mask:0xf bound_ctrl:1
	v_add_f32_dpp v53, v53, v53 row_shl:4 row_mask:0xf bank_mask:0xf bound_ctrl:1
	v_add_f32_dpp v54, v54, v54 row_shl:4 row_mask:0xf bank_mask:0xf bound_ctrl:1
	v_add_f32_dpp v55, v55, v55 row_shl:4 row_mask:0xf bank_mask:0xf bound_ctrl:1
	v_add_f32_dpp v48, v48, v48 row_shl:8 row_mask:0xf bank_mask:0xf bound_ctrl:1
	v_add_f32_dpp v49, v49, v49 row_shl:8 row_mask:0xf bank_mask:0xf bound_ctrl:1
	v_add_f32_dpp v50, v50, v50 row_shl:8 row_mask:0xf bank_mask:0xf bound_ctrl:1
	v_add_f32_dpp v51, v51, v51 row_shl:8 row_mask:0xf bank_mask:0xf bound_ctrl:1
	v_add_f32_dpp v52, v52, v52 row_shl:8 row_mask:0xf bank_mask:0xf bound_ctrl:1
	v_add_f32_dpp v53, v53, v53 row_shl:8 row_mask:0xf bank_mask:0xf bound_ctrl:1
	v_add_f32_dpp v54, v54, v54 row_shl:8 row_mask:0xf bank_mask:0xf bound_ctrl:1
	v_add_f32_dpp v55, v55, v55 row_shl:8 row_mask:0xf bank_mask:0xf bound_ctrl:1
	v_mov_b32_dpp v88, v48 row_newbcast:0 row_mask:0xf bank_mask:0xf
	v_mov_b32_dpp v89, v49 row_newbcast:0 row_mask:0xf bank_mask:0xf
	v_mov_b32_dpp v90, v50 row_newbcast:0 row_mask:0xf bank_mask:0xf
	v_mov_b32_dpp v91, v51 row_newbcast:0 row_mask:0xf bank_mask:0xf
	v_mov_b32_dpp v92, v52 row_newbcast:0 row_mask:0xf bank_mask:0xf
	v_mov_b32_dpp v93, v53 row_newbcast:0 row_mask:0xf bank_mask:0xf
	v_mov_b32_dpp v94, v54 row_newbcast:0 row_mask:0xf bank_mask:0xf
	v_mov_b32_dpp v95, v55 row_newbcast:0 row_mask:0xf bank_mask:0xf
	v_add_f32_e32 v48, v48, v170
	v_add_f32_e32 v52, v52, v171
	v_add_f32_e32 v49, v49, v172
	v_add_f32_e32 v53, v53, v173
	v_add_f32_e32 v50, v50, v174
	v_add_f32_e32 v54, v54, v175
	v_add_f32_e32 v51, v51, v176
	v_add_f32_e32 v55, v55, v177
	v_mul_f32_e32 v132, v48, v141
	v_mul_f32_e32 v48, v48, v140
	v_fma_f32 v48, -v52, v141, v48
	v_fma_f32 v52, v52, v140, v132
	v_mul_f32_e32 v133, v49, v145
	v_mul_f32_e32 v49, v49, v144
	v_fma_f32 v49, -v53, v145, v49
	v_fma_f32 v53, v53, v144, v133
	v_mul_f32_e32 v132, v50, v149
	v_mul_f32_e32 v50, v50, v148
	v_fma_f32 v50, -v54, v149, v50
	v_fma_f32 v54, v54, v148, v132
	v_mul_f32_e32 v133, v51, v153
	v_mul_f32_e32 v51, v51, v152
	v_fma_f32 v51, -v55, v153, v51
	v_fma_f32 v55, v55, v152, v133
	v_add_f32_e32 v88, v88, v170
	v_add_f32_e32 v92, v92, v171
	v_mul_f32_e32 v132, v92, v155
	v_mul_f32_e32 v171, v88, v155
	v_fma_f32 v170, v88, v154, -v132
	v_fma_f32 v171, v92, v154, v171
	v_add_f32_e32 v89, v89, v172
	v_add_f32_e32 v93, v93, v173
	v_mul_f32_e32 v133, v93, v159
	v_mul_f32_e32 v173, v89, v159
	v_fma_f32 v172, v89, v158, -v133
	v_fma_f32 v173, v93, v158, v173
	v_add_f32_e32 v90, v90, v174
	v_add_f32_e32 v94, v94, v175
	v_mul_f32_e32 v132, v94, v163
	v_mul_f32_e32 v175, v90, v163
	v_fma_f32 v174, v90, v162, -v132
	v_fma_f32 v175, v94, v162, v175
	v_add_f32_e32 v91, v91, v176
	v_add_f32_e32 v95, v95, v177
	v_mul_f32_e32 v133, v95, v167
	v_mul_f32_e32 v177, v91, v167
	v_fma_f32 v176, v91, v166, -v133
	v_fma_f32 v177, v95, v166, v177
	v_mul_f32_e32 v132, v40, v139
	v_mul_f32_e32 v40, v40, v138
	v_fma_f32 v40, -v44, v139, v40
	v_fma_f32 v44, v44, v138, v132
	v_mul_f32_e32 v133, v41, v143
	v_mul_f32_e32 v41, v41, v142
	v_fma_f32 v41, -v45, v143, v41
	v_fma_f32 v45, v45, v142, v133
	v_mul_f32_e32 v132, v42, v147
	v_mul_f32_e32 v42, v42, v146
	v_fma_f32 v42, -v46, v147, v42
	v_fma_f32 v46, v46, v146, v132
	v_mul_f32_e32 v133, v43, v151
	v_mul_f32_e32 v43, v43, v150
	v_fma_f32 v43, -v47, v151, v43
	v_fma_f32 v47, v47, v150, v133
	v_add_f32_dpp v40, v40, v40 row_shl:1 row_mask:0xf bank_mask:0xf bound_ctrl:1
	v_add_f32_dpp v41, v41, v41 row_shl:1 row_mask:0xf bank_mask:0xf bound_ctrl:1
	v_add_f32_dpp v42, v42, v42 row_shl:1 row_mask:0xf bank_mask:0xf bound_ctrl:1
	v_add_f32_dpp v43, v43, v43 row_shl:1 row_mask:0xf bank_mask:0xf bound_ctrl:1
	v_add_f32_dpp v44, v44, v44 row_shl:1 row_mask:0xf bank_mask:0xf bound_ctrl:1
	v_add_f32_dpp v45, v45, v45 row_shl:1 row_mask:0xf bank_mask:0xf bound_ctrl:1
	v_add_f32_dpp v46, v46, v46 row_shl:1 row_mask:0xf bank_mask:0xf bound_ctrl:1
	v_add_f32_dpp v47, v47, v47 row_shl:1 row_mask:0xf bank_mask:0xf bound_ctrl:1
	v_add_f32_dpp v40, v40, v40 row_shl:2 row_mask:0xf bank_mask:0xf bound_ctrl:1
	v_add_f32_dpp v41, v41, v41 row_shl:2 row_mask:0xf bank_mask:0xf bound_ctrl:1
	v_add_f32_dpp v42, v42, v42 row_shl:2 row_mask:0xf bank_mask:0xf bound_ctrl:1
	v_add_f32_dpp v43, v43, v43 row_shl:2 row_mask:0xf bank_mask:0xf bound_ctrl:1
	v_add_f32_dpp v44, v44, v44 row_shl:2 row_mask:0xf bank_mask:0xf bound_ctrl:1
	v_add_f32_dpp v45, v45, v45 row_shl:2 row_mask:0xf bank_mask:0xf bound_ctrl:1
	v_add_f32_dpp v46, v46, v46 row_shl:2 row_mask:0xf bank_mask:0xf bound_ctrl:1
	v_add_f32_dpp v47, v47, v47 row_shl:2 row_mask:0xf bank_mask:0xf bound_ctrl:1
	v_add_f32_dpp v40, v40, v40 row_shl:4 row_mask:0xf bank_mask:0xf bound_ctrl:1
	v_add_f32_dpp v41, v41, v41 row_shl:4 row_mask:0xf bank_mask:0xf bound_ctrl:1
	v_add_f32_dpp v42, v42, v42 row_shl:4 row_mask:0xf bank_mask:0xf bound_ctrl:1
	v_add_f32_dpp v43, v43, v43 row_shl:4 row_mask:0xf bank_mask:0xf bound_ctrl:1
	v_add_f32_dpp v44, v44, v44 row_shl:4 row_mask:0xf bank_mask:0xf bound_ctrl:1
	v_add_f32_dpp v45, v45, v45 row_shl:4 row_mask:0xf bank_mask:0xf bound_ctrl:1
	v_add_f32_dpp v46, v46, v46 row_shl:4 row_mask:0xf bank_mask:0xf bound_ctrl:1
	v_add_f32_dpp v47, v47, v47 row_shl:4 row_mask:0xf bank_mask:0xf bound_ctrl:1
	v_add_f32_dpp v40, v40, v40 row_shl:8 row_mask:0xf bank_mask:0xf bound_ctrl:1
	v_add_f32_dpp v41, v41, v41 row_shl:8 row_mask:0xf bank_mask:0xf bound_ctrl:1
	v_add_f32_dpp v42, v42, v42 row_shl:8 row_mask:0xf bank_mask:0xf bound_ctrl:1
	v_add_f32_dpp v43, v43, v43 row_shl:8 row_mask:0xf bank_mask:0xf bound_ctrl:1
	v_add_f32_dpp v44, v44, v44 row_shl:8 row_mask:0xf bank_mask:0xf bound_ctrl:1
	v_add_f32_dpp v45, v45, v45 row_shl:8 row_mask:0xf bank_mask:0xf bound_ctrl:1
	v_add_f32_dpp v46, v46, v46 row_shl:8 row_mask:0xf bank_mask:0xf bound_ctrl:1
	v_add_f32_dpp v47, v47, v47 row_shl:8 row_mask:0xf bank_mask:0xf bound_ctrl:1
	v_mov_b32_dpp v88, v40 row_newbcast:0 row_mask:0xf bank_mask:0xf
	v_mov_b32_dpp v89, v41 row_newbcast:0 row_mask:0xf bank_mask:0xf
	v_mov_b32_dpp v90, v42 row_newbcast:0 row_mask:0xf bank_mask:0xf
	v_mov_b32_dpp v91, v43 row_newbcast:0 row_mask:0xf bank_mask:0xf
	v_mov_b32_dpp v92, v44 row_newbcast:0 row_mask:0xf bank_mask:0xf
	v_mov_b32_dpp v93, v45 row_newbcast:0 row_mask:0xf bank_mask:0xf
	v_mov_b32_dpp v94, v46 row_newbcast:0 row_mask:0xf bank_mask:0xf
	v_mov_b32_dpp v95, v47 row_newbcast:0 row_mask:0xf bank_mask:0xf
	v_add_f32_e32 v40, v40, v170
	v_add_f32_e32 v44, v44, v171
	v_add_f32_e32 v41, v41, v172
	v_add_f32_e32 v45, v45, v173
	v_add_f32_e32 v42, v42, v174
	v_add_f32_e32 v46, v46, v175
	v_add_f32_e32 v43, v43, v176
	v_add_f32_e32 v47, v47, v177
	v_mul_f32_e32 v132, v40, v141
	v_mul_f32_e32 v40, v40, v140
	v_fma_f32 v40, -v44, v141, v40
	v_fma_f32 v44, v44, v140, v132
	v_mul_f32_e32 v133, v41, v145
	v_mul_f32_e32 v41, v41, v144
	v_fma_f32 v41, -v45, v145, v41
	v_fma_f32 v45, v45, v144, v133
	v_mul_f32_e32 v132, v42, v149
	v_mul_f32_e32 v42, v42, v148
	v_fma_f32 v42, -v46, v149, v42
	v_fma_f32 v46, v46, v148, v132
	v_mul_f32_e32 v133, v43, v153
	v_mul_f32_e32 v43, v43, v152
	v_fma_f32 v43, -v47, v153, v43
	v_fma_f32 v47, v47, v152, v133
	v_add_f32_e32 v88, v88, v170
	v_add_f32_e32 v92, v92, v171
	v_mul_f32_e32 v132, v92, v155
	v_mul_f32_e32 v171, v88, v155
	v_fma_f32 v170, v88, v154, -v132
	v_fma_f32 v171, v92, v154, v171
	v_add_f32_e32 v89, v89, v172
	v_add_f32_e32 v93, v93, v173
	v_mul_f32_e32 v133, v93, v159
	v_mul_f32_e32 v173, v89, v159
	v_fma_f32 v172, v89, v158, -v133
	v_fma_f32 v173, v93, v158, v173
	v_add_f32_e32 v90, v90, v174
	v_add_f32_e32 v94, v94, v175
	v_mul_f32_e32 v132, v94, v163
	v_mul_f32_e32 v175, v90, v163
	v_fma_f32 v174, v90, v162, -v132
	v_fma_f32 v175, v94, v162, v175
	v_add_f32_e32 v91, v91, v176
	v_add_f32_e32 v95, v95, v177
	v_mul_f32_e32 v133, v95, v167
	v_mul_f32_e32 v177, v91, v167
	v_fma_f32 v176, v91, v166, -v133
	v_fma_f32 v177, v95, v166, v177
	v_mul_f32_e32 v132, v32, v139
	v_mul_f32_e32 v32, v32, v138
	v_fma_f32 v32, -v36, v139, v32
	v_fma_f32 v36, v36, v138, v132
	v_mul_f32_e32 v133, v33, v143
	v_mul_f32_e32 v33, v33, v142
	v_fma_f32 v33, -v37, v143, v33
	v_fma_f32 v37, v37, v142, v133
	v_mul_f32_e32 v132, v34, v147
	v_mul_f32_e32 v34, v34, v146
	v_fma_f32 v34, -v38, v147, v34
	v_fma_f32 v38, v38, v146, v132
	v_mul_f32_e32 v133, v35, v151
	v_mul_f32_e32 v35, v35, v150
	v_fma_f32 v35, -v39, v151, v35
	v_fma_f32 v39, v39, v150, v133
	v_add_f32_dpp v32, v32, v32 row_shl:1 row_mask:0xf bank_mask:0xf bound_ctrl:1
	v_add_f32_dpp v33, v33, v33 row_shl:1 row_mask:0xf bank_mask:0xf bound_ctrl:1
	v_add_f32_dpp v34, v34, v34 row_shl:1 row_mask:0xf bank_mask:0xf bound_ctrl:1
	v_add_f32_dpp v35, v35, v35 row_shl:1 row_mask:0xf bank_mask:0xf bound_ctrl:1
	v_add_f32_dpp v36, v36, v36 row_shl:1 row_mask:0xf bank_mask:0xf bound_ctrl:1
	v_add_f32_dpp v37, v37, v37 row_shl:1 row_mask:0xf bank_mask:0xf bound_ctrl:1
	v_add_f32_dpp v38, v38, v38 row_shl:1 row_mask:0xf bank_mask:0xf bound_ctrl:1
	v_add_f32_dpp v39, v39, v39 row_shl:1 row_mask:0xf bank_mask:0xf bound_ctrl:1
	v_add_f32_dpp v32, v32, v32 row_shl:2 row_mask:0xf bank_mask:0xf bound_ctrl:1
	v_add_f32_dpp v33, v33, v33 row_shl:2 row_mask:0xf bank_mask:0xf bound_ctrl:1
	v_add_f32_dpp v34, v34, v34 row_shl:2 row_mask:0xf bank_mask:0xf bound_ctrl:1
	v_add_f32_dpp v35, v35, v35 row_shl:2 row_mask:0xf bank_mask:0xf bound_ctrl:1
	v_add_f32_dpp v36, v36, v36 row_shl:2 row_mask:0xf bank_mask:0xf bound_ctrl:1
	v_add_f32_dpp v37, v37, v37 row_shl:2 row_mask:0xf bank_mask:0xf bound_ctrl:1
	v_add_f32_dpp v38, v38, v38 row_shl:2 row_mask:0xf bank_mask:0xf bound_ctrl:1
	v_add_f32_dpp v39, v39, v39 row_shl:2 row_mask:0xf bank_mask:0xf bound_ctrl:1
	v_add_f32_dpp v32, v32, v32 row_shl:4 row_mask:0xf bank_mask:0xf bound_ctrl:1
	v_add_f32_dpp v33, v33, v33 row_shl:4 row_mask:0xf bank_mask:0xf bound_ctrl:1
	v_add_f32_dpp v34, v34, v34 row_shl:4 row_mask:0xf bank_mask:0xf bound_ctrl:1
	v_add_f32_dpp v35, v35, v35 row_shl:4 row_mask:0xf bank_mask:0xf bound_ctrl:1
	v_add_f32_dpp v36, v36, v36 row_shl:4 row_mask:0xf bank_mask:0xf bound_ctrl:1
	v_add_f32_dpp v37, v37, v37 row_shl:4 row_mask:0xf bank_mask:0xf bound_ctrl:1
	v_add_f32_dpp v38, v38, v38 row_shl:4 row_mask:0xf bank_mask:0xf bound_ctrl:1
	v_add_f32_dpp v39, v39, v39 row_shl:4 row_mask:0xf bank_mask:0xf bound_ctrl:1
	v_add_f32_dpp v32, v32, v32 row_shl:8 row_mask:0xf bank_mask:0xf bound_ctrl:1
	v_add_f32_dpp v33, v33, v33 row_shl:8 row_mask:0xf bank_mask:0xf bound_ctrl:1
	v_add_f32_dpp v34, v34, v34 row_shl:8 row_mask:0xf bank_mask:0xf bound_ctrl:1
	v_add_f32_dpp v35, v35, v35 row_shl:8 row_mask:0xf bank_mask:0xf bound_ctrl:1
	v_add_f32_dpp v36, v36, v36 row_shl:8 row_mask:0xf bank_mask:0xf bound_ctrl:1
	v_add_f32_dpp v37, v37, v37 row_shl:8 row_mask:0xf bank_mask:0xf bound_ctrl:1
	v_add_f32_dpp v38, v38, v38 row_shl:8 row_mask:0xf bank_mask:0xf bound_ctrl:1
	v_add_f32_dpp v39, v39, v39 row_shl:8 row_mask:0xf bank_mask:0xf bound_ctrl:1
	v_mov_b32_dpp v88, v32 row_newbcast:0 row_mask:0xf bank_mask:0xf
	v_mov_b32_dpp v89, v33 row_newbcast:0 row_mask:0xf bank_mask:0xf
	v_mov_b32_dpp v90, v34 row_newbcast:0 row_mask:0xf bank_mask:0xf
	v_mov_b32_dpp v91, v35 row_newbcast:0 row_mask:0xf bank_mask:0xf
	v_mov_b32_dpp v92, v36 row_newbcast:0 row_mask:0xf bank_mask:0xf
	v_mov_b32_dpp v93, v37 row_newbcast:0 row_mask:0xf bank_mask:0xf
	v_mov_b32_dpp v94, v38 row_newbcast:0 row_mask:0xf bank_mask:0xf
	v_mov_b32_dpp v95, v39 row_newbcast:0 row_mask:0xf bank_mask:0xf
	v_add_f32_e32 v32, v32, v170
	v_add_f32_e32 v36, v36, v171
	v_add_f32_e32 v33, v33, v172
	v_add_f32_e32 v37, v37, v173
	v_add_f32_e32 v34, v34, v174
	v_add_f32_e32 v38, v38, v175
	v_add_f32_e32 v35, v35, v176
	v_add_f32_e32 v39, v39, v177
	v_mul_f32_e32 v132, v32, v141
	v_mul_f32_e32 v32, v32, v140
	v_fma_f32 v32, -v36, v141, v32
	v_fma_f32 v36, v36, v140, v132
	v_mul_f32_e32 v133, v33, v145
	v_mul_f32_e32 v33, v33, v144
	v_fma_f32 v33, -v37, v145, v33
	v_fma_f32 v37, v37, v144, v133
	v_mul_f32_e32 v132, v34, v149
	v_mul_f32_e32 v34, v34, v148
	v_fma_f32 v34, -v38, v149, v34
	v_fma_f32 v38, v38, v148, v132
	v_mul_f32_e32 v133, v35, v153
	v_mul_f32_e32 v35, v35, v152
	v_fma_f32 v35, -v39, v153, v35
	v_fma_f32 v39, v39, v152, v133
	v_add_f32_e32 v88, v88, v170
	v_add_f32_e32 v92, v92, v171
	v_mul_f32_e32 v132, v92, v155
	v_mul_f32_e32 v171, v88, v155
	v_fma_f32 v170, v88, v154, -v132
	v_fma_f32 v171, v92, v154, v171
	v_add_f32_e32 v89, v89, v172
	v_add_f32_e32 v93, v93, v173
	v_mul_f32_e32 v133, v93, v159
	v_mul_f32_e32 v173, v89, v159
	v_fma_f32 v172, v89, v158, -v133
	v_fma_f32 v173, v93, v158, v173
	v_add_f32_e32 v90, v90, v174
	v_add_f32_e32 v94, v94, v175
	v_mul_f32_e32 v132, v94, v163
	v_mul_f32_e32 v175, v90, v163
	v_fma_f32 v174, v90, v162, -v132
	v_fma_f32 v175, v94, v162, v175
	v_add_f32_e32 v91, v91, v176
	v_add_f32_e32 v95, v95, v177
	v_mul_f32_e32 v133, v95, v167
	v_mul_f32_e32 v177, v91, v167
	v_fma_f32 v176, v91, v166, -v133
	v_fma_f32 v177, v95, v166, v177
	s_waitcnt vmcnt(14)
	v_cvt_pk_bf16_f32 v80, v80, v81
	v_cvt_pk_bf16_f32 v81, v82, v83
	v_cvt_pk_bf16_f32 v82, -v84, -v85
	v_cvt_pk_bf16_f32 v83, -v86, -v87
	v_cvt_pk_bf16_f32 v96, v32, v33
	v_cvt_pk_bf16_f32 v97, v34, v35
	v_cvt_pk_bf16_f32 v98, v36, v37
	v_cvt_pk_bf16_f32 v99, v38, v39
	s_nop 1
	v_mfma_f32_16x16x32_bf16 v[16:19], v[80:83], v[96:99], v[16:19]
	v_cvt_pk_bf16_f32 v96, v40, v41
	v_cvt_pk_bf16_f32 v97, v42, v43
	v_cvt_pk_bf16_f32 v98, v44, v45
	v_cvt_pk_bf16_f32 v99, v46, v47
	s_nop 1
	v_mfma_f32_16x16x32_bf16 v[20:23], v[80:83], v[96:99], v[20:23]
	v_cvt_pk_bf16_f32 v96, v48, v49
	v_cvt_pk_bf16_f32 v97, v50, v51
	v_cvt_pk_bf16_f32 v98, v52, v53
	v_cvt_pk_bf16_f32 v99, v54, v55
	s_nop 1
	v_mfma_f32_16x16x32_bf16 v[24:27], v[80:83], v[96:99], v[24:27]
	v_cvt_pk_bf16_f32 v96, v56, v57
	v_cvt_pk_bf16_f32 v97, v58, v59
	v_cvt_pk_bf16_f32 v98, v60, v61
	v_cvt_pk_bf16_f32 v99, v62, v63
	s_nop 1
	v_mfma_f32_16x16x32_bf16 v[28:31], v[80:83], v[96:99], v[28:31]
	s_waitcnt vmcnt(10)
	v_cvt_pk_bf16_f32 v64, v64, v65
	v_cvt_pk_bf16_f32 v65, v66, v67
	v_cvt_pk_bf16_f32 v66, v68, v69
	v_cvt_pk_bf16_f32 v67, v70, v71
	v_cvt_pk_bf16_f32 v72, v72, v73
	v_cvt_pk_bf16_f32 v73, v74, v75
	v_cvt_pk_bf16_f32 v74, v76, v77
	v_cvt_pk_bf16_f32 v75, v78, v79
	global_load_dwordx4 v[80:83], v136, s[38:39]
	global_load_dwordx4 v[84:87], v136, s[40:41]
	s_add_u32 s38, s38, 0x40
	s_addc_u32 s39, s39, 0
	s_add_u32 s40, s40, 0x40
	s_addc_u32 s41, s41, 0
	s_nop 0
	v_mfma_f32_16x16x32_bf16 v[32:35], v[64:67], v[0:3], 0
	v_mfma_f32_16x16x32_bf16 v[36:39], v[72:75], v[0:3], 0
	v_mfma_f32_16x16x32_bf16 v[40:43], v[64:67], v[4:7], 0
	v_mfma_f32_16x16x32_bf16 v[44:47], v[72:75], v[4:7], 0
	v_mfma_f32_16x16x32_bf16 v[48:51], v[64:67], v[8:11], 0
	v_mfma_f32_16x16x32_bf16 v[52:55], v[72:75], v[8:11], 0
	v_mfma_f32_16x16x32_bf16 v[56:59], v[64:67], v[12:15], 0
	v_mfma_f32_16x16x32_bf16 v[60:63], v[72:75], v[12:15], 0
	s_mov_b32 exec_hi, 0
	global_load_dwordx4 v[64:67], v135, s[20:21]
	global_load_dwordx4 v[68:71], v135, s[20:21] offset:16
	global_load_dwordx4 v[72:75], v135, s[22:23]
	global_load_dwordx4 v[76:79], v135, s[22:23] offset:16
	s_mov_b64 exec, -1
	s_add_u32 s20, s20, 0x400
	s_addc_u32 s21, s21, 0
	s_add_u32 s22, s22, 0x400
	s_addc_u32 s23, s23, 0
	global_load_dwordx4 v[138:141], v134, s[42:43] offset:0
	global_load_dwordx4 v[142:145], v134, s[42:43] offset:1024
	global_load_dwordx4 v[146:149], v134, s[42:43] offset:2048
	global_load_dwordx4 v[150:153], v134, s[42:43] offset:3072
	global_load_dwordx4 v[154:157], v208, s[42:43] offset:0
	global_load_dwordx4 v[158:161], v208, s[42:43] offset:1024
	global_load_dwordx4 v[162:165], v208, s[42:43] offset:2048
	global_load_dwordx4 v[166:169], v208, s[42:43] offset:3072
	global_load_dwordx4 v[170:173], v206, s[44:45]
	global_load_dwordx4 v[174:177], v206, s[44:45] offset:16
	s_add_u32 s42, s42, 0x2000
	s_addc_u32 s43, s43, 0
	s_add_u32 s44, s44, 0x80
	s_addc_u32 s45, s45, 0
	s_waitcnt vmcnt(16)
	v_mul_f32_e32 v132, v179, v119
	v_mul_f32_e32 v133, v178, v119
	v_fma_f32 v178, v178, v118, -v132
	v_fma_f32 v179, v179, v118, v133
	v_mul_f32_e32 v132, v181, v123
	v_mul_f32_e32 v133, v180, v123
	v_fma_f32 v180, v180, v122, -v132
	v_fma_f32 v181, v181, v122, v133
	v_mul_f32_e32 v132, v183, v127
	v_mul_f32_e32 v133, v182, v127
	v_fma_f32 v182, v182, v126, -v132
	v_fma_f32 v183, v183, v126, v133
	v_mul_f32_e32 v132, v185, v131
	v_mul_f32_e32 v133, v184, v131
	v_fma_f32 v184, v184, v130, -v132
	v_fma_f32 v185, v185, v130, v133
	v_mul_f32_e32 v132, v56, v101
	v_mul_f32_e32 v56, v56, v100
	v_fma_f32 v56, -v60, v101, v56
	v_fma_f32 v60, v60, v100, v132
	v_mul_f32_e32 v133, v57, v105
	v_mul_f32_e32 v57, v57, v104
	v_fma_f32 v57, -v61, v105, v57
	v_fma_f32 v61, v61, v104, v133
	v_mul_f32_e32 v132, v58, v109
	v_mul_f32_e32 v58, v58, v108
	v_fma_f32 v58, -v62, v109, v58
	v_fma_f32 v62, v62, v108, v132
	v_mul_f32_e32 v133, v59, v113
	v_mul_f32_e32 v59, v59, v112
	v_fma_f32 v59, -v63, v113, v59
	v_fma_f32 v63, v63, v112, v133
	v_add_f32_dpp v56, v56, v56 row_shl:1 row_mask:0xf bank_mask:0xf bound_ctrl:1
	v_add_f32_dpp v57, v57, v57 row_shl:1 row_mask:0xf bank_mask:0xf bound_ctrl:1
	v_add_f32_dpp v58, v58, v58 row_shl:1 row_mask:0xf bank_mask:0xf bound_ctrl:1
	v_add_f32_dpp v59, v59, v59 row_shl:1 row_mask:0xf bank_mask:0xf bound_ctrl:1
	v_add_f32_dpp v60, v60, v60 row_shl:1 row_mask:0xf bank_mask:0xf bound_ctrl:1
	v_add_f32_dpp v61, v61, v61 row_shl:1 row_mask:0xf bank_mask:0xf bound_ctrl:1
	v_add_f32_dpp v62, v62, v62 row_shl:1 row_mask:0xf bank_mask:0xf bound_ctrl:1
	v_add_f32_dpp v63, v63, v63 row_shl:1 row_mask:0xf bank_mask:0xf bound_ctrl:1
	v_add_f32_dpp v56, v56, v56 row_shl:2 row_mask:0xf bank_mask:0xf bound_ctrl:1
	v_add_f32_dpp v57, v57, v57 row_shl:2 row_mask:0xf bank_mask:0xf bound_ctrl:1
	v_add_f32_dpp v58, v58, v58 row_shl:2 row_mask:0xf bank_mask:0xf bound_ctrl:1
	v_add_f32_dpp v59, v59, v59 row_shl:2 row_mask:0xf bank_mask:0xf bound_ctrl:1
	v_add_f32_dpp v60, v60, v60 row_shl:2 row_mask:0xf bank_mask:0xf bound_ctrl:1
	v_add_f32_dpp v61, v61, v61 row_shl:2 row_mask:0xf bank_mask:0xf bound_ctrl:1
	v_add_f32_dpp v62, v62, v62 row_shl:2 row_mask:0xf bank_mask:0xf bound_ctrl:1
	v_add_f32_dpp v63, v63, v63 row_shl:2 row_mask:0xf bank_mask:0xf bound_ctrl:1
	v_add_f32_dpp v56, v56, v56 row_shl:4 row_mask:0xf bank_mask:0xf bound_ctrl:1
	v_add_f32_dpp v57, v57, v57 row_shl:4 row_mask:0xf bank_mask:0xf bound_ctrl:1
	v_add_f32_dpp v58, v58, v58 row_shl:4 row_mask:0xf bank_mask:0xf bound_ctrl:1
	v_add_f32_dpp v59, v59, v59 row_shl:4 row_mask:0xf bank_mask:0xf bound_ctrl:1
	v_add_f32_dpp v60, v60, v60 row_shl:4 row_mask:0xf bank_mask:0xf bound_ctrl:1
	v_add_f32_dpp v61, v61, v61 row_shl:4 row_mask:0xf bank_mask:0xf bound_ctrl:1
	v_add_f32_dpp v62, v62, v62 row_shl:4 row_mask:0xf bank_mask:0xf bound_ctrl:1
	v_add_f32_dpp v63, v63, v63 row_shl:4 row_mask:0xf bank_mask:0xf bound_ctrl:1
	v_add_f32_dpp v56, v56, v56 row_shl:8 row_mask:0xf bank_mask:0xf bound_ctrl:1
	v_add_f32_dpp v57, v57, v57 row_shl:8 row_mask:0xf bank_mask:0xf bound_ctrl:1
	v_add_f32_dpp v58, v58, v58 row_shl:8 row_mask:0xf bank_mask:0xf bound_ctrl:1
	v_add_f32_dpp v59, v59, v59 row_shl:8 row_mask:0xf bank_mask:0xf bound_ctrl:1
	v_add_f32_dpp v60, v60, v60 row_shl:8 row_mask:0xf bank_mask:0xf bound_ctrl:1
	v_add_f32_dpp v61, v61, v61 row_shl:8 row_mask:0xf bank_mask:0xf bound_ctrl:1
	v_add_f32_dpp v62, v62, v62 row_shl:8 row_mask:0xf bank_mask:0xf bound_ctrl:1
	v_add_f32_dpp v63, v63, v63 row_shl:8 row_mask:0xf bank_mask:0xf bound_ctrl:1
	v_mov_b32_dpp v88, v56 row_newbcast:0 row_mask:0xf bank_mask:0xf
	v_mov_b32_dpp v89, v57 row_newbcast:0 row_mask:0xf bank_mask:0xf
	v_mov_b32_dpp v90, v58 row_newbcast:0 row_mask:0xf bank_mask:0xf
	v_mov_b32_dpp v91, v59 row_newbcast:0 row_mask:0xf bank_mask:0xf
	v_mov_b32_dpp v92, v60 row_newbcast:0 row_mask:0xf bank_mask:0xf
	v_mov_b32_dpp v93, v61 row_newbcast:0 row_mask:0xf bank_mask:0xf
	v_mov_b32_dpp v94, v62 row_newbcast:0 row_mask:0xf bank_mask:0xf
	v_mov_b32_dpp v95, v63 row_newbcast:0 row_mask:0xf bank_mask:0xf
	v_add_f32_e32 v56, v56, v178
	v_add_f32_e32 v60, v60, v179
	v_add_f32_e32 v57, v57, v180
	v_add_f32_e32 v61, v61, v181
	v_add_f32_e32 v58, v58, v182
	v_add_f32_e32 v62, v62, v183
	v_add_f32_e32 v59, v59, v184
	v_add_f32_e32 v63, v63, v185
	v_mul_f32_e32 v132, v56, v103
	v_mul_f32_e32 v56, v56, v102
	v_fma_f32 v56, -v60, v103, v56
	v_fma_f32 v60, v60, v102, v132
	v_mul_f32_e32 v133, v57, v107
	v_mul_f32_e32 v57, v57, v106
	v_fma_f32 v57, -v61, v107, v57
	v_fma_f32 v61, v61, v106, v133
	v_mul_f32_e32 v132, v58, v111
	v_mul_f32_e32 v58, v58, v110
	v_fma_f32 v58, -v62, v111, v58
	v_fma_f32 v62, v62, v110, v132
	v_mul_f32_e32 v133, v59, v115
	v_mul_f32_e32 v59, v59, v114
	v_fma_f32 v59, -v63, v115, v59
	v_fma_f32 v63, v63, v114, v133
	v_add_f32_e32 v88, v88, v178
	v_add_f32_e32 v92, v92, v179
	v_mul_f32_e32 v132, v92, v117
	v_mul_f32_e32 v179, v88, v117
	v_fma_f32 v178, v88, v116, -v132
	v_fma_f32 v179, v92, v116, v179
	v_add_f32_e32 v89, v89, v180
	v_add_f32_e32 v93, v93, v181
	v_mul_f32_e32 v133, v93, v121
	v_mul_f32_e32 v181, v89, v121
	v_fma_f32 v180, v89, v120, -v133
	v_fma_f32 v181, v93, v120, v181
	v_add_f32_e32 v90, v90, v182
	v_add_f32_e32 v94, v94, v183
	v_mul_f32_e32 v132, v94, v125
	v_mul_f32_e32 v183, v90, v125
	v_fma_f32 v182, v90, v124, -v132
	v_fma_f32 v183, v94, v124, v183
	v_add_f32_e32 v91, v91, v184
	v_add_f32_e32 v95, v95, v185
	v_mul_f32_e32 v133, v95, v129
	v_mul_f32_e32 v185, v91, v129
	v_fma_f32 v184, v91, v128, -v133
	v_fma_f32 v185, v95, v128, v185
	v_mul_f32_e32 v132, v48, v101
	v_mul_f32_e32 v48, v48, v100
	v_fma_f32 v48, -v52, v101, v48
	v_fma_f32 v52, v52, v100, v132
	v_mul_f32_e32 v133, v49, v105
	v_mul_f32_e32 v49, v49, v104
	v_fma_f32 v49, -v53, v105, v49
	v_fma_f32 v53, v53, v104, v133
	v_mul_f32_e32 v132, v50, v109
	v_mul_f32_e32 v50, v50, v108
	v_fma_f32 v50, -v54, v109, v50
	v_fma_f32 v54, v54, v108, v132
	v_mul_f32_e32 v133, v51, v113
	v_mul_f32_e32 v51, v51, v112
	v_fma_f32 v51, -v55, v113, v51
	v_fma_f32 v55, v55, v112, v133
	v_add_f32_dpp v48, v48, v48 row_shl:1 row_mask:0xf bank_mask:0xf bound_ctrl:1
	v_add_f32_dpp v49, v49, v49 row_shl:1 row_mask:0xf bank_mask:0xf bound_ctrl:1
	v_add_f32_dpp v50, v50, v50 row_shl:1 row_mask:0xf bank_mask:0xf bound_ctrl:1
	v_add_f32_dpp v51, v51, v51 row_shl:1 row_mask:0xf bank_mask:0xf bound_ctrl:1
	v_add_f32_dpp v52, v52, v52 row_shl:1 row_mask:0xf bank_mask:0xf bound_ctrl:1
	v_add_f32_dpp v53, v53, v53 row_shl:1 row_mask:0xf bank_mask:0xf bound_ctrl:1
	v_add_f32_dpp v54, v54, v54 row_shl:1 row_mask:0xf bank_mask:0xf bound_ctrl:1
	v_add_f32_dpp v55, v55, v55 row_shl:1 row_mask:0xf bank_mask:0xf bound_ctrl:1
	v_add_f32_dpp v48, v48, v48 row_shl:2 row_mask:0xf bank_mask:0xf bound_ctrl:1
	v_add_f32_dpp v49, v49, v49 row_shl:2 row_mask:0xf bank_mask:0xf bound_ctrl:1
	v_add_f32_dpp v50, v50, v50 row_shl:2 row_mask:0xf bank_mask:0xf bound_ctrl:1
	v_add_f32_dpp v51, v51, v51 row_shl:2 row_mask:0xf bank_mask:0xf bound_ctrl:1
	v_add_f32_dpp v52, v52, v52 row_shl:2 row_mask:0xf bank_mask:0xf bound_ctrl:1
	v_add_f32_dpp v53, v53, v53 row_shl:2 row_mask:0xf bank_mask:0xf bound_ctrl:1
	v_add_f32_dpp v54, v54, v54 row_shl:2 row_mask:0xf bank_mask:0xf bound_ctrl:1
	v_add_f32_dpp v55, v55, v55 row_shl:2 row_mask:0xf bank_mask:0xf bound_ctrl:1
	v_add_f32_dpp v48, v48, v48 row_shl:4 row_mask:0xf bank_mask:0xf bound_ctrl:1
	v_add_f32_dpp v49, v49, v49 row_shl:4 row_mask:0xf bank_mask:0xf bound_ctrl:1
	v_add_f32_dpp v50, v50, v50 row_shl:4 row_mask:0xf bank_mask:0xf bound_ctrl:1
	v_add_f32_dpp v51, v51, v51 row_shl:4 row_mask:0xf bank_mask:0xf bound_ctrl:1
	v_add_f32_dpp v52, v52, v52 row_shl:4 row_mask:0xf bank_mask:0xf bound_ctrl:1
	v_add_f32_dpp v53, v53, v53 row_shl:4 row_mask:0xf bank_mask:0xf bound_ctrl:1
	v_add_f32_dpp v54, v54, v54 row_shl:4 row_mask:0xf bank_mask:0xf bound_ctrl:1
	v_add_f32_dpp v55, v55, v55 row_shl:4 row_mask:0xf bank_mask:0xf bound_ctrl:1
	v_add_f32_dpp v48, v48, v48 row_shl:8 row_mask:0xf bank_mask:0xf bound_ctrl:1
	v_add_f32_dpp v49, v49, v49 row_shl:8 row_mask:0xf bank_mask:0xf bound_ctrl:1
	v_add_f32_dpp v50, v50, v50 row_shl:8 row_mask:0xf bank_mask:0xf bound_ctrl:1
	v_add_f32_dpp v51, v51, v51 row_shl:8 row_mask:0xf bank_mask:0xf bound_ctrl:1
	v_add_f32_dpp v52, v52, v52 row_shl:8 row_mask:0xf bank_mask:0xf bound_ctrl:1
	v_add_f32_dpp v53, v53, v53 row_shl:8 row_mask:0xf bank_mask:0xf bound_ctrl:1
	v_add_f32_dpp v54, v54, v54 row_shl:8 row_mask:0xf bank_mask:0xf bound_ctrl:1
	v_add_f32_dpp v55, v55, v55 row_shl:8 row_mask:0xf bank_mask:0xf bound_ctrl:1
	v_mov_b32_dpp v88, v48 row_newbcast:0 row_mask:0xf bank_mask:0xf
	v_mov_b32_dpp v89, v49 row_newbcast:0 row_mask:0xf bank_mask:0xf
	v_mov_b32_dpp v90, v50 row_newbcast:0 row_mask:0xf bank_mask:0xf
	v_mov_b32_dpp v91, v51 row_newbcast:0 row_mask:0xf bank_mask:0xf
	v_mov_b32_dpp v92, v52 row_newbcast:0 row_mask:0xf bank_mask:0xf
	v_mov_b32_dpp v93, v53 row_newbcast:0 row_mask:0xf bank_mask:0xf
	v_mov_b32_dpp v94, v54 row_newbcast:0 row_mask:0xf bank_mask:0xf
	v_mov_b32_dpp v95, v55 row_newbcast:0 row_mask:0xf bank_mask:0xf
	v_add_f32_e32 v48, v48, v178
	v_add_f32_e32 v52, v52, v179
	v_add_f32_e32 v49, v49, v180
	v_add_f32_e32 v53, v53, v181
	v_add_f32_e32 v50, v50, v182
	v_add_f32_e32 v54, v54, v183
	v_add_f32_e32 v51, v51, v184
	v_add_f32_e32 v55, v55, v185
	v_mul_f32_e32 v132, v48, v103
	v_mul_f32_e32 v48, v48, v102
	v_fma_f32 v48, -v52, v103, v48
	v_fma_f32 v52, v52, v102, v132
	v_mul_f32_e32 v133, v49, v107
	v_mul_f32_e32 v49, v49, v106
	v_fma_f32 v49, -v53, v107, v49
	v_fma_f32 v53, v53, v106, v133
	v_mul_f32_e32 v132, v50, v111
	v_mul_f32_e32 v50, v50, v110
	v_fma_f32 v50, -v54, v111, v50
	v_fma_f32 v54, v54, v110, v132
	v_mul_f32_e32 v133, v51, v115
	v_mul_f32_e32 v51, v51, v114
	v_fma_f32 v51, -v55, v115, v51
	v_fma_f32 v55, v55, v114, v133
	v_add_f32_e32 v88, v88, v178
	v_add_f32_e32 v92, v92, v179
	v_mul_f32_e32 v132, v92, v117
	v_mul_f32_e32 v179, v88, v117
	v_fma_f32 v178, v88, v116, -v132
	v_fma_f32 v179, v92, v116, v179
	v_add_f32_e32 v89, v89, v180
	v_add_f32_e32 v93, v93, v181
	v_mul_f32_e32 v133, v93, v121
	v_mul_f32_e32 v181, v89, v121
	v_fma_f32 v180, v89, v120, -v133
	v_fma_f32 v181, v93, v120, v181
	v_add_f32_e32 v90, v90, v182
	v_add_f32_e32 v94, v94, v183
	v_mul_f32_e32 v132, v94, v125
	v_mul_f32_e32 v183, v90, v125
	v_fma_f32 v182, v90, v124, -v132
	v_fma_f32 v183, v94, v124, v183
	v_add_f32_e32 v91, v91, v184
	v_add_f32_e32 v95, v95, v185
	v_mul_f32_e32 v133, v95, v129
	v_mul_f32_e32 v185, v91, v129
	v_fma_f32 v184, v91, v128, -v133
	v_fma_f32 v185, v95, v128, v185
	v_mul_f32_e32 v132, v40, v101
	v_mul_f32_e32 v40, v40, v100
	v_fma_f32 v40, -v44, v101, v40
	v_fma_f32 v44, v44, v100, v132
	v_mul_f32_e32 v133, v41, v105
	v_mul_f32_e32 v41, v41, v104
	v_fma_f32 v41, -v45, v105, v41
	v_fma_f32 v45, v45, v104, v133
	v_mul_f32_e32 v132, v42, v109
	v_mul_f32_e32 v42, v42, v108
	v_fma_f32 v42, -v46, v109, v42
	v_fma_f32 v46, v46, v108, v132
	v_mul_f32_e32 v133, v43, v113
	v_mul_f32_e32 v43, v43, v112
	v_fma_f32 v43, -v47, v113, v43
	v_fma_f32 v47, v47, v112, v133
	v_add_f32_dpp v40, v40, v40 row_shl:1 row_mask:0xf bank_mask:0xf bound_ctrl:1
	v_add_f32_dpp v41, v41, v41 row_shl:1 row_mask:0xf bank_mask:0xf bound_ctrl:1
	v_add_f32_dpp v42, v42, v42 row_shl:1 row_mask:0xf bank_mask:0xf bound_ctrl:1
	v_add_f32_dpp v43, v43, v43 row_shl:1 row_mask:0xf bank_mask:0xf bound_ctrl:1
	v_add_f32_dpp v44, v44, v44 row_shl:1 row_mask:0xf bank_mask:0xf bound_ctrl:1
	v_add_f32_dpp v45, v45, v45 row_shl:1 row_mask:0xf bank_mask:0xf bound_ctrl:1
	v_add_f32_dpp v46, v46, v46 row_shl:1 row_mask:0xf bank_mask:0xf bound_ctrl:1
	v_add_f32_dpp v47, v47, v47 row_shl:1 row_mask:0xf bank_mask:0xf bound_ctrl:1
	v_add_f32_dpp v40, v40, v40 row_shl:2 row_mask:0xf bank_mask:0xf bound_ctrl:1
	v_add_f32_dpp v41, v41, v41 row_shl:2 row_mask:0xf bank_mask:0xf bound_ctrl:1
	v_add_f32_dpp v42, v42, v42 row_shl:2 row_mask:0xf bank_mask:0xf bound_ctrl:1
	v_add_f32_dpp v43, v43, v43 row_shl:2 row_mask:0xf bank_mask:0xf bound_ctrl:1
	v_add_f32_dpp v44, v44, v44 row_shl:2 row_mask:0xf bank_mask:0xf bound_ctrl:1
	v_add_f32_dpp v45, v45, v45 row_shl:2 row_mask:0xf bank_mask:0xf bound_ctrl:1
	v_add_f32_dpp v46, v46, v46 row_shl:2 row_mask:0xf bank_mask:0xf bound_ctrl:1
	v_add_f32_dpp v47, v47, v47 row_shl:2 row_mask:0xf bank_mask:0xf bound_ctrl:1
	v_add_f32_dpp v40, v40, v40 row_shl:4 row_mask:0xf bank_mask:0xf bound_ctrl:1
	v_add_f32_dpp v41, v41, v41 row_shl:4 row_mask:0xf bank_mask:0xf bound_ctrl:1
	v_add_f32_dpp v42, v42, v42 row_shl:4 row_mask:0xf bank_mask:0xf bound_ctrl:1
	v_add_f32_dpp v43, v43, v43 row_shl:4 row_mask:0xf bank_mask:0xf bound_ctrl:1
	v_add_f32_dpp v44, v44, v44 row_shl:4 row_mask:0xf bank_mask:0xf bound_ctrl:1
	v_add_f32_dpp v45, v45, v45 row_shl:4 row_mask:0xf bank_mask:0xf bound_ctrl:1
	v_add_f32_dpp v46, v46, v46 row_shl:4 row_mask:0xf bank_mask:0xf bound_ctrl:1
	v_add_f32_dpp v47, v47, v47 row_shl:4 row_mask:0xf bank_mask:0xf bound_ctrl:1
	v_add_f32_dpp v40, v40, v40 row_shl:8 row_mask:0xf bank_mask:0xf bound_ctrl:1
	v_add_f32_dpp v41, v41, v41 row_shl:8 row_mask:0xf bank_mask:0xf bound_ctrl:1
	v_add_f32_dpp v42, v42, v42 row_shl:8 row_mask:0xf bank_mask:0xf bound_ctrl:1
	v_add_f32_dpp v43, v43, v43 row_shl:8 row_mask:0xf bank_mask:0xf bound_ctrl:1
	v_add_f32_dpp v44, v44, v44 row_shl:8 row_mask:0xf bank_mask:0xf bound_ctrl:1
	v_add_f32_dpp v45, v45, v45 row_shl:8 row_mask:0xf bank_mask:0xf bound_ctrl:1
	v_add_f32_dpp v46, v46, v46 row_shl:8 row_mask:0xf bank_mask:0xf bound_ctrl:1
	v_add_f32_dpp v47, v47, v47 row_shl:8 row_mask:0xf bank_mask:0xf bound_ctrl:1
	v_mov_b32_dpp v88, v40 row_newbcast:0 row_mask:0xf bank_mask:0xf
	v_mov_b32_dpp v89, v41 row_newbcast:0 row_mask:0xf bank_mask:0xf
	v_mov_b32_dpp v90, v42 row_newbcast:0 row_mask:0xf bank_mask:0xf
	v_mov_b32_dpp v91, v43 row_newbcast:0 row_mask:0xf bank_mask:0xf
	v_mov_b32_dpp v92, v44 row_newbcast:0 row_mask:0xf bank_mask:0xf
	v_mov_b32_dpp v93, v45 row_newbcast:0 row_mask:0xf bank_mask:0xf
	v_mov_b32_dpp v94, v46 row_newbcast:0 row_mask:0xf bank_mask:0xf
	v_mov_b32_dpp v95, v47 row_newbcast:0 row_mask:0xf bank_mask:0xf
	v_add_f32_e32 v40, v40, v178
	v_add_f32_e32 v44, v44, v179
	v_add_f32_e32 v41, v41, v180
	v_add_f32_e32 v45, v45, v181
	v_add_f32_e32 v42, v42, v182
	v_add_f32_e32 v46, v46, v183
	v_add_f32_e32 v43, v43, v184
	v_add_f32_e32 v47, v47, v185
	v_mul_f32_e32 v132, v40, v103
	v_mul_f32_e32 v40, v40, v102
	v_fma_f32 v40, -v44, v103, v40
	v_fma_f32 v44, v44, v102, v132
	v_mul_f32_e32 v133, v41, v107
	v_mul_f32_e32 v41, v41, v106
	v_fma_f32 v41, -v45, v107, v41
	v_fma_f32 v45, v45, v106, v133
	v_mul_f32_e32 v132, v42, v111
	v_mul_f32_e32 v42, v42, v110
	v_fma_f32 v42, -v46, v111, v42
	v_fma_f32 v46, v46, v110, v132
	v_mul_f32_e32 v133, v43, v115
	v_mul_f32_e32 v43, v43, v114
	v_fma_f32 v43, -v47, v115, v43
	v_fma_f32 v47, v47, v114, v133
	v_add_f32_e32 v88, v88, v178
	v_add_f32_e32 v92, v92, v179
	v_mul_f32_e32 v132, v92, v117
	v_mul_f32_e32 v179, v88, v117
	v_fma_f32 v178, v88, v116, -v132
	v_fma_f32 v179, v92, v116, v179
	v_add_f32_e32 v89, v89, v180
	v_add_f32_e32 v93, v93, v181
	v_mul_f32_e32 v133, v93, v121
	v_mul_f32_e32 v181, v89, v121
	v_fma_f32 v180, v89, v120, -v133
	v_fma_f32 v181, v93, v120, v181
	v_add_f32_e32 v90, v90, v182
	v_add_f32_e32 v94, v94, v183
	v_mul_f32_e32 v132, v94, v125
	v_mul_f32_e32 v183, v90, v125
	v_fma_f32 v182, v90, v124, -v132
	v_fma_f32 v183, v94, v124, v183
	v_add_f32_e32 v91, v91, v184
	v_add_f32_e32 v95, v95, v185
	v_mul_f32_e32 v133, v95, v129
	v_mul_f32_e32 v185, v91, v129
	v_fma_f32 v184, v91, v128, -v133
	v_fma_f32 v185, v95, v128, v185
	v_mul_f32_e32 v132, v32, v101
	v_mul_f32_e32 v32, v32, v100
	v_fma_f32 v32, -v36, v101, v32
	v_fma_f32 v36, v36, v100, v132
	v_mul_f32_e32 v133, v33, v105
	v_mul_f32_e32 v33, v33, v104
	v_fma_f32 v33, -v37, v105, v33
	v_fma_f32 v37, v37, v104, v133
	v_mul_f32_e32 v132, v34, v109
	v_mul_f32_e32 v34, v34, v108
	v_fma_f32 v34, -v38, v109, v34
	v_fma_f32 v38, v38, v108, v132
	v_mul_f32_e32 v133, v35, v113
	v_mul_f32_e32 v35, v35, v112
	v_fma_f32 v35, -v39, v113, v35
	v_fma_f32 v39, v39, v112, v133
	v_add_f32_dpp v32, v32, v32 row_shl:1 row_mask:0xf bank_mask:0xf bound_ctrl:1
	v_add_f32_dpp v33, v33, v33 row_shl:1 row_mask:0xf bank_mask:0xf bound_ctrl:1
	v_add_f32_dpp v34, v34, v34 row_shl:1 row_mask:0xf bank_mask:0xf bound_ctrl:1
	v_add_f32_dpp v35, v35, v35 row_shl:1 row_mask:0xf bank_mask:0xf bound_ctrl:1
	v_add_f32_dpp v36, v36, v36 row_shl:1 row_mask:0xf bank_mask:0xf bound_ctrl:1
	v_add_f32_dpp v37, v37, v37 row_shl:1 row_mask:0xf bank_mask:0xf bound_ctrl:1
	v_add_f32_dpp v38, v38, v38 row_shl:1 row_mask:0xf bank_mask:0xf bound_ctrl:1
	v_add_f32_dpp v39, v39, v39 row_shl:1 row_mask:0xf bank_mask:0xf bound_ctrl:1
	v_add_f32_dpp v32, v32, v32 row_shl:2 row_mask:0xf bank_mask:0xf bound_ctrl:1
	v_add_f32_dpp v33, v33, v33 row_shl:2 row_mask:0xf bank_mask:0xf bound_ctrl:1
	v_add_f32_dpp v34, v34, v34 row_shl:2 row_mask:0xf bank_mask:0xf bound_ctrl:1
	v_add_f32_dpp v35, v35, v35 row_shl:2 row_mask:0xf bank_mask:0xf bound_ctrl:1
	v_add_f32_dpp v36, v36, v36 row_shl:2 row_mask:0xf bank_mask:0xf bound_ctrl:1
	v_add_f32_dpp v37, v37, v37 row_shl:2 row_mask:0xf bank_mask:0xf bound_ctrl:1
	v_add_f32_dpp v38, v38, v38 row_shl:2 row_mask:0xf bank_mask:0xf bound_ctrl:1
	v_add_f32_dpp v39, v39, v39 row_shl:2 row_mask:0xf bank_mask:0xf bound_ctrl:1
	v_add_f32_dpp v32, v32, v32 row_shl:4 row_mask:0xf bank_mask:0xf bound_ctrl:1
	v_add_f32_dpp v33, v33, v33 row_shl:4 row_mask:0xf bank_mask:0xf bound_ctrl:1
	v_add_f32_dpp v34, v34, v34 row_shl:4 row_mask:0xf bank_mask:0xf bound_ctrl:1
	v_add_f32_dpp v35, v35, v35 row_shl:4 row_mask:0xf bank_mask:0xf bound_ctrl:1
	v_add_f32_dpp v36, v36, v36 row_shl:4 row_mask:0xf bank_mask:0xf bound_ctrl:1
	v_add_f32_dpp v37, v37, v37 row_shl:4 row_mask:0xf bank_mask:0xf bound_ctrl:1
	v_add_f32_dpp v38, v38, v38 row_shl:4 row_mask:0xf bank_mask:0xf bound_ctrl:1
	v_add_f32_dpp v39, v39, v39 row_shl:4 row_mask:0xf bank_mask:0xf bound_ctrl:1
	v_add_f32_dpp v32, v32, v32 row_shl:8 row_mask:0xf bank_mask:0xf bound_ctrl:1
	v_add_f32_dpp v33, v33, v33 row_shl:8 row_mask:0xf bank_mask:0xf bound_ctrl:1
	v_add_f32_dpp v34, v34, v34 row_shl:8 row_mask:0xf bank_mask:0xf bound_ctrl:1
	v_add_f32_dpp v35, v35, v35 row_shl:8 row_mask:0xf bank_mask:0xf bound_ctrl:1
	v_add_f32_dpp v36, v36, v36 row_shl:8 row_mask:0xf bank_mask:0xf bound_ctrl:1
	v_add_f32_dpp v37, v37, v37 row_shl:8 row_mask:0xf bank_mask:0xf bound_ctrl:1
	v_add_f32_dpp v38, v38, v38 row_shl:8 row_mask:0xf bank_mask:0xf bound_ctrl:1
	v_add_f32_dpp v39, v39, v39 row_shl:8 row_mask:0xf bank_mask:0xf bound_ctrl:1
	v_mov_b32_dpp v88, v32 row_newbcast:0 row_mask:0xf bank_mask:0xf
	v_mov_b32_dpp v89, v33 row_newbcast:0 row_mask:0xf bank_mask:0xf
	v_mov_b32_dpp v90, v34 row_newbcast:0 row_mask:0xf bank_mask:0xf
	v_mov_b32_dpp v91, v35 row_newbcast:0 row_mask:0xf bank_mask:0xf
	v_mov_b32_dpp v92, v36 row_newbcast:0 row_mask:0xf bank_mask:0xf
	v_mov_b32_dpp v93, v37 row_newbcast:0 row_mask:0xf bank_mask:0xf
	v_mov_b32_dpp v94, v38 row_newbcast:0 row_mask:0xf bank_mask:0xf
	v_mov_b32_dpp v95, v39 row_newbcast:0 row_mask:0xf bank_mask:0xf
	v_add_f32_e32 v32, v32, v178
	v_add_f32_e32 v36, v36, v179
	v_add_f32_e32 v33, v33, v180
	v_add_f32_e32 v37, v37, v181
	v_add_f32_e32 v34, v34, v182
	v_add_f32_e32 v38, v38, v183
	v_add_f32_e32 v35, v35, v184
	v_add_f32_e32 v39, v39, v185
	v_mul_f32_e32 v132, v32, v103
	v_mul_f32_e32 v32, v32, v102
	v_fma_f32 v32, -v36, v103, v32
	v_fma_f32 v36, v36, v102, v132
	v_mul_f32_e32 v133, v33, v107
	v_mul_f32_e32 v33, v33, v106
	v_fma_f32 v33, -v37, v107, v33
	v_fma_f32 v37, v37, v106, v133
	v_mul_f32_e32 v132, v34, v111
	v_mul_f32_e32 v34, v34, v110
	v_fma_f32 v34, -v38, v111, v34
	v_fma_f32 v38, v38, v110, v132
	v_mul_f32_e32 v133, v35, v115
	v_mul_f32_e32 v35, v35, v114
	v_fma_f32 v35, -v39, v115, v35
	v_fma_f32 v39, v39, v114, v133
	v_add_f32_e32 v88, v88, v178
	v_add_f32_e32 v92, v92, v179
	v_mul_f32_e32 v132, v92, v117
	v_mul_f32_e32 v179, v88, v117
	v_fma_f32 v178, v88, v116, -v132
	v_fma_f32 v179, v92, v116, v179
	v_add_f32_e32 v89, v89, v180
	v_add_f32_e32 v93, v93, v181
	v_mul_f32_e32 v133, v93, v121
	v_mul_f32_e32 v181, v89, v121
	v_fma_f32 v180, v89, v120, -v133
	v_fma_f32 v181, v93, v120, v181
	v_add_f32_e32 v90, v90, v182
	v_add_f32_e32 v94, v94, v183
	v_mul_f32_e32 v132, v94, v125
	v_mul_f32_e32 v183, v90, v125
	v_fma_f32 v182, v90, v124, -v132
	v_fma_f32 v183, v94, v124, v183
	v_add_f32_e32 v91, v91, v184
	v_add_f32_e32 v95, v95, v185
	v_mul_f32_e32 v133, v95, v129
	v_mul_f32_e32 v185, v91, v129
	v_fma_f32 v184, v91, v128, -v133
	v_fma_f32 v185, v95, v128, v185
	s_waitcnt vmcnt(14)
	v_cvt_pk_bf16_f32 v80, v80, v81
	v_cvt_pk_bf16_f32 v81, v82, v83
	v_cvt_pk_bf16_f32 v82, -v84, -v85
	v_cvt_pk_bf16_f32 v83, -v86, -v87
	v_cvt_pk_bf16_f32 v96, v32, v33
	v_cvt_pk_bf16_f32 v97, v34, v35
	v_cvt_pk_bf16_f32 v98, v36, v37
	v_cvt_pk_bf16_f32 v99, v38, v39
	s_nop 1
	v_mfma_f32_16x16x32_bf16 v[16:19], v[80:83], v[96:99], v[16:19]
	v_cvt_pk_bf16_f32 v96, v40, v41
	v_cvt_pk_bf16_f32 v97, v42, v43
	v_cvt_pk_bf16_f32 v98, v44, v45
	v_cvt_pk_bf16_f32 v99, v46, v47
	s_nop 1
	v_mfma_f32_16x16x32_bf16 v[20:23], v[80:83], v[96:99], v[20:23]
	v_cvt_pk_bf16_f32 v96, v48, v49
	v_cvt_pk_bf16_f32 v97, v50, v51
	v_cvt_pk_bf16_f32 v98, v52, v53
	v_cvt_pk_bf16_f32 v99, v54, v55
	s_nop 1
	v_mfma_f32_16x16x32_bf16 v[24:27], v[80:83], v[96:99], v[24:27]
	v_cvt_pk_bf16_f32 v96, v56, v57
	v_cvt_pk_bf16_f32 v97, v58, v59
	v_cvt_pk_bf16_f32 v98, v60, v61
	v_cvt_pk_bf16_f32 v99, v62, v63
	s_nop 1
	v_mfma_f32_16x16x32_bf16 v[28:31], v[80:83], v[96:99], v[28:31]
	s_waitcnt vmcnt(10)
	v_cvt_pk_bf16_f32 v64, v64, v65
	v_cvt_pk_bf16_f32 v65, v66, v67
	v_cvt_pk_bf16_f32 v66, v68, v69
	v_cvt_pk_bf16_f32 v67, v70, v71
	v_cvt_pk_bf16_f32 v72, v72, v73
	v_cvt_pk_bf16_f32 v73, v74, v75
	v_cvt_pk_bf16_f32 v74, v76, v77
	v_cvt_pk_bf16_f32 v75, v78, v79
	global_load_dwordx4 v[80:83], v136, s[38:39]
	global_load_dwordx4 v[84:87], v136, s[40:41]
	s_add_u32 s38, s38, 0x40
	s_addc_u32 s39, s39, 0
	s_add_u32 s40, s40, 0x40
	s_addc_u32 s41, s41, 0
	s_nop 0
	v_mfma_f32_16x16x32_bf16 v[32:35], v[64:67], v[0:3], 0
	v_mfma_f32_16x16x32_bf16 v[36:39], v[72:75], v[0:3], 0
	v_mfma_f32_16x16x32_bf16 v[40:43], v[64:67], v[4:7], 0
	v_mfma_f32_16x16x32_bf16 v[44:47], v[72:75], v[4:7], 0
	v_mfma_f32_16x16x32_bf16 v[48:51], v[64:67], v[8:11], 0
	v_mfma_f32_16x16x32_bf16 v[52:55], v[72:75], v[8:11], 0
	v_mfma_f32_16x16x32_bf16 v[56:59], v[64:67], v[12:15], 0
	v_mfma_f32_16x16x32_bf16 v[60:63], v[72:75], v[12:15], 0
	s_mov_b32 exec_hi, 0
	global_load_dwordx4 v[64:67], v135, s[20:21]
	global_load_dwordx4 v[68:71], v135, s[20:21] offset:16
	global_load_dwordx4 v[72:75], v135, s[22:23]
	global_load_dwordx4 v[76:79], v135, s[22:23] offset:16
	s_mov_b64 exec, -1
	global_load_dwordx4 v[100:103], v134, s[42:43] offset:0
	global_load_dwordx4 v[104:107], v134, s[42:43] offset:1024
	global_load_dwordx4 v[108:111], v134, s[42:43] offset:2048
	global_load_dwordx4 v[112:115], v134, s[42:43] offset:3072
	global_load_dwordx4 v[116:119], v208, s[42:43] offset:0
	global_load_dwordx4 v[120:123], v208, s[42:43] offset:1024
	global_load_dwordx4 v[124:127], v208, s[42:43] offset:2048
	global_load_dwordx4 v[128:131], v208, s[42:43] offset:3072
	global_load_dwordx4 v[178:181], v206, s[44:45]
	global_load_dwordx4 v[182:185], v206, s[44:45] offset:16
	s_waitcnt vmcnt(16)
	v_mul_f32_e32 v132, v171, v157
	v_mul_f32_e32 v133, v170, v157
	v_fma_f32 v170, v170, v156, -v132
	v_fma_f32 v171, v171, v156, v133
	v_mul_f32_e32 v132, v173, v161
	v_mul_f32_e32 v133, v172, v161
	v_fma_f32 v172, v172, v160, -v132
	v_fma_f32 v173, v173, v160, v133
	v_mul_f32_e32 v132, v175, v165
	v_mul_f32_e32 v133, v174, v165
	v_fma_f32 v174, v174, v164, -v132
	v_fma_f32 v175, v175, v164, v133
	v_mul_f32_e32 v132, v177, v169
	v_mul_f32_e32 v133, v176, v169
	v_fma_f32 v176, v176, v168, -v132
	v_fma_f32 v177, v177, v168, v133
	v_mul_f32_e32 v132, v56, v139
	v_mul_f32_e32 v56, v56, v138
	v_fma_f32 v56, -v60, v139, v56
	v_fma_f32 v60, v60, v138, v132
	v_mul_f32_e32 v133, v57, v143
	v_mul_f32_e32 v57, v57, v142
	v_fma_f32 v57, -v61, v143, v57
	v_fma_f32 v61, v61, v142, v133
	v_mul_f32_e32 v132, v58, v147
	v_mul_f32_e32 v58, v58, v146
	v_fma_f32 v58, -v62, v147, v58
	v_fma_f32 v62, v62, v146, v132
	v_mul_f32_e32 v133, v59, v151
	v_mul_f32_e32 v59, v59, v150
	v_fma_f32 v59, -v63, v151, v59
	v_fma_f32 v63, v63, v150, v133
	v_add_f32_dpp v56, v56, v56 row_shl:1 row_mask:0xf bank_mask:0xf bound_ctrl:1
	v_add_f32_dpp v57, v57, v57 row_shl:1 row_mask:0xf bank_mask:0xf bound_ctrl:1
	v_add_f32_dpp v58, v58, v58 row_shl:1 row_mask:0xf bank_mask:0xf bound_ctrl:1
	v_add_f32_dpp v59, v59, v59 row_shl:1 row_mask:0xf bank_mask:0xf bound_ctrl:1
	v_add_f32_dpp v60, v60, v60 row_shl:1 row_mask:0xf bank_mask:0xf bound_ctrl:1
	v_add_f32_dpp v61, v61, v61 row_shl:1 row_mask:0xf bank_mask:0xf bound_ctrl:1
	v_add_f32_dpp v62, v62, v62 row_shl:1 row_mask:0xf bank_mask:0xf bound_ctrl:1
	v_add_f32_dpp v63, v63, v63 row_shl:1 row_mask:0xf bank_mask:0xf bound_ctrl:1
	v_add_f32_dpp v56, v56, v56 row_shl:2 row_mask:0xf bank_mask:0xf bound_ctrl:1
	v_add_f32_dpp v57, v57, v57 row_shl:2 row_mask:0xf bank_mask:0xf bound_ctrl:1
	v_add_f32_dpp v58, v58, v58 row_shl:2 row_mask:0xf bank_mask:0xf bound_ctrl:1
	v_add_f32_dpp v59, v59, v59 row_shl:2 row_mask:0xf bank_mask:0xf bound_ctrl:1
	v_add_f32_dpp v60, v60, v60 row_shl:2 row_mask:0xf bank_mask:0xf bound_ctrl:1
	v_add_f32_dpp v61, v61, v61 row_shl:2 row_mask:0xf bank_mask:0xf bound_ctrl:1
	v_add_f32_dpp v62, v62, v62 row_shl:2 row_mask:0xf bank_mask:0xf bound_ctrl:1
	v_add_f32_dpp v63, v63, v63 row_shl:2 row_mask:0xf bank_mask:0xf bound_ctrl:1
	v_add_f32_dpp v56, v56, v56 row_shl:4 row_mask:0xf bank_mask:0xf bound_ctrl:1
	v_add_f32_dpp v57, v57, v57 row_shl:4 row_mask:0xf bank_mask:0xf bound_ctrl:1
	v_add_f32_dpp v58, v58, v58 row_shl:4 row_mask:0xf bank_mask:0xf bound_ctrl:1
	v_add_f32_dpp v59, v59, v59 row_shl:4 row_mask:0xf bank_mask:0xf bound_ctrl:1
	v_add_f32_dpp v60, v60, v60 row_shl:4 row_mask:0xf bank_mask:0xf bound_ctrl:1
	v_add_f32_dpp v61, v61, v61 row_shl:4 row_mask:0xf bank_mask:0xf bound_ctrl:1
	v_add_f32_dpp v62, v62, v62 row_shl:4 row_mask:0xf bank_mask:0xf bound_ctrl:1
	v_add_f32_dpp v63, v63, v63 row_shl:4 row_mask:0xf bank_mask:0xf bound_ctrl:1
	v_add_f32_dpp v56, v56, v56 row_shl:8 row_mask:0xf bank_mask:0xf bound_ctrl:1
	v_add_f32_dpp v57, v57, v57 row_shl:8 row_mask:0xf bank_mask:0xf bound_ctrl:1
	v_add_f32_dpp v58, v58, v58 row_shl:8 row_mask:0xf bank_mask:0xf bound_ctrl:1
	v_add_f32_dpp v59, v59, v59 row_shl:8 row_mask:0xf bank_mask:0xf bound_ctrl:1
	v_add_f32_dpp v60, v60, v60 row_shl:8 row_mask:0xf bank_mask:0xf bound_ctrl:1
	v_add_f32_dpp v61, v61, v61 row_shl:8 row_mask:0xf bank_mask:0xf bound_ctrl:1
	v_add_f32_dpp v62, v62, v62 row_shl:8 row_mask:0xf bank_mask:0xf bound_ctrl:1
	v_add_f32_dpp v63, v63, v63 row_shl:8 row_mask:0xf bank_mask:0xf bound_ctrl:1
	v_mov_b32_dpp v88, v56 row_newbcast:0 row_mask:0xf bank_mask:0xf
	v_mov_b32_dpp v89, v57 row_newbcast:0 row_mask:0xf bank_mask:0xf
	v_mov_b32_dpp v90, v58 row_newbcast:0 row_mask:0xf bank_mask:0xf
	v_mov_b32_dpp v91, v59 row_newbcast:0 row_mask:0xf bank_mask:0xf
	v_mov_b32_dpp v92, v60 row_newbcast:0 row_mask:0xf bank_mask:0xf
	v_mov_b32_dpp v93, v61 row_newbcast:0 row_mask:0xf bank_mask:0xf
	v_mov_b32_dpp v94, v62 row_newbcast:0 row_mask:0xf bank_mask:0xf
	v_mov_b32_dpp v95, v63 row_newbcast:0 row_mask:0xf bank_mask:0xf
	v_add_f32_e32 v56, v56, v170
	v_add_f32_e32 v60, v60, v171
	v_add_f32_e32 v57, v57, v172
	v_add_f32_e32 v61, v61, v173
	v_add_f32_e32 v58, v58, v174
	v_add_f32_e32 v62, v62, v175
	v_add_f32_e32 v59, v59, v176
	v_add_f32_e32 v63, v63, v177
	v_mul_f32_e32 v132, v56, v141
	v_mul_f32_e32 v56, v56, v140
	v_fma_f32 v56, -v60, v141, v56
	v_fma_f32 v60, v60, v140, v132
	v_mul_f32_e32 v133, v57, v145
	v_mul_f32_e32 v57, v57, v144
	v_fma_f32 v57, -v61, v145, v57
	v_fma_f32 v61, v61, v144, v133
	v_mul_f32_e32 v132, v58, v149
	v_mul_f32_e32 v58, v58, v148
	v_fma_f32 v58, -v62, v149, v58
	v_fma_f32 v62, v62, v148, v132
	v_mul_f32_e32 v133, v59, v153
	v_mul_f32_e32 v59, v59, v152
	v_fma_f32 v59, -v63, v153, v59
	v_fma_f32 v63, v63, v152, v133
	v_add_f32_e32 v88, v88, v170
	v_add_f32_e32 v92, v92, v171
	v_mul_f32_e32 v132, v92, v155
	v_mul_f32_e32 v171, v88, v155
	v_fma_f32 v170, v88, v154, -v132
	v_fma_f32 v171, v92, v154, v171
	v_add_f32_e32 v89, v89, v172
	v_add_f32_e32 v93, v93, v173
	v_mul_f32_e32 v133, v93, v159
	v_mul_f32_e32 v173, v89, v159
	v_fma_f32 v172, v89, v158, -v133
	v_fma_f32 v173, v93, v158, v173
	v_add_f32_e32 v90, v90, v174
	v_add_f32_e32 v94, v94, v175
	v_mul_f32_e32 v132, v94, v163
	v_mul_f32_e32 v175, v90, v163
	v_fma_f32 v174, v90, v162, -v132
	v_fma_f32 v175, v94, v162, v175
	v_add_f32_e32 v91, v91, v176
	v_add_f32_e32 v95, v95, v177
	v_mul_f32_e32 v133, v95, v167
	v_mul_f32_e32 v177, v91, v167
	v_fma_f32 v176, v91, v166, -v133
	v_fma_f32 v177, v95, v166, v177
	v_mul_f32_e32 v132, v48, v139
	v_mul_f32_e32 v48, v48, v138
	v_fma_f32 v48, -v52, v139, v48
	v_fma_f32 v52, v52, v138, v132
	v_mul_f32_e32 v133, v49, v143
	v_mul_f32_e32 v49, v49, v142
	v_fma_f32 v49, -v53, v143, v49
	v_fma_f32 v53, v53, v142, v133
	v_mul_f32_e32 v132, v50, v147
	v_mul_f32_e32 v50, v50, v146
	v_fma_f32 v50, -v54, v147, v50
	v_fma_f32 v54, v54, v146, v132
	v_mul_f32_e32 v133, v51, v151
	v_mul_f32_e32 v51, v51, v150
	v_fma_f32 v51, -v55, v151, v51
	v_fma_f32 v55, v55, v150, v133
	v_add_f32_dpp v48, v48, v48 row_shl:1 row_mask:0xf bank_mask:0xf bound_ctrl:1
	v_add_f32_dpp v49, v49, v49 row_shl:1 row_mask:0xf bank_mask:0xf bound_ctrl:1
	v_add_f32_dpp v50, v50, v50 row_shl:1 row_mask:0xf bank_mask:0xf bound_ctrl:1
	v_add_f32_dpp v51, v51, v51 row_shl:1 row_mask:0xf bank_mask:0xf bound_ctrl:1
	v_add_f32_dpp v52, v52, v52 row_shl:1 row_mask:0xf bank_mask:0xf bound_ctrl:1
	v_add_f32_dpp v53, v53, v53 row_shl:1 row_mask:0xf bank_mask:0xf bound_ctrl:1
	v_add_f32_dpp v54, v54, v54 row_shl:1 row_mask:0xf bank_mask:0xf bound_ctrl:1
	v_add_f32_dpp v55, v55, v55 row_shl:1 row_mask:0xf bank_mask:0xf bound_ctrl:1
	v_add_f32_dpp v48, v48, v48 row_shl:2 row_mask:0xf bank_mask:0xf bound_ctrl:1
	v_add_f32_dpp v49, v49, v49 row_shl:2 row_mask:0xf bank_mask:0xf bound_ctrl:1
	v_add_f32_dpp v50, v50, v50 row_shl:2 row_mask:0xf bank_mask:0xf bound_ctrl:1
	v_add_f32_dpp v51, v51, v51 row_shl:2 row_mask:0xf bank_mask:0xf bound_ctrl:1
	v_add_f32_dpp v52, v52, v52 row_shl:2 row_mask:0xf bank_mask:0xf bound_ctrl:1
	v_add_f32_dpp v53, v53, v53 row_shl:2 row_mask:0xf bank_mask:0xf bound_ctrl:1
	v_add_f32_dpp v54, v54, v54 row_shl:2 row_mask:0xf bank_mask:0xf bound_ctrl:1
	v_add_f32_dpp v55, v55, v55 row_shl:2 row_mask:0xf bank_mask:0xf bound_ctrl:1
	v_add_f32_dpp v48, v48, v48 row_shl:4 row_mask:0xf bank_mask:0xf bound_ctrl:1
	v_add_f32_dpp v49, v49, v49 row_shl:4 row_mask:0xf bank_mask:0xf bound_ctrl:1
	v_add_f32_dpp v50, v50, v50 row_shl:4 row_mask:0xf bank_mask:0xf bound_ctrl:1
	v_add_f32_dpp v51, v51, v51 row_shl:4 row_mask:0xf bank_mask:0xf bound_ctrl:1
	v_add_f32_dpp v52, v52, v52 row_shl:4 row_mask:0xf bank_mask:0xf bound_ctrl:1
	v_add_f32_dpp v53, v53, v53 row_shl:4 row_mask:0xf bank_mask:0xf bound_ctrl:1
	v_add_f32_dpp v54, v54, v54 row_shl:4 row_mask:0xf bank_mask:0xf bound_ctrl:1
	v_add_f32_dpp v55, v55, v55 row_shl:4 row_mask:0xf bank_mask:0xf bound_ctrl:1
	v_add_f32_dpp v48, v48, v48 row_shl:8 row_mask:0xf bank_mask:0xf bound_ctrl:1
	v_add_f32_dpp v49, v49, v49 row_shl:8 row_mask:0xf bank_mask:0xf bound_ctrl:1
	v_add_f32_dpp v50, v50, v50 row_shl:8 row_mask:0xf bank_mask:0xf bound_ctrl:1
	v_add_f32_dpp v51, v51, v51 row_shl:8 row_mask:0xf bank_mask:0xf bound_ctrl:1
	v_add_f32_dpp v52, v52, v52 row_shl:8 row_mask:0xf bank_mask:0xf bound_ctrl:1
	v_add_f32_dpp v53, v53, v53 row_shl:8 row_mask:0xf bank_mask:0xf bound_ctrl:1
	v_add_f32_dpp v54, v54, v54 row_shl:8 row_mask:0xf bank_mask:0xf bound_ctrl:1
	v_add_f32_dpp v55, v55, v55 row_shl:8 row_mask:0xf bank_mask:0xf bound_ctrl:1
	v_mov_b32_dpp v88, v48 row_newbcast:0 row_mask:0xf bank_mask:0xf
	v_mov_b32_dpp v89, v49 row_newbcast:0 row_mask:0xf bank_mask:0xf
	v_mov_b32_dpp v90, v50 row_newbcast:0 row_mask:0xf bank_mask:0xf
	v_mov_b32_dpp v91, v51 row_newbcast:0 row_mask:0xf bank_mask:0xf
	v_mov_b32_dpp v92, v52 row_newbcast:0 row_mask:0xf bank_mask:0xf
	v_mov_b32_dpp v93, v53 row_newbcast:0 row_mask:0xf bank_mask:0xf
	v_mov_b32_dpp v94, v54 row_newbcast:0 row_mask:0xf bank_mask:0xf
	v_mov_b32_dpp v95, v55 row_newbcast:0 row_mask:0xf bank_mask:0xf
	v_add_f32_e32 v48, v48, v170
	v_add_f32_e32 v52, v52, v171
	v_add_f32_e32 v49, v49, v172
	v_add_f32_e32 v53, v53, v173
	v_add_f32_e32 v50, v50, v174
	v_add_f32_e32 v54, v54, v175
	v_add_f32_e32 v51, v51, v176
	v_add_f32_e32 v55, v55, v177
	v_mul_f32_e32 v132, v48, v141
	v_mul_f32_e32 v48, v48, v140
	v_fma_f32 v48, -v52, v141, v48
	v_fma_f32 v52, v52, v140, v132
	v_mul_f32_e32 v133, v49, v145
	v_mul_f32_e32 v49, v49, v144
	v_fma_f32 v49, -v53, v145, v49
	v_fma_f32 v53, v53, v144, v133
	v_mul_f32_e32 v132, v50, v149
	v_mul_f32_e32 v50, v50, v148
	v_fma_f32 v50, -v54, v149, v50
	v_fma_f32 v54, v54, v148, v132
	v_mul_f32_e32 v133, v51, v153
	v_mul_f32_e32 v51, v51, v152
	v_fma_f32 v51, -v55, v153, v51
	v_fma_f32 v55, v55, v152, v133
	v_add_f32_e32 v88, v88, v170
	v_add_f32_e32 v92, v92, v171
	v_mul_f32_e32 v132, v92, v155
	v_mul_f32_e32 v171, v88, v155
	v_fma_f32 v170, v88, v154, -v132
	v_fma_f32 v171, v92, v154, v171
	v_add_f32_e32 v89, v89, v172
	v_add_f32_e32 v93, v93, v173
	v_mul_f32_e32 v133, v93, v159
	v_mul_f32_e32 v173, v89, v159
	v_fma_f32 v172, v89, v158, -v133
	v_fma_f32 v173, v93, v158, v173
	v_add_f32_e32 v90, v90, v174
	v_add_f32_e32 v94, v94, v175
	v_mul_f32_e32 v132, v94, v163
	v_mul_f32_e32 v175, v90, v163
	v_fma_f32 v174, v90, v162, -v132
	v_fma_f32 v175, v94, v162, v175
	v_add_f32_e32 v91, v91, v176
	v_add_f32_e32 v95, v95, v177
	v_mul_f32_e32 v133, v95, v167
	v_mul_f32_e32 v177, v91, v167
	v_fma_f32 v176, v91, v166, -v133
	v_fma_f32 v177, v95, v166, v177
	v_mul_f32_e32 v132, v40, v139
	v_mul_f32_e32 v40, v40, v138
	v_fma_f32 v40, -v44, v139, v40
	v_fma_f32 v44, v44, v138, v132
	v_mul_f32_e32 v133, v41, v143
	v_mul_f32_e32 v41, v41, v142
	v_fma_f32 v41, -v45, v143, v41
	v_fma_f32 v45, v45, v142, v133
	v_mul_f32_e32 v132, v42, v147
	v_mul_f32_e32 v42, v42, v146
	v_fma_f32 v42, -v46, v147, v42
	v_fma_f32 v46, v46, v146, v132
	v_mul_f32_e32 v133, v43, v151
	v_mul_f32_e32 v43, v43, v150
	v_fma_f32 v43, -v47, v151, v43
	v_fma_f32 v47, v47, v150, v133
	v_add_f32_dpp v40, v40, v40 row_shl:1 row_mask:0xf bank_mask:0xf bound_ctrl:1
	v_add_f32_dpp v41, v41, v41 row_shl:1 row_mask:0xf bank_mask:0xf bound_ctrl:1
	v_add_f32_dpp v42, v42, v42 row_shl:1 row_mask:0xf bank_mask:0xf bound_ctrl:1
	v_add_f32_dpp v43, v43, v43 row_shl:1 row_mask:0xf bank_mask:0xf bound_ctrl:1
	v_add_f32_dpp v44, v44, v44 row_shl:1 row_mask:0xf bank_mask:0xf bound_ctrl:1
	v_add_f32_dpp v45, v45, v45 row_shl:1 row_mask:0xf bank_mask:0xf bound_ctrl:1
	v_add_f32_dpp v46, v46, v46 row_shl:1 row_mask:0xf bank_mask:0xf bound_ctrl:1
	v_add_f32_dpp v47, v47, v47 row_shl:1 row_mask:0xf bank_mask:0xf bound_ctrl:1
	v_add_f32_dpp v40, v40, v40 row_shl:2 row_mask:0xf bank_mask:0xf bound_ctrl:1
	v_add_f32_dpp v41, v41, v41 row_shl:2 row_mask:0xf bank_mask:0xf bound_ctrl:1
	v_add_f32_dpp v42, v42, v42 row_shl:2 row_mask:0xf bank_mask:0xf bound_ctrl:1
	v_add_f32_dpp v43, v43, v43 row_shl:2 row_mask:0xf bank_mask:0xf bound_ctrl:1
	v_add_f32_dpp v44, v44, v44 row_shl:2 row_mask:0xf bank_mask:0xf bound_ctrl:1
	v_add_f32_dpp v45, v45, v45 row_shl:2 row_mask:0xf bank_mask:0xf bound_ctrl:1
	v_add_f32_dpp v46, v46, v46 row_shl:2 row_mask:0xf bank_mask:0xf bound_ctrl:1
	v_add_f32_dpp v47, v47, v47 row_shl:2 row_mask:0xf bank_mask:0xf bound_ctrl:1
	v_add_f32_dpp v40, v40, v40 row_shl:4 row_mask:0xf bank_mask:0xf bound_ctrl:1
	v_add_f32_dpp v41, v41, v41 row_shl:4 row_mask:0xf bank_mask:0xf bound_ctrl:1
	v_add_f32_dpp v42, v42, v42 row_shl:4 row_mask:0xf bank_mask:0xf bound_ctrl:1
	v_add_f32_dpp v43, v43, v43 row_shl:4 row_mask:0xf bank_mask:0xf bound_ctrl:1
	v_add_f32_dpp v44, v44, v44 row_shl:4 row_mask:0xf bank_mask:0xf bound_ctrl:1
	v_add_f32_dpp v45, v45, v45 row_shl:4 row_mask:0xf bank_mask:0xf bound_ctrl:1
	v_add_f32_dpp v46, v46, v46 row_shl:4 row_mask:0xf bank_mask:0xf bound_ctrl:1
	v_add_f32_dpp v47, v47, v47 row_shl:4 row_mask:0xf bank_mask:0xf bound_ctrl:1
	v_add_f32_dpp v40, v40, v40 row_shl:8 row_mask:0xf bank_mask:0xf bound_ctrl:1
	v_add_f32_dpp v41, v41, v41 row_shl:8 row_mask:0xf bank_mask:0xf bound_ctrl:1
	v_add_f32_dpp v42, v42, v42 row_shl:8 row_mask:0xf bank_mask:0xf bound_ctrl:1
	v_add_f32_dpp v43, v43, v43 row_shl:8 row_mask:0xf bank_mask:0xf bound_ctrl:1
	v_add_f32_dpp v44, v44, v44 row_shl:8 row_mask:0xf bank_mask:0xf bound_ctrl:1
	v_add_f32_dpp v45, v45, v45 row_shl:8 row_mask:0xf bank_mask:0xf bound_ctrl:1
	v_add_f32_dpp v46, v46, v46 row_shl:8 row_mask:0xf bank_mask:0xf bound_ctrl:1
	v_add_f32_dpp v47, v47, v47 row_shl:8 row_mask:0xf bank_mask:0xf bound_ctrl:1
	v_mov_b32_dpp v88, v40 row_newbcast:0 row_mask:0xf bank_mask:0xf
	v_mov_b32_dpp v89, v41 row_newbcast:0 row_mask:0xf bank_mask:0xf
	v_mov_b32_dpp v90, v42 row_newbcast:0 row_mask:0xf bank_mask:0xf
	v_mov_b32_dpp v91, v43 row_newbcast:0 row_mask:0xf bank_mask:0xf
	v_mov_b32_dpp v92, v44 row_newbcast:0 row_mask:0xf bank_mask:0xf
	v_mov_b32_dpp v93, v45 row_newbcast:0 row_mask:0xf bank_mask:0xf
	v_mov_b32_dpp v94, v46 row_newbcast:0 row_mask:0xf bank_mask:0xf
	v_mov_b32_dpp v95, v47 row_newbcast:0 row_mask:0xf bank_mask:0xf
	v_add_f32_e32 v40, v40, v170
	v_add_f32_e32 v44, v44, v171
	v_add_f32_e32 v41, v41, v172
	v_add_f32_e32 v45, v45, v173
	v_add_f32_e32 v42, v42, v174
	v_add_f32_e32 v46, v46, v175
	v_add_f32_e32 v43, v43, v176
	v_add_f32_e32 v47, v47, v177
	v_mul_f32_e32 v132, v40, v141
	v_mul_f32_e32 v40, v40, v140
	v_fma_f32 v40, -v44, v141, v40
	v_fma_f32 v44, v44, v140, v132
	v_mul_f32_e32 v133, v41, v145
	v_mul_f32_e32 v41, v41, v144
	v_fma_f32 v41, -v45, v145, v41
	v_fma_f32 v45, v45, v144, v133
	v_mul_f32_e32 v132, v42, v149
	v_mul_f32_e32 v42, v42, v148
	v_fma_f32 v42, -v46, v149, v42
	v_fma_f32 v46, v46, v148, v132
	v_mul_f32_e32 v133, v43, v153
	v_mul_f32_e32 v43, v43, v152
	v_fma_f32 v43, -v47, v153, v43
	v_fma_f32 v47, v47, v152, v133
	v_add_f32_e32 v88, v88, v170
	v_add_f32_e32 v92, v92, v171
	v_mul_f32_e32 v132, v92, v155
	v_mul_f32_e32 v171, v88, v155
	v_fma_f32 v170, v88, v154, -v132
	v_fma_f32 v171, v92, v154, v171
	v_add_f32_e32 v89, v89, v172
	v_add_f32_e32 v93, v93, v173
	v_mul_f32_e32 v133, v93, v159
	v_mul_f32_e32 v173, v89, v159
	v_fma_f32 v172, v89, v158, -v133
	v_fma_f32 v173, v93, v158, v173
	v_add_f32_e32 v90, v90, v174
	v_add_f32_e32 v94, v94, v175
	v_mul_f32_e32 v132, v94, v163
	v_mul_f32_e32 v175, v90, v163
	v_fma_f32 v174, v90, v162, -v132
	v_fma_f32 v175, v94, v162, v175
	v_add_f32_e32 v91, v91, v176
	v_add_f32_e32 v95, v95, v177
	v_mul_f32_e32 v133, v95, v167
	v_mul_f32_e32 v177, v91, v167
	v_fma_f32 v176, v91, v166, -v133
	v_fma_f32 v177, v95, v166, v177
	v_mul_f32_e32 v132, v32, v139
	v_mul_f32_e32 v32, v32, v138
	v_fma_f32 v32, -v36, v139, v32
	v_fma_f32 v36, v36, v138, v132
	v_mul_f32_e32 v133, v33, v143
	v_mul_f32_e32 v33, v33, v142
	v_fma_f32 v33, -v37, v143, v33
	v_fma_f32 v37, v37, v142, v133
	v_mul_f32_e32 v132, v34, v147
	v_mul_f32_e32 v34, v34, v146
	v_fma_f32 v34, -v38, v147, v34
	v_fma_f32 v38, v38, v146, v132
	v_mul_f32_e32 v133, v35, v151
	v_mul_f32_e32 v35, v35, v150
	v_fma_f32 v35, -v39, v151, v35
	v_fma_f32 v39, v39, v150, v133
	v_add_f32_dpp v32, v32, v32 row_shl:1 row_mask:0xf bank_mask:0xf bound_ctrl:1
	v_add_f32_dpp v33, v33, v33 row_shl:1 row_mask:0xf bank_mask:0xf bound_ctrl:1
	v_add_f32_dpp v34, v34, v34 row_shl:1 row_mask:0xf bank_mask:0xf bound_ctrl:1
	v_add_f32_dpp v35, v35, v35 row_shl:1 row_mask:0xf bank_mask:0xf bound_ctrl:1
	v_add_f32_dpp v36, v36, v36 row_shl:1 row_mask:0xf bank_mask:0xf bound_ctrl:1
	v_add_f32_dpp v37, v37, v37 row_shl:1 row_mask:0xf bank_mask:0xf bound_ctrl:1
	v_add_f32_dpp v38, v38, v38 row_shl:1 row_mask:0xf bank_mask:0xf bound_ctrl:1
	v_add_f32_dpp v39, v39, v39 row_shl:1 row_mask:0xf bank_mask:0xf bound_ctrl:1
	v_add_f32_dpp v32, v32, v32 row_shl:2 row_mask:0xf bank_mask:0xf bound_ctrl:1
	v_add_f32_dpp v33, v33, v33 row_shl:2 row_mask:0xf bank_mask:0xf bound_ctrl:1
	v_add_f32_dpp v34, v34, v34 row_shl:2 row_mask:0xf bank_mask:0xf bound_ctrl:1
	v_add_f32_dpp v35, v35, v35 row_shl:2 row_mask:0xf bank_mask:0xf bound_ctrl:1
	v_add_f32_dpp v36, v36, v36 row_shl:2 row_mask:0xf bank_mask:0xf bound_ctrl:1
	v_add_f32_dpp v37, v37, v37 row_shl:2 row_mask:0xf bank_mask:0xf bound_ctrl:1
	v_add_f32_dpp v38, v38, v38 row_shl:2 row_mask:0xf bank_mask:0xf bound_ctrl:1
	v_add_f32_dpp v39, v39, v39 row_shl:2 row_mask:0xf bank_mask:0xf bound_ctrl:1
	v_add_f32_dpp v32, v32, v32 row_shl:4 row_mask:0xf bank_mask:0xf bound_ctrl:1
	v_add_f32_dpp v33, v33, v33 row_shl:4 row_mask:0xf bank_mask:0xf bound_ctrl:1
	v_add_f32_dpp v34, v34, v34 row_shl:4 row_mask:0xf bank_mask:0xf bound_ctrl:1
	v_add_f32_dpp v35, v35, v35 row_shl:4 row_mask:0xf bank_mask:0xf bound_ctrl:1
	v_add_f32_dpp v36, v36, v36 row_shl:4 row_mask:0xf bank_mask:0xf bound_ctrl:1
	v_add_f32_dpp v37, v37, v37 row_shl:4 row_mask:0xf bank_mask:0xf bound_ctrl:1
	v_add_f32_dpp v38, v38, v38 row_shl:4 row_mask:0xf bank_mask:0xf bound_ctrl:1
	v_add_f32_dpp v39, v39, v39 row_shl:4 row_mask:0xf bank_mask:0xf bound_ctrl:1
	v_add_f32_dpp v32, v32, v32 row_shl:8 row_mask:0xf bank_mask:0xf bound_ctrl:1
	v_add_f32_dpp v33, v33, v33 row_shl:8 row_mask:0xf bank_mask:0xf bound_ctrl:1
	v_add_f32_dpp v34, v34, v34 row_shl:8 row_mask:0xf bank_mask:0xf bound_ctrl:1
	v_add_f32_dpp v35, v35, v35 row_shl:8 row_mask:0xf bank_mask:0xf bound_ctrl:1
	v_add_f32_dpp v36, v36, v36 row_shl:8 row_mask:0xf bank_mask:0xf bound_ctrl:1
	v_add_f32_dpp v37, v37, v37 row_shl:8 row_mask:0xf bank_mask:0xf bound_ctrl:1
	v_add_f32_dpp v38, v38, v38 row_shl:8 row_mask:0xf bank_mask:0xf bound_ctrl:1
	v_add_f32_dpp v39, v39, v39 row_shl:8 row_mask:0xf bank_mask:0xf bound_ctrl:1
	v_mov_b32_dpp v88, v32 row_newbcast:0 row_mask:0xf bank_mask:0xf
	v_mov_b32_dpp v89, v33 row_newbcast:0 row_mask:0xf bank_mask:0xf
	v_mov_b32_dpp v90, v34 row_newbcast:0 row_mask:0xf bank_mask:0xf
	v_mov_b32_dpp v91, v35 row_newbcast:0 row_mask:0xf bank_mask:0xf
	v_mov_b32_dpp v92, v36 row_newbcast:0 row_mask:0xf bank_mask:0xf
	v_mov_b32_dpp v93, v37 row_newbcast:0 row_mask:0xf bank_mask:0xf
	v_mov_b32_dpp v94, v38 row_newbcast:0 row_mask:0xf bank_mask:0xf
	v_mov_b32_dpp v95, v39 row_newbcast:0 row_mask:0xf bank_mask:0xf
	v_add_f32_e32 v32, v32, v170
	v_add_f32_e32 v36, v36, v171
	v_add_f32_e32 v33, v33, v172
	v_add_f32_e32 v37, v37, v173
	v_add_f32_e32 v34, v34, v174
	v_add_f32_e32 v38, v38, v175
	v_add_f32_e32 v35, v35, v176
	v_add_f32_e32 v39, v39, v177
	v_mul_f32_e32 v132, v32, v141
	v_mul_f32_e32 v32, v32, v140
	v_fma_f32 v32, -v36, v141, v32
	v_fma_f32 v36, v36, v140, v132
	v_mul_f32_e32 v133, v33, v145
	v_mul_f32_e32 v33, v33, v144
	v_fma_f32 v33, -v37, v145, v33
	v_fma_f32 v37, v37, v144, v133
	v_mul_f32_e32 v132, v34, v149
	v_mul_f32_e32 v34, v34, v148
	v_fma_f32 v34, -v38, v149, v34
	v_fma_f32 v38, v38, v148, v132
	v_mul_f32_e32 v133, v35, v153
	v_mul_f32_e32 v35, v35, v152
	v_fma_f32 v35, -v39, v153, v35
	v_fma_f32 v39, v39, v152, v133
	v_add_f32_e32 v88, v88, v170
	v_add_f32_e32 v92, v92, v171
	v_mul_f32_e32 v132, v92, v155
	v_mul_f32_e32 v171, v88, v155
	v_fma_f32 v170, v88, v154, -v132
	v_fma_f32 v171, v92, v154, v171
	v_add_f32_e32 v89, v89, v172
	v_add_f32_e32 v93, v93, v173
	v_mul_f32_e32 v133, v93, v159
	v_mul_f32_e32 v173, v89, v159
	v_fma_f32 v172, v89, v158, -v133
	v_fma_f32 v173, v93, v158, v173
	v_add_f32_e32 v90, v90, v174
	v_add_f32_e32 v94, v94, v175
	v_mul_f32_e32 v132, v94, v163
	v_mul_f32_e32 v175, v90, v163
	v_fma_f32 v174, v90, v162, -v132
	v_fma_f32 v175, v94, v162, v175
	v_add_f32_e32 v91, v91, v176
	v_add_f32_e32 v95, v95, v177
	v_mul_f32_e32 v133, v95, v167
	v_mul_f32_e32 v177, v91, v167
	v_fma_f32 v176, v91, v166, -v133
	v_fma_f32 v177, v95, v166, v177
	s_waitcnt vmcnt(14)
	v_cvt_pk_bf16_f32 v80, v80, v81
	v_cvt_pk_bf16_f32 v81, v82, v83
	v_cvt_pk_bf16_f32 v82, -v84, -v85
	v_cvt_pk_bf16_f32 v83, -v86, -v87
	v_cvt_pk_bf16_f32 v96, v32, v33
	v_cvt_pk_bf16_f32 v97, v34, v35
	v_cvt_pk_bf16_f32 v98, v36, v37
	v_cvt_pk_bf16_f32 v99, v38, v39
	s_nop 1
	v_mfma_f32_16x16x32_bf16 v[16:19], v[80:83], v[96:99], v[16:19]
	v_cvt_pk_bf16_f32 v96, v40, v41
	v_cvt_pk_bf16_f32 v97, v42, v43
	v_cvt_pk_bf16_f32 v98, v44, v45
	v_cvt_pk_bf16_f32 v99, v46, v47
	s_nop 1
	v_mfma_f32_16x16x32_bf16 v[20:23], v[80:83], v[96:99], v[20:23]
	v_cvt_pk_bf16_f32 v96, v48, v49
	v_cvt_pk_bf16_f32 v97, v50, v51
	v_cvt_pk_bf16_f32 v98, v52, v53
	v_cvt_pk_bf16_f32 v99, v54, v55
	s_nop 1
	v_mfma_f32_16x16x32_bf16 v[24:27], v[80:83], v[96:99], v[24:27]
	v_cvt_pk_bf16_f32 v96, v56, v57
	v_cvt_pk_bf16_f32 v97, v58, v59
	v_cvt_pk_bf16_f32 v98, v60, v61
	v_cvt_pk_bf16_f32 v99, v62, v63
	s_nop 1
	v_mfma_f32_16x16x32_bf16 v[28:31], v[80:83], v[96:99], v[28:31]
	s_waitcnt vmcnt(10)
	v_cvt_pk_bf16_f32 v64, v64, v65
	v_cvt_pk_bf16_f32 v65, v66, v67
	v_cvt_pk_bf16_f32 v66, v68, v69
	v_cvt_pk_bf16_f32 v67, v70, v71
	v_cvt_pk_bf16_f32 v72, v72, v73
	v_cvt_pk_bf16_f32 v73, v74, v75
	v_cvt_pk_bf16_f32 v74, v76, v77
	v_cvt_pk_bf16_f32 v75, v78, v79
	global_load_dwordx4 v[80:83], v136, s[38:39]
	global_load_dwordx4 v[84:87], v136, s[40:41]
	s_nop 0
	v_mfma_f32_16x16x32_bf16 v[32:35], v[64:67], v[0:3], 0
	v_mfma_f32_16x16x32_bf16 v[36:39], v[72:75], v[0:3], 0
	v_mfma_f32_16x16x32_bf16 v[40:43], v[64:67], v[4:7], 0
	v_mfma_f32_16x16x32_bf16 v[44:47], v[72:75], v[4:7], 0
	v_mfma_f32_16x16x32_bf16 v[48:51], v[64:67], v[8:11], 0
	v_mfma_f32_16x16x32_bf16 v[52:55], v[72:75], v[8:11], 0
	v_mfma_f32_16x16x32_bf16 v[56:59], v[64:67], v[12:15], 0
	v_mfma_f32_16x16x32_bf16 v[60:63], v[72:75], v[12:15], 0
	s_waitcnt vmcnt(2)
	v_mul_f32_e32 v132, v179, v119
	v_mul_f32_e32 v133, v178, v119
	v_fma_f32 v178, v178, v118, -v132
	v_fma_f32 v179, v179, v118, v133
	v_mul_f32_e32 v132, v181, v123
	v_mul_f32_e32 v133, v180, v123
	v_fma_f32 v180, v180, v122, -v132
	v_fma_f32 v181, v181, v122, v133
	v_mul_f32_e32 v132, v183, v127
	v_mul_f32_e32 v133, v182, v127
	v_fma_f32 v182, v182, v126, -v132
	v_fma_f32 v183, v183, v126, v133
	v_mul_f32_e32 v132, v185, v131
	v_mul_f32_e32 v133, v184, v131
	v_fma_f32 v184, v184, v130, -v132
	v_fma_f32 v185, v185, v130, v133
	v_mul_f32_e32 v132, v56, v101
	v_mul_f32_e32 v56, v56, v100
	v_fma_f32 v56, -v60, v101, v56
	v_fma_f32 v60, v60, v100, v132
	v_mul_f32_e32 v133, v57, v105
	v_mul_f32_e32 v57, v57, v104
	v_fma_f32 v57, -v61, v105, v57
	v_fma_f32 v61, v61, v104, v133
	v_mul_f32_e32 v132, v58, v109
	v_mul_f32_e32 v58, v58, v108
	v_fma_f32 v58, -v62, v109, v58
	v_fma_f32 v62, v62, v108, v132
	v_mul_f32_e32 v133, v59, v113
	v_mul_f32_e32 v59, v59, v112
	v_fma_f32 v59, -v63, v113, v59
	v_fma_f32 v63, v63, v112, v133
	v_add_f32_dpp v56, v56, v56 row_shl:1 row_mask:0xf bank_mask:0xf bound_ctrl:1
	v_add_f32_dpp v57, v57, v57 row_shl:1 row_mask:0xf bank_mask:0xf bound_ctrl:1
	v_add_f32_dpp v58, v58, v58 row_shl:1 row_mask:0xf bank_mask:0xf bound_ctrl:1
	v_add_f32_dpp v59, v59, v59 row_shl:1 row_mask:0xf bank_mask:0xf bound_ctrl:1
	v_add_f32_dpp v60, v60, v60 row_shl:1 row_mask:0xf bank_mask:0xf bound_ctrl:1
	v_add_f32_dpp v61, v61, v61 row_shl:1 row_mask:0xf bank_mask:0xf bound_ctrl:1
	v_add_f32_dpp v62, v62, v62 row_shl:1 row_mask:0xf bank_mask:0xf bound_ctrl:1
	v_add_f32_dpp v63, v63, v63 row_shl:1 row_mask:0xf bank_mask:0xf bound_ctrl:1
	v_add_f32_dpp v56, v56, v56 row_shl:2 row_mask:0xf bank_mask:0xf bound_ctrl:1
	v_add_f32_dpp v57, v57, v57 row_shl:2 row_mask:0xf bank_mask:0xf bound_ctrl:1
	v_add_f32_dpp v58, v58, v58 row_shl:2 row_mask:0xf bank_mask:0xf bound_ctrl:1
	v_add_f32_dpp v59, v59, v59 row_shl:2 row_mask:0xf bank_mask:0xf bound_ctrl:1
	v_add_f32_dpp v60, v60, v60 row_shl:2 row_mask:0xf bank_mask:0xf bound_ctrl:1
	v_add_f32_dpp v61, v61, v61 row_shl:2 row_mask:0xf bank_mask:0xf bound_ctrl:1
	v_add_f32_dpp v62, v62, v62 row_shl:2 row_mask:0xf bank_mask:0xf bound_ctrl:1
	v_add_f32_dpp v63, v63, v63 row_shl:2 row_mask:0xf bank_mask:0xf bound_ctrl:1
	v_add_f32_dpp v56, v56, v56 row_shl:4 row_mask:0xf bank_mask:0xf bound_ctrl:1
	v_add_f32_dpp v57, v57, v57 row_shl:4 row_mask:0xf bank_mask:0xf bound_ctrl:1
	v_add_f32_dpp v58, v58, v58 row_shl:4 row_mask:0xf bank_mask:0xf bound_ctrl:1
	v_add_f32_dpp v59, v59, v59 row_shl:4 row_mask:0xf bank_mask:0xf bound_ctrl:1
	v_add_f32_dpp v60, v60, v60 row_shl:4 row_mask:0xf bank_mask:0xf bound_ctrl:1
	v_add_f32_dpp v61, v61, v61 row_shl:4 row_mask:0xf bank_mask:0xf bound_ctrl:1
	v_add_f32_dpp v62, v62, v62 row_shl:4 row_mask:0xf bank_mask:0xf bound_ctrl:1
	v_add_f32_dpp v63, v63, v63 row_shl:4 row_mask:0xf bank_mask:0xf bound_ctrl:1
	v_add_f32_dpp v56, v56, v56 row_shl:8 row_mask:0xf bank_mask:0xf bound_ctrl:1
	v_add_f32_dpp v57, v57, v57 row_shl:8 row_mask:0xf bank_mask:0xf bound_ctrl:1
	v_add_f32_dpp v58, v58, v58 row_shl:8 row_mask:0xf bank_mask:0xf bound_ctrl:1
	v_add_f32_dpp v59, v59, v59 row_shl:8 row_mask:0xf bank_mask:0xf bound_ctrl:1
	v_add_f32_dpp v60, v60, v60 row_shl:8 row_mask:0xf bank_mask:0xf bound_ctrl:1
	v_add_f32_dpp v61, v61, v61 row_shl:8 row_mask:0xf bank_mask:0xf bound_ctrl:1
	v_add_f32_dpp v62, v62, v62 row_shl:8 row_mask:0xf bank_mask:0xf bound_ctrl:1
	v_add_f32_dpp v63, v63, v63 row_shl:8 row_mask:0xf bank_mask:0xf bound_ctrl:1
	v_mov_b32_dpp v88, v56 row_newbcast:0 row_mask:0xf bank_mask:0xf
	v_mov_b32_dpp v89, v57 row_newbcast:0 row_mask:0xf bank_mask:0xf
	v_mov_b32_dpp v90, v58 row_newbcast:0 row_mask:0xf bank_mask:0xf
	v_mov_b32_dpp v91, v59 row_newbcast:0 row_mask:0xf bank_mask:0xf
	v_mov_b32_dpp v92, v60 row_newbcast:0 row_mask:0xf bank_mask:0xf
	v_mov_b32_dpp v93, v61 row_newbcast:0 row_mask:0xf bank_mask:0xf
	v_mov_b32_dpp v94, v62 row_newbcast:0 row_mask:0xf bank_mask:0xf
	v_mov_b32_dpp v95, v63 row_newbcast:0 row_mask:0xf bank_mask:0xf
	v_add_f32_e32 v56, v56, v178
	v_add_f32_e32 v60, v60, v179
	v_add_f32_e32 v57, v57, v180
	v_add_f32_e32 v61, v61, v181
	v_add_f32_e32 v58, v58, v182
	v_add_f32_e32 v62, v62, v183
	v_add_f32_e32 v59, v59, v184
	v_add_f32_e32 v63, v63, v185
	v_mul_f32_e32 v132, v56, v103
	v_mul_f32_e32 v56, v56, v102
	v_fma_f32 v56, -v60, v103, v56
	v_fma_f32 v60, v60, v102, v132
	v_mul_f32_e32 v133, v57, v107
	v_mul_f32_e32 v57, v57, v106
	v_fma_f32 v57, -v61, v107, v57
	v_fma_f32 v61, v61, v106, v133
	v_mul_f32_e32 v132, v58, v111
	v_mul_f32_e32 v58, v58, v110
	v_fma_f32 v58, -v62, v111, v58
	v_fma_f32 v62, v62, v110, v132
	v_mul_f32_e32 v133, v59, v115
	v_mul_f32_e32 v59, v59, v114
	v_fma_f32 v59, -v63, v115, v59
	v_fma_f32 v63, v63, v114, v133
	v_add_f32_e32 v88, v88, v178
	v_add_f32_e32 v92, v92, v179
	v_mul_f32_e32 v132, v92, v117
	v_mul_f32_e32 v179, v88, v117
	v_fma_f32 v178, v88, v116, -v132
	v_fma_f32 v179, v92, v116, v179
	v_add_f32_e32 v89, v89, v180
	v_add_f32_e32 v93, v93, v181
	v_mul_f32_e32 v133, v93, v121
	v_mul_f32_e32 v181, v89, v121
	v_fma_f32 v180, v89, v120, -v133
	v_fma_f32 v181, v93, v120, v181
	v_add_f32_e32 v90, v90, v182
	v_add_f32_e32 v94, v94, v183
	v_mul_f32_e32 v132, v94, v125
	v_mul_f32_e32 v183, v90, v125
	v_fma_f32 v182, v90, v124, -v132
	v_fma_f32 v183, v94, v124, v183
	v_add_f32_e32 v91, v91, v184
	v_add_f32_e32 v95, v95, v185
	v_mul_f32_e32 v133, v95, v129
	v_mul_f32_e32 v185, v91, v129
	v_fma_f32 v184, v91, v128, -v133
	v_fma_f32 v185, v95, v128, v185
	v_mul_f32_e32 v132, v48, v101
	v_mul_f32_e32 v48, v48, v100
	v_fma_f32 v48, -v52, v101, v48
	v_fma_f32 v52, v52, v100, v132
	v_mul_f32_e32 v133, v49, v105
	v_mul_f32_e32 v49, v49, v104
	v_fma_f32 v49, -v53, v105, v49
	v_fma_f32 v53, v53, v104, v133
	v_mul_f32_e32 v132, v50, v109
	v_mul_f32_e32 v50, v50, v108
	v_fma_f32 v50, -v54, v109, v50
	v_fma_f32 v54, v54, v108, v132
	v_mul_f32_e32 v133, v51, v113
	v_mul_f32_e32 v51, v51, v112
	v_fma_f32 v51, -v55, v113, v51
	v_fma_f32 v55, v55, v112, v133
	v_add_f32_dpp v48, v48, v48 row_shl:1 row_mask:0xf bank_mask:0xf bound_ctrl:1
	v_add_f32_dpp v49, v49, v49 row_shl:1 row_mask:0xf bank_mask:0xf bound_ctrl:1
	v_add_f32_dpp v50, v50, v50 row_shl:1 row_mask:0xf bank_mask:0xf bound_ctrl:1
	v_add_f32_dpp v51, v51, v51 row_shl:1 row_mask:0xf bank_mask:0xf bound_ctrl:1
	v_add_f32_dpp v52, v52, v52 row_shl:1 row_mask:0xf bank_mask:0xf bound_ctrl:1
	v_add_f32_dpp v53, v53, v53 row_shl:1 row_mask:0xf bank_mask:0xf bound_ctrl:1
	v_add_f32_dpp v54, v54, v54 row_shl:1 row_mask:0xf bank_mask:0xf bound_ctrl:1
	v_add_f32_dpp v55, v55, v55 row_shl:1 row_mask:0xf bank_mask:0xf bound_ctrl:1
	v_add_f32_dpp v48, v48, v48 row_shl:2 row_mask:0xf bank_mask:0xf bound_ctrl:1
	v_add_f32_dpp v49, v49, v49 row_shl:2 row_mask:0xf bank_mask:0xf bound_ctrl:1
	v_add_f32_dpp v50, v50, v50 row_shl:2 row_mask:0xf bank_mask:0xf bound_ctrl:1
	v_add_f32_dpp v51, v51, v51 row_shl:2 row_mask:0xf bank_mask:0xf bound_ctrl:1
	v_add_f32_dpp v52, v52, v52 row_shl:2 row_mask:0xf bank_mask:0xf bound_ctrl:1
	v_add_f32_dpp v53, v53, v53 row_shl:2 row_mask:0xf bank_mask:0xf bound_ctrl:1
	v_add_f32_dpp v54, v54, v54 row_shl:2 row_mask:0xf bank_mask:0xf bound_ctrl:1
	v_add_f32_dpp v55, v55, v55 row_shl:2 row_mask:0xf bank_mask:0xf bound_ctrl:1
	v_add_f32_dpp v48, v48, v48 row_shl:4 row_mask:0xf bank_mask:0xf bound_ctrl:1
	v_add_f32_dpp v49, v49, v49 row_shl:4 row_mask:0xf bank_mask:0xf bound_ctrl:1
	v_add_f32_dpp v50, v50, v50 row_shl:4 row_mask:0xf bank_mask:0xf bound_ctrl:1
	v_add_f32_dpp v51, v51, v51 row_shl:4 row_mask:0xf bank_mask:0xf bound_ctrl:1
	v_add_f32_dpp v52, v52, v52 row_shl:4 row_mask:0xf bank_mask:0xf bound_ctrl:1
	v_add_f32_dpp v53, v53, v53 row_shl:4 row_mask:0xf bank_mask:0xf bound_ctrl:1
	v_add_f32_dpp v54, v54, v54 row_shl:4 row_mask:0xf bank_mask:0xf bound_ctrl:1
	v_add_f32_dpp v55, v55, v55 row_shl:4 row_mask:0xf bank_mask:0xf bound_ctrl:1
	v_add_f32_dpp v48, v48, v48 row_shl:8 row_mask:0xf bank_mask:0xf bound_ctrl:1
	v_add_f32_dpp v49, v49, v49 row_shl:8 row_mask:0xf bank_mask:0xf bound_ctrl:1
	v_add_f32_dpp v50, v50, v50 row_shl:8 row_mask:0xf bank_mask:0xf bound_ctrl:1
	v_add_f32_dpp v51, v51, v51 row_shl:8 row_mask:0xf bank_mask:0xf bound_ctrl:1
	v_add_f32_dpp v52, v52, v52 row_shl:8 row_mask:0xf bank_mask:0xf bound_ctrl:1
	v_add_f32_dpp v53, v53, v53 row_shl:8 row_mask:0xf bank_mask:0xf bound_ctrl:1
	v_add_f32_dpp v54, v54, v54 row_shl:8 row_mask:0xf bank_mask:0xf bound_ctrl:1
	v_add_f32_dpp v55, v55, v55 row_shl:8 row_mask:0xf bank_mask:0xf bound_ctrl:1
	v_mov_b32_dpp v88, v48 row_newbcast:0 row_mask:0xf bank_mask:0xf
	v_mov_b32_dpp v89, v49 row_newbcast:0 row_mask:0xf bank_mask:0xf
	v_mov_b32_dpp v90, v50 row_newbcast:0 row_mask:0xf bank_mask:0xf
	v_mov_b32_dpp v91, v51 row_newbcast:0 row_mask:0xf bank_mask:0xf
	v_mov_b32_dpp v92, v52 row_newbcast:0 row_mask:0xf bank_mask:0xf
	v_mov_b32_dpp v93, v53 row_newbcast:0 row_mask:0xf bank_mask:0xf
	v_mov_b32_dpp v94, v54 row_newbcast:0 row_mask:0xf bank_mask:0xf
	v_mov_b32_dpp v95, v55 row_newbcast:0 row_mask:0xf bank_mask:0xf
	v_add_f32_e32 v48, v48, v178
	v_add_f32_e32 v52, v52, v179
	v_add_f32_e32 v49, v49, v180
	v_add_f32_e32 v53, v53, v181
	v_add_f32_e32 v50, v50, v182
	v_add_f32_e32 v54, v54, v183
	v_add_f32_e32 v51, v51, v184
	v_add_f32_e32 v55, v55, v185
	v_mul_f32_e32 v132, v48, v103
	v_mul_f32_e32 v48, v48, v102
	v_fma_f32 v48, -v52, v103, v48
	v_fma_f32 v52, v52, v102, v132
	v_mul_f32_e32 v133, v49, v107
	v_mul_f32_e32 v49, v49, v106
	v_fma_f32 v49, -v53, v107, v49
	v_fma_f32 v53, v53, v106, v133
	v_mul_f32_e32 v132, v50, v111
	v_mul_f32_e32 v50, v50, v110
	v_fma_f32 v50, -v54, v111, v50
	v_fma_f32 v54, v54, v110, v132
	v_mul_f32_e32 v133, v51, v115
	v_mul_f32_e32 v51, v51, v114
	v_fma_f32 v51, -v55, v115, v51
	v_fma_f32 v55, v55, v114, v133
	v_add_f32_e32 v88, v88, v178
	v_add_f32_e32 v92, v92, v179
	v_mul_f32_e32 v132, v92, v117
	v_mul_f32_e32 v179, v88, v117
	v_fma_f32 v178, v88, v116, -v132
	v_fma_f32 v179, v92, v116, v179
	v_add_f32_e32 v89, v89, v180
	v_add_f32_e32 v93, v93, v181
	v_mul_f32_e32 v133, v93, v121
	v_mul_f32_e32 v181, v89, v121
	v_fma_f32 v180, v89, v120, -v133
	v_fma_f32 v181, v93, v120, v181
	v_add_f32_e32 v90, v90, v182
	v_add_f32_e32 v94, v94, v183
	v_mul_f32_e32 v132, v94, v125
	v_mul_f32_e32 v183, v90, v125
	v_fma_f32 v182, v90, v124, -v132
	v_fma_f32 v183, v94, v124, v183
	v_add_f32_e32 v91, v91, v184
	v_add_f32_e32 v95, v95, v185
	v_mul_f32_e32 v133, v95, v129
	v_mul_f32_e32 v185, v91, v129
	v_fma_f32 v184, v91, v128, -v133
	v_fma_f32 v185, v95, v128, v185
	v_mul_f32_e32 v132, v40, v101
	v_mul_f32_e32 v40, v40, v100
	v_fma_f32 v40, -v44, v101, v40
	v_fma_f32 v44, v44, v100, v132
	v_mul_f32_e32 v133, v41, v105
	v_mul_f32_e32 v41, v41, v104
	v_fma_f32 v41, -v45, v105, v41
	v_fma_f32 v45, v45, v104, v133
	v_mul_f32_e32 v132, v42, v109
	v_mul_f32_e32 v42, v42, v108
	v_fma_f32 v42, -v46, v109, v42
	v_fma_f32 v46, v46, v108, v132
	v_mul_f32_e32 v133, v43, v113
	v_mul_f32_e32 v43, v43, v112
	v_fma_f32 v43, -v47, v113, v43
	v_fma_f32 v47, v47, v112, v133
	v_add_f32_dpp v40, v40, v40 row_shl:1 row_mask:0xf bank_mask:0xf bound_ctrl:1
	v_add_f32_dpp v41, v41, v41 row_shl:1 row_mask:0xf bank_mask:0xf bound_ctrl:1
	v_add_f32_dpp v42, v42, v42 row_shl:1 row_mask:0xf bank_mask:0xf bound_ctrl:1
	v_add_f32_dpp v43, v43, v43 row_shl:1 row_mask:0xf bank_mask:0xf bound_ctrl:1
	v_add_f32_dpp v44, v44, v44 row_shl:1 row_mask:0xf bank_mask:0xf bound_ctrl:1
	v_add_f32_dpp v45, v45, v45 row_shl:1 row_mask:0xf bank_mask:0xf bound_ctrl:1
	v_add_f32_dpp v46, v46, v46 row_shl:1 row_mask:0xf bank_mask:0xf bound_ctrl:1
	v_add_f32_dpp v47, v47, v47 row_shl:1 row_mask:0xf bank_mask:0xf bound_ctrl:1
	v_add_f32_dpp v40, v40, v40 row_shl:2 row_mask:0xf bank_mask:0xf bound_ctrl:1
	v_add_f32_dpp v41, v41, v41 row_shl:2 row_mask:0xf bank_mask:0xf bound_ctrl:1
	v_add_f32_dpp v42, v42, v42 row_shl:2 row_mask:0xf bank_mask:0xf bound_ctrl:1
	v_add_f32_dpp v43, v43, v43 row_shl:2 row_mask:0xf bank_mask:0xf bound_ctrl:1
	v_add_f32_dpp v44, v44, v44 row_shl:2 row_mask:0xf bank_mask:0xf bound_ctrl:1
	v_add_f32_dpp v45, v45, v45 row_shl:2 row_mask:0xf bank_mask:0xf bound_ctrl:1
	v_add_f32_dpp v46, v46, v46 row_shl:2 row_mask:0xf bank_mask:0xf bound_ctrl:1
	v_add_f32_dpp v47, v47, v47 row_shl:2 row_mask:0xf bank_mask:0xf bound_ctrl:1
	v_add_f32_dpp v40, v40, v40 row_shl:4 row_mask:0xf bank_mask:0xf bound_ctrl:1
	v_add_f32_dpp v41, v41, v41 row_shl:4 row_mask:0xf bank_mask:0xf bound_ctrl:1
	v_add_f32_dpp v42, v42, v42 row_shl:4 row_mask:0xf bank_mask:0xf bound_ctrl:1
	v_add_f32_dpp v43, v43, v43 row_shl:4 row_mask:0xf bank_mask:0xf bound_ctrl:1
	v_add_f32_dpp v44, v44, v44 row_shl:4 row_mask:0xf bank_mask:0xf bound_ctrl:1
	v_add_f32_dpp v45, v45, v45 row_shl:4 row_mask:0xf bank_mask:0xf bound_ctrl:1
	v_add_f32_dpp v46, v46, v46 row_shl:4 row_mask:0xf bank_mask:0xf bound_ctrl:1
	v_add_f32_dpp v47, v47, v47 row_shl:4 row_mask:0xf bank_mask:0xf bound_ctrl:1
	v_add_f32_dpp v40, v40, v40 row_shl:8 row_mask:0xf bank_mask:0xf bound_ctrl:1
	v_add_f32_dpp v41, v41, v41 row_shl:8 row_mask:0xf bank_mask:0xf bound_ctrl:1
	v_add_f32_dpp v42, v42, v42 row_shl:8 row_mask:0xf bank_mask:0xf bound_ctrl:1
	v_add_f32_dpp v43, v43, v43 row_shl:8 row_mask:0xf bank_mask:0xf bound_ctrl:1
	v_add_f32_dpp v44, v44, v44 row_shl:8 row_mask:0xf bank_mask:0xf bound_ctrl:1
	v_add_f32_dpp v45, v45, v45 row_shl:8 row_mask:0xf bank_mask:0xf bound_ctrl:1
	v_add_f32_dpp v46, v46, v46 row_shl:8 row_mask:0xf bank_mask:0xf bound_ctrl:1
	v_add_f32_dpp v47, v47, v47 row_shl:8 row_mask:0xf bank_mask:0xf bound_ctrl:1
	v_mov_b32_dpp v88, v40 row_newbcast:0 row_mask:0xf bank_mask:0xf
	v_mov_b32_dpp v89, v41 row_newbcast:0 row_mask:0xf bank_mask:0xf
	v_mov_b32_dpp v90, v42 row_newbcast:0 row_mask:0xf bank_mask:0xf
	v_mov_b32_dpp v91, v43 row_newbcast:0 row_mask:0xf bank_mask:0xf
	v_mov_b32_dpp v92, v44 row_newbcast:0 row_mask:0xf bank_mask:0xf
	v_mov_b32_dpp v93, v45 row_newbcast:0 row_mask:0xf bank_mask:0xf
	v_mov_b32_dpp v94, v46 row_newbcast:0 row_mask:0xf bank_mask:0xf
	v_mov_b32_dpp v95, v47 row_newbcast:0 row_mask:0xf bank_mask:0xf
	v_add_f32_e32 v40, v40, v178
	v_add_f32_e32 v44, v44, v179
	v_add_f32_e32 v41, v41, v180
	v_add_f32_e32 v45, v45, v181
	v_add_f32_e32 v42, v42, v182
	v_add_f32_e32 v46, v46, v183
	v_add_f32_e32 v43, v43, v184
	v_add_f32_e32 v47, v47, v185
	v_mul_f32_e32 v132, v40, v103
	v_mul_f32_e32 v40, v40, v102
	v_fma_f32 v40, -v44, v103, v40
	v_fma_f32 v44, v44, v102, v132
	v_mul_f32_e32 v133, v41, v107
	v_mul_f32_e32 v41, v41, v106
	v_fma_f32 v41, -v45, v107, v41
	v_fma_f32 v45, v45, v106, v133
	v_mul_f32_e32 v132, v42, v111
	v_mul_f32_e32 v42, v42, v110
	v_fma_f32 v42, -v46, v111, v42
	v_fma_f32 v46, v46, v110, v132
	v_mul_f32_e32 v133, v43, v115
	v_mul_f32_e32 v43, v43, v114
	v_fma_f32 v43, -v47, v115, v43
	v_fma_f32 v47, v47, v114, v133
	v_add_f32_e32 v88, v88, v178
	v_add_f32_e32 v92, v92, v179
	v_mul_f32_e32 v132, v92, v117
	v_mul_f32_e32 v179, v88, v117
	v_fma_f32 v178, v88, v116, -v132
	v_fma_f32 v179, v92, v116, v179
	v_add_f32_e32 v89, v89, v180
	v_add_f32_e32 v93, v93, v181
	v_mul_f32_e32 v133, v93, v121
	v_mul_f32_e32 v181, v89, v121
	v_fma_f32 v180, v89, v120, -v133
	v_fma_f32 v181, v93, v120, v181
	v_add_f32_e32 v90, v90, v182
	v_add_f32_e32 v94, v94, v183
	v_mul_f32_e32 v132, v94, v125
	v_mul_f32_e32 v183, v90, v125
	v_fma_f32 v182, v90, v124, -v132
	v_fma_f32 v183, v94, v124, v183
	v_add_f32_e32 v91, v91, v184
	v_add_f32_e32 v95, v95, v185
	v_mul_f32_e32 v133, v95, v129
	v_mul_f32_e32 v185, v91, v129
	v_fma_f32 v184, v91, v128, -v133
	v_fma_f32 v185, v95, v128, v185
	v_mul_f32_e32 v132, v32, v101
	v_mul_f32_e32 v32, v32, v100
	v_fma_f32 v32, -v36, v101, v32
	v_fma_f32 v36, v36, v100, v132
	v_mul_f32_e32 v133, v33, v105
	v_mul_f32_e32 v33, v33, v104
	v_fma_f32 v33, -v37, v105, v33
	v_fma_f32 v37, v37, v104, v133
	v_mul_f32_e32 v132, v34, v109
	v_mul_f32_e32 v34, v34, v108
	v_fma_f32 v34, -v38, v109, v34
	v_fma_f32 v38, v38, v108, v132
	v_mul_f32_e32 v133, v35, v113
	v_mul_f32_e32 v35, v35, v112
	v_fma_f32 v35, -v39, v113, v35
	v_fma_f32 v39, v39, v112, v133
	v_add_f32_dpp v32, v32, v32 row_shl:1 row_mask:0xf bank_mask:0xf bound_ctrl:1
	v_add_f32_dpp v33, v33, v33 row_shl:1 row_mask:0xf bank_mask:0xf bound_ctrl:1
	v_add_f32_dpp v34, v34, v34 row_shl:1 row_mask:0xf bank_mask:0xf bound_ctrl:1
	v_add_f32_dpp v35, v35, v35 row_shl:1 row_mask:0xf bank_mask:0xf bound_ctrl:1
	v_add_f32_dpp v36, v36, v36 row_shl:1 row_mask:0xf bank_mask:0xf bound_ctrl:1
	v_add_f32_dpp v37, v37, v37 row_shl:1 row_mask:0xf bank_mask:0xf bound_ctrl:1
	v_add_f32_dpp v38, v38, v38 row_shl:1 row_mask:0xf bank_mask:0xf bound_ctrl:1
	v_add_f32_dpp v39, v39, v39 row_shl:1 row_mask:0xf bank_mask:0xf bound_ctrl:1
	v_add_f32_dpp v32, v32, v32 row_shl:2 row_mask:0xf bank_mask:0xf bound_ctrl:1
	v_add_f32_dpp v33, v33, v33 row_shl:2 row_mask:0xf bank_mask:0xf bound_ctrl:1
	v_add_f32_dpp v34, v34, v34 row_shl:2 row_mask:0xf bank_mask:0xf bound_ctrl:1
	v_add_f32_dpp v35, v35, v35 row_shl:2 row_mask:0xf bank_mask:0xf bound_ctrl:1
	v_add_f32_dpp v36, v36, v36 row_shl:2 row_mask:0xf bank_mask:0xf bound_ctrl:1
	v_add_f32_dpp v37, v37, v37 row_shl:2 row_mask:0xf bank_mask:0xf bound_ctrl:1
	v_add_f32_dpp v38, v38, v38 row_shl:2 row_mask:0xf bank_mask:0xf bound_ctrl:1
	v_add_f32_dpp v39, v39, v39 row_shl:2 row_mask:0xf bank_mask:0xf bound_ctrl:1
	v_add_f32_dpp v32, v32, v32 row_shl:4 row_mask:0xf bank_mask:0xf bound_ctrl:1
	v_add_f32_dpp v33, v33, v33 row_shl:4 row_mask:0xf bank_mask:0xf bound_ctrl:1
	v_add_f32_dpp v34, v34, v34 row_shl:4 row_mask:0xf bank_mask:0xf bound_ctrl:1
	v_add_f32_dpp v35, v35, v35 row_shl:4 row_mask:0xf bank_mask:0xf bound_ctrl:1
	v_add_f32_dpp v36, v36, v36 row_shl:4 row_mask:0xf bank_mask:0xf bound_ctrl:1
	v_add_f32_dpp v37, v37, v37 row_shl:4 row_mask:0xf bank_mask:0xf bound_ctrl:1
	v_add_f32_dpp v38, v38, v38 row_shl:4 row_mask:0xf bank_mask:0xf bound_ctrl:1
	v_add_f32_dpp v39, v39, v39 row_shl:4 row_mask:0xf bank_mask:0xf bound_ctrl:1
	v_add_f32_dpp v32, v32, v32 row_shl:8 row_mask:0xf bank_mask:0xf bound_ctrl:1
	v_add_f32_dpp v33, v33, v33 row_shl:8 row_mask:0xf bank_mask:0xf bound_ctrl:1
	v_add_f32_dpp v34, v34, v34 row_shl:8 row_mask:0xf bank_mask:0xf bound_ctrl:1
	v_add_f32_dpp v35, v35, v35 row_shl:8 row_mask:0xf bank_mask:0xf bound_ctrl:1
	v_add_f32_dpp v36, v36, v36 row_shl:8 row_mask:0xf bank_mask:0xf bound_ctrl:1
	v_add_f32_dpp v37, v37, v37 row_shl:8 row_mask:0xf bank_mask:0xf bound_ctrl:1
	v_add_f32_dpp v38, v38, v38 row_shl:8 row_mask:0xf bank_mask:0xf bound_ctrl:1
	v_add_f32_dpp v39, v39, v39 row_shl:8 row_mask:0xf bank_mask:0xf bound_ctrl:1
	v_mov_b32_dpp v88, v32 row_newbcast:0 row_mask:0xf bank_mask:0xf
	v_mov_b32_dpp v89, v33 row_newbcast:0 row_mask:0xf bank_mask:0xf
	v_mov_b32_dpp v90, v34 row_newbcast:0 row_mask:0xf bank_mask:0xf
	v_mov_b32_dpp v91, v35 row_newbcast:0 row_mask:0xf bank_mask:0xf
	v_mov_b32_dpp v92, v36 row_newbcast:0 row_mask:0xf bank_mask:0xf
	v_mov_b32_dpp v93, v37 row_newbcast:0 row_mask:0xf bank_mask:0xf
	v_mov_b32_dpp v94, v38 row_newbcast:0 row_mask:0xf bank_mask:0xf
	v_mov_b32_dpp v95, v39 row_newbcast:0 row_mask:0xf bank_mask:0xf
	v_add_f32_e32 v32, v32, v178
	v_add_f32_e32 v36, v36, v179
	v_add_f32_e32 v33, v33, v180
	v_add_f32_e32 v37, v37, v181
	v_add_f32_e32 v34, v34, v182
	v_add_f32_e32 v38, v38, v183
	v_add_f32_e32 v35, v35, v184
	v_add_f32_e32 v39, v39, v185
	v_mul_f32_e32 v132, v32, v103
	v_mul_f32_e32 v32, v32, v102
	v_fma_f32 v32, -v36, v103, v32
	v_fma_f32 v36, v36, v102, v132
	v_mul_f32_e32 v133, v33, v107
	v_mul_f32_e32 v33, v33, v106
	v_fma_f32 v33, -v37, v107, v33
	v_fma_f32 v37, v37, v106, v133
	v_mul_f32_e32 v132, v34, v111
	v_mul_f32_e32 v34, v34, v110
	v_fma_f32 v34, -v38, v111, v34
	v_fma_f32 v38, v38, v110, v132
	v_mul_f32_e32 v133, v35, v115
	v_mul_f32_e32 v35, v35, v114
	v_fma_f32 v35, -v39, v115, v35
	v_fma_f32 v39, v39, v114, v133
	v_add_f32_e32 v88, v88, v178
	v_add_f32_e32 v92, v92, v179
	v_mul_f32_e32 v132, v92, v117
	v_mul_f32_e32 v179, v88, v117
	v_fma_f32 v178, v88, v116, -v132
	v_fma_f32 v179, v92, v116, v179
	v_add_f32_e32 v89, v89, v180
	v_add_f32_e32 v93, v93, v181
	v_mul_f32_e32 v133, v93, v121
	v_mul_f32_e32 v181, v89, v121
	v_fma_f32 v180, v89, v120, -v133
	v_fma_f32 v181, v93, v120, v181
	v_add_f32_e32 v90, v90, v182
	v_add_f32_e32 v94, v94, v183
	v_mul_f32_e32 v132, v94, v125
	v_mul_f32_e32 v183, v90, v125
	v_fma_f32 v182, v90, v124, -v132
	v_fma_f32 v183, v94, v124, v183
	v_add_f32_e32 v91, v91, v184
	v_add_f32_e32 v95, v95, v185
	v_mul_f32_e32 v133, v95, v129
	v_mul_f32_e32 v185, v91, v129
	v_fma_f32 v184, v91, v128, -v133
	v_fma_f32 v185, v95, v128, v185
	s_waitcnt vmcnt(0)
	v_cvt_pk_bf16_f32 v80, v80, v81
	v_cvt_pk_bf16_f32 v81, v82, v83
	v_cvt_pk_bf16_f32 v82, -v84, -v85
	v_cvt_pk_bf16_f32 v83, -v86, -v87
	v_cvt_pk_bf16_f32 v96, v32, v33
	v_cvt_pk_bf16_f32 v97, v34, v35
	v_cvt_pk_bf16_f32 v98, v36, v37
	v_cvt_pk_bf16_f32 v99, v38, v39
	s_nop 1
	v_mfma_f32_16x16x32_bf16 v[16:19], v[80:83], v[96:99], v[16:19]
	v_cvt_pk_bf16_f32 v96, v40, v41
	v_cvt_pk_bf16_f32 v97, v42, v43
	v_cvt_pk_bf16_f32 v98, v44, v45
	v_cvt_pk_bf16_f32 v99, v46, v47
	s_nop 1
	v_mfma_f32_16x16x32_bf16 v[20:23], v[80:83], v[96:99], v[20:23]
	v_cvt_pk_bf16_f32 v96, v48, v49
	v_cvt_pk_bf16_f32 v97, v50, v51
	v_cvt_pk_bf16_f32 v98, v52, v53
	v_cvt_pk_bf16_f32 v99, v54, v55
	s_nop 1
	v_mfma_f32_16x16x32_bf16 v[24:27], v[80:83], v[96:99], v[24:27]
	v_cvt_pk_bf16_f32 v96, v56, v57
	v_cvt_pk_bf16_f32 v97, v58, v59
	v_cvt_pk_bf16_f32 v98, v60, v61
	v_cvt_pk_bf16_f32 v99, v62, v63
	s_nop 1
	v_mfma_f32_16x16x32_bf16 v[28:31], v[80:83], v[96:99], v[28:31]
	v_and_b32_e32 v100, 15, v205
	v_lshrrev_b32_e32 v101, 4, v205
	v_mul_u32_u24_e32 v102, 0xe00, v100
	v_lshl_add_u32 v102, v101, 3, v102
	v_lshlrev_b32_e32 v103, 9, v100
	v_lshl_add_u32 v103, v101, 3, v103
	v_lshlrev_b32_e32 v104, 4, v101
	s_mul_i32 s18, s9, 0xe00
	s_lshl_b32 s19, s7, 5
	s_add_i32 s18, s18, s19
	s_add_u32 s18, s18, 0x5e00c00
	s_add_u32 s18, s4, s18
	s_addc_u32 s19, s5, 0
	global_load_dwordx2 v[108:109], v102, s[18:19]
	s_add_u32 s18, s18, 0xe000
	s_addc_u32 s19, s19, 0
	global_load_dwordx2 v[110:111], v102, s[18:19]
	s_add_u32 s18, s18, 0xe000
	s_addc_u32 s19, s19, 0
	global_load_dwordx2 v[112:113], v102, s[18:19]
	s_add_u32 s18, s18, 0xe000
	s_addc_u32 s19, s19, 0
	global_load_dwordx2 v[114:115], v102, s[18:19]
	v_readlane_b32 s10, v247, 28
	s_lshl_b32 s10, s10, 10
	s_lshl_b32 s11, s7, 6
	s_add_i32 s10, s10, s11
	s_add_u32 s10, s10, 0x21fb20
	s_add_u32 s20, s4, s10
	s_addc_u32 s21, s5, 0
	global_load_dwordx4 v[116:119], v104, s[20:21]
	s_lshl_b32 s10, s9, 9
	s_add_i32 s10, s10, s11
	s_lshr_b32 s11, s11, 1
	s_sub_i32 s10, s10, s11
	s_add_u32 s10, s10, 0xc500000
	s_add_u32 s22, s4, s10
	s_addc_u32 s23, s5, 0
	s_waitcnt vmcnt(0)
	s_nop 4
	v_lshlrev_b32_e32 v120, 16, v108
	v_and_b32_e32 v121, 0xffff0000, v108
	v_lshlrev_b32_e32 v122, 16, v109
	v_and_b32_e32 v123, 0xffff0000, v109
	v_fmac_f32_e32 v16, v116, v120
	v_fmac_f32_e32 v17, v117, v121
	v_fmac_f32_e32 v18, v118, v122
	v_fmac_f32_e32 v19, v119, v123
	v_cvt_pk_bf16_f32 v124, v16, v17
	v_cvt_pk_bf16_f32 v125, v18, v19
	global_store_dwordx2 v103, v[124:125], s[22:23] offset:0
	s_add_u32 s22, s22, 0x2000
	s_addc_u32 s23, s23, 0
	v_lshlrev_b32_e32 v120, 16, v110
	v_and_b32_e32 v121, 0xffff0000, v110
	v_lshlrev_b32_e32 v122, 16, v111
	v_and_b32_e32 v123, 0xffff0000, v111
	v_fmac_f32_e32 v20, v116, v120
	v_fmac_f32_e32 v21, v117, v121
	v_fmac_f32_e32 v22, v118, v122
	v_fmac_f32_e32 v23, v119, v123
	v_cvt_pk_bf16_f32 v124, v20, v21
	v_cvt_pk_bf16_f32 v125, v22, v23
	global_store_dwordx2 v103, v[124:125], s[22:23] offset:0
	s_add_u32 s22, s22, 0x2000
	s_addc_u32 s23, s23, 0
	v_lshlrev_b32_e32 v120, 16, v112
	v_and_b32_e32 v121, 0xffff0000, v112
	v_lshlrev_b32_e32 v122, 16, v113
	v_and_b32_e32 v123, 0xffff0000, v113
	v_fmac_f32_e32 v24, v116, v120
	v_fmac_f32_e32 v25, v117, v121
	v_fmac_f32_e32 v26, v118, v122
	v_fmac_f32_e32 v27, v119, v123
	v_cvt_pk_bf16_f32 v124, v24, v25
	v_cvt_pk_bf16_f32 v125, v26, v27
	global_store_dwordx2 v103, v[124:125], s[22:23] offset:0
	s_add_u32 s22, s22, 0x2000
	s_addc_u32 s23, s23, 0
	v_lshlrev_b32_e32 v120, 16, v114
	v_and_b32_e32 v121, 0xffff0000, v114
	v_lshlrev_b32_e32 v122, 16, v115
	v_and_b32_e32 v123, 0xffff0000, v115
	v_fmac_f32_e32 v28, v116, v120
	v_fmac_f32_e32 v29, v117, v121
	v_fmac_f32_e32 v30, v118, v122
	v_fmac_f32_e32 v31, v119, v123
	v_cvt_pk_bf16_f32 v124, v28, v29
	v_cvt_pk_bf16_f32 v125, v30, v31
	global_store_dwordx2 v103, v[124:125], s[22:23] offset:0
	s_cmp_eq_u32 s37, 1
	s_cbranch_scc1 .Lss3_done
	s_add_i32 s36, s36, s30
	s_branch .Lss3_top

.LBB0_449:
	s_andn2_b64 vcc, exec, s[0:1]
	s_cbranch_vccnz .LBB0_478
	s_sub_i32 s86, s12, s60
	s_mul_i32 s10, s86, 0xf0f1
	s_lshr_b32 s10, s10, 22
	s_mul_i32 s11, s10, 68
	s_sub_i32 s8, s86, s11
	s_and_b32 s7, s10, 15
	s_lshr_b32 s6, s10, 4
	s_lshl_b32 s10, s8, 6
	s_lshl_b32 s11, s6, 8
	s_add_i32 s9, s10, s11
	s_lshl_b32 s11, s6, 12
	s_add_i32 s11, s11, s10
	s_add_i32 s11, s11, 0x300
	s_cmp_lt_u32 s8, 4
	s_cselect_b32 s9, s9, s11
	v_mov_b32_e32 v0, 0
	v_mov_b32_e32 v1, 0
	v_mov_b32_e32 v2, 0
	v_mov_b32_e32 v3, 0
	v_mov_b32_e32 v4, 0
	v_mov_b32_e32 v5, 0
	v_mov_b32_e32 v6, 0
	v_mov_b32_e32 v7, 0
	v_mov_b32_e32 v8, 0
	v_mov_b32_e32 v9, 0
	v_mov_b32_e32 v10, 0
	v_mov_b32_e32 v11, 0
	v_mov_b32_e32 v12, 0
	v_mov_b32_e32 v13, 0
	v_mov_b32_e32 v14, 0
	v_mov_b32_e32 v15, 0
	v_and_b32_e32 v100, 15, v205
	v_mul_u32_u24_e32 v100, 0xe00, v100
	v_and_b32_e32 v101, 16, v205
	v_add_u32_e32 v100, v100, v101
	s_mul_i32 s18, s9, 0xe00
	s_lshl_b32 s19, s7, 5
	s_add_i32 s18, s18, s19
	s_add_u32 s18, s18, 0x5e00c00
	s_add_u32 s18, s4, s18
	s_addc_u32 s19, s5, 0
	s_mov_b32 exec_hi, 0
	global_load_dwordx4 v[0:3], v100, s[18:19]
	s_add_u32 s18, s18, 0xe000
	s_addc_u32 s19, s19, 0
	global_load_dwordx4 v[4:7], v100, s[18:19]
	s_add_u32 s18, s18, 0xe000
	s_addc_u32 s19, s19, 0
	global_load_dwordx4 v[8:11], v100, s[18:19]
	s_add_u32 s18, s18, 0xe000
	s_addc_u32 s19, s19, 0
	global_load_dwordx4 v[12:15], v100, s[18:19]
	s_mov_b64 exec, -1
	v_mov_b32_e32 v48, 0
	v_mov_b32_e32 v49, 0
	v_mov_b32_e32 v50, 0
	v_mov_b32_e32 v51, 0
	v_mov_b32_e32 v52, 0
	v_mov_b32_e32 v53, 0
	v_mov_b32_e32 v54, 0
	v_mov_b32_e32 v55, 0
	v_mov_b32_e32 v56, 0
	v_mov_b32_e32 v57, 0
	v_mov_b32_e32 v58, 0
	v_mov_b32_e32 v59, 0
	v_mov_b32_e32 v60, 0
	v_mov_b32_e32 v61, 0
	v_mov_b32_e32 v62, 0
	v_mov_b32_e32 v63, 0
	v_mov_b32_e32 v64, 0
	v_mov_b32_e32 v65, 0
	v_mov_b32_e32 v66, 0
	v_mov_b32_e32 v67, 0
	v_mov_b32_e32 v68, 0
	v_mov_b32_e32 v69, 0
	v_mov_b32_e32 v70, 0
	v_mov_b32_e32 v71, 0
	v_mov_b32_e32 v72, 0
	v_mov_b32_e32 v73, 0
	v_mov_b32_e32 v74, 0
	v_mov_b32_e32 v75, 0
	v_mov_b32_e32 v76, 0
	v_mov_b32_e32 v77, 0
	v_mov_b32_e32 v78, 0
	v_mov_b32_e32 v79, 0
	v_and_b32_e32 v112, 15, v205
	v_lshlrev_b32_e32 v112, 6, v112
	v_and_b32_e32 v113, 16, v205
	v_lshl_add_u32 v112, v113, 1, v112
	v_lshlrev_b32_e32 v113, 4, v205
	v_lshrrev_b32_e32 v114, 4, v205
	v_lshlrev_b32_e32 v114, 5, v114
	v_readlane_b32 s10, v247, 28
	s_mov_b32 s11, s8
	s_lshl_b32 s16, s10, 1
	s_add_i32 s16, s16, 0
	s_lshl_b32 s16, s16, 4
	s_add_i32 s16, s16, s7
	s_lshl_b32 s17, s6, 1
	s_add_i32 s17, s17, 0
	s_lshl_b32 s17, s17, 4
	s_add_i32 s17, s17, s7
	s_mul_i32 s17, s17, 68
	s_add_i32 s17, s17, s11
	s_lshl_b32 s17, s17, 6
	s_lshl_b32 s20, s16, 12
	s_add_u32 s20, s20, 0x11fb20
	s_add_u32 s20, s4, s20
	s_addc_u32 s21, s5, 0
	s_add_u32 s22, s20, 0x40000
	s_addc_u32 s23, s21, 0
	s_lshl_b32 s24, s16, 14
	s_add_u32 s24, s24, 0xfc00000
	s_add_u32 s24, s4, s24
	s_addc_u32 s25, s5, 0
	s_lshl_b32 s26, s17, 3
	s_add_u32 s26, s26, 0x300000
	s_add_u32 s26, s4, s26
	s_addc_u32 s27, s5, 0
	s_mov_b32 exec_hi, 0
	global_load_dwordx4 v[48:51], v112, s[20:21]
	global_load_dwordx4 v[52:55], v112, s[20:21] offset:16
	global_load_dwordx4 v[56:59], v112, s[22:23]
	global_load_dwordx4 v[60:63], v112, s[22:23] offset:16
	s_mov_b64 exec, -1
	global_load_dwordx4 v[80:83], v113, s[24:25] offset:0
	global_load_dwordx4 v[84:87], v113, s[24:25] offset:1024
	global_load_dwordx4 v[88:91], v113, s[24:25] offset:2048
	global_load_dwordx4 v[92:95], v113, s[24:25] offset:3072
	s_add_u32 s20, s20, 0x400
	s_addc_u32 s21, s21, 0
	s_add_u32 s22, s22, 0x400
	s_addc_u32 s23, s23, 0
	s_add_u32 s24, s24, 0x1000
	s_addc_u32 s25, s25, 0
	s_waitcnt vmcnt(8)
	s_waitcnt vmcnt(4)
	v_cvt_pk_bf16_f32 v48, v48, v49
	v_cvt_pk_bf16_f32 v49, v50, v51
	v_cvt_pk_bf16_f32 v50, v52, v53
	v_cvt_pk_bf16_f32 v51, v54, v55
	v_cvt_pk_bf16_f32 v56, v56, v57
	v_cvt_pk_bf16_f32 v57, v58, v59
	v_cvt_pk_bf16_f32 v58, v60, v61
	v_cvt_pk_bf16_f32 v59, v62, v63
	s_mov_b32 exec_hi, 0
	global_load_dwordx4 v[64:67], v112, s[20:21]
	global_load_dwordx4 v[68:71], v112, s[20:21] offset:16
	global_load_dwordx4 v[72:75], v112, s[22:23]
	global_load_dwordx4 v[76:79], v112, s[22:23] offset:16
	s_mov_b64 exec, -1
	global_load_dwordx4 v[96:99], v113, s[24:25] offset:0
	global_load_dwordx4 v[100:103], v113, s[24:25] offset:1024
	global_load_dwordx4 v[104:107], v113, s[24:25] offset:2048
	global_load_dwordx4 v[108:111], v113, s[24:25] offset:3072
	s_add_u32 s20, s20, 0x400
	s_addc_u32 s21, s21, 0
	s_add_u32 s22, s22, 0x400
	s_addc_u32 s23, s23, 0
	s_add_u32 s24, s24, 0x1000
	s_addc_u32 s25, s25, 0
	v_mfma_f32_16x16x32_bf16 v[16:19], v[48:51], v[0:3], 0
	v_mfma_f32_16x16x32_bf16 v[20:23], v[56:59], v[0:3], 0
	v_mfma_f32_16x16x32_bf16 v[24:27], v[48:51], v[4:7], 0
	v_mfma_f32_16x16x32_bf16 v[28:31], v[56:59], v[4:7], 0
	v_mfma_f32_16x16x32_bf16 v[32:35], v[48:51], v[8:11], 0
	v_mfma_f32_16x16x32_bf16 v[36:39], v[56:59], v[8:11], 0
	v_mfma_f32_16x16x32_bf16 v[40:43], v[48:51], v[12:15], 0
	v_mfma_f32_16x16x32_bf16 v[44:47], v[56:59], v[12:15], 0
	s_waitcnt vmcnt(8)
	s_nop 7
	v_mul_f32_e32 v116, v81, v20
	v_fma_f32 v120, v80, v16, -v116
	v_mul_f32_e32 v116, v80, v20
	v_fma_f32 v124, v81, v16, v116
	v_mul_f32_e32 v116, v85, v21
	v_fma_f32 v121, v84, v17, -v116
	v_mul_f32_e32 v116, v84, v21
	v_fma_f32 v125, v85, v17, v116
	v_mul_f32_e32 v116, v89, v22
	v_fma_f32 v122, v88, v18, -v116
	v_mul_f32_e32 v116, v88, v22
	v_fma_f32 v126, v89, v18, v116
	v_mul_f32_e32 v116, v93, v23
	v_fma_f32 v123, v92, v19, -v116
	v_mul_f32_e32 v116, v92, v23
	v_fma_f32 v127, v93, v19, v116
	v_mul_f32_e32 v116, v81, v28
	v_fma_f32 v117, v80, v24, -v116
	v_mul_f32_e32 v116, v80, v28
	v_fma_f32 v118, v81, v24, v116
	v_fma_f32 v117, v120, v82, v117
	v_fma_f32 v118, v120, v83, v118
	v_fma_f32 v117, -v124, v83, v117
	v_fma_f32 v124, v124, v82, v118
	v_mov_b32_e32 v120, v117
	v_mul_f32_e32 v116, v85, v29
	v_fma_f32 v117, v84, v25, -v116
	v_mul_f32_e32 v116, v84, v29
	v_fma_f32 v118, v85, v25, v116
	v_fma_f32 v117, v121, v86, v117
	v_fma_f32 v118, v121, v87, v118
	v_fma_f32 v117, -v125, v87, v117
	v_fma_f32 v125, v125, v86, v118
	v_mov_b32_e32 v121, v117
	v_mul_f32_e32 v116, v89, v30
	v_fma_f32 v117, v88, v26, -v116
	v_mul_f32_e32 v116, v88, v30
	v_fma_f32 v118, v89, v26, v116
	v_fma_f32 v117, v122, v90, v117
	v_fma_f32 v118, v122, v91, v118
	v_fma_f32 v117, -v126, v91, v117
	v_fma_f32 v126, v126, v90, v118
	v_mov_b32_e32 v122, v117
	v_mul_f32_e32 v116, v93, v31
	v_fma_f32 v117, v92, v27, -v116
	v_mul_f32_e32 v116, v92, v31
	v_fma_f32 v118, v93, v27, v116
	v_fma_f32 v117, v123, v94, v117
	v_fma_f32 v118, v123, v95, v118
	v_fma_f32 v117, -v127, v95, v117
	v_fma_f32 v127, v127, v94, v118
	v_mov_b32_e32 v123, v117
	v_mul_f32_e32 v116, v81, v36
	v_fma_f32 v117, v80, v32, -v116
	v_mul_f32_e32 v116, v80, v36
	v_fma_f32 v118, v81, v32, v116
	v_fma_f32 v117, v120, v82, v117
	v_fma_f32 v118, v120, v83, v118
	v_fma_f32 v117, -v124, v83, v117
	v_fma_f32 v124, v124, v82, v118
	v_mov_b32_e32 v120, v117
	v_mul_f32_e32 v116, v85, v37
	v_fma_f32 v117, v84, v33, -v116
	v_mul_f32_e32 v116, v84, v37
	v_fma_f32 v118, v85, v33, v116
	v_fma_f32 v117, v121, v86, v117
	v_fma_f32 v118, v121, v87, v118
	v_fma_f32 v117, -v125, v87, v117
	v_fma_f32 v125, v125, v86, v118
	v_mov_b32_e32 v121, v117
	v_mul_f32_e32 v116, v89, v38
	v_fma_f32 v117, v88, v34, -v116
	v_mul_f32_e32 v116, v88, v38
	v_fma_f32 v118, v89, v34, v116
	v_fma_f32 v117, v122, v90, v117
	v_fma_f32 v118, v122, v91, v118
	v_fma_f32 v117, -v126, v91, v117
	v_fma_f32 v126, v126, v90, v118
	v_mov_b32_e32 v122, v117
	v_mul_f32_e32 v116, v93, v39
	v_fma_f32 v117, v92, v35, -v116
	v_mul_f32_e32 v116, v92, v39
	v_fma_f32 v118, v93, v35, v116
	v_fma_f32 v117, v123, v94, v117
	v_fma_f32 v118, v123, v95, v118
	v_fma_f32 v117, -v127, v95, v117
	v_fma_f32 v127, v127, v94, v118
	v_mov_b32_e32 v123, v117
	v_mul_f32_e32 v116, v81, v44
	v_fma_f32 v117, v80, v40, -v116
	v_mul_f32_e32 v116, v80, v44
	v_fma_f32 v118, v81, v40, v116
	v_fma_f32 v117, v120, v82, v117
	v_fma_f32 v118, v120, v83, v118
	v_fma_f32 v117, -v124, v83, v117
	v_fma_f32 v124, v124, v82, v118
	v_mov_b32_e32 v120, v117
	v_mul_f32_e32 v116, v85, v45
	v_fma_f32 v117, v84, v41, -v116
	v_mul_f32_e32 v116, v84, v45
	v_fma_f32 v118, v85, v41, v116
	v_fma_f32 v117, v121, v86, v117
	v_fma_f32 v118, v121, v87, v118
	v_fma_f32 v117, -v125, v87, v117
	v_fma_f32 v125, v125, v86, v118
	v_mov_b32_e32 v121, v117
	v_mul_f32_e32 v116, v89, v46
	v_fma_f32 v117, v88, v42, -v116
	v_mul_f32_e32 v116, v88, v46
	v_fma_f32 v118, v89, v42, v116
	v_fma_f32 v117, v122, v90, v117
	v_fma_f32 v118, v122, v91, v118
	v_fma_f32 v117, -v126, v91, v117
	v_fma_f32 v126, v126, v90, v118
	v_mov_b32_e32 v122, v117
	v_mul_f32_e32 v116, v93, v47
	v_fma_f32 v117, v92, v43, -v116
	v_mul_f32_e32 v116, v92, v47
	v_fma_f32 v118, v93, v43, v116
	v_fma_f32 v117, v123, v94, v117
	v_fma_f32 v118, v123, v95, v118
	v_fma_f32 v117, -v127, v95, v117
	v_fma_f32 v127, v127, v94, v118
	v_mov_b32_e32 v123, v117
	v_add_f32_dpp v120, v120, v120 row_ror:8 row_mask:0xf bank_mask:0xf
	v_add_f32_dpp v121, v121, v121 row_ror:8 row_mask:0xf bank_mask:0xf
	v_add_f32_dpp v122, v122, v122 row_ror:8 row_mask:0xf bank_mask:0xf
	v_add_f32_dpp v123, v123, v123 row_ror:8 row_mask:0xf bank_mask:0xf
	v_add_f32_dpp v124, v124, v124 row_ror:8 row_mask:0xf bank_mask:0xf
	v_add_f32_dpp v125, v125, v125 row_ror:8 row_mask:0xf bank_mask:0xf
	v_add_f32_dpp v126, v126, v126 row_ror:8 row_mask:0xf bank_mask:0xf
	v_add_f32_dpp v127, v127, v127 row_ror:8 row_mask:0xf bank_mask:0xf
	v_add_f32_dpp v120, v120, v120 row_ror:4 row_mask:0xf bank_mask:0xf
	v_add_f32_dpp v121, v121, v121 row_ror:4 row_mask:0xf bank_mask:0xf
	v_add_f32_dpp v122, v122, v122 row_ror:4 row_mask:0xf bank_mask:0xf
	v_add_f32_dpp v123, v123, v123 row_ror:4 row_mask:0xf bank_mask:0xf
	v_add_f32_dpp v124, v124, v124 row_ror:4 row_mask:0xf bank_mask:0xf
	v_add_f32_dpp v125, v125, v125 row_ror:4 row_mask:0xf bank_mask:0xf
	v_add_f32_dpp v126, v126, v126 row_ror:4 row_mask:0xf bank_mask:0xf
	v_add_f32_dpp v127, v127, v127 row_ror:4 row_mask:0xf bank_mask:0xf
	v_add_f32_dpp v120, v120, v120 row_ror:2 row_mask:0xf bank_mask:0xf
	v_add_f32_dpp v121, v121, v121 row_ror:2 row_mask:0xf bank_mask:0xf
	v_add_f32_dpp v122, v122, v122 row_ror:2 row_mask:0xf bank_mask:0xf
	v_add_f32_dpp v123, v123, v123 row_ror:2 row_mask:0xf bank_mask:0xf
	v_add_f32_dpp v124, v124, v124 row_ror:2 row_mask:0xf bank_mask:0xf
	v_add_f32_dpp v125, v125, v125 row_ror:2 row_mask:0xf bank_mask:0xf
	v_add_f32_dpp v126, v126, v126 row_ror:2 row_mask:0xf bank_mask:0xf
	v_add_f32_dpp v127, v127, v127 row_ror:2 row_mask:0xf bank_mask:0xf
	v_add_f32_dpp v120, v120, v120 row_ror:1 row_mask:0xf bank_mask:0xf
	v_add_f32_dpp v121, v121, v121 row_ror:1 row_mask:0xf bank_mask:0xf
	v_add_f32_dpp v122, v122, v122 row_ror:1 row_mask:0xf bank_mask:0xf
	v_add_f32_dpp v123, v123, v123 row_ror:1 row_mask:0xf bank_mask:0xf
	v_add_f32_dpp v124, v124, v124 row_ror:1 row_mask:0xf bank_mask:0xf
	v_add_f32_dpp v125, v125, v125 row_ror:1 row_mask:0xf bank_mask:0xf
	v_add_f32_dpp v126, v126, v126 row_ror:1 row_mask:0xf bank_mask:0xf
	v_add_f32_dpp v127, v127, v127 row_ror:1 row_mask:0xf bank_mask:0xf
	s_add_u32 s18, s26, 0
	s_addc_u32 s19, s27, 0
	v_mov_b32_e32 v128, v120
	v_mov_b32_e32 v129, v124
	v_mov_b32_e32 v130, v121
	v_mov_b32_e32 v131, v125
	v_mov_b32_e32 v132, v122
	v_mov_b32_e32 v133, v126
	v_mov_b32_e32 v134, v123
	v_mov_b32_e32 v135, v127
	s_mov_b32 exec_lo, 0x10001
	s_mov_b32 exec_hi, 0x10001
	global_store_dwordx4 v114, v[128:131], s[18:19]
	global_store_dwordx4 v114, v[132:135], s[18:19] offset:16
	s_mov_b64 exec, -1
	s_nop 1
	s_waitcnt vmcnt(4)
	v_cvt_pk_bf16_f32 v64, v64, v65
	v_cvt_pk_bf16_f32 v65, v66, v67
	v_cvt_pk_bf16_f32 v66, v68, v69
	v_cvt_pk_bf16_f32 v67, v70, v71
	v_cvt_pk_bf16_f32 v72, v72, v73
	v_cvt_pk_bf16_f32 v73, v74, v75
	v_cvt_pk_bf16_f32 v74, v76, v77
	v_cvt_pk_bf16_f32 v75, v78, v79
	s_mov_b32 exec_hi, 0
	global_load_dwordx4 v[48:51], v112, s[20:21]
	global_load_dwordx4 v[52:55], v112, s[20:21] offset:16
	global_load_dwordx4 v[56:59], v112, s[22:23]
	global_load_dwordx4 v[60:63], v112, s[22:23] offset:16
	s_mov_b64 exec, -1
	global_load_dwordx4 v[80:83], v113, s[24:25] offset:0
	global_load_dwordx4 v[84:87], v113, s[24:25] offset:1024
	global_load_dwordx4 v[88:91], v113, s[24:25] offset:2048
	global_load_dwordx4 v[92:95], v113, s[24:25] offset:3072
	s_add_u32 s20, s20, 0x400
	s_addc_u32 s21, s21, 0
	s_add_u32 s22, s22, 0x400
	s_addc_u32 s23, s23, 0
	s_add_u32 s24, s24, 0x1000
	s_addc_u32 s25, s25, 0
	v_mfma_f32_16x16x32_bf16 v[16:19], v[64:67], v[0:3], 0
	v_mfma_f32_16x16x32_bf16 v[20:23], v[72:75], v[0:3], 0
	v_mfma_f32_16x16x32_bf16 v[24:27], v[64:67], v[4:7], 0
	v_mfma_f32_16x16x32_bf16 v[28:31], v[72:75], v[4:7], 0
	v_mfma_f32_16x16x32_bf16 v[32:35], v[64:67], v[8:11], 0
	v_mfma_f32_16x16x32_bf16 v[36:39], v[72:75], v[8:11], 0
	v_mfma_f32_16x16x32_bf16 v[40:43], v[64:67], v[12:15], 0
	v_mfma_f32_16x16x32_bf16 v[44:47], v[72:75], v[12:15], 0
	s_waitcnt vmcnt(8)
	s_nop 7
	v_mul_f32_e32 v116, v97, v20
	v_fma_f32 v120, v96, v16, -v116
	v_mul_f32_e32 v116, v96, v20
	v_fma_f32 v124, v97, v16, v116
	v_mul_f32_e32 v116, v101, v21
	v_fma_f32 v121, v100, v17, -v116
	v_mul_f32_e32 v116, v100, v21
	v_fma_f32 v125, v101, v17, v116
	v_mul_f32_e32 v116, v105, v22
	v_fma_f32 v122, v104, v18, -v116
	v_mul_f32_e32 v116, v104, v22
	v_fma_f32 v126, v105, v18, v116
	v_mul_f32_e32 v116, v109, v23
	v_fma_f32 v123, v108, v19, -v116
	v_mul_f32_e32 v116, v108, v23
	v_fma_f32 v127, v109, v19, v116
	v_mul_f32_e32 v116, v97, v28
	v_fma_f32 v117, v96, v24, -v116
	v_mul_f32_e32 v116, v96, v28
	v_fma_f32 v118, v97, v24, v116
	v_fma_f32 v117, v120, v98, v117
	v_fma_f32 v118, v120, v99, v118
	v_fma_f32 v117, -v124, v99, v117
	v_fma_f32 v124, v124, v98, v118
	v_mov_b32_e32 v120, v117
	v_mul_f32_e32 v116, v101, v29
	v_fma_f32 v117, v100, v25, -v116
	v_mul_f32_e32 v116, v100, v29
	v_fma_f32 v118, v101, v25, v116
	v_fma_f32 v117, v121, v102, v117
	v_fma_f32 v118, v121, v103, v118
	v_fma_f32 v117, -v125, v103, v117
	v_fma_f32 v125, v125, v102, v118
	v_mov_b32_e32 v121, v117
	v_mul_f32_e32 v116, v105, v30
	v_fma_f32 v117, v104, v26, -v116
	v_mul_f32_e32 v116, v104, v30
	v_fma_f32 v118, v105, v26, v116
	v_fma_f32 v117, v122, v106, v117
	v_fma_f32 v118, v122, v107, v118
	v_fma_f32 v117, -v126, v107, v117
	v_fma_f32 v126, v126, v106, v118
	v_mov_b32_e32 v122, v117
	v_mul_f32_e32 v116, v109, v31
	v_fma_f32 v117, v108, v27, -v116
	v_mul_f32_e32 v116, v108, v31
	v_fma_f32 v118, v109, v27, v116
	v_fma_f32 v117, v123, v110, v117
	v_fma_f32 v118, v123, v111, v118
	v_fma_f32 v117, -v127, v111, v117
	v_fma_f32 v127, v127, v110, v118
	v_mov_b32_e32 v123, v117
	v_mul_f32_e32 v116, v97, v36
	v_fma_f32 v117, v96, v32, -v116
	v_mul_f32_e32 v116, v96, v36
	v_fma_f32 v118, v97, v32, v116
	v_fma_f32 v117, v120, v98, v117
	v_fma_f32 v118, v120, v99, v118
	v_fma_f32 v117, -v124, v99, v117
	v_fma_f32 v124, v124, v98, v118
	v_mov_b32_e32 v120, v117
	v_mul_f32_e32 v116, v101, v37
	v_fma_f32 v117, v100, v33, -v116
	v_mul_f32_e32 v116, v100, v37
	v_fma_f32 v118, v101, v33, v116
	v_fma_f32 v117, v121, v102, v117
	v_fma_f32 v118, v121, v103, v118
	v_fma_f32 v117, -v125, v103, v117
	v_fma_f32 v125, v125, v102, v118
	v_mov_b32_e32 v121, v117
	v_mul_f32_e32 v116, v105, v38
	v_fma_f32 v117, v104, v34, -v116
	v_mul_f32_e32 v116, v104, v38
	v_fma_f32 v118, v105, v34, v116
	v_fma_f32 v117, v122, v106, v117
	v_fma_f32 v118, v122, v107, v118
	v_fma_f32 v117, -v126, v107, v117
	v_fma_f32 v126, v126, v106, v118
	v_mov_b32_e32 v122, v117
	v_mul_f32_e32 v116, v109, v39
	v_fma_f32 v117, v108, v35, -v116
	v_mul_f32_e32 v116, v108, v39
	v_fma_f32 v118, v109, v35, v116
	v_fma_f32 v117, v123, v110, v117
	v_fma_f32 v118, v123, v111, v118
	v_fma_f32 v117, -v127, v111, v117
	v_fma_f32 v127, v127, v110, v118
	v_mov_b32_e32 v123, v117
	v_mul_f32_e32 v116, v97, v44
	v_fma_f32 v117, v96, v40, -v116
	v_mul_f32_e32 v116, v96, v44
	v_fma_f32 v118, v97, v40, v116
	v_fma_f32 v117, v120, v98, v117
	v_fma_f32 v118, v120, v99, v118
	v_fma_f32 v117, -v124, v99, v117
	v_fma_f32 v124, v124, v98, v118
	v_mov_b32_e32 v120, v117
	v_mul_f32_e32 v116, v101, v45
	v_fma_f32 v117, v100, v41, -v116
	v_mul_f32_e32 v116, v100, v45
	v_fma_f32 v118, v101, v41, v116
	v_fma_f32 v117, v121, v102, v117
	v_fma_f32 v118, v121, v103, v118
	v_fma_f32 v117, -v125, v103, v117
	v_fma_f32 v125, v125, v102, v118
	v_mov_b32_e32 v121, v117
	v_mul_f32_e32 v116, v105, v46
	v_fma_f32 v117, v104, v42, -v116
	v_mul_f32_e32 v116, v104, v46
	v_fma_f32 v118, v105, v42, v116
	v_fma_f32 v117, v122, v106, v117
	v_fma_f32 v118, v122, v107, v118
	v_fma_f32 v117, -v126, v107, v117
	v_fma_f32 v126, v126, v106, v118
	v_mov_b32_e32 v122, v117
	v_mul_f32_e32 v116, v109, v47
	v_fma_f32 v117, v108, v43, -v116
	v_mul_f32_e32 v116, v108, v47
	v_fma_f32 v118, v109, v43, v116
	v_fma_f32 v117, v123, v110, v117
	v_fma_f32 v118, v123, v111, v118
	v_fma_f32 v117, -v127, v111, v117
	v_fma_f32 v127, v127, v110, v118
	v_mov_b32_e32 v123, v117
	v_add_f32_dpp v120, v120, v120 row_ror:8 row_mask:0xf bank_mask:0xf
	v_add_f32_dpp v121, v121, v121 row_ror:8 row_mask:0xf bank_mask:0xf
	v_add_f32_dpp v122, v122, v122 row_ror:8 row_mask:0xf bank_mask:0xf
	v_add_f32_dpp v123, v123, v123 row_ror:8 row_mask:0xf bank_mask:0xf
	v_add_f32_dpp v124, v124, v124 row_ror:8 row_mask:0xf bank_mask:0xf
	v_add_f32_dpp v125, v125, v125 row_ror:8 row_mask:0xf bank_mask:0xf
	v_add_f32_dpp v126, v126, v126 row_ror:8 row_mask:0xf bank_mask:0xf
	v_add_f32_dpp v127, v127, v127 row_ror:8 row_mask:0xf bank_mask:0xf
	v_add_f32_dpp v120, v120, v120 row_ror:4 row_mask:0xf bank_mask:0xf
	v_add_f32_dpp v121, v121, v121 row_ror:4 row_mask:0xf bank_mask:0xf
	v_add_f32_dpp v122, v122, v122 row_ror:4 row_mask:0xf bank_mask:0xf
	v_add_f32_dpp v123, v123, v123 row_ror:4 row_mask:0xf bank_mask:0xf
	v_add_f32_dpp v124, v124, v124 row_ror:4 row_mask:0xf bank_mask:0xf
	v_add_f32_dpp v125, v125, v125 row_ror:4 row_mask:0xf bank_mask:0xf
	v_add_f32_dpp v126, v126, v126 row_ror:4 row_mask:0xf bank_mask:0xf
	v_add_f32_dpp v127, v127, v127 row_ror:4 row_mask:0xf bank_mask:0xf
	v_add_f32_dpp v120, v120, v120 row_ror:2 row_mask:0xf bank_mask:0xf
	v_add_f32_dpp v121, v121, v121 row_ror:2 row_mask:0xf bank_mask:0xf
	v_add_f32_dpp v122, v122, v122 row_ror:2 row_mask:0xf bank_mask:0xf
	v_add_f32_dpp v123, v123, v123 row_ror:2 row_mask:0xf bank_mask:0xf
	v_add_f32_dpp v124, v124, v124 row_ror:2 row_mask:0xf bank_mask:0xf
	v_add_f32_dpp v125, v125, v125 row_ror:2 row_mask:0xf bank_mask:0xf
	v_add_f32_dpp v126, v126, v126 row_ror:2 row_mask:0xf bank_mask:0xf
	v_add_f32_dpp v127, v127, v127 row_ror:2 row_mask:0xf bank_mask:0xf
	v_add_f32_dpp v120, v120, v120 row_ror:1 row_mask:0xf bank_mask:0xf
	v_add_f32_dpp v121, v121, v121 row_ror:1 row_mask:0xf bank_mask:0xf
	v_add_f32_dpp v122, v122, v122 row_ror:1 row_mask:0xf bank_mask:0xf
	v_add_f32_dpp v123, v123, v123 row_ror:1 row_mask:0xf bank_mask:0xf
	v_add_f32_dpp v124, v124, v124 row_ror:1 row_mask:0xf bank_mask:0xf
	v_add_f32_dpp v125, v125, v125 row_ror:1 row_mask:0xf bank_mask:0xf
	v_add_f32_dpp v126, v126, v126 row_ror:1 row_mask:0xf bank_mask:0xf
	v_add_f32_dpp v127, v127, v127 row_ror:1 row_mask:0xf bank_mask:0xf
	s_add_u32 s18, s26, 128
	s_addc_u32 s19, s27, 0
	v_mov_b32_e32 v128, v120
	v_mov_b32_e32 v129, v124
	v_mov_b32_e32 v130, v121
	v_mov_b32_e32 v131, v125
	v_mov_b32_e32 v132, v122
	v_mov_b32_e32 v133, v126
	v_mov_b32_e32 v134, v123
	v_mov_b32_e32 v135, v127
	s_mov_b32 exec_lo, 0x10001
	s_mov_b32 exec_hi, 0x10001
	global_store_dwordx4 v114, v[128:131], s[18:19]
	global_store_dwordx4 v114, v[132:135], s[18:19] offset:16
	s_mov_b64 exec, -1
	s_nop 1
	s_waitcnt vmcnt(4)
	v_cvt_pk_bf16_f32 v48, v48, v49
	v_cvt_pk_bf16_f32 v49, v50, v51
	v_cvt_pk_bf16_f32 v50, v52, v53
	v_cvt_pk_bf16_f32 v51, v54, v55
	v_cvt_pk_bf16_f32 v56, v56, v57
	v_cvt_pk_bf16_f32 v57, v58, v59
	v_cvt_pk_bf16_f32 v58, v60, v61
	v_cvt_pk_bf16_f32 v59, v62, v63
	s_mov_b32 exec_hi, 0
	global_load_dwordx4 v[64:67], v112, s[20:21]
	global_load_dwordx4 v[68:71], v112, s[20:21] offset:16
	global_load_dwordx4 v[72:75], v112, s[22:23]
	global_load_dwordx4 v[76:79], v112, s[22:23] offset:16
	s_mov_b64 exec, -1
	global_load_dwordx4 v[96:99], v113, s[24:25] offset:0
	global_load_dwordx4 v[100:103], v113, s[24:25] offset:1024
	global_load_dwordx4 v[104:107], v113, s[24:25] offset:2048
	global_load_dwordx4 v[108:111], v113, s[24:25] offset:3072
	v_mfma_f32_16x16x32_bf16 v[16:19], v[48:51], v[0:3], 0
	v_mfma_f32_16x16x32_bf16 v[20:23], v[56:59], v[0:3], 0
	v_mfma_f32_16x16x32_bf16 v[24:27], v[48:51], v[4:7], 0
	v_mfma_f32_16x16x32_bf16 v[28:31], v[56:59], v[4:7], 0
	v_mfma_f32_16x16x32_bf16 v[32:35], v[48:51], v[8:11], 0
	v_mfma_f32_16x16x32_bf16 v[36:39], v[56:59], v[8:11], 0
	v_mfma_f32_16x16x32_bf16 v[40:43], v[48:51], v[12:15], 0
	v_mfma_f32_16x16x32_bf16 v[44:47], v[56:59], v[12:15], 0
	s_waitcnt vmcnt(8)
	s_nop 7
	v_mul_f32_e32 v116, v81, v20
	v_fma_f32 v120, v80, v16, -v116
	v_mul_f32_e32 v116, v80, v20
	v_fma_f32 v124, v81, v16, v116
	v_mul_f32_e32 v116, v85, v21
	v_fma_f32 v121, v84, v17, -v116
	v_mul_f32_e32 v116, v84, v21
	v_fma_f32 v125, v85, v17, v116
	v_mul_f32_e32 v116, v89, v22
	v_fma_f32 v122, v88, v18, -v116
	v_mul_f32_e32 v116, v88, v22
	v_fma_f32 v126, v89, v18, v116
	v_mul_f32_e32 v116, v93, v23
	v_fma_f32 v123, v92, v19, -v116
	v_mul_f32_e32 v116, v92, v23
	v_fma_f32 v127, v93, v19, v116
	v_mul_f32_e32 v116, v81, v28
	v_fma_f32 v117, v80, v24, -v116
	v_mul_f32_e32 v116, v80, v28
	v_fma_f32 v118, v81, v24, v116
	v_fma_f32 v117, v120, v82, v117
	v_fma_f32 v118, v120, v83, v118
	v_fma_f32 v117, -v124, v83, v117
	v_fma_f32 v124, v124, v82, v118
	v_mov_b32_e32 v120, v117
	v_mul_f32_e32 v116, v85, v29
	v_fma_f32 v117, v84, v25, -v116
	v_mul_f32_e32 v116, v84, v29
	v_fma_f32 v118, v85, v25, v116
	v_fma_f32 v117, v121, v86, v117
	v_fma_f32 v118, v121, v87, v118
	v_fma_f32 v117, -v125, v87, v117
	v_fma_f32 v125, v125, v86, v118
	v_mov_b32_e32 v121, v117
	v_mul_f32_e32 v116, v89, v30
	v_fma_f32 v117, v88, v26, -v116
	v_mul_f32_e32 v116, v88, v30
	v_fma_f32 v118, v89, v26, v116
	v_fma_f32 v117, v122, v90, v117
	v_fma_f32 v118, v122, v91, v118
	v_fma_f32 v117, -v126, v91, v117
	v_fma_f32 v126, v126, v90, v118
	v_mov_b32_e32 v122, v117
	v_mul_f32_e32 v116, v93, v31
	v_fma_f32 v117, v92, v27, -v116
	v_mul_f32_e32 v116, v92, v31
	v_fma_f32 v118, v93, v27, v116
	v_fma_f32 v117, v123, v94, v117
	v_fma_f32 v118, v123, v95, v118
	v_fma_f32 v117, -v127, v95, v117
	v_fma_f32 v127, v127, v94, v118
	v_mov_b32_e32 v123, v117
	v_mul_f32_e32 v116, v81, v36
	v_fma_f32 v117, v80, v32, -v116
	v_mul_f32_e32 v116, v80, v36
	v_fma_f32 v118, v81, v32, v116
	v_fma_f32 v117, v120, v82, v117
	v_fma_f32 v118, v120, v83, v118
	v_fma_f32 v117, -v124, v83, v117
	v_fma_f32 v124, v124, v82, v118
	v_mov_b32_e32 v120, v117
	v_mul_f32_e32 v116, v85, v37
	v_fma_f32 v117, v84, v33, -v116
	v_mul_f32_e32 v116, v84, v37
	v_fma_f32 v118, v85, v33, v116
	v_fma_f32 v117, v121, v86, v117
	v_fma_f32 v118, v121, v87, v118
	v_fma_f32 v117, -v125, v87, v117
	v_fma_f32 v125, v125, v86, v118
	v_mov_b32_e32 v121, v117
	v_mul_f32_e32 v116, v89, v38
	v_fma_f32 v117, v88, v34, -v116
	v_mul_f32_e32 v116, v88, v38
	v_fma_f32 v118, v89, v34, v116
	v_fma_f32 v117, v122, v90, v117
	v_fma_f32 v118, v122, v91, v118
	v_fma_f32 v117, -v126, v91, v117
	v_fma_f32 v126, v126, v90, v118
	v_mov_b32_e32 v122, v117
	v_mul_f32_e32 v116, v93, v39
	v_fma_f32 v117, v92, v35, -v116
	v_mul_f32_e32 v116, v92, v39
	v_fma_f32 v118, v93, v35, v116
	v_fma_f32 v117, v123, v94, v117
	v_fma_f32 v118, v123, v95, v118
	v_fma_f32 v117, -v127, v95, v117
	v_fma_f32 v127, v127, v94, v118
	v_mov_b32_e32 v123, v117
	v_mul_f32_e32 v116, v81, v44
	v_fma_f32 v117, v80, v40, -v116
	v_mul_f32_e32 v116, v80, v44
	v_fma_f32 v118, v81, v40, v116
	v_fma_f32 v117, v120, v82, v117
	v_fma_f32 v118, v120, v83, v118
	v_fma_f32 v117, -v124, v83, v117
	v_fma_f32 v124, v124, v82, v118
	v_mov_b32_e32 v120, v117
	v_mul_f32_e32 v116, v85, v45
	v_fma_f32 v117, v84, v41, -v116
	v_mul_f32_e32 v116, v84, v45
	v_fma_f32 v118, v85, v41, v116
	v_fma_f32 v117, v121, v86, v117
	v_fma_f32 v118, v121, v87, v118
	v_fma_f32 v117, -v125, v87, v117
	v_fma_f32 v125, v125, v86, v118
	v_mov_b32_e32 v121, v117
	v_mul_f32_e32 v116, v89, v46
	v_fma_f32 v117, v88, v42, -v116
	v_mul_f32_e32 v116, v88, v46
	v_fma_f32 v118, v89, v42, v116
	v_fma_f32 v117, v122, v90, v117
	v_fma_f32 v118, v122, v91, v118
	v_fma_f32 v117, -v126, v91, v117
	v_fma_f32 v126, v126, v90, v118
	v_mov_b32_e32 v122, v117
	v_mul_f32_e32 v116, v93, v47
	v_fma_f32 v117, v92, v43, -v116
	v_mul_f32_e32 v116, v92, v47
	v_fma_f32 v118, v93, v43, v116
	v_fma_f32 v117, v123, v94, v117
	v_fma_f32 v118, v123, v95, v118
	v_fma_f32 v117, -v127, v95, v117
	v_fma_f32 v127, v127, v94, v118
	v_mov_b32_e32 v123, v117
	v_add_f32_dpp v120, v120, v120 row_ror:8 row_mask:0xf bank_mask:0xf
	v_add_f32_dpp v121, v121, v121 row_ror:8 row_mask:0xf bank_mask:0xf
	v_add_f32_dpp v122, v122, v122 row_ror:8 row_mask:0xf bank_mask:0xf
	v_add_f32_dpp v123, v123, v123 row_ror:8 row_mask:0xf bank_mask:0xf
	v_add_f32_dpp v124, v124, v124 row_ror:8 row_mask:0xf bank_mask:0xf
	v_add_f32_dpp v125, v125, v125 row_ror:8 row_mask:0xf bank_mask:0xf
	v_add_f32_dpp v126, v126, v126 row_ror:8 row_mask:0xf bank_mask:0xf
	v_add_f32_dpp v127, v127, v127 row_ror:8 row_mask:0xf bank_mask:0xf
	v_add_f32_dpp v120, v120, v120 row_ror:4 row_mask:0xf bank_mask:0xf
	v_add_f32_dpp v121, v121, v121 row_ror:4 row_mask:0xf bank_mask:0xf
	v_add_f32_dpp v122, v122, v122 row_ror:4 row_mask:0xf bank_mask:0xf
	v_add_f32_dpp v123, v123, v123 row_ror:4 row_mask:0xf bank_mask:0xf
	v_add_f32_dpp v124, v124, v124 row_ror:4 row_mask:0xf bank_mask:0xf
	v_add_f32_dpp v125, v125, v125 row_ror:4 row_mask:0xf bank_mask:0xf
	v_add_f32_dpp v126, v126, v126 row_ror:4 row_mask:0xf bank_mask:0xf
	v_add_f32_dpp v127, v127, v127 row_ror:4 row_mask:0xf bank_mask:0xf
	v_add_f32_dpp v120, v120, v120 row_ror:2 row_mask:0xf bank_mask:0xf
	v_add_f32_dpp v121, v121, v121 row_ror:2 row_mask:0xf bank_mask:0xf
	v_add_f32_dpp v122, v122, v122 row_ror:2 row_mask:0xf bank_mask:0xf
	v_add_f32_dpp v123, v123, v123 row_ror:2 row_mask:0xf bank_mask:0xf
	v_add_f32_dpp v124, v124, v124 row_ror:2 row_mask:0xf bank_mask:0xf
	v_add_f32_dpp v125, v125, v125 row_ror:2 row_mask:0xf bank_mask:0xf
	v_add_f32_dpp v126, v126, v126 row_ror:2 row_mask:0xf bank_mask:0xf
	v_add_f32_dpp v127, v127, v127 row_ror:2 row_mask:0xf bank_mask:0xf
	v_add_f32_dpp v120, v120, v120 row_ror:1 row_mask:0xf bank_mask:0xf
	v_add_f32_dpp v121, v121, v121 row_ror:1 row_mask:0xf bank_mask:0xf
	v_add_f32_dpp v122, v122, v122 row_ror:1 row_mask:0xf bank_mask:0xf
	v_add_f32_dpp v123, v123, v123 row_ror:1 row_mask:0xf bank_mask:0xf
	v_add_f32_dpp v124, v124, v124 row_ror:1 row_mask:0xf bank_mask:0xf
	v_add_f32_dpp v125, v125, v125 row_ror:1 row_mask:0xf bank_mask:0xf
	v_add_f32_dpp v126, v126, v126 row_ror:1 row_mask:0xf bank_mask:0xf
	v_add_f32_dpp v127, v127, v127 row_ror:1 row_mask:0xf bank_mask:0xf
	s_add_u32 s18, s26, 256
	s_addc_u32 s19, s27, 0
	v_mov_b32_e32 v128, v120
	v_mov_b32_e32 v129, v124
	v_mov_b32_e32 v130, v121
	v_mov_b32_e32 v131, v125
	v_mov_b32_e32 v132, v122
	v_mov_b32_e32 v133, v126
	v_mov_b32_e32 v134, v123
	v_mov_b32_e32 v135, v127
	s_mov_b32 exec_lo, 0x10001
	s_mov_b32 exec_hi, 0x10001
	global_store_dwordx4 v114, v[128:131], s[18:19]
	global_store_dwordx4 v114, v[132:135], s[18:19] offset:16
	s_mov_b64 exec, -1
	s_nop 1
	s_waitcnt vmcnt(4)
	v_cvt_pk_bf16_f32 v64, v64, v65
	v_cvt_pk_bf16_f32 v65, v66, v67
	v_cvt_pk_bf16_f32 v66, v68, v69
	v_cvt_pk_bf16_f32 v67, v70, v71
	v_cvt_pk_bf16_f32 v72, v72, v73
	v_cvt_pk_bf16_f32 v73, v74, v75
	v_cvt_pk_bf16_f32 v74, v76, v77
	v_cvt_pk_bf16_f32 v75, v78, v79
	v_readlane_b32 s10, v247, 28
	s_sub_i32 s11, 3, s8
	s_sub_i32 s17, 71, s8
	s_cmp_lt_u32 s8, 4
	s_cselect_b32 s11, s11, s17
	s_lshl_b32 s16, s10, 1
	s_add_i32 s16, s16, 1
	s_lshl_b32 s16, s16, 4
	s_add_i32 s16, s16, s7
	s_lshl_b32 s17, s6, 1
	s_add_i32 s17, s17, 1
	s_lshl_b32 s17, s17, 4
	s_add_i32 s17, s17, s7
	s_mul_i32 s17, s17, 68
	s_add_i32 s17, s17, s11
	s_lshl_b32 s17, s17, 6
	s_lshl_b32 s20, s16, 12
	s_add_u32 s20, s20, 0x11fb20
	s_add_u32 s20, s4, s20
	s_addc_u32 s21, s5, 0
	s_add_u32 s22, s20, 0x40000
	s_addc_u32 s23, s21, 0
	s_lshl_b32 s24, s16, 14
	s_add_u32 s24, s24, 0xfc00000
	s_add_u32 s24, s4, s24
	s_addc_u32 s25, s5, 0
	s_lshl_b32 s36, s17, 3
	s_add_u32 s36, s36, 0x300000
	s_add_u32 s36, s4, s36
	s_addc_u32 s37, s5, 0
	s_mov_b32 exec_hi, 0
	global_load_dwordx4 v[48:51], v112, s[20:21]
	global_load_dwordx4 v[52:55], v112, s[20:21] offset:16
	global_load_dwordx4 v[56:59], v112, s[22:23]
	global_load_dwordx4 v[60:63], v112, s[22:23] offset:16
	s_mov_b64 exec, -1
	global_load_dwordx4 v[80:83], v113, s[24:25] offset:0
	global_load_dwordx4 v[84:87], v113, s[24:25] offset:1024
	global_load_dwordx4 v[88:91], v113, s[24:25] offset:2048
	global_load_dwordx4 v[92:95], v113, s[24:25] offset:3072
	s_add_u32 s20, s20, 0x400
	s_addc_u32 s21, s21, 0
	s_add_u32 s22, s22, 0x400
	s_addc_u32 s23, s23, 0
	s_add_u32 s24, s24, 0x1000
	s_addc_u32 s25, s25, 0
	v_mfma_f32_16x16x32_bf16 v[16:19], v[64:67], v[0:3], 0
	v_mfma_f32_16x16x32_bf16 v[20:23], v[72:75], v[0:3], 0
	v_mfma_f32_16x16x32_bf16 v[24:27], v[64:67], v[4:7], 0
	v_mfma_f32_16x16x32_bf16 v[28:31], v[72:75], v[4:7], 0
	v_mfma_f32_16x16x32_bf16 v[32:35], v[64:67], v[8:11], 0
	v_mfma_f32_16x16x32_bf16 v[36:39], v[72:75], v[8:11], 0
	v_mfma_f32_16x16x32_bf16 v[40:43], v[64:67], v[12:15], 0
	v_mfma_f32_16x16x32_bf16 v[44:47], v[72:75], v[12:15], 0
	s_waitcnt vmcnt(8)
	s_nop 7
	v_mul_f32_e32 v116, v97, v20
	v_fma_f32 v120, v96, v16, -v116
	v_mul_f32_e32 v116, v96, v20
	v_fma_f32 v124, v97, v16, v116
	v_mul_f32_e32 v116, v101, v21
	v_fma_f32 v121, v100, v17, -v116
	v_mul_f32_e32 v116, v100, v21
	v_fma_f32 v125, v101, v17, v116
	v_mul_f32_e32 v116, v105, v22
	v_fma_f32 v122, v104, v18, -v116
	v_mul_f32_e32 v116, v104, v22
	v_fma_f32 v126, v105, v18, v116
	v_mul_f32_e32 v116, v109, v23
	v_fma_f32 v123, v108, v19, -v116
	v_mul_f32_e32 v116, v108, v23
	v_fma_f32 v127, v109, v19, v116
	v_mul_f32_e32 v116, v97, v28
	v_fma_f32 v117, v96, v24, -v116
	v_mul_f32_e32 v116, v96, v28
	v_fma_f32 v118, v97, v24, v116
	v_fma_f32 v117, v120, v98, v117
	v_fma_f32 v118, v120, v99, v118
	v_fma_f32 v117, -v124, v99, v117
	v_fma_f32 v124, v124, v98, v118
	v_mov_b32_e32 v120, v117
	v_mul_f32_e32 v116, v101, v29
	v_fma_f32 v117, v100, v25, -v116
	v_mul_f32_e32 v116, v100, v29
	v_fma_f32 v118, v101, v25, v116
	v_fma_f32 v117, v121, v102, v117
	v_fma_f32 v118, v121, v103, v118
	v_fma_f32 v117, -v125, v103, v117
	v_fma_f32 v125, v125, v102, v118
	v_mov_b32_e32 v121, v117
	v_mul_f32_e32 v116, v105, v30
	v_fma_f32 v117, v104, v26, -v116
	v_mul_f32_e32 v116, v104, v30
	v_fma_f32 v118, v105, v26, v116
	v_fma_f32 v117, v122, v106, v117
	v_fma_f32 v118, v122, v107, v118
	v_fma_f32 v117, -v126, v107, v117
	v_fma_f32 v126, v126, v106, v118
	v_mov_b32_e32 v122, v117
	v_mul_f32_e32 v116, v109, v31
	v_fma_f32 v117, v108, v27, -v116
	v_mul_f32_e32 v116, v108, v31
	v_fma_f32 v118, v109, v27, v116
	v_fma_f32 v117, v123, v110, v117
	v_fma_f32 v118, v123, v111, v118
	v_fma_f32 v117, -v127, v111, v117
	v_fma_f32 v127, v127, v110, v118
	v_mov_b32_e32 v123, v117
	v_mul_f32_e32 v116, v97, v36
	v_fma_f32 v117, v96, v32, -v116
	v_mul_f32_e32 v116, v96, v36
	v_fma_f32 v118, v97, v32, v116
	v_fma_f32 v117, v120, v98, v117
	v_fma_f32 v118, v120, v99, v118
	v_fma_f32 v117, -v124, v99, v117
	v_fma_f32 v124, v124, v98, v118
	v_mov_b32_e32 v120, v117
	v_mul_f32_e32 v116, v101, v37
	v_fma_f32 v117, v100, v33, -v116
	v_mul_f32_e32 v116, v100, v37
	v_fma_f32 v118, v101, v33, v116
	v_fma_f32 v117, v121, v102, v117
	v_fma_f32 v118, v121, v103, v118
	v_fma_f32 v117, -v125, v103, v117
	v_fma_f32 v125, v125, v102, v118
	v_mov_b32_e32 v121, v117
	v_mul_f32_e32 v116, v105, v38
	v_fma_f32 v117, v104, v34, -v116
	v_mul_f32_e32 v116, v104, v38
	v_fma_f32 v118, v105, v34, v116
	v_fma_f32 v117, v122, v106, v117
	v_fma_f32 v118, v122, v107, v118
	v_fma_f32 v117, -v126, v107, v117
	v_fma_f32 v126, v126, v106, v118
	v_mov_b32_e32 v122, v117
	v_mul_f32_e32 v116, v109, v39
	v_fma_f32 v117, v108, v35, -v116
	v_mul_f32_e32 v116, v108, v39
	v_fma_f32 v118, v109, v35, v116
	v_fma_f32 v117, v123, v110, v117
	v_fma_f32 v118, v123, v111, v118
	v_fma_f32 v117, -v127, v111, v117
	v_fma_f32 v127, v127, v110, v118
	v_mov_b32_e32 v123, v117
	v_mul_f32_e32 v116, v97, v44
	v_fma_f32 v117, v96, v40, -v116
	v_mul_f32_e32 v116, v96, v44
	v_fma_f32 v118, v97, v40, v116
	v_fma_f32 v117, v120, v98, v117
	v_fma_f32 v118, v120, v99, v118
	v_fma_f32 v117, -v124, v99, v117
	v_fma_f32 v124, v124, v98, v118
	v_mov_b32_e32 v120, v117
	v_mul_f32_e32 v116, v101, v45
	v_fma_f32 v117, v100, v41, -v116
	v_mul_f32_e32 v116, v100, v45
	v_fma_f32 v118, v101, v41, v116
	v_fma_f32 v117, v121, v102, v117
	v_fma_f32 v118, v121, v103, v118
	v_fma_f32 v117, -v125, v103, v117
	v_fma_f32 v125, v125, v102, v118
	v_mov_b32_e32 v121, v117
	v_mul_f32_e32 v116, v105, v46
	v_fma_f32 v117, v104, v42, -v116
	v_mul_f32_e32 v116, v104, v46
	v_fma_f32 v118, v105, v42, v116
	v_fma_f32 v117, v122, v106, v117
	v_fma_f32 v118, v122, v107, v118
	v_fma_f32 v117, -v126, v107, v117
	v_fma_f32 v126, v126, v106, v118
	v_mov_b32_e32 v122, v117
	v_mul_f32_e32 v116, v109, v47
	v_fma_f32 v117, v108, v43, -v116
	v_mul_f32_e32 v116, v108, v47
	v_fma_f32 v118, v109, v43, v116
	v_fma_f32 v117, v123, v110, v117
	v_fma_f32 v118, v123, v111, v118
	v_fma_f32 v117, -v127, v111, v117
	v_fma_f32 v127, v127, v110, v118
	v_mov_b32_e32 v123, v117
	v_add_f32_dpp v120, v120, v120 row_ror:8 row_mask:0xf bank_mask:0xf
	v_add_f32_dpp v121, v121, v121 row_ror:8 row_mask:0xf bank_mask:0xf
	v_add_f32_dpp v122, v122, v122 row_ror:8 row_mask:0xf bank_mask:0xf
	v_add_f32_dpp v123, v123, v123 row_ror:8 row_mask:0xf bank_mask:0xf
	v_add_f32_dpp v124, v124, v124 row_ror:8 row_mask:0xf bank_mask:0xf
	v_add_f32_dpp v125, v125, v125 row_ror:8 row_mask:0xf bank_mask:0xf
	v_add_f32_dpp v126, v126, v126 row_ror:8 row_mask:0xf bank_mask:0xf
	v_add_f32_dpp v127, v127, v127 row_ror:8 row_mask:0xf bank_mask:0xf
	v_add_f32_dpp v120, v120, v120 row_ror:4 row_mask:0xf bank_mask:0xf
	v_add_f32_dpp v121, v121, v121 row_ror:4 row_mask:0xf bank_mask:0xf
	v_add_f32_dpp v122, v122, v122 row_ror:4 row_mask:0xf bank_mask:0xf
	v_add_f32_dpp v123, v123, v123 row_ror:4 row_mask:0xf bank_mask:0xf
	v_add_f32_dpp v124, v124, v124 row_ror:4 row_mask:0xf bank_mask:0xf
	v_add_f32_dpp v125, v125, v125 row_ror:4 row_mask:0xf bank_mask:0xf
	v_add_f32_dpp v126, v126, v126 row_ror:4 row_mask:0xf bank_mask:0xf
	v_add_f32_dpp v127, v127, v127 row_ror:4 row_mask:0xf bank_mask:0xf
	v_add_f32_dpp v120, v120, v120 row_ror:2 row_mask:0xf bank_mask:0xf
	v_add_f32_dpp v121, v121, v121 row_ror:2 row_mask:0xf bank_mask:0xf
	v_add_f32_dpp v122, v122, v122 row_ror:2 row_mask:0xf bank_mask:0xf
	v_add_f32_dpp v123, v123, v123 row_ror:2 row_mask:0xf bank_mask:0xf
	v_add_f32_dpp v124, v124, v124 row_ror:2 row_mask:0xf bank_mask:0xf
	v_add_f32_dpp v125, v125, v125 row_ror:2 row_mask:0xf bank_mask:0xf
	v_add_f32_dpp v126, v126, v126 row_ror:2 row_mask:0xf bank_mask:0xf
	v_add_f32_dpp v127, v127, v127 row_ror:2 row_mask:0xf bank_mask:0xf
	v_add_f32_dpp v120, v120, v120 row_ror:1 row_mask:0xf bank_mask:0xf
	v_add_f32_dpp v121, v121, v121 row_ror:1 row_mask:0xf bank_mask:0xf
	v_add_f32_dpp v122, v122, v122 row_ror:1 row_mask:0xf bank_mask:0xf
	v_add_f32_dpp v123, v123, v123 row_ror:1 row_mask:0xf bank_mask:0xf
	v_add_f32_dpp v124, v124, v124 row_ror:1 row_mask:0xf bank_mask:0xf
	v_add_f32_dpp v125, v125, v125 row_ror:1 row_mask:0xf bank_mask:0xf
	v_add_f32_dpp v126, v126, v126 row_ror:1 row_mask:0xf bank_mask:0xf
	v_add_f32_dpp v127, v127, v127 row_ror:1 row_mask:0xf bank_mask:0xf
	s_add_u32 s18, s26, 384
	s_addc_u32 s19, s27, 0
	v_mov_b32_e32 v128, v120
	v_mov_b32_e32 v129, v124
	v_mov_b32_e32 v130, v121
	v_mov_b32_e32 v131, v125
	v_mov_b32_e32 v132, v122
	v_mov_b32_e32 v133, v126
	v_mov_b32_e32 v134, v123
	v_mov_b32_e32 v135, v127
	s_mov_b32 exec_lo, 0x10001
	s_mov_b32 exec_hi, 0x10001
	global_store_dwordx4 v114, v[128:131], s[18:19]
	global_store_dwordx4 v114, v[132:135], s[18:19] offset:16
	s_mov_b64 exec, -1
	s_nop 1
	s_waitcnt vmcnt(4)
	v_cvt_pk_bf16_f32 v48, v48, v49
	v_cvt_pk_bf16_f32 v49, v50, v51
	v_cvt_pk_bf16_f32 v50, v52, v53
	v_cvt_pk_bf16_f32 v51, v54, v55
	v_cvt_pk_bf16_f32 v56, v56, v57
	v_cvt_pk_bf16_f32 v57, v58, v59
	v_cvt_pk_bf16_f32 v58, v60, v61
	v_cvt_pk_bf16_f32 v59, v62, v63
	s_mov_b32 exec_hi, 0
	global_load_dwordx4 v[64:67], v112, s[20:21]
	global_load_dwordx4 v[68:71], v112, s[20:21] offset:16
	global_load_dwordx4 v[72:75], v112, s[22:23]
	global_load_dwordx4 v[76:79], v112, s[22:23] offset:16
	s_mov_b64 exec, -1
	global_load_dwordx4 v[96:99], v113, s[24:25] offset:0
	global_load_dwordx4 v[100:103], v113, s[24:25] offset:1024
	global_load_dwordx4 v[104:107], v113, s[24:25] offset:2048
	global_load_dwordx4 v[108:111], v113, s[24:25] offset:3072
	s_add_u32 s20, s20, 0x400
	s_addc_u32 s21, s21, 0
	s_add_u32 s22, s22, 0x400
	s_addc_u32 s23, s23, 0
	s_add_u32 s24, s24, 0x1000
	s_addc_u32 s25, s25, 0
	v_mfma_f32_16x16x32_bf16 v[16:19], v[48:51], v[0:3], 0
	v_mfma_f32_16x16x32_bf16 v[20:23], v[56:59], v[0:3], 0
	v_mfma_f32_16x16x32_bf16 v[24:27], v[48:51], v[4:7], 0
	v_mfma_f32_16x16x32_bf16 v[28:31], v[56:59], v[4:7], 0
	v_mfma_f32_16x16x32_bf16 v[32:35], v[48:51], v[8:11], 0
	v_mfma_f32_16x16x32_bf16 v[36:39], v[56:59], v[8:11], 0
	v_mfma_f32_16x16x32_bf16 v[40:43], v[48:51], v[12:15], 0
	v_mfma_f32_16x16x32_bf16 v[44:47], v[56:59], v[12:15], 0
	s_waitcnt vmcnt(8)
	s_nop 7
	v_mul_f32_e32 v116, v81, v44
	v_fma_f32 v120, v80, v40, -v116
	v_mul_f32_e32 v116, v80, v44
	v_fma_f32 v124, v81, v40, v116
	v_mul_f32_e32 v116, v85, v45
	v_fma_f32 v121, v84, v41, -v116
	v_mul_f32_e32 v116, v84, v45
	v_fma_f32 v125, v85, v41, v116
	v_mul_f32_e32 v116, v89, v46
	v_fma_f32 v122, v88, v42, -v116
	v_mul_f32_e32 v116, v88, v46
	v_fma_f32 v126, v89, v42, v116
	v_mul_f32_e32 v116, v93, v47
	v_fma_f32 v123, v92, v43, -v116
	v_mul_f32_e32 v116, v92, v47
	v_fma_f32 v127, v93, v43, v116
	v_mul_f32_e32 v116, v81, v36
	v_fma_f32 v117, v80, v32, -v116
	v_mul_f32_e32 v116, v80, v36
	v_fma_f32 v118, v81, v32, v116
	v_fma_f32 v117, v120, v82, v117
	v_fma_f32 v118, v120, v83, v118
	v_fma_f32 v117, -v124, v83, v117
	v_fma_f32 v124, v124, v82, v118
	v_mov_b32_e32 v120, v117
	v_mul_f32_e32 v116, v85, v37
	v_fma_f32 v117, v84, v33, -v116
	v_mul_f32_e32 v116, v84, v37
	v_fma_f32 v118, v85, v33, v116
	v_fma_f32 v117, v121, v86, v117
	v_fma_f32 v118, v121, v87, v118
	v_fma_f32 v117, -v125, v87, v117
	v_fma_f32 v125, v125, v86, v118
	v_mov_b32_e32 v121, v117
	v_mul_f32_e32 v116, v89, v38
	v_fma_f32 v117, v88, v34, -v116
	v_mul_f32_e32 v116, v88, v38
	v_fma_f32 v118, v89, v34, v116
	v_fma_f32 v117, v122, v90, v117
	v_fma_f32 v118, v122, v91, v118
	v_fma_f32 v117, -v126, v91, v117
	v_fma_f32 v126, v126, v90, v118
	v_mov_b32_e32 v122, v117
	v_mul_f32_e32 v116, v93, v39
	v_fma_f32 v117, v92, v35, -v116
	v_mul_f32_e32 v116, v92, v39
	v_fma_f32 v118, v93, v35, v116
	v_fma_f32 v117, v123, v94, v117
	v_fma_f32 v118, v123, v95, v118
	v_fma_f32 v117, -v127, v95, v117
	v_fma_f32 v127, v127, v94, v118
	v_mov_b32_e32 v123, v117
	v_mul_f32_e32 v116, v81, v28
	v_fma_f32 v117, v80, v24, -v116
	v_mul_f32_e32 v116, v80, v28
	v_fma_f32 v118, v81, v24, v116
	v_fma_f32 v117, v120, v82, v117
	v_fma_f32 v118, v120, v83, v118
	v_fma_f32 v117, -v124, v83, v117
	v_fma_f32 v124, v124, v82, v118
	v_mov_b32_e32 v120, v117
	v_mul_f32_e32 v116, v85, v29
	v_fma_f32 v117, v84, v25, -v116
	v_mul_f32_e32 v116, v84, v29
	v_fma_f32 v118, v85, v25, v116
	v_fma_f32 v117, v121, v86, v117
	v_fma_f32 v118, v121, v87, v118
	v_fma_f32 v117, -v125, v87, v117
	v_fma_f32 v125, v125, v86, v118
	v_mov_b32_e32 v121, v117
	v_mul_f32_e32 v116, v89, v30
	v_fma_f32 v117, v88, v26, -v116
	v_mul_f32_e32 v116, v88, v30
	v_fma_f32 v118, v89, v26, v116
	v_fma_f32 v117, v122, v90, v117
	v_fma_f32 v118, v122, v91, v118
	v_fma_f32 v117, -v126, v91, v117
	v_fma_f32 v126, v126, v90, v118
	v_mov_b32_e32 v122, v117
	v_mul_f32_e32 v116, v93, v31
	v_fma_f32 v117, v92, v27, -v116
	v_mul_f32_e32 v116, v92, v31
	v_fma_f32 v118, v93, v27, v116
	v_fma_f32 v117, v123, v94, v117
	v_fma_f32 v118, v123, v95, v118
	v_fma_f32 v117, -v127, v95, v117
	v_fma_f32 v127, v127, v94, v118
	v_mov_b32_e32 v123, v117
	v_mul_f32_e32 v116, v81, v20
	v_fma_f32 v117, v80, v16, -v116
	v_mul_f32_e32 v116, v80, v20
	v_fma_f32 v118, v81, v16, v116
	v_fma_f32 v117, v120, v82, v117
	v_fma_f32 v118, v120, v83, v118
	v_fma_f32 v117, -v124, v83, v117
	v_fma_f32 v124, v124, v82, v118
	v_mov_b32_e32 v120, v117
	v_mul_f32_e32 v116, v85, v21
	v_fma_f32 v117, v84, v17, -v116
	v_mul_f32_e32 v116, v84, v21
	v_fma_f32 v118, v85, v17, v116
	v_fma_f32 v117, v121, v86, v117
	v_fma_f32 v118, v121, v87, v118
	v_fma_f32 v117, -v125, v87, v117
	v_fma_f32 v125, v125, v86, v118
	v_mov_b32_e32 v121, v117
	v_mul_f32_e32 v116, v89, v22
	v_fma_f32 v117, v88, v18, -v116
	v_mul_f32_e32 v116, v88, v22
	v_fma_f32 v118, v89, v18, v116
	v_fma_f32 v117, v122, v90, v117
	v_fma_f32 v118, v122, v91, v118
	v_fma_f32 v117, -v126, v91, v117
	v_fma_f32 v126, v126, v90, v118
	v_mov_b32_e32 v122, v117
	v_mul_f32_e32 v116, v93, v23
	v_fma_f32 v117, v92, v19, -v116
	v_mul_f32_e32 v116, v92, v23
	v_fma_f32 v118, v93, v19, v116
	v_fma_f32 v117, v123, v94, v117
	v_fma_f32 v118, v123, v95, v118
	v_fma_f32 v117, -v127, v95, v117
	v_fma_f32 v127, v127, v94, v118
	v_mov_b32_e32 v123, v117
	v_add_f32_dpp v120, v120, v120 row_ror:8 row_mask:0xf bank_mask:0xf
	v_add_f32_dpp v121, v121, v121 row_ror:8 row_mask:0xf bank_mask:0xf
	v_add_f32_dpp v122, v122, v122 row_ror:8 row_mask:0xf bank_mask:0xf
	v_add_f32_dpp v123, v123, v123 row_ror:8 row_mask:0xf bank_mask:0xf
	v_add_f32_dpp v124, v124, v124 row_ror:8 row_mask:0xf bank_mask:0xf
	v_add_f32_dpp v125, v125, v125 row_ror:8 row_mask:0xf bank_mask:0xf
	v_add_f32_dpp v126, v126, v126 row_ror:8 row_mask:0xf bank_mask:0xf
	v_add_f32_dpp v127, v127, v127 row_ror:8 row_mask:0xf bank_mask:0xf
	v_add_f32_dpp v120, v120, v120 row_ror:4 row_mask:0xf bank_mask:0xf
	v_add_f32_dpp v121, v121, v121 row_ror:4 row_mask:0xf bank_mask:0xf
	v_add_f32_dpp v122, v122, v122 row_ror:4 row_mask:0xf bank_mask:0xf
	v_add_f32_dpp v123, v123, v123 row_ror:4 row_mask:0xf bank_mask:0xf
	v_add_f32_dpp v124, v124, v124 row_ror:4 row_mask:0xf bank_mask:0xf
	v_add_f32_dpp v125, v125, v125 row_ror:4 row_mask:0xf bank_mask:0xf
	v_add_f32_dpp v126, v126, v126 row_ror:4 row_mask:0xf bank_mask:0xf
	v_add_f32_dpp v127, v127, v127 row_ror:4 row_mask:0xf bank_mask:0xf
	v_add_f32_dpp v120, v120, v120 row_ror:2 row_mask:0xf bank_mask:0xf
	v_add_f32_dpp v121, v121, v121 row_ror:2 row_mask:0xf bank_mask:0xf
	v_add_f32_dpp v122, v122, v122 row_ror:2 row_mask:0xf bank_mask:0xf
	v_add_f32_dpp v123, v123, v123 row_ror:2 row_mask:0xf bank_mask:0xf
	v_add_f32_dpp v124, v124, v124 row_ror:2 row_mask:0xf bank_mask:0xf
	v_add_f32_dpp v125, v125, v125 row_ror:2 row_mask:0xf bank_mask:0xf
	v_add_f32_dpp v126, v126, v126 row_ror:2 row_mask:0xf bank_mask:0xf
	v_add_f32_dpp v127, v127, v127 row_ror:2 row_mask:0xf bank_mask:0xf
	v_add_f32_dpp v120, v120, v120 row_ror:1 row_mask:0xf bank_mask:0xf
	v_add_f32_dpp v121, v121, v121 row_ror:1 row_mask:0xf bank_mask:0xf
	v_add_f32_dpp v122, v122, v122 row_ror:1 row_mask:0xf bank_mask:0xf
	v_add_f32_dpp v123, v123, v123 row_ror:1 row_mask:0xf bank_mask:0xf
	v_add_f32_dpp v124, v124, v124 row_ror:1 row_mask:0xf bank_mask:0xf
	v_add_f32_dpp v125, v125, v125 row_ror:1 row_mask:0xf bank_mask:0xf
	v_add_f32_dpp v126, v126, v126 row_ror:1 row_mask:0xf bank_mask:0xf
	v_add_f32_dpp v127, v127, v127 row_ror:1 row_mask:0xf bank_mask:0xf
	s_add_u32 s18, s36, 0
	s_addc_u32 s19, s37, 0
	v_mov_b32_e32 v128, v120
	v_mov_b32_e32 v129, v124
	v_mov_b32_e32 v130, v121
	v_mov_b32_e32 v131, v125
	v_mov_b32_e32 v132, v122
	v_mov_b32_e32 v133, v126
	v_mov_b32_e32 v134, v123
	v_mov_b32_e32 v135, v127
	s_mov_b32 exec_lo, 0x10001
	s_mov_b32 exec_hi, 0x10001
	global_store_dwordx4 v114, v[128:131], s[18:19]
	global_store_dwordx4 v114, v[132:135], s[18:19] offset:16
	s_mov_b64 exec, -1
	s_nop 1
	s_waitcnt vmcnt(4)
	v_cvt_pk_bf16_f32 v64, v64, v65
	v_cvt_pk_bf16_f32 v65, v66, v67
	v_cvt_pk_bf16_f32 v66, v68, v69
	v_cvt_pk_bf16_f32 v67, v70, v71
	v_cvt_pk_bf16_f32 v72, v72, v73
	v_cvt_pk_bf16_f32 v73, v74, v75
	v_cvt_pk_bf16_f32 v74, v76, v77
	v_cvt_pk_bf16_f32 v75, v78, v79
	s_mov_b32 exec_hi, 0
	global_load_dwordx4 v[48:51], v112, s[20:21]
	global_load_dwordx4 v[52:55], v112, s[20:21] offset:16
	global_load_dwordx4 v[56:59], v112, s[22:23]
	global_load_dwordx4 v[60:63], v112, s[22:23] offset:16
	s_mov_b64 exec, -1
	global_load_dwordx4 v[80:83], v113, s[24:25] offset:0
	global_load_dwordx4 v[84:87], v113, s[24:25] offset:1024
	global_load_dwordx4 v[88:91], v113, s[24:25] offset:2048
	global_load_dwordx4 v[92:95], v113, s[24:25] offset:3072
	s_add_u32 s20, s20, 0x400
	s_addc_u32 s21, s21, 0
	s_add_u32 s22, s22, 0x400
	s_addc_u32 s23, s23, 0
	s_add_u32 s24, s24, 0x1000
	s_addc_u32 s25, s25, 0
	v_mfma_f32_16x16x32_bf16 v[16:19], v[64:67], v[0:3], 0
	v_mfma_f32_16x16x32_bf16 v[20:23], v[72:75], v[0:3], 0
	v_mfma_f32_16x16x32_bf16 v[24:27], v[64:67], v[4:7], 0
	v_mfma_f32_16x16x32_bf16 v[28:31], v[72:75], v[4:7], 0
	v_mfma_f32_16x16x32_bf16 v[32:35], v[64:67], v[8:11], 0
	v_mfma_f32_16x16x32_bf16 v[36:39], v[72:75], v[8:11], 0
	v_mfma_f32_16x16x32_bf16 v[40:43], v[64:67], v[12:15], 0
	v_mfma_f32_16x16x32_bf16 v[44:47], v[72:75], v[12:15], 0
	s_waitcnt vmcnt(8)
	s_nop 7
	v_mul_f32_e32 v116, v97, v44
	v_fma_f32 v120, v96, v40, -v116
	v_mul_f32_e32 v116, v96, v44
	v_fma_f32 v124, v97, v40, v116
	v_mul_f32_e32 v116, v101, v45
	v_fma_f32 v121, v100, v41, -v116
	v_mul_f32_e32 v116, v100, v45
	v_fma_f32 v125, v101, v41, v116
	v_mul_f32_e32 v116, v105, v46
	v_fma_f32 v122, v104, v42, -v116
	v_mul_f32_e32 v116, v104, v46
	v_fma_f32 v126, v105, v42, v116
	v_mul_f32_e32 v116, v109, v47
	v_fma_f32 v123, v108, v43, -v116
	v_mul_f32_e32 v116, v108, v47
	v_fma_f32 v127, v109, v43, v116
	v_mul_f32_e32 v116, v97, v36
	v_fma_f32 v117, v96, v32, -v116
	v_mul_f32_e32 v116, v96, v36
	v_fma_f32 v118, v97, v32, v116
	v_fma_f32 v117, v120, v98, v117
	v_fma_f32 v118, v120, v99, v118
	v_fma_f32 v117, -v124, v99, v117
	v_fma_f32 v124, v124, v98, v118
	v_mov_b32_e32 v120, v117
	v_mul_f32_e32 v116, v101, v37
	v_fma_f32 v117, v100, v33, -v116
	v_mul_f32_e32 v116, v100, v37
	v_fma_f32 v118, v101, v33, v116
	v_fma_f32 v117, v121, v102, v117
	v_fma_f32 v118, v121, v103, v118
	v_fma_f32 v117, -v125, v103, v117
	v_fma_f32 v125, v125, v102, v118
	v_mov_b32_e32 v121, v117
	v_mul_f32_e32 v116, v105, v38
	v_fma_f32 v117, v104, v34, -v116
	v_mul_f32_e32 v116, v104, v38
	v_fma_f32 v118, v105, v34, v116
	v_fma_f32 v117, v122, v106, v117
	v_fma_f32 v118, v122, v107, v118
	v_fma_f32 v117, -v126, v107, v117
	v_fma_f32 v126, v126, v106, v118
	v_mov_b32_e32 v122, v117
	v_mul_f32_e32 v116, v109, v39
	v_fma_f32 v117, v108, v35, -v116
	v_mul_f32_e32 v116, v108, v39
	v_fma_f32 v118, v109, v35, v116
	v_fma_f32 v117, v123, v110, v117
	v_fma_f32 v118, v123, v111, v118
	v_fma_f32 v117, -v127, v111, v117
	v_fma_f32 v127, v127, v110, v118
	v_mov_b32_e32 v123, v117
	v_mul_f32_e32 v116, v97, v28
	v_fma_f32 v117, v96, v24, -v116
	v_mul_f32_e32 v116, v96, v28
	v_fma_f32 v118, v97, v24, v116
	v_fma_f32 v117, v120, v98, v117
	v_fma_f32 v118, v120, v99, v118
	v_fma_f32 v117, -v124, v99, v117
	v_fma_f32 v124, v124, v98, v118
	v_mov_b32_e32 v120, v117
	v_mul_f32_e32 v116, v101, v29
	v_fma_f32 v117, v100, v25, -v116
	v_mul_f32_e32 v116, v100, v29
	v_fma_f32 v118, v101, v25, v116
	v_fma_f32 v117, v121, v102, v117
	v_fma_f32 v118, v121, v103, v118
	v_fma_f32 v117, -v125, v103, v117
	v_fma_f32 v125, v125, v102, v118
	v_mov_b32_e32 v121, v117
	v_mul_f32_e32 v116, v105, v30
	v_fma_f32 v117, v104, v26, -v116
	v_mul_f32_e32 v116, v104, v30
	v_fma_f32 v118, v105, v26, v116
	v_fma_f32 v117, v122, v106, v117
	v_fma_f32 v118, v122, v107, v118
	v_fma_f32 v117, -v126, v107, v117
	v_fma_f32 v126, v126, v106, v118
	v_mov_b32_e32 v122, v117
	v_mul_f32_e32 v116, v109, v31
	v_fma_f32 v117, v108, v27, -v116
	v_mul_f32_e32 v116, v108, v31
	v_fma_f32 v118, v109, v27, v116
	v_fma_f32 v117, v123, v110, v117
	v_fma_f32 v118, v123, v111, v118
	v_fma_f32 v117, -v127, v111, v117
	v_fma_f32 v127, v127, v110, v118
	v_mov_b32_e32 v123, v117
	v_mul_f32_e32 v116, v97, v20
	v_fma_f32 v117, v96, v16, -v116
	v_mul_f32_e32 v116, v96, v20
	v_fma_f32 v118, v97, v16, v116
	v_fma_f32 v117, v120, v98, v117
	v_fma_f32 v118, v120, v99, v118
	v_fma_f32 v117, -v124, v99, v117
	v_fma_f32 v124, v124, v98, v118
	v_mov_b32_e32 v120, v117
	v_mul_f32_e32 v116, v101, v21
	v_fma_f32 v117, v100, v17, -v116
	v_mul_f32_e32 v116, v100, v21
	v_fma_f32 v118, v101, v17, v116
	v_fma_f32 v117, v121, v102, v117
	v_fma_f32 v118, v121, v103, v118
	v_fma_f32 v117, -v125, v103, v117
	v_fma_f32 v125, v125, v102, v118
	v_mov_b32_e32 v121, v117
	v_mul_f32_e32 v116, v105, v22
	v_fma_f32 v117, v104, v18, -v116
	v_mul_f32_e32 v116, v104, v22
	v_fma_f32 v118, v105, v18, v116
	v_fma_f32 v117, v122, v106, v117
	v_fma_f32 v118, v122, v107, v118
	v_fma_f32 v117, -v126, v107, v117
	v_fma_f32 v126, v126, v106, v118
	v_mov_b32_e32 v122, v117
	v_mul_f32_e32 v116, v109, v23
	v_fma_f32 v117, v108, v19, -v116
	v_mul_f32_e32 v116, v108, v23
	v_fma_f32 v118, v109, v19, v116
	v_fma_f32 v117, v123, v110, v117
	v_fma_f32 v118, v123, v111, v118
	v_fma_f32 v117, -v127, v111, v117
	v_fma_f32 v127, v127, v110, v118
	v_mov_b32_e32 v123, v117
	v_add_f32_dpp v120, v120, v120 row_ror:8 row_mask:0xf bank_mask:0xf
	v_add_f32_dpp v121, v121, v121 row_ror:8 row_mask:0xf bank_mask:0xf
	v_add_f32_dpp v122, v122, v122 row_ror:8 row_mask:0xf bank_mask:0xf
	v_add_f32_dpp v123, v123, v123 row_ror:8 row_mask:0xf bank_mask:0xf
	v_add_f32_dpp v124, v124, v124 row_ror:8 row_mask:0xf bank_mask:0xf
	v_add_f32_dpp v125, v125, v125 row_ror:8 row_mask:0xf bank_mask:0xf
	v_add_f32_dpp v126, v126, v126 row_ror:8 row_mask:0xf bank_mask:0xf
	v_add_f32_dpp v127, v127, v127 row_ror:8 row_mask:0xf bank_mask:0xf
	v_add_f32_dpp v120, v120, v120 row_ror:4 row_mask:0xf bank_mask:0xf
	v_add_f32_dpp v121, v121, v121 row_ror:4 row_mask:0xf bank_mask:0xf
	v_add_f32_dpp v122, v122, v122 row_ror:4 row_mask:0xf bank_mask:0xf
	v_add_f32_dpp v123, v123, v123 row_ror:4 row_mask:0xf bank_mask:0xf
	v_add_f32_dpp v124, v124, v124 row_ror:4 row_mask:0xf bank_mask:0xf
	v_add_f32_dpp v125, v125, v125 row_ror:4 row_mask:0xf bank_mask:0xf
	v_add_f32_dpp v126, v126, v126 row_ror:4 row_mask:0xf bank_mask:0xf
	v_add_f32_dpp v127, v127, v127 row_ror:4 row_mask:0xf bank_mask:0xf
	v_add_f32_dpp v120, v120, v120 row_ror:2 row_mask:0xf bank_mask:0xf
	v_add_f32_dpp v121, v121, v121 row_ror:2 row_mask:0xf bank_mask:0xf
	v_add_f32_dpp v122, v122, v122 row_ror:2 row_mask:0xf bank_mask:0xf
	v_add_f32_dpp v123, v123, v123 row_ror:2 row_mask:0xf bank_mask:0xf
	v_add_f32_dpp v124, v124, v124 row_ror:2 row_mask:0xf bank_mask:0xf
	v_add_f32_dpp v125, v125, v125 row_ror:2 row_mask:0xf bank_mask:0xf
	v_add_f32_dpp v126, v126, v126 row_ror:2 row_mask:0xf bank_mask:0xf
	v_add_f32_dpp v127, v127, v127 row_ror:2 row_mask:0xf bank_mask:0xf
	v_add_f32_dpp v120, v120, v120 row_ror:1 row_mask:0xf bank_mask:0xf
	v_add_f32_dpp v121, v121, v121 row_ror:1 row_mask:0xf bank_mask:0xf
	v_add_f32_dpp v122, v122, v122 row_ror:1 row_mask:0xf bank_mask:0xf
	v_add_f32_dpp v123, v123, v123 row_ror:1 row_mask:0xf bank_mask:0xf
	v_add_f32_dpp v124, v124, v124 row_ror:1 row_mask:0xf bank_mask:0xf
	v_add_f32_dpp v125, v125, v125 row_ror:1 row_mask:0xf bank_mask:0xf
	v_add_f32_dpp v126, v126, v126 row_ror:1 row_mask:0xf bank_mask:0xf
	v_add_f32_dpp v127, v127, v127 row_ror:1 row_mask:0xf bank_mask:0xf
	s_add_u32 s18, s36, 128
	s_addc_u32 s19, s37, 0
	v_mov_b32_e32 v128, v120
	v_mov_b32_e32 v129, v124
	v_mov_b32_e32 v130, v121
	v_mov_b32_e32 v131, v125
	v_mov_b32_e32 v132, v122
	v_mov_b32_e32 v133, v126
	v_mov_b32_e32 v134, v123
	v_mov_b32_e32 v135, v127
	s_mov_b32 exec_lo, 0x10001
	s_mov_b32 exec_hi, 0x10001
	global_store_dwordx4 v114, v[128:131], s[18:19]
	global_store_dwordx4 v114, v[132:135], s[18:19] offset:16
	s_mov_b64 exec, -1
	s_nop 1
	s_waitcnt vmcnt(4)
	v_cvt_pk_bf16_f32 v48, v48, v49
	v_cvt_pk_bf16_f32 v49, v50, v51
	v_cvt_pk_bf16_f32 v50, v52, v53
	v_cvt_pk_bf16_f32 v51, v54, v55
	v_cvt_pk_bf16_f32 v56, v56, v57
	v_cvt_pk_bf16_f32 v57, v58, v59
	v_cvt_pk_bf16_f32 v58, v60, v61
	v_cvt_pk_bf16_f32 v59, v62, v63
	s_mov_b32 exec_hi, 0
	global_load_dwordx4 v[64:67], v112, s[20:21]
	global_load_dwordx4 v[68:71], v112, s[20:21] offset:16
	global_load_dwordx4 v[72:75], v112, s[22:23]
	global_load_dwordx4 v[76:79], v112, s[22:23] offset:16
	s_mov_b64 exec, -1
	global_load_dwordx4 v[96:99], v113, s[24:25] offset:0
	global_load_dwordx4 v[100:103], v113, s[24:25] offset:1024
	global_load_dwordx4 v[104:107], v113, s[24:25] offset:2048
	global_load_dwordx4 v[108:111], v113, s[24:25] offset:3072
	v_mfma_f32_16x16x32_bf16 v[16:19], v[48:51], v[0:3], 0
	v_mfma_f32_16x16x32_bf16 v[20:23], v[56:59], v[0:3], 0
	v_mfma_f32_16x16x32_bf16 v[24:27], v[48:51], v[4:7], 0
	v_mfma_f32_16x16x32_bf16 v[28:31], v[56:59], v[4:7], 0
	v_mfma_f32_16x16x32_bf16 v[32:35], v[48:51], v[8:11], 0
	v_mfma_f32_16x16x32_bf16 v[36:39], v[56:59], v[8:11], 0
	v_mfma_f32_16x16x32_bf16 v[40:43], v[48:51], v[12:15], 0
	v_mfma_f32_16x16x32_bf16 v[44:47], v[56:59], v[12:15], 0
	s_waitcnt vmcnt(8)
	s_nop 7
	v_mul_f32_e32 v116, v81, v44
	v_fma_f32 v120, v80, v40, -v116
	v_mul_f32_e32 v116, v80, v44
	v_fma_f32 v124, v81, v40, v116
	v_mul_f32_e32 v116, v85, v45
	v_fma_f32 v121, v84, v41, -v116
	v_mul_f32_e32 v116, v84, v45
	v_fma_f32 v125, v85, v41, v116
	v_mul_f32_e32 v116, v89, v46
	v_fma_f32 v122, v88, v42, -v116
	v_mul_f32_e32 v116, v88, v46
	v_fma_f32 v126, v89, v42, v116
	v_mul_f32_e32 v116, v93, v47
	v_fma_f32 v123, v92, v43, -v116
	v_mul_f32_e32 v116, v92, v47
	v_fma_f32 v127, v93, v43, v116
	v_mul_f32_e32 v116, v81, v36
	v_fma_f32 v117, v80, v32, -v116
	v_mul_f32_e32 v116, v80, v36
	v_fma_f32 v118, v81, v32, v116
	v_fma_f32 v117, v120, v82, v117
	v_fma_f32 v118, v120, v83, v118
	v_fma_f32 v117, -v124, v83, v117
	v_fma_f32 v124, v124, v82, v118
	v_mov_b32_e32 v120, v117
	v_mul_f32_e32 v116, v85, v37
	v_fma_f32 v117, v84, v33, -v116
	v_mul_f32_e32 v116, v84, v37
	v_fma_f32 v118, v85, v33, v116
	v_fma_f32 v117, v121, v86, v117
	v_fma_f32 v118, v121, v87, v118
	v_fma_f32 v117, -v125, v87, v117
	v_fma_f32 v125, v125, v86, v118
	v_mov_b32_e32 v121, v117
	v_mul_f32_e32 v116, v89, v38
	v_fma_f32 v117, v88, v34, -v116
	v_mul_f32_e32 v116, v88, v38
	v_fma_f32 v118, v89, v34, v116
	v_fma_f32 v117, v122, v90, v117
	v_fma_f32 v118, v122, v91, v118
	v_fma_f32 v117, -v126, v91, v117
	v_fma_f32 v126, v126, v90, v118
	v_mov_b32_e32 v122, v117
	v_mul_f32_e32 v116, v93, v39
	v_fma_f32 v117, v92, v35, -v116
	v_mul_f32_e32 v116, v92, v39
	v_fma_f32 v118, v93, v35, v116
	v_fma_f32 v117, v123, v94, v117
	v_fma_f32 v118, v123, v95, v118
	v_fma_f32 v117, -v127, v95, v117
	v_fma_f32 v127, v127, v94, v118
	v_mov_b32_e32 v123, v117
	v_mul_f32_e32 v116, v81, v28
	v_fma_f32 v117, v80, v24, -v116
	v_mul_f32_e32 v116, v80, v28
	v_fma_f32 v118, v81, v24, v116
	v_fma_f32 v117, v120, v82, v117
	v_fma_f32 v118, v120, v83, v118
	v_fma_f32 v117, -v124, v83, v117
	v_fma_f32 v124, v124, v82, v118
	v_mov_b32_e32 v120, v117
	v_mul_f32_e32 v116, v85, v29
	v_fma_f32 v117, v84, v25, -v116
	v_mul_f32_e32 v116, v84, v29
	v_fma_f32 v118, v85, v25, v116
	v_fma_f32 v117, v121, v86, v117
	v_fma_f32 v118, v121, v87, v118
	v_fma_f32 v117, -v125, v87, v117
	v_fma_f32 v125, v125, v86, v118
	v_mov_b32_e32 v121, v117
	v_mul_f32_e32 v116, v89, v30
	v_fma_f32 v117, v88, v26, -v116
	v_mul_f32_e32 v116, v88, v30
	v_fma_f32 v118, v89, v26, v116
	v_fma_f32 v117, v122, v90, v117
	v_fma_f32 v118, v122, v91, v118
	v_fma_f32 v117, -v126, v91, v117
	v_fma_f32 v126, v126, v90, v118
	v_mov_b32_e32 v122, v117
	v_mul_f32_e32 v116, v93, v31
	v_fma_f32 v117, v92, v27, -v116
	v_mul_f32_e32 v116, v92, v31
	v_fma_f32 v118, v93, v27, v116
	v_fma_f32 v117, v123, v94, v117
	v_fma_f32 v118, v123, v95, v118
	v_fma_f32 v117, -v127, v95, v117
	v_fma_f32 v127, v127, v94, v118
	v_mov_b32_e32 v123, v117
	v_mul_f32_e32 v116, v81, v20
	v_fma_f32 v117, v80, v16, -v116
	v_mul_f32_e32 v116, v80, v20
	v_fma_f32 v118, v81, v16, v116
	v_fma_f32 v117, v120, v82, v117
	v_fma_f32 v118, v120, v83, v118
	v_fma_f32 v117, -v124, v83, v117
	v_fma_f32 v124, v124, v82, v118
	v_mov_b32_e32 v120, v117
	v_mul_f32_e32 v116, v85, v21
	v_fma_f32 v117, v84, v17, -v116
	v_mul_f32_e32 v116, v84, v21
	v_fma_f32 v118, v85, v17, v116
	v_fma_f32 v117, v121, v86, v117
	v_fma_f32 v118, v121, v87, v118
	v_fma_f32 v117, -v125, v87, v117
	v_fma_f32 v125, v125, v86, v118
	v_mov_b32_e32 v121, v117
	v_mul_f32_e32 v116, v89, v22
	v_fma_f32 v117, v88, v18, -v116
	v_mul_f32_e32 v116, v88, v22
	v_fma_f32 v118, v89, v18, v116
	v_fma_f32 v117, v122, v90, v117
	v_fma_f32 v118, v122, v91, v118
	v_fma_f32 v117, -v126, v91, v117
	v_fma_f32 v126, v126, v90, v118
	v_mov_b32_e32 v122, v117
	v_mul_f32_e32 v116, v93, v23
	v_fma_f32 v117, v92, v19, -v116
	v_mul_f32_e32 v116, v92, v23
	v_fma_f32 v118, v93, v19, v116
	v_fma_f32 v117, v123, v94, v117
	v_fma_f32 v118, v123, v95, v118
	v_fma_f32 v117, -v127, v95, v117
	v_fma_f32 v127, v127, v94, v118
	v_mov_b32_e32 v123, v117
	v_add_f32_dpp v120, v120, v120 row_ror:8 row_mask:0xf bank_mask:0xf
	v_add_f32_dpp v121, v121, v121 row_ror:8 row_mask:0xf bank_mask:0xf
	v_add_f32_dpp v122, v122, v122 row_ror:8 row_mask:0xf bank_mask:0xf
	v_add_f32_dpp v123, v123, v123 row_ror:8 row_mask:0xf bank_mask:0xf
	v_add_f32_dpp v124, v124, v124 row_ror:8 row_mask:0xf bank_mask:0xf
	v_add_f32_dpp v125, v125, v125 row_ror:8 row_mask:0xf bank_mask:0xf
	v_add_f32_dpp v126, v126, v126 row_ror:8 row_mask:0xf bank_mask:0xf
	v_add_f32_dpp v127, v127, v127 row_ror:8 row_mask:0xf bank_mask:0xf
	v_add_f32_dpp v120, v120, v120 row_ror:4 row_mask:0xf bank_mask:0xf
	v_add_f32_dpp v121, v121, v121 row_ror:4 row_mask:0xf bank_mask:0xf
	v_add_f32_dpp v122, v122, v122 row_ror:4 row_mask:0xf bank_mask:0xf
	v_add_f32_dpp v123, v123, v123 row_ror:4 row_mask:0xf bank_mask:0xf
	v_add_f32_dpp v124, v124, v124 row_ror:4 row_mask:0xf bank_mask:0xf
	v_add_f32_dpp v125, v125, v125 row_ror:4 row_mask:0xf bank_mask:0xf
	v_add_f32_dpp v126, v126, v126 row_ror:4 row_mask:0xf bank_mask:0xf
	v_add_f32_dpp v127, v127, v127 row_ror:4 row_mask:0xf bank_mask:0xf
	v_add_f32_dpp v120, v120, v120 row_ror:2 row_mask:0xf bank_mask:0xf
	v_add_f32_dpp v121, v121, v121 row_ror:2 row_mask:0xf bank_mask:0xf
	v_add_f32_dpp v122, v122, v122 row_ror:2 row_mask:0xf bank_mask:0xf
	v_add_f32_dpp v123, v123, v123 row_ror:2 row_mask:0xf bank_mask:0xf
	v_add_f32_dpp v124, v124, v124 row_ror:2 row_mask:0xf bank_mask:0xf
	v_add_f32_dpp v125, v125, v125 row_ror:2 row_mask:0xf bank_mask:0xf
	v_add_f32_dpp v126, v126, v126 row_ror:2 row_mask:0xf bank_mask:0xf
	v_add_f32_dpp v127, v127, v127 row_ror:2 row_mask:0xf bank_mask:0xf
	v_add_f32_dpp v120, v120, v120 row_ror:1 row_mask:0xf bank_mask:0xf
	v_add_f32_dpp v121, v121, v121 row_ror:1 row_mask:0xf bank_mask:0xf
	v_add_f32_dpp v122, v122, v122 row_ror:1 row_mask:0xf bank_mask:0xf
	v_add_f32_dpp v123, v123, v123 row_ror:1 row_mask:0xf bank_mask:0xf
	v_add_f32_dpp v124, v124, v124 row_ror:1 row_mask:0xf bank_mask:0xf
	v_add_f32_dpp v125, v125, v125 row_ror:1 row_mask:0xf bank_mask:0xf
	v_add_f32_dpp v126, v126, v126 row_ror:1 row_mask:0xf bank_mask:0xf
	v_add_f32_dpp v127, v127, v127 row_ror:1 row_mask:0xf bank_mask:0xf
	s_add_u32 s18, s36, 256
	s_addc_u32 s19, s37, 0
	v_mov_b32_e32 v128, v120
	v_mov_b32_e32 v129, v124
	v_mov_b32_e32 v130, v121
	v_mov_b32_e32 v131, v125
	v_mov_b32_e32 v132, v122
	v_mov_b32_e32 v133, v126
	v_mov_b32_e32 v134, v123
	v_mov_b32_e32 v135, v127
	s_mov_b32 exec_lo, 0x10001
	s_mov_b32 exec_hi, 0x10001
	global_store_dwordx4 v114, v[128:131], s[18:19]
	global_store_dwordx4 v114, v[132:135], s[18:19] offset:16
	s_mov_b64 exec, -1
	s_nop 1
	s_waitcnt vmcnt(4)
	v_cvt_pk_bf16_f32 v64, v64, v65
	v_cvt_pk_bf16_f32 v65, v66, v67
	v_cvt_pk_bf16_f32 v66, v68, v69
	v_cvt_pk_bf16_f32 v67, v70, v71
	v_cvt_pk_bf16_f32 v72, v72, v73
	v_cvt_pk_bf16_f32 v73, v74, v75
	v_cvt_pk_bf16_f32 v74, v76, v77
	v_cvt_pk_bf16_f32 v75, v78, v79
	s_nop 1
	v_mfma_f32_16x16x32_bf16 v[16:19], v[64:67], v[0:3], 0
	v_mfma_f32_16x16x32_bf16 v[20:23], v[72:75], v[0:3], 0
	v_mfma_f32_16x16x32_bf16 v[24:27], v[64:67], v[4:7], 0
	v_mfma_f32_16x16x32_bf16 v[28:31], v[72:75], v[4:7], 0
	v_mfma_f32_16x16x32_bf16 v[32:35], v[64:67], v[8:11], 0
	v_mfma_f32_16x16x32_bf16 v[36:39], v[72:75], v[8:11], 0
	v_mfma_f32_16x16x32_bf16 v[40:43], v[64:67], v[12:15], 0
	v_mfma_f32_16x16x32_bf16 v[44:47], v[72:75], v[12:15], 0
	s_waitcnt vmcnt(0)
	s_nop 7
	v_mul_f32_e32 v116, v97, v44
	v_fma_f32 v120, v96, v40, -v116
	v_mul_f32_e32 v116, v96, v44
	v_fma_f32 v124, v97, v40, v116
	v_mul_f32_e32 v116, v101, v45
	v_fma_f32 v121, v100, v41, -v116
	v_mul_f32_e32 v116, v100, v45
	v_fma_f32 v125, v101, v41, v116
	v_mul_f32_e32 v116, v105, v46
	v_fma_f32 v122, v104, v42, -v116
	v_mul_f32_e32 v116, v104, v46
	v_fma_f32 v126, v105, v42, v116
	v_mul_f32_e32 v116, v109, v47
	v_fma_f32 v123, v108, v43, -v116
	v_mul_f32_e32 v116, v108, v47
	v_fma_f32 v127, v109, v43, v116
	v_mul_f32_e32 v116, v97, v36
	v_fma_f32 v117, v96, v32, -v116
	v_mul_f32_e32 v116, v96, v36
	v_fma_f32 v118, v97, v32, v116
	v_fma_f32 v117, v120, v98, v117
	v_fma_f32 v118, v120, v99, v118
	v_fma_f32 v117, -v124, v99, v117
	v_fma_f32 v124, v124, v98, v118
	v_mov_b32_e32 v120, v117
	v_mul_f32_e32 v116, v101, v37
	v_fma_f32 v117, v100, v33, -v116
	v_mul_f32_e32 v116, v100, v37
	v_fma_f32 v118, v101, v33, v116
	v_fma_f32 v117, v121, v102, v117
	v_fma_f32 v118, v121, v103, v118
	v_fma_f32 v117, -v125, v103, v117
	v_fma_f32 v125, v125, v102, v118
	v_mov_b32_e32 v121, v117
	v_mul_f32_e32 v116, v105, v38
	v_fma_f32 v117, v104, v34, -v116
	v_mul_f32_e32 v116, v104, v38
	v_fma_f32 v118, v105, v34, v116
	v_fma_f32 v117, v122, v106, v117
	v_fma_f32 v118, v122, v107, v118
	v_fma_f32 v117, -v126, v107, v117
	v_fma_f32 v126, v126, v106, v118
	v_mov_b32_e32 v122, v117
	v_mul_f32_e32 v116, v109, v39
	v_fma_f32 v117, v108, v35, -v116
	v_mul_f32_e32 v116, v108, v39
	v_fma_f32 v118, v109, v35, v116
	v_fma_f32 v117, v123, v110, v117
	v_fma_f32 v118, v123, v111, v118
	v_fma_f32 v117, -v127, v111, v117
	v_fma_f32 v127, v127, v110, v118
	v_mov_b32_e32 v123, v117
	v_mul_f32_e32 v116, v97, v28
	v_fma_f32 v117, v96, v24, -v116
	v_mul_f32_e32 v116, v96, v28
	v_fma_f32 v118, v97, v24, v116
	v_fma_f32 v117, v120, v98, v117
	v_fma_f32 v118, v120, v99, v118
	v_fma_f32 v117, -v124, v99, v117
	v_fma_f32 v124, v124, v98, v118
	v_mov_b32_e32 v120, v117
	v_mul_f32_e32 v116, v101, v29
	v_fma_f32 v117, v100, v25, -v116
	v_mul_f32_e32 v116, v100, v29
	v_fma_f32 v118, v101, v25, v116
	v_fma_f32 v117, v121, v102, v117
	v_fma_f32 v118, v121, v103, v118
	v_fma_f32 v117, -v125, v103, v117
	v_fma_f32 v125, v125, v102, v118
	v_mov_b32_e32 v121, v117
	v_mul_f32_e32 v116, v105, v30
	v_fma_f32 v117, v104, v26, -v116
	v_mul_f32_e32 v116, v104, v30
	v_fma_f32 v118, v105, v26, v116
	v_fma_f32 v117, v122, v106, v117
	v_fma_f32 v118, v122, v107, v118
	v_fma_f32 v117, -v126, v107, v117
	v_fma_f32 v126, v126, v106, v118
	v_mov_b32_e32 v122, v117
	v_mul_f32_e32 v116, v109, v31
	v_fma_f32 v117, v108, v27, -v116
	v_mul_f32_e32 v116, v108, v31
	v_fma_f32 v118, v109, v27, v116
	v_fma_f32 v117, v123, v110, v117
	v_fma_f32 v118, v123, v111, v118
	v_fma_f32 v117, -v127, v111, v117
	v_fma_f32 v127, v127, v110, v118
	v_mov_b32_e32 v123, v117
	v_mul_f32_e32 v116, v97, v20
	v_fma_f32 v117, v96, v16, -v116
	v_mul_f32_e32 v116, v96, v20
	v_fma_f32 v118, v97, v16, v116
	v_fma_f32 v117, v120, v98, v117
	v_fma_f32 v118, v120, v99, v118
	v_fma_f32 v117, -v124, v99, v117
	v_fma_f32 v124, v124, v98, v118
	v_mov_b32_e32 v120, v117
	v_mul_f32_e32 v116, v101, v21
	v_fma_f32 v117, v100, v17, -v116
	v_mul_f32_e32 v116, v100, v21
	v_fma_f32 v118, v101, v17, v116
	v_fma_f32 v117, v121, v102, v117
	v_fma_f32 v118, v121, v103, v118
	v_fma_f32 v117, -v125, v103, v117
	v_fma_f32 v125, v125, v102, v118
	v_mov_b32_e32 v121, v117
	v_mul_f32_e32 v116, v105, v22
	v_fma_f32 v117, v104, v18, -v116
	v_mul_f32_e32 v116, v104, v22
	v_fma_f32 v118, v105, v18, v116
	v_fma_f32 v117, v122, v106, v117
	v_fma_f32 v118, v122, v107, v118
	v_fma_f32 v117, -v126, v107, v117
	v_fma_f32 v126, v126, v106, v118
	v_mov_b32_e32 v122, v117
	v_mul_f32_e32 v116, v109, v23
	v_fma_f32 v117, v108, v19, -v116
	v_mul_f32_e32 v116, v108, v23
	v_fma_f32 v118, v109, v19, v116
	v_fma_f32 v117, v123, v110, v117
	v_fma_f32 v118, v123, v111, v118
	v_fma_f32 v117, -v127, v111, v117
	v_fma_f32 v127, v127, v110, v118
	v_mov_b32_e32 v123, v117
	v_add_f32_dpp v120, v120, v120 row_ror:8 row_mask:0xf bank_mask:0xf
	v_add_f32_dpp v121, v121, v121 row_ror:8 row_mask:0xf bank_mask:0xf
	v_add_f32_dpp v122, v122, v122 row_ror:8 row_mask:0xf bank_mask:0xf
	v_add_f32_dpp v123, v123, v123 row_ror:8 row_mask:0xf bank_mask:0xf
	v_add_f32_dpp v124, v124, v124 row_ror:8 row_mask:0xf bank_mask:0xf
	v_add_f32_dpp v125, v125, v125 row_ror:8 row_mask:0xf bank_mask:0xf
	v_add_f32_dpp v126, v126, v126 row_ror:8 row_mask:0xf bank_mask:0xf
	v_add_f32_dpp v127, v127, v127 row_ror:8 row_mask:0xf bank_mask:0xf
	v_add_f32_dpp v120, v120, v120 row_ror:4 row_mask:0xf bank_mask:0xf
	v_add_f32_dpp v121, v121, v121 row_ror:4 row_mask:0xf bank_mask:0xf
	v_add_f32_dpp v122, v122, v122 row_ror:4 row_mask:0xf bank_mask:0xf
	v_add_f32_dpp v123, v123, v123 row_ror:4 row_mask:0xf bank_mask:0xf
	v_add_f32_dpp v124, v124, v124 row_ror:4 row_mask:0xf bank_mask:0xf
	v_add_f32_dpp v125, v125, v125 row_ror:4 row_mask:0xf bank_mask:0xf
	v_add_f32_dpp v126, v126, v126 row_ror:4 row_mask:0xf bank_mask:0xf
	v_add_f32_dpp v127, v127, v127 row_ror:4 row_mask:0xf bank_mask:0xf
	v_add_f32_dpp v120, v120, v120 row_ror:2 row_mask:0xf bank_mask:0xf
	v_add_f32_dpp v121, v121, v121 row_ror:2 row_mask:0xf bank_mask:0xf
	v_add_f32_dpp v122, v122, v122 row_ror:2 row_mask:0xf bank_mask:0xf
	v_add_f32_dpp v123, v123, v123 row_ror:2 row_mask:0xf bank_mask:0xf
	v_add_f32_dpp v124, v124, v124 row_ror:2 row_mask:0xf bank_mask:0xf
	v_add_f32_dpp v125, v125, v125 row_ror:2 row_mask:0xf bank_mask:0xf
	v_add_f32_dpp v126, v126, v126 row_ror:2 row_mask:0xf bank_mask:0xf
	v_add_f32_dpp v127, v127, v127 row_ror:2 row_mask:0xf bank_mask:0xf
	v_add_f32_dpp v120, v120, v120 row_ror:1 row_mask:0xf bank_mask:0xf
	v_add_f32_dpp v121, v121, v121 row_ror:1 row_mask:0xf bank_mask:0xf
	v_add_f32_dpp v122, v122, v122 row_ror:1 row_mask:0xf bank_mask:0xf
	v_add_f32_dpp v123, v123, v123 row_ror:1 row_mask:0xf bank_mask:0xf
	v_add_f32_dpp v124, v124, v124 row_ror:1 row_mask:0xf bank_mask:0xf
	v_add_f32_dpp v125, v125, v125 row_ror:1 row_mask:0xf bank_mask:0xf
	v_add_f32_dpp v126, v126, v126 row_ror:1 row_mask:0xf bank_mask:0xf
	v_add_f32_dpp v127, v127, v127 row_ror:1 row_mask:0xf bank_mask:0xf
	s_add_u32 s18, s36, 384
	s_addc_u32 s19, s37, 0
	v_mov_b32_e32 v128, v120
	v_mov_b32_e32 v129, v124
	v_mov_b32_e32 v130, v121
	v_mov_b32_e32 v131, v125
	v_mov_b32_e32 v132, v122
	v_mov_b32_e32 v133, v126
	v_mov_b32_e32 v134, v123
	v_mov_b32_e32 v135, v127
	s_mov_b32 exec_lo, 0x10001
	s_mov_b32 exec_hi, 0x10001
	global_store_dwordx4 v114, v[128:131], s[18:19]
	global_store_dwordx4 v114, v[132:135], s[18:19] offset:16
	s_mov_b64 exec, -1
	s_nop 1

.LBB0_612:
	v_readlane_b32 s78, v247, 22
	s_bitcmp0_b32 s94, 0
	v_readlane_b32 s79, v247, 23
	v_readlane_b32 s24, v247, 28
	v_readlane_b32 s25, v244, 30
	v_readlane_b32 s26, v244, 31
	v_readlane_b32 s27, v245, 40
	s_cbranch_scc1 .LBB0_620
	v_readlane_b32 s0, v246, 3
	v_readlane_b32 s1, v246, 4
	s_andn2_b64 vcc, exec, s[0:1]
	s_cbranch_vccnz .LBB0_620
	v_readlane_b32 s0, v245, 21
	s_nop 0
	s_cmp_ge_u32 s0, 0x80
	s_cbranch_scc1 .Lstab_end
	s_lshr_b32 s1, s0, 2
	s_and_b32 s6, s0, 3
	s_lshl_b32 s7, s24, 5
	s_add_i32 s7, s7, s1
	s_bfe_u32 s8, s1, 0x10004
	s_mul_i32 s9, s8, 15
	v_and_b32_e32 v0, 15, v205
	v_lshrrev_b32_e32 v1, 4, v205
	v_xor_b32_e32 v2, s9, v0
	v_and_b32_e32 v3, 1, v2
	v_cmp_ne_u32_e64 s[10:11], 0, v3
	v_and_b32_e32 v3, 2, v2
	v_cmp_ne_u32_e64 s[12:13], 0, v3
	v_and_b32_e32 v3, 4, v2
	v_cmp_ne_u32_e64 s[14:15], 0, v3
	v_and_b32_e32 v3, 8, v2
	v_cmp_ne_u32_e64 s[16:17], 0, v3
	s_lshl_b32 s18, s7, 6
	s_lshl_b32 s19, s6, 4
	s_add_i32 s18, s18, s19
	s_lshl_b32 s18, s18, 2
	s_add_u32 s18, s18, 0x117a20
	s_add_u32 s20, s4, s18
	s_addc_u32 s21, s5, 0
	s_add_u32 s22, s20, 0x4000
	s_addc_u32 s23, s21, 0
	v_lshlrev_b32_e32 v3, 4, v1
	global_load_dwordx4 v[4:7], v3, s[20:21]
	global_load_dwordx4 v[8:11], v3, s[22:23]
	s_lshl_b32 s19, s7, 2
	s_add_u32 s19, s19, 0x11fa20
	s_add_u32 s0, s4, s19
	s_addc_u32 s1, s5, 0
	global_load_dword v12, v137, s[0:1]
	s_lshl_b32 s18, s7, 2
	s_add_i32 s18, s18, s6
	s_lshl_b32 s19, s18, 13
	s_add_u32 s19, s19, 0xf900000
	s_add_u32 s20, s4, s19
	s_addc_u32 s21, s5, 0
	s_lshl_b32 s19, s18, 12
	s_add_u32 s19, s19, 0xfc00000
	s_add_u32 s22, s4, s19
	s_addc_u32 s23, s5, 0
	v_lshlrev_b32_e32 v13, 4, v205
	v_lshlrev_b32_e32 v14, 4, v205
	v_add_u32_e32 v44, 0x1000, v13
	s_waitcnt vmcnt(0)
	v_mul_f32_e32 v12, 0x3fb8aa3b, v12
	v_exp_f32_e32 v12, v12
	s_nop 0
	v_mul_f32_e32 v15, v12, v4
	v_mul_f32_e32 v16, 0x3fb8aa3b, v15
	v_mul_f32_e32 v17, 0xbfb8aa3b, v15
	v_exp_f32_e32 v16, v16
	v_exp_f32_e32 v17, v17
	v_mul_f32_e32 v18, v12, v8
	v_mul_f32_e32 v19, 0.15915494, v18
	v_rndne_f32_e32 v19, v19
	v_fma_f32 v18, v18, 0.15915494, -v19
	v_cos_f32_e32 v19, v18
	v_sin_f32_e32 v20, v18
	s_nop 0
	v_mul_f32_e32 v22, v16, v19
	v_mul_f32_e32 v23, v16, v20
	v_mul_f32_e32 v24, v17, v19
	v_mul_f32_e64 v25, -v17, v20
	v_add_f32_e32 v26, -1.0, v22
	v_mul_f32_e32 v27, v8, v8
	v_fmac_f32_e32 v27, v4, v4
	v_rcp_f32_e32 v27, v27
	v_mul_f32_e32 v28, v26, v4
	v_fmac_f32_e32 v28, v23, v8
	v_mul_f32_e32 v29, v23, v4
	v_fma_f32 v29, -v26, v8, v29
	v_mul_f32_e32 v28, v28, v27
	v_mul_f32_e32 v29, v29, v27
	v_mul_f32_e32 v42, v23, v23
	v_mul_f32_e32 v43, v22, v23
	v_fma_f32 v30, v22, v22, -v42
	v_add_f32_e32 v31, v43, v43
	v_mul_f32_e32 v42, v31, v31
	v_mul_f32_e32 v43, v30, v31
	v_fma_f32 v32, v30, v30, -v42
	v_add_f32_e32 v33, v43, v43
	v_mul_f32_e32 v42, v33, v33
	v_mul_f32_e32 v43, v32, v33
	v_fma_f32 v34, v32, v32, -v42
	v_add_f32_e32 v35, v43, v43
	v_mul_f32_e32 v42, v35, v35
	v_mul_f32_e32 v43, v34, v35
	v_fma_f32 v36, v34, v34, -v42
	v_add_f32_e32 v37, v43, v43
	v_mov_b32_e32 v38, 1.0
	v_mov_b32_e32 v39, 0
	v_mov_b32_e32 v40, 1.0
	v_mov_b32_e32 v41, 0
	v_mul_f32_e32 v15, v39, v23
	v_fma_f32 v42, v38, v22, -v15
	v_mul_f32_e32 v15, v38, v23
	v_fma_f32 v43, v39, v22, v15
	v_cndmask_b32_e64 v38, v38, v42, s[10:11]
	v_cndmask_b32_e64 v39, v39, v43, s[10:11]
	v_mul_f32_e32 v15, v41, v23
	v_fma_f32 v42, v40, v22, -v15
	v_mul_f32_e32 v15, v40, v23
	v_fma_f32 v43, v41, v22, v15
	v_cndmask_b32_e64 v40, v42, v40, s[10:11]
	v_cndmask_b32_e64 v41, v43, v41, s[10:11]
	v_mul_f32_e32 v15, v39, v31
	v_fma_f32 v42, v38, v30, -v15
	v_mul_f32_e32 v15, v38, v31
	v_fma_f32 v43, v39, v30, v15
	v_cndmask_b32_e64 v38, v38, v42, s[12:13]
	v_cndmask_b32_e64 v39, v39, v43, s[12:13]
	v_mul_f32_e32 v15, v41, v31
	v_fma_f32 v42, v40, v30, -v15
	v_mul_f32_e32 v15, v40, v31
	v_fma_f32 v43, v41, v30, v15
	v_cndmask_b32_e64 v40, v42, v40, s[12:13]
	v_cndmask_b32_e64 v41, v43, v41, s[12:13]
	v_mul_f32_e32 v15, v39, v33
	v_fma_f32 v42, v38, v32, -v15
	v_mul_f32_e32 v15, v38, v33
	v_fma_f32 v43, v39, v32, v15
	v_cndmask_b32_e64 v38, v38, v42, s[14:15]
	v_cndmask_b32_e64 v39, v39, v43, s[14:15]
	v_mul_f32_e32 v15, v41, v33
	v_fma_f32 v42, v40, v32, -v15
	v_mul_f32_e32 v15, v40, v33
	v_fma_f32 v43, v41, v32, v15
	v_cndmask_b32_e64 v40, v42, v40, s[14:15]
	v_cndmask_b32_e64 v41, v43, v41, s[14:15]
	v_mul_f32_e32 v15, v39, v35
	v_fma_f32 v42, v38, v34, -v15
	v_mul_f32_e32 v15, v38, v35
	v_fma_f32 v43, v39, v34, v15
	v_cndmask_b32_e64 v38, v38, v42, s[16:17]
	v_cndmask_b32_e64 v39, v39, v43, s[16:17]
	v_mul_f32_e32 v15, v41, v35
	v_fma_f32 v42, v40, v34, -v15
	v_mul_f32_e32 v15, v40, v35
	v_fma_f32 v43, v41, v34, v15
	v_cndmask_b32_e64 v40, v42, v40, s[16:17]
	v_cndmask_b32_e64 v41, v43, v41, s[16:17]
	v_mul_f32_e32 v42, v25, v25
	v_mul_f32_e32 v43, v24, v25
	v_fma_f32 v30, v24, v24, -v42
	v_add_f32_e32 v31, v43, v43
	v_mul_f32_e32 v42, v31, v31
	v_mul_f32_e32 v43, v30, v31
	v_fma_f32 v32, v30, v30, -v42
	v_add_f32_e32 v33, v43, v43
	v_mul_f32_e32 v42, v33, v33
	v_mul_f32_e32 v43, v32, v33
	v_fma_f32 v34, v32, v32, -v42
	v_add_f32_e32 v35, v43, v43
	v_mov_b32_e32 v16, 1.0
	v_mov_b32_e32 v17, 0
	v_mul_f32_e32 v15, v17, v25
	v_fma_f32 v42, v16, v24, -v15
	v_mul_f32_e32 v15, v16, v25
	v_fma_f32 v43, v17, v24, v15
	v_cndmask_b32_e64 v16, v16, v42, s[10:11]
	v_cndmask_b32_e64 v17, v17, v43, s[10:11]
	v_mul_f32_e32 v15, v17, v31
	v_fma_f32 v42, v16, v30, -v15
	v_mul_f32_e32 v15, v16, v31
	v_fma_f32 v43, v17, v30, v15
	v_cndmask_b32_e64 v16, v16, v42, s[12:13]
	v_cndmask_b32_e64 v17, v17, v43, s[12:13]
	v_mul_f32_e32 v15, v17, v33
	v_fma_f32 v42, v16, v32, -v15
	v_mul_f32_e32 v15, v16, v33
	v_fma_f32 v43, v17, v32, v15
	v_cndmask_b32_e64 v16, v16, v42, s[14:15]
	v_cndmask_b32_e64 v17, v17, v43, s[14:15]
	v_mul_f32_e32 v15, v17, v35
	v_fma_f32 v42, v16, v34, -v15
	v_mul_f32_e32 v15, v16, v35
	v_fma_f32 v43, v17, v34, v15
	v_cndmask_b32_e64 v16, v16, v42, s[16:17]
	v_cndmask_b32_e64 v17, v17, v43, s[16:17]
	v_mul_f32_e32 v15, v29, v17
	v_fma_f32 v18, v28, v16, -v15
	v_mul_f32_e32 v15, v28, v17
	v_fma_f32 v19, v29, v16, v15
	v_mul_f32_e32 v15, v29, v41
	v_fma_f32 v20, v28, v40, -v15
	v_mul_f32_e32 v15, v28, v41
	v_fma_f32 v21, v29, v40, v15
	global_store_dwordx2 v13, v[18:19], s[20:21] offset:0
	global_store_dwordx2 v13, v[38:39], s[20:21] offset:8
	global_store_dwordx2 v44, v[36:37], s[20:21] offset:0
	global_store_dwordx2 v44, v[22:23], s[20:21] offset:8
	global_store_dwordx2 v14, v[20:21], s[22:23] offset:0
	global_store_dwordx2 v14, v[36:37], s[22:23] offset:8
	s_nop 1
	v_mul_f32_e32 v15, v12, v5
	v_mul_f32_e32 v16, 0x3fb8aa3b, v15
	v_mul_f32_e32 v17, 0xbfb8aa3b, v15
	v_exp_f32_e32 v16, v16
	v_exp_f32_e32 v17, v17
	v_mul_f32_e32 v18, v12, v9
	v_mul_f32_e32 v19, 0.15915494, v18
	v_rndne_f32_e32 v19, v19
	v_fma_f32 v18, v18, 0.15915494, -v19
	v_cos_f32_e32 v19, v18
	v_sin_f32_e32 v20, v18
	s_nop 0
	v_mul_f32_e32 v22, v16, v19
	v_mul_f32_e32 v23, v16, v20
	v_mul_f32_e32 v24, v17, v19
	v_mul_f32_e64 v25, -v17, v20
	v_add_f32_e32 v26, -1.0, v22
	v_mul_f32_e32 v27, v9, v9
	v_fmac_f32_e32 v27, v5, v5
	v_rcp_f32_e32 v27, v27
	v_mul_f32_e32 v28, v26, v5
	v_fmac_f32_e32 v28, v23, v9
	v_mul_f32_e32 v29, v23, v5
	v_fma_f32 v29, -v26, v9, v29
	v_mul_f32_e32 v28, v28, v27
	v_mul_f32_e32 v29, v29, v27
	v_mul_f32_e32 v42, v23, v23
	v_mul_f32_e32 v43, v22, v23
	v_fma_f32 v30, v22, v22, -v42
	v_add_f32_e32 v31, v43, v43
	v_mul_f32_e32 v42, v31, v31
	v_mul_f32_e32 v43, v30, v31
	v_fma_f32 v32, v30, v30, -v42
	v_add_f32_e32 v33, v43, v43
	v_mul_f32_e32 v42, v33, v33
	v_mul_f32_e32 v43, v32, v33
	v_fma_f32 v34, v32, v32, -v42
	v_add_f32_e32 v35, v43, v43
	v_mul_f32_e32 v42, v35, v35
	v_mul_f32_e32 v43, v34, v35
	v_fma_f32 v36, v34, v34, -v42
	v_add_f32_e32 v37, v43, v43
	v_mov_b32_e32 v38, 1.0
	v_mov_b32_e32 v39, 0
	v_mov_b32_e32 v40, 1.0
	v_mov_b32_e32 v41, 0
	v_mul_f32_e32 v15, v39, v23
	v_fma_f32 v42, v38, v22, -v15
	v_mul_f32_e32 v15, v38, v23
	v_fma_f32 v43, v39, v22, v15
	v_cndmask_b32_e64 v38, v38, v42, s[10:11]
	v_cndmask_b32_e64 v39, v39, v43, s[10:11]
	v_mul_f32_e32 v15, v41, v23
	v_fma_f32 v42, v40, v22, -v15
	v_mul_f32_e32 v15, v40, v23
	v_fma_f32 v43, v41, v22, v15
	v_cndmask_b32_e64 v40, v42, v40, s[10:11]
	v_cndmask_b32_e64 v41, v43, v41, s[10:11]
	v_mul_f32_e32 v15, v39, v31
	v_fma_f32 v42, v38, v30, -v15
	v_mul_f32_e32 v15, v38, v31
	v_fma_f32 v43, v39, v30, v15
	v_cndmask_b32_e64 v38, v38, v42, s[12:13]
	v_cndmask_b32_e64 v39, v39, v43, s[12:13]
	v_mul_f32_e32 v15, v41, v31
	v_fma_f32 v42, v40, v30, -v15
	v_mul_f32_e32 v15, v40, v31
	v_fma_f32 v43, v41, v30, v15
	v_cndmask_b32_e64 v40, v42, v40, s[12:13]
	v_cndmask_b32_e64 v41, v43, v41, s[12:13]
	v_mul_f32_e32 v15, v39, v33
	v_fma_f32 v42, v38, v32, -v15
	v_mul_f32_e32 v15, v38, v33
	v_fma_f32 v43, v39, v32, v15
	v_cndmask_b32_e64 v38, v38, v42, s[14:15]
	v_cndmask_b32_e64 v39, v39, v43, s[14:15]
	v_mul_f32_e32 v15, v41, v33
	v_fma_f32 v42, v40, v32, -v15
	v_mul_f32_e32 v15, v40, v33
	v_fma_f32 v43, v41, v32, v15
	v_cndmask_b32_e64 v40, v42, v40, s[14:15]
	v_cndmask_b32_e64 v41, v43, v41, s[14:15]
	v_mul_f32_e32 v15, v39, v35
	v_fma_f32 v42, v38, v34, -v15
	v_mul_f32_e32 v15, v38, v35
	v_fma_f32 v43, v39, v34, v15
	v_cndmask_b32_e64 v38, v38, v42, s[16:17]
	v_cndmask_b32_e64 v39, v39, v43, s[16:17]
	v_mul_f32_e32 v15, v41, v35
	v_fma_f32 v42, v40, v34, -v15
	v_mul_f32_e32 v15, v40, v35
	v_fma_f32 v43, v41, v34, v15
	v_cndmask_b32_e64 v40, v42, v40, s[16:17]
	v_cndmask_b32_e64 v41, v43, v41, s[16:17]
	v_mul_f32_e32 v42, v25, v25
	v_mul_f32_e32 v43, v24, v25
	v_fma_f32 v30, v24, v24, -v42
	v_add_f32_e32 v31, v43, v43
	v_mul_f32_e32 v42, v31, v31
	v_mul_f32_e32 v43, v30, v31
	v_fma_f32 v32, v30, v30, -v42
	v_add_f32_e32 v33, v43, v43
	v_mul_f32_e32 v42, v33, v33
	v_mul_f32_e32 v43, v32, v33
	v_fma_f32 v34, v32, v32, -v42
	v_add_f32_e32 v35, v43, v43
	v_mov_b32_e32 v16, 1.0
	v_mov_b32_e32 v17, 0
	v_mul_f32_e32 v15, v17, v25
	v_fma_f32 v42, v16, v24, -v15
	v_mul_f32_e32 v15, v16, v25
	v_fma_f32 v43, v17, v24, v15
	v_cndmask_b32_e64 v16, v16, v42, s[10:11]
	v_cndmask_b32_e64 v17, v17, v43, s[10:11]
	v_mul_f32_e32 v15, v17, v31
	v_fma_f32 v42, v16, v30, -v15
	v_mul_f32_e32 v15, v16, v31
	v_fma_f32 v43, v17, v30, v15
	v_cndmask_b32_e64 v16, v16, v42, s[12:13]
	v_cndmask_b32_e64 v17, v17, v43, s[12:13]
	v_mul_f32_e32 v15, v17, v33
	v_fma_f32 v42, v16, v32, -v15
	v_mul_f32_e32 v15, v16, v33
	v_fma_f32 v43, v17, v32, v15
	v_cndmask_b32_e64 v16, v16, v42, s[14:15]
	v_cndmask_b32_e64 v17, v17, v43, s[14:15]
	v_mul_f32_e32 v15, v17, v35
	v_fma_f32 v42, v16, v34, -v15
	v_mul_f32_e32 v15, v16, v35
	v_fma_f32 v43, v17, v34, v15
	v_cndmask_b32_e64 v16, v16, v42, s[16:17]
	v_cndmask_b32_e64 v17, v17, v43, s[16:17]
	v_mul_f32_e32 v15, v29, v17
	v_fma_f32 v18, v28, v16, -v15
	v_mul_f32_e32 v15, v28, v17
	v_fma_f32 v19, v29, v16, v15
	v_mul_f32_e32 v15, v29, v41
	v_fma_f32 v20, v28, v40, -v15
	v_mul_f32_e32 v15, v28, v41
	v_fma_f32 v21, v29, v40, v15
	global_store_dwordx2 v13, v[18:19], s[20:21] offset:1024
	global_store_dwordx2 v13, v[38:39], s[20:21] offset:1032
	global_store_dwordx2 v44, v[36:37], s[20:21] offset:1024
	global_store_dwordx2 v44, v[22:23], s[20:21] offset:1032
	global_store_dwordx2 v14, v[20:21], s[22:23] offset:1024
	global_store_dwordx2 v14, v[36:37], s[22:23] offset:1032
	s_nop 1
	v_mul_f32_e32 v15, v12, v6
	v_mul_f32_e32 v16, 0x3fb8aa3b, v15
	v_mul_f32_e32 v17, 0xbfb8aa3b, v15
	v_exp_f32_e32 v16, v16
	v_exp_f32_e32 v17, v17
	v_mul_f32_e32 v18, v12, v10
	v_mul_f32_e32 v19, 0.15915494, v18
	v_rndne_f32_e32 v19, v19
	v_fma_f32 v18, v18, 0.15915494, -v19
	v_cos_f32_e32 v19, v18
	v_sin_f32_e32 v20, v18
	s_nop 0
	v_mul_f32_e32 v22, v16, v19
	v_mul_f32_e32 v23, v16, v20
	v_mul_f32_e32 v24, v17, v19
	v_mul_f32_e64 v25, -v17, v20
	v_add_f32_e32 v26, -1.0, v22
	v_mul_f32_e32 v27, v10, v10
	v_fmac_f32_e32 v27, v6, v6
	v_rcp_f32_e32 v27, v27
	v_mul_f32_e32 v28, v26, v6
	v_fmac_f32_e32 v28, v23, v10
	v_mul_f32_e32 v29, v23, v6
	v_fma_f32 v29, -v26, v10, v29
	v_mul_f32_e32 v28, v28, v27
	v_mul_f32_e32 v29, v29, v27
	v_mul_f32_e32 v42, v23, v23
	v_mul_f32_e32 v43, v22, v23
	v_fma_f32 v30, v22, v22, -v42
	v_add_f32_e32 v31, v43, v43
	v_mul_f32_e32 v42, v31, v31
	v_mul_f32_e32 v43, v30, v31
	v_fma_f32 v32, v30, v30, -v42
	v_add_f32_e32 v33, v43, v43
	v_mul_f32_e32 v42, v33, v33
	v_mul_f32_e32 v43, v32, v33
	v_fma_f32 v34, v32, v32, -v42
	v_add_f32_e32 v35, v43, v43
	v_mul_f32_e32 v42, v35, v35
	v_mul_f32_e32 v43, v34, v35
	v_fma_f32 v36, v34, v34, -v42
	v_add_f32_e32 v37, v43, v43
	v_mov_b32_e32 v38, 1.0
	v_mov_b32_e32 v39, 0
	v_mov_b32_e32 v40, 1.0
	v_mov_b32_e32 v41, 0
	v_mul_f32_e32 v15, v39, v23
	v_fma_f32 v42, v38, v22, -v15
	v_mul_f32_e32 v15, v38, v23
	v_fma_f32 v43, v39, v22, v15
	v_cndmask_b32_e64 v38, v38, v42, s[10:11]
	v_cndmask_b32_e64 v39, v39, v43, s[10:11]
	v_mul_f32_e32 v15, v41, v23
	v_fma_f32 v42, v40, v22, -v15
	v_mul_f32_e32 v15, v40, v23
	v_fma_f32 v43, v41, v22, v15
	v_cndmask_b32_e64 v40, v42, v40, s[10:11]
	v_cndmask_b32_e64 v41, v43, v41, s[10:11]
	v_mul_f32_e32 v15, v39, v31
	v_fma_f32 v42, v38, v30, -v15
	v_mul_f32_e32 v15, v38, v31
	v_fma_f32 v43, v39, v30, v15
	v_cndmask_b32_e64 v38, v38, v42, s[12:13]
	v_cndmask_b32_e64 v39, v39, v43, s[12:13]
	v_mul_f32_e32 v15, v41, v31
	v_fma_f32 v42, v40, v30, -v15
	v_mul_f32_e32 v15, v40, v31
	v_fma_f32 v43, v41, v30, v15
	v_cndmask_b32_e64 v40, v42, v40, s[12:13]
	v_cndmask_b32_e64 v41, v43, v41, s[12:13]
	v_mul_f32_e32 v15, v39, v33
	v_fma_f32 v42, v38, v32, -v15
	v_mul_f32_e32 v15, v38, v33
	v_fma_f32 v43, v39, v32, v15
	v_cndmask_b32_e64 v38, v38, v42, s[14:15]
	v_cndmask_b32_e64 v39, v39, v43, s[14:15]
	v_mul_f32_e32 v15, v41, v33
	v_fma_f32 v42, v40, v32, -v15
	v_mul_f32_e32 v15, v40, v33
	v_fma_f32 v43, v41, v32, v15
	v_cndmask_b32_e64 v40, v42, v40, s[14:15]
	v_cndmask_b32_e64 v41, v43, v41, s[14:15]
	v_mul_f32_e32 v15, v39, v35
	v_fma_f32 v42, v38, v34, -v15
	v_mul_f32_e32 v15, v38, v35
	v_fma_f32 v43, v39, v34, v15
	v_cndmask_b32_e64 v38, v38, v42, s[16:17]
	v_cndmask_b32_e64 v39, v39, v43, s[16:17]
	v_mul_f32_e32 v15, v41, v35
	v_fma_f32 v42, v40, v34, -v15
	v_mul_f32_e32 v15, v40, v35
	v_fma_f32 v43, v41, v34, v15
	v_cndmask_b32_e64 v40, v42, v40, s[16:17]
	v_cndmask_b32_e64 v41, v43, v41, s[16:17]
	v_mul_f32_e32 v42, v25, v25
	v_mul_f32_e32 v43, v24, v25
	v_fma_f32 v30, v24, v24, -v42
	v_add_f32_e32 v31, v43, v43
	v_mul_f32_e32 v42, v31, v31
	v_mul_f32_e32 v43, v30, v31
	v_fma_f32 v32, v30, v30, -v42
	v_add_f32_e32 v33, v43, v43
	v_mul_f32_e32 v42, v33, v33
	v_mul_f32_e32 v43, v32, v33
	v_fma_f32 v34, v32, v32, -v42
	v_add_f32_e32 v35, v43, v43
	v_mov_b32_e32 v16, 1.0
	v_mov_b32_e32 v17, 0
	v_mul_f32_e32 v15, v17, v25
	v_fma_f32 v42, v16, v24, -v15
	v_mul_f32_e32 v15, v16, v25
	v_fma_f32 v43, v17, v24, v15
	v_cndmask_b32_e64 v16, v16, v42, s[10:11]
	v_cndmask_b32_e64 v17, v17, v43, s[10:11]
	v_mul_f32_e32 v15, v17, v31
	v_fma_f32 v42, v16, v30, -v15
	v_mul_f32_e32 v15, v16, v31
	v_fma_f32 v43, v17, v30, v15
	v_cndmask_b32_e64 v16, v16, v42, s[12:13]
	v_cndmask_b32_e64 v17, v17, v43, s[12:13]
	v_mul_f32_e32 v15, v17, v33
	v_fma_f32 v42, v16, v32, -v15
	v_mul_f32_e32 v15, v16, v33
	v_fma_f32 v43, v17, v32, v15
	v_cndmask_b32_e64 v16, v16, v42, s[14:15]
	v_cndmask_b32_e64 v17, v17, v43, s[14:15]
	v_mul_f32_e32 v15, v17, v35
	v_fma_f32 v42, v16, v34, -v15
	v_mul_f32_e32 v15, v16, v35
	v_fma_f32 v43, v17, v34, v15
	v_cndmask_b32_e64 v16, v16, v42, s[16:17]
	v_cndmask_b32_e64 v17, v17, v43, s[16:17]
	v_mul_f32_e32 v15, v29, v17
	v_fma_f32 v18, v28, v16, -v15
	v_mul_f32_e32 v15, v28, v17
	v_fma_f32 v19, v29, v16, v15
	v_mul_f32_e32 v15, v29, v41
	v_fma_f32 v20, v28, v40, -v15
	v_mul_f32_e32 v15, v28, v41
	v_fma_f32 v21, v29, v40, v15
	global_store_dwordx2 v13, v[18:19], s[20:21] offset:2048
	global_store_dwordx2 v13, v[38:39], s[20:21] offset:2056
	global_store_dwordx2 v44, v[36:37], s[20:21] offset:2048
	global_store_dwordx2 v44, v[22:23], s[20:21] offset:2056
	global_store_dwordx2 v14, v[20:21], s[22:23] offset:2048
	global_store_dwordx2 v14, v[36:37], s[22:23] offset:2056
	s_nop 1
	v_mul_f32_e32 v15, v12, v7
	v_mul_f32_e32 v16, 0x3fb8aa3b, v15
	v_mul_f32_e32 v17, 0xbfb8aa3b, v15
	v_exp_f32_e32 v16, v16
	v_exp_f32_e32 v17, v17
	v_mul_f32_e32 v18, v12, v11
	v_mul_f32_e32 v19, 0.15915494, v18
	v_rndne_f32_e32 v19, v19
	v_fma_f32 v18, v18, 0.15915494, -v19
	v_cos_f32_e32 v19, v18
	v_sin_f32_e32 v20, v18
	s_nop 0
	v_mul_f32_e32 v22, v16, v19
	v_mul_f32_e32 v23, v16, v20
	v_mul_f32_e32 v24, v17, v19
	v_mul_f32_e64 v25, -v17, v20
	v_add_f32_e32 v26, -1.0, v22
	v_mul_f32_e32 v27, v11, v11
	v_fmac_f32_e32 v27, v7, v7
	v_rcp_f32_e32 v27, v27
	v_mul_f32_e32 v28, v26, v7
	v_fmac_f32_e32 v28, v23, v11
	v_mul_f32_e32 v29, v23, v7
	v_fma_f32 v29, -v26, v11, v29
	v_mul_f32_e32 v28, v28, v27
	v_mul_f32_e32 v29, v29, v27
	v_mul_f32_e32 v42, v23, v23
	v_mul_f32_e32 v43, v22, v23
	v_fma_f32 v30, v22, v22, -v42
	v_add_f32_e32 v31, v43, v43
	v_mul_f32_e32 v42, v31, v31
	v_mul_f32_e32 v43, v30, v31
	v_fma_f32 v32, v30, v30, -v42
	v_add_f32_e32 v33, v43, v43
	v_mul_f32_e32 v42, v33, v33
	v_mul_f32_e32 v43, v32, v33
	v_fma_f32 v34, v32, v32, -v42
	v_add_f32_e32 v35, v43, v43
	v_mul_f32_e32 v42, v35, v35
	v_mul_f32_e32 v43, v34, v35
	v_fma_f32 v36, v34, v34, -v42
	v_add_f32_e32 v37, v43, v43
	v_mov_b32_e32 v38, 1.0
	v_mov_b32_e32 v39, 0
	v_mov_b32_e32 v40, 1.0
	v_mov_b32_e32 v41, 0
	v_mul_f32_e32 v15, v39, v23
	v_fma_f32 v42, v38, v22, -v15
	v_mul_f32_e32 v15, v38, v23
	v_fma_f32 v43, v39, v22, v15
	v_cndmask_b32_e64 v38, v38, v42, s[10:11]
	v_cndmask_b32_e64 v39, v39, v43, s[10:11]
	v_mul_f32_e32 v15, v41, v23
	v_fma_f32 v42, v40, v22, -v15
	v_mul_f32_e32 v15, v40, v23
	v_fma_f32 v43, v41, v22, v15
	v_cndmask_b32_e64 v40, v42, v40, s[10:11]
	v_cndmask_b32_e64 v41, v43, v41, s[10:11]
	v_mul_f32_e32 v15, v39, v31
	v_fma_f32 v42, v38, v30, -v15
	v_mul_f32_e32 v15, v38, v31
	v_fma_f32 v43, v39, v30, v15
	v_cndmask_b32_e64 v38, v38, v42, s[12:13]
	v_cndmask_b32_e64 v39, v39, v43, s[12:13]
	v_mul_f32_e32 v15, v41, v31
	v_fma_f32 v42, v40, v30, -v15
	v_mul_f32_e32 v15, v40, v31
	v_fma_f32 v43, v41, v30, v15
	v_cndmask_b32_e64 v40, v42, v40, s[12:13]
	v_cndmask_b32_e64 v41, v43, v41, s[12:13]
	v_mul_f32_e32 v15, v39, v33
	v_fma_f32 v42, v38, v32, -v15
	v_mul_f32_e32 v15, v38, v33
	v_fma_f32 v43, v39, v32, v15
	v_cndmask_b32_e64 v38, v38, v42, s[14:15]
	v_cndmask_b32_e64 v39, v39, v43, s[14:15]
	v_mul_f32_e32 v15, v41, v33
	v_fma_f32 v42, v40, v32, -v15
	v_mul_f32_e32 v15, v40, v33
	v_fma_f32 v43, v41, v32, v15
	v_cndmask_b32_e64 v40, v42, v40, s[14:15]
	v_cndmask_b32_e64 v41, v43, v41, s[14:15]
	v_mul_f32_e32 v15, v39, v35
	v_fma_f32 v42, v38, v34, -v15
	v_mul_f32_e32 v15, v38, v35
	v_fma_f32 v43, v39, v34, v15
	v_cndmask_b32_e64 v38, v38, v42, s[16:17]
	v_cndmask_b32_e64 v39, v39, v43, s[16:17]
	v_mul_f32_e32 v15, v41, v35
	v_fma_f32 v42, v40, v34, -v15
	v_mul_f32_e32 v15, v40, v35
	v_fma_f32 v43, v41, v34, v15
	v_cndmask_b32_e64 v40, v42, v40, s[16:17]
	v_cndmask_b32_e64 v41, v43, v41, s[16:17]
	v_mul_f32_e32 v42, v25, v25
	v_mul_f32_e32 v43, v24, v25
	v_fma_f32 v30, v24, v24, -v42
	v_add_f32_e32 v31, v43, v43
	v_mul_f32_e32 v42, v31, v31
	v_mul_f32_e32 v43, v30, v31
	v_fma_f32 v32, v30, v30, -v42
	v_add_f32_e32 v33, v43, v43
	v_mul_f32_e32 v42, v33, v33
	v_mul_f32_e32 v43, v32, v33
	v_fma_f32 v34, v32, v32, -v42
	v_add_f32_e32 v35, v43, v43
	v_mov_b32_e32 v16, 1.0
	v_mov_b32_e32 v17, 0
	v_mul_f32_e32 v15, v17, v25
	v_fma_f32 v42, v16, v24, -v15
	v_mul_f32_e32 v15, v16, v25
	v_fma_f32 v43, v17, v24, v15
	v_cndmask_b32_e64 v16, v16, v42, s[10:11]
	v_cndmask_b32_e64 v17, v17, v43, s[10:11]
	v_mul_f32_e32 v15, v17, v31
	v_fma_f32 v42, v16, v30, -v15
	v_mul_f32_e32 v15, v16, v31
	v_fma_f32 v43, v17, v30, v15
	v_cndmask_b32_e64 v16, v16, v42, s[12:13]
	v_cndmask_b32_e64 v17, v17, v43, s[12:13]
	v_mul_f32_e32 v15, v17, v33
	v_fma_f32 v42, v16, v32, -v15
	v_mul_f32_e32 v15, v16, v33
	v_fma_f32 v43, v17, v32, v15
	v_cndmask_b32_e64 v16, v16, v42, s[14:15]
	v_cndmask_b32_e64 v17, v17, v43, s[14:15]
	v_mul_f32_e32 v15, v17, v35
	v_fma_f32 v42, v16, v34, -v15
	v_mul_f32_e32 v15, v16, v35
	v_fma_f32 v43, v17, v34, v15
	v_cndmask_b32_e64 v16, v16, v42, s[16:17]
	v_cndmask_b32_e64 v17, v17, v43, s[16:17]
	v_mul_f32_e32 v15, v29, v17
	v_fma_f32 v18, v28, v16, -v15
	v_mul_f32_e32 v15, v28, v17
	v_fma_f32 v19, v29, v16, v15
	v_mul_f32_e32 v15, v29, v41
	v_fma_f32 v20, v28, v40, -v15
	v_mul_f32_e32 v15, v28, v41
	v_fma_f32 v21, v29, v40, v15
	global_store_dwordx2 v13, v[18:19], s[20:21] offset:3072
	global_store_dwordx2 v13, v[38:39], s[20:21] offset:3080
	global_store_dwordx2 v44, v[36:37], s[20:21] offset:3072
	global_store_dwordx2 v44, v[22:23], s[20:21] offset:3080
	global_store_dwordx2 v14, v[20:21], s[22:23] offset:3072
	global_store_dwordx2 v14, v[36:37], s[22:23] offset:3080
	s_nop 1
